# plus EpiRes epilogue residual prefetch (rolling 7-deep, no store-serialised waits) and LRU pass-1 weight hoist + batched conv tap loads
# speedup vs baseline: 1.0260x; 1.0187x over previous
; __device__ __forceinline__ float log_sigmoid(float x) { return fminf(x, 0.f) - log1pf(expf(-fabsf(x))); }
; __device__ __forceinline__ void lru_gate_consts(LruGateC& gc, const Args& a, int l, int lane, int wave) { const int k = wave & 3, dir = wave >> 2;
; #pragma unroll
;     for (int ct = 0; ct < 2; ++ct) { const int ch = 64 * k + 32 * ct + (lane & 31); gc.ba[ct] = a.lru_ba[(l * 2 + dir) * 256 + ch]; gc.bx[ct] = a.lru_bx[(l * 2 + dir) * 256 + ch]; gc.lsl[ct] = 8.0f * log_sigmoid(a.lru_lam[(l * 2 + dir) * 256 + ch]); } }
.LBB0_549:
	v_readlane_b32 s0, v254, 22
	v_mov_b32_e32 v2, v212
	v_readlane_b32 s1, v254, 23
	s_andn2_b64 vcc, exec, s[0:1]
	v_readfirstlane_b32 s0, v2
	s_cbranch_vccnz .LBB0_576
	v_readlane_b32 s2, v253, 41
	s_lshl_b32 s1, s2, 9
	s_and_b32 s7, s0, 0xffffff00
	s_and_b32 s6, s0, 0xc0
	s_add_i32 s7, s7, s1
	v_and_b32_e32 v3, 31, v2
	s_or_b32 s1, s7, s6
	v_or_b32_e32 v4, s1, v3
	v_ashrrev_i32_e32 v5, 31, v4
	v_readlane_b32 s4, v253, 2
	v_lshlrev_b64 v[4:5], 2, v[4:5]
	v_readlane_b32 s5, v253, 3
	v_readlane_b32 s6, v253, 4
	v_readlane_b32 s7, v253, 5
	v_lshl_add_u64 v[6:7], s[4:5], 0, v[4:5]
	global_load_dword v0, v[6:7], off
	global_load_dword v8, v[6:7], off offset:128
	v_readlane_b32 s8, v253, 6
	v_readlane_b32 s9, v253, 7
	v_readlane_b32 s10, v253, 8
	v_readlane_b32 s11, v253, 9
	v_readlane_b32 s12, v253, 10
	v_readlane_b32 s13, v253, 11
	v_readlane_b32 s14, v253, 12
	v_readlane_b32 s15, v253, 13
	v_readlane_b32 s16, v253, 14
	v_readlane_b32 s17, v253, 15
	v_readlane_b32 s18, v253, 16
	v_readlane_b32 s19, v253, 17
	v_readlane_b32 s4, v253, 25
	v_readlane_b32 s14, v253, 35
	v_readlane_b32 s15, v253, 36
	v_readlane_b32 s18, v253, 39
	v_readlane_b32 s19, v253, 40
	v_lshl_add_u64 v[6:7], s[14:15], 0, v[4:5]
	v_readlane_b32 s6, v253, 27
	v_lshl_add_u64 v[4:5], s[18:19], 0, v[4:5]
	global_load_dword v136, v[6:7], off
	global_load_dword v137, v[6:7], off offset:128
	global_load_dword v138, v[4:5], off
	global_load_dword v139, v[4:5], off offset:128
	v_readlane_b32 s8, v253, 29
	s_lshl_b32 s1, s2, 12
	v_readlane_b32 s7, v253, 28
	v_readlane_b32 s9, v253, 30
	s_add_u32 s6, s8, s1
	v_readlane_b32 s3, v253, 42
	s_addc_u32 s7, s9, 0
	s_lshl_b32 s1, s2, 1
	s_bfe_u32 s8, s0, 0x20006
	s_ashr_i32 s0, s0, 8
	v_readlane_b32 s10, v253, 31
	v_readlane_b32 s11, v253, 32
	v_ashrrev_i32_e32 v142, 5, v2
	v_readlane_b32 s4, v255, 49
	v_ashrrev_i32_e32 v84, 8, v2
	v_ashrrev_i32_e32 v85, 31, v84
	v_readlane_b32 s5, v253, 26
	v_readlane_b32 s12, v253, 33
	v_readlane_b32 s13, v253, 34
	v_readlane_b32 s16, v253, 37
	v_readlane_b32 s17, v253, 38
	s_waitcnt vmcnt(5)
	v_mul_f32_e64 v5, |v0|, s35
	s_waitcnt vmcnt(4)
	v_mul_f32_e64 v7, |v8|, s35
	v_fma_f32 v9, |v0|, s35, -v5
	v_rndne_f32_e32 v10, v5
	v_fma_f32 v11, |v8|, s35, -v7
	v_rndne_f32_e32 v12, v7
	v_fma_f32 v9, |v0|, s37, v9
	v_sub_f32_e32 v5, v5, v10
	v_fma_f32 v11, |v8|, s37, v11
	v_sub_f32_e32 v7, v7, v12
	v_add_f32_e32 v5, v5, v9
	v_cvt_i32_f32_e32 v10, v10
	v_add_f32_e32 v7, v7, v11
	v_exp_f32_e32 v5, v5
	v_cvt_i32_f32_e32 v12, v12
	v_exp_f32_e32 v7, v7
	v_max_f32_e32 v4, v0, v0
	v_min_f32_e32 v9, 0, v4
	v_ldexp_f32 v4, v5, v10
	v_cmp_ngt_f32_e64 vcc, |v0|, s38
	v_ldexp_f32 v5, v7, v12
	v_max_f32_e32 v6, v8, v8
	v_cndmask_b32_e32 v4, 0, v4, vcc
	v_cmp_ngt_f32_e64 vcc, |v8|, s38
	v_min_f32_e32 v6, 0, v6
	s_nop 0
	v_cndmask_b32_e32 v5, 0, v5, vcc
	v_cmp_nlt_f32_e64 vcc, |v0|, s39
	s_nop 1
	v_cndmask_b32_e32 v0, v219, v4, vcc
	v_cmp_nlt_f32_e64 vcc, |v8|, s39
	v_add_f32_e32 v8, 1.0, v0
	v_frexp_mant_f32_e32 v12, v8
	v_cndmask_b32_e32 v7, v219, v5, vcc
	v_cvt_f64_f32_e32 v[4:5], v8
	v_add_f32_e32 v11, -1.0, v8
	v_frexp_exp_i32_f64_e32 v4, v[4:5]
	v_cmp_gt_f32_e32 vcc, s48, v12
	v_sub_f32_e32 v14, v11, v8
	v_sub_f32_e32 v11, v0, v11
	v_subbrev_co_u32_e32 v4, vcc, 0, v4, vcc
	v_add_f32_e32 v14, 1.0, v14
	v_sub_u32_e32 v12, 0, v4
	v_add_f32_e32 v11, v11, v14
	v_cvt_f32_i32_e32 v4, v4
	v_ldexp_f32 v8, v8, v12
	v_ldexp_f32 v11, v11, v12
	v_add_f32_e32 v12, -1.0, v8
	v_add_f32_e32 v14, 1.0, v8
	v_add_f32_e32 v15, 1.0, v12
	v_add_f32_e32 v16, -1.0, v14
	v_sub_f32_e32 v15, v8, v15
	v_sub_f32_e32 v8, v8, v16
	v_mul_f32_e32 v16, 0x3f317218, v4
	v_add_f32_e32 v15, v11, v15
	v_add_f32_e32 v8, v11, v8
	v_fma_f32 v11, v4, s49, -v16
	v_add_f32_e32 v17, v12, v15
	v_add_f32_e32 v18, v14, v8
	v_fmac_f32_e32 v11, 0xb102e308, v4
	v_sub_f32_e32 v4, v12, v17
	v_sub_f32_e32 v12, v14, v18
	v_rcp_f32_e32 v14, v18
	v_add_f32_e32 v19, v16, v11
	v_add_f32_e32 v8, v8, v12
	v_sub_f32_e32 v12, v19, v16
	v_sub_f32_e32 v11, v11, v12
	v_mul_f32_e32 v12, v17, v14
	v_add_f32_e32 v4, v15, v4
	v_mul_f32_e32 v15, v18, v12
	v_fma_f32 v16, v12, v18, -v15
	v_fmac_f32_e32 v16, v12, v8
	v_add_f32_e32 v20, v15, v16
	v_sub_f32_e32 v21, v17, v20
	v_sub_f32_e32 v15, v20, v15
	v_sub_f32_e32 v17, v17, v21
	v_sub_f32_e32 v15, v15, v16
	v_sub_f32_e32 v16, v17, v20
	v_add_f32_e32 v4, v4, v16
	v_add_f32_e32 v4, v15, v4
	v_add_f32_e32 v15, v21, v4
	v_mul_f32_e32 v16, v14, v15
	v_sub_f32_e32 v17, v21, v15
	v_mul_f32_e32 v20, v18, v16
	v_add_f32_e32 v4, v4, v17
	v_add_f32_e32 v17, v12, v16
	v_fma_f32 v18, v16, v18, -v20
	v_sub_f32_e32 v12, v17, v12
	v_fmac_f32_e32 v18, v16, v8
	v_sub_f32_e32 v8, v16, v12
	v_add_f32_e32 v12, v20, v18
	v_sub_f32_e32 v16, v12, v20
	v_sub_f32_e32 v20, v15, v12
	v_sub_f32_e32 v15, v15, v20
	v_sub_f32_e32 v12, v15, v12
	v_sub_f32_e32 v16, v16, v18
	v_add_f32_e32 v4, v4, v12
	v_add_f32_e32 v4, v16, v4
	v_add_f32_e32 v4, v20, v4
	v_mul_f32_e32 v4, v14, v4
	v_add_f32_e32 v4, v8, v4
	v_add_f32_e32 v8, v17, v4
	v_mul_f32_e32 v12, v8, v8
	v_fmamk_f32 v16, v12, 0x3e9b6dac, v217
	v_sub_f32_e32 v14, v8, v17
	v_ldexp_f32 v15, v8, 1
	v_mul_f32_e32 v8, v8, v12
	v_fmaak_f32 v12, v12, v16, 0x3f2aaada
	v_mul_f32_e32 v8, v8, v12
	v_add_f32_e32 v12, v15, v8
	v_sub_f32_e32 v4, v4, v14
	v_sub_f32_e32 v14, v12, v15
	v_ldexp_f32 v4, v4, 1
	v_sub_f32_e32 v8, v8, v14
	v_add_f32_e32 v4, v4, v8
	v_add_f32_e32 v8, v12, v4
	v_sub_f32_e32 v12, v8, v12
	v_add_f32_e32 v14, v19, v8
	v_sub_f32_e32 v4, v4, v12
	v_sub_f32_e32 v12, v14, v19
	v_sub_f32_e32 v15, v14, v12
	v_sub_f32_e32 v8, v8, v12
	v_add_f32_e32 v12, v11, v4
	v_sub_f32_e32 v15, v19, v15
	v_sub_f32_e32 v16, v12, v11
; #define LAS __attribute__((address_space(3)))
; __device__ __forceinline__ float log_sigmoid(float x) { return fminf(x, 0.f) - log1pf(expf(-fabsf(x))); }
; __device__ __forceinline__ void lru_gate_consts(LruGateC& gc, const Args& a, int l, int lane, int wave) { const int k = wave & 3, dir = wave >> 2;
; #pragma unroll
;     for (int ct = 0; ct < 2; ++ct) { const int ch = 64 * k + 32 * ct + (lane & 31); gc.ba[ct] = a.lru_ba[(l * 2 + dir) * 256 + ch]; gc.bx[ct] = a.lru_bx[(l * 2 + dir) * 256 + ch]; gc.lsl[ct] = 8.0f * log_sigmoid(a.lru_lam[(l * 2 + dir) * 256 + ch]); } }
; __device__ __forceinline__ void lru_pass1_unit(int cu4, const Args& a, int l, const bf16* LX, const bf16* WLRU, h2* AD, float2* LCS4, lds_t* lds, int tid, int lane, int wave, const LruGateC& gc) {
;     const int cu = cu4 >> 2, rt0 = cu4 & 3;
;     const int b = cu < 256 ? cu >> 5 : (cu - 256) >> 1, c = cu < 256 ? cu & 31 : 32 + ((cu - 256) & 1);
;     const int m0 = chunk_row0(b, c), ms = c < 32 ? b * SEQ : ML + b * CTXL, me = ms + (c < 32 ? SEQ : CTXL);
;     lds_t* XR = lds; LAS h2* ADL = (LAS h2*)(lds + 128 * LR_LDX);
;     { const int w8 = (tid & 31) * 8, tr = tid >> 5; float cw[4][8], cb[8];
; #pragma unroll
;         for (int j = 0; j < 4; ++j)
; #pragma unroll
;             for (int e = 0; e < 8; ++e) cw[j][e] = a.conv_w[(size_t)l * 1024 + j * 256 + w8 + e];
; #pragma unroll
;         for (int e = 0; e < 8; ++e) cb[e] = a.conv_b[l * 256 + w8 + e];
	v_add_f32_e32 v8, v8, v15
	v_sub_f32_e32 v15, v12, v16
	v_sub_f32_e32 v4, v4, v16
	v_sub_f32_e32 v11, v11, v15
	v_add_f32_e32 v8, v12, v8
	v_add_f32_e32 v4, v4, v11
	v_add_f32_e32 v11, v14, v8
	v_sub_f32_e32 v12, v11, v14
	v_sub_f32_e32 v8, v8, v12
	v_add_f32_e32 v4, v4, v8
	v_add_f32_e32 v4, v11, v4
	v_cmp_neq_f32_e32 vcc, s46, v0
	v_add_f32_e32 v10, 1.0, v7
	v_add_f32_e32 v13, -1.0, v10
	v_cndmask_b32_e32 v4, v219, v4, vcc
	v_cmp_lt_f32_e64 vcc, |v0|, s50
	v_sub_f32_e32 v5, v13, v10
	v_frexp_mant_f32_e32 v8, v10
	v_cndmask_b32_e32 v0, v4, v0, vcc
	v_sub_f32_e32 v0, v9, v0
	v_mul_f32_e32 v140, 0x41000000, v0
	v_add_f32_e32 v0, 1.0, v5
	v_sub_f32_e32 v4, v7, v13
	v_add_f32_e32 v0, v4, v0
	v_cvt_f64_f32_e32 v[4:5], v10
	v_frexp_exp_i32_f64_e32 v4, v[4:5]
	v_cmp_gt_f32_e32 vcc, s48, v8
	s_nop 1
	v_subbrev_co_u32_e32 v4, vcc, 0, v4, vcc
	v_sub_u32_e32 v5, 0, v4
	v_ldexp_f32 v8, v10, v5
	v_ldexp_f32 v0, v0, v5
	v_add_f32_e32 v5, -1.0, v8
	v_add_f32_e32 v11, 1.0, v8
	v_add_f32_e32 v9, 1.0, v5
	v_add_f32_e32 v12, -1.0, v11
	v_sub_f32_e32 v9, v8, v9
	v_sub_f32_e32 v8, v8, v12
	v_add_f32_e32 v9, v0, v9
	v_add_f32_e32 v0, v0, v8
	v_add_f32_e32 v8, v11, v0
	v_rcp_f32_e32 v12, v8
	v_add_f32_e32 v10, v5, v9
	v_sub_f32_e32 v5, v5, v10
	v_add_f32_e32 v5, v9, v5
	v_sub_f32_e32 v9, v11, v8
	v_add_f32_e32 v0, v0, v9
	v_mul_f32_e32 v9, v10, v12
	v_mul_f32_e32 v11, v8, v9
	v_fma_f32 v13, v9, v8, -v11
	v_fmac_f32_e32 v13, v9, v0
	v_add_f32_e32 v14, v11, v13
	v_sub_f32_e32 v15, v10, v14
	v_sub_f32_e32 v10, v10, v15
	v_sub_f32_e32 v11, v14, v11
	v_sub_f32_e32 v10, v10, v14
	v_add_f32_e32 v5, v5, v10
	v_sub_f32_e32 v10, v11, v13
	v_add_f32_e32 v5, v10, v5
	v_add_f32_e32 v10, v15, v5
	v_mul_f32_e32 v11, v12, v10
	v_mul_f32_e32 v13, v8, v11
	v_fma_f32 v8, v11, v8, -v13
	v_fmac_f32_e32 v8, v11, v0
	v_sub_f32_e32 v0, v15, v10
	v_add_f32_e32 v0, v5, v0
	v_add_f32_e32 v5, v13, v8
	v_sub_f32_e32 v14, v10, v5
	v_sub_f32_e32 v10, v10, v14
	v_sub_f32_e32 v13, v5, v13
	v_sub_f32_e32 v5, v10, v5
	v_add_f32_e32 v0, v0, v5
	v_sub_f32_e32 v5, v13, v8
	v_cvt_f32_i32_e32 v4, v4
	v_add_f32_e32 v0, v5, v0
	v_add_f32_e32 v5, v9, v11
	v_add_f32_e32 v0, v14, v0
	v_sub_f32_e32 v8, v5, v9
	v_mul_f32_e32 v0, v12, v0
	v_sub_f32_e32 v8, v11, v8
	v_add_f32_e32 v0, v8, v0
	v_mul_f32_e32 v11, 0x3f317218, v4
	v_add_f32_e32 v8, v5, v0
	v_fma_f32 v12, v4, s49, -v11
	v_mul_f32_e32 v9, v8, v8
	v_fmac_f32_e32 v12, 0xb102e308, v4
	v_sub_f32_e32 v4, v8, v5
	v_fmamk_f32 v10, v9, 0x3e9b6dac, v217
	v_sub_f32_e32 v0, v0, v4
	v_add_f32_e32 v4, v11, v12
	v_fmaak_f32 v10, v9, v10, 0x3f2aaada
	v_sub_f32_e32 v5, v4, v11
	v_ldexp_f32 v11, v8, 1
	v_mul_f32_e32 v8, v8, v9
	v_mul_f32_e32 v8, v8, v10
	v_add_f32_e32 v9, v11, v8
	v_sub_f32_e32 v10, v9, v11
	v_ldexp_f32 v0, v0, 1
	v_sub_f32_e32 v8, v8, v10
	v_add_f32_e32 v0, v0, v8
	v_add_f32_e32 v8, v9, v0
	v_sub_f32_e32 v9, v8, v9
	v_sub_f32_e32 v0, v0, v9
	v_add_f32_e32 v9, v4, v8
	v_sub_f32_e32 v10, v9, v4
	v_sub_f32_e32 v11, v9, v10
	v_sub_f32_e32 v5, v12, v5
	v_sub_f32_e32 v4, v4, v11
	v_sub_f32_e32 v8, v8, v10
	v_add_f32_e32 v4, v8, v4
	v_add_f32_e32 v8, v5, v0
	v_sub_f32_e32 v10, v8, v5
	v_sub_f32_e32 v11, v8, v10
	v_sub_f32_e32 v5, v5, v11
	v_sub_f32_e32 v0, v0, v10
	v_add_f32_e32 v4, v8, v4
	v_add_f32_e32 v0, v0, v5
	v_add_f32_e32 v5, v9, v4
	v_sub_f32_e32 v8, v5, v9
	v_sub_f32_e32 v4, v4, v8
	v_add_f32_e32 v0, v0, v4
	v_add_f32_e32 v0, v5, v0
	v_cmp_neq_f32_e32 vcc, s46, v7
	v_lshrrev_b32_e32 v10, 3, v2
	v_and_b32_e32 v144, 4, v10
	v_cndmask_b32_e32 v0, v219, v0, vcc
	v_cmp_lt_f32_e64 vcc, |v7|, s50
	v_and_b32_e32 v10, 0x3fffff00, v2
	v_mov_b32_e32 v12, 2
	v_cndmask_b32_e32 v0, v0, v7, vcc
	v_sub_f32_e32 v0, v6, v0
	v_mul_f32_e32 v141, 0x41000000, v0
	v_lshlrev_b32_e32 v0, 3, v2
	v_and_b32_e32 v4, 0xf8, v0
	v_lshlrev_b32_e32 v0, 2, v4
	v_lshl_add_u64 v[50:51], s[6:7], 0, v[0:1]
	v_lshl_or_b32 v0, s2, 8, v4
	v_readlane_b32 s2, v252, 39
	s_add_i32 s6, s0, s1
	v_lshl_add_u64 v[52:53], v[0:1], 2, s[10:11]
	v_lshlrev_b32_e32 v0, 1, v4
	v_readlane_b32 s3, v252, 40
	s_ashr_i32 s7, s6, 31
	v_add_u32_e32 v143, 0, v0
	v_lshl_add_u64 v[54:55], s[2:3], 0, v[0:1]
	v_and_b32_e32 v0, 31, v142
	s_lshl_b64 s[6:7], s[6:7], 9
	s_lshl_b32 s1, s8, 6
	v_mul_u32_u24_e32 v8, 0x210, v0
	s_or_b32 s6, s6, s1
	v_lshrrev_b32_e32 v0, 1, v2
; #define LAS __attribute__((address_space(3)))
; __device__ __forceinline__ unsigned pk2(float lo, float hi) { return f2bf(lo) | (f2bf(hi) << 16); }
; __device__ __forceinline__ void lru_pass1_unit(int cu4, const Args& a, int l, const bf16* LX, const bf16* WLRU, h2* AD, float2* LCS4, lds_t* lds, int tid, int lane, int wave, const LruGateC& gc) {
;     ...
;     { const int w8 = (tid & 31) * 8, tr = tid >> 5; float cw[4][8], cb[8];
; #pragma unroll
;         for (int j = 0; j < 4; ++j)
; #pragma unroll
;             for (int e = 0; e < 8; ++e) cw[j][e] = a.conv_w[(size_t)l * 1024 + j * 256 + w8 + e];
; #pragma unroll
;         for (int e = 0; e < 8; ++e) cb[e] = a.conv_b[l * 256 + w8 + e];
;         for (int i = 0; i < 2; ++i) { const int t = 32 * rt0 + tr + 16 * i; float acc[8];
; #pragma unroll
;             for (int e = 0; e < 8; ++e) acc[e] = cb[e];
; #pragma unroll
;             for (int j = 0; j < 4; ++j) { const int m = m0 + t + j - 2;
;                 if (m >= ms && m < me) { const v4u xv = *(const v4u*)(LX + (size_t)m * 256 + w8);
; #pragma unroll
;                     for (int e = 0; e < 4; ++e) { acc[2 * e] += bflo(xv[e]) * cw[j][2 * e]; acc[2 * e + 1] += bfhi(xv[e]) * cw[j][2 * e + 1]; } } }
;             v4u ow;
; #pragma unroll
;             for (int e = 0; e < 4; ++e) ow[e] = pk2(acc[2 * e], acc[2 * e + 1]);
;             *(LAS v4u*)(XR + (t & 31) * LR_LDX + w8 * 2) = ow; } }
;     __syncthreads();
;     const int k = wave & 3, dir = wave >> 2;
;     const float (&ba)[2] = gc.ba; const float (&bx)[2] = gc.bx; const float (&lsl)[2] = gc.lsl;
;     float At = 1.f, Ht = 0.f;
;     for (int rt = rt0; rt < rt0 + 1; ++rt) {
;         bf16x8 af[4];
; #pragma unroll
;         for (int ks = 0; ks < 4; ++ks) af[ks] = *(const LAS bf16x8*)(XR + (lane & 31) * LR_LDX + (64 * k + 16 * ks + 8 * (lane >> 5)) * 2);
; #pragma unroll
;         for (int ct = 0; ct < 2; ++ct) { f32x16 ga = {}, gx = {};
; #pragma unroll
;             for (int ks = 0; ks < 4; ++ks) { const bf16* wb = WLRU + (((size_t)(l * 2 + dir) * 2 * 4 + k) * 64 + 32 * ct + (lane & 31)) * 64 + 16 * ks + 8 * (lane >> 5);
;                 ga = __builtin_amdgcn_mfma_f32_32x32x16_bf16(af[ks], *(const bf16x8*)wb, ga, 0, 0, 0); gx = __builtin_amdgcn_mfma_f32_32x32x16_bf16(af[ks], *(const bf16x8*)(wb + 4 * 4096), gx, 0, 0, 0); }
	v_readlane_b32 s2, v252, 4
	v_or_b32_e32 v9, s1, v3
	s_lshl_b32 s1, s0, 10
	v_and_b32_e32 v0, 16, v0
	v_readlane_b32 s3, v252, 5
	s_add_i32 s10, s4, s1
	s_ashr_i32 s1, s0, 31
	v_or_b32_e32 v4, s6, v3
	v_mov_b32_e32 v5, s7
	v_lshl_add_u64 v[6:7], s[2:3], 0, v[0:1]
	s_lshl_b64 s[0:1], s[0:1], 10
	v_readlane_b32 s2, v252, 43
	v_readlane_b32 s3, v252, 44
	s_add_u32 s0, s2, s0
	v_lshlrev_b64 v[4:5], 7, v[4:5]
	s_addc_u32 s1, s3, s1
	v_lshl_add_u64 v[56:57], v[6:7], 0, v[4:5]
	v_lshlrev_b32_e32 v4, 2, v9
	v_mov_b32_e32 v5, v1
	v_lshl_add_u64 v[66:67], s[0:1], 0, v[4:5]
	s_mov_b64 s[0:1], 0x9000
	v_lshl_add_u64 v[70:71], v[56:57], 0, s[0:1]
	s_mov_b64 s[0:1], 0x1020
	v_lshl_add_u64 v[72:73], v[56:57], 0, s[0:1]
	s_mov_b64 s[0:1], 0x9020
	v_lshl_add_u64 v[74:75], v[56:57], 0, s[0:1]
	s_mov_b64 s[0:1], 0x1040
	s_lshl_b32 s8, s8, 7
	v_lshl_add_u64 v[76:77], v[56:57], 0, s[0:1]
	s_mov_b64 s[0:1], 0x9040
	v_lshlrev_b32_e32 v10, 2, v10
	v_lshlrev_b32_sdwa v12, v12, v2 dst_sel:DWORD dst_unused:UNUSED_PAD src0_sel:DWORD src1_sel:BYTE_0
	s_add_i32 s8, s8, 0
	v_lshl_add_u64 v[78:79], v[56:57], 0, s[0:1]
	s_mov_b64 s[0:1], 0x1060
	v_bfe_u32 v11, v2, 3, 3
	v_add3_u32 v145, s4, v10, v12
	v_mov_b32_e32 v10, s8
	s_mov_b64 s[8:9], 0x8020
	v_lshl_add_u64 v[80:81], v[56:57], 0, s[0:1]
	s_mov_b64 s[0:1], 0x9060
	v_mad_u32_u24 v10, v3, s51, v10
	v_lshl_add_u64 v[60:61], v[56:57], 0, s[8:9]
	s_mov_b64 s[8:9], 0x8040
	v_or_b32_e32 v148, 1, v144
	v_or_b32_e32 v149, 2, v144
	v_or_b32_e32 v150, 3, v11
	v_or_b32_e32 v152, 8, v144
	v_or_b32_e32 v153, 9, v144
	v_or_b32_e32 v154, 10, v144
	v_or_b32_e32 v155, 11, v11
	v_or_b32_e32 v157, 16, v144
	v_or_b32_e32 v158, 17, v144
	v_or_b32_e32 v159, 18, v144
	v_or_b32_e32 v160, 19, v11
	v_or_b32_e32 v162, 24, v144
	v_or_b32_e32 v163, 25, v144
	v_or_b32_e32 v164, 26, v144
	v_or_b32_e32 v165, 27, v11
	v_lshl_add_u64 v[82:83], v[56:57], 0, s[0:1]
	v_mov_b32_e32 v3, 3
	v_readlane_b32 s0, v252, 28
	v_cmp_lt_u32_e64 s[6:7], s34, v2
	v_lshl_add_u64 v[62:63], v[56:57], 0, s[8:9]
	s_mov_b64 s[8:9], 0x8060
	v_lshl_add_u32 v146, v9, 1, 0
	v_add_u32_e32 v6, s10, v4
	v_lshlrev_b32_e32 v4, 11, v144
	v_lshlrev_b32_e32 v5, 11, v148
	v_lshlrev_b32_e32 v7, 11, v149
	v_lshlrev_b32_e32 v9, 11, v150
	v_lshlrev_b32_e32 v12, 11, v152
	v_lshlrev_b32_e32 v13, 11, v153
	v_lshlrev_b32_e32 v14, 11, v154
	v_lshlrev_b32_e32 v15, 11, v155
	v_lshlrev_b32_e32 v16, 11, v157
	v_lshlrev_b32_e32 v17, 11, v158
	v_lshlrev_b32_e32 v18, 11, v159
	v_lshlrev_b32_e32 v19, 11, v160
	v_lshlrev_b32_e32 v20, 11, v162
	v_lshlrev_b32_e32 v21, 11, v163
	v_lshlrev_b32_e32 v22, 11, v164
	v_lshlrev_b32_e32 v11, 11, v165
	v_lshlrev_b32_sdwa v2, v3, v2 dst_sel:DWORD dst_unused:UNUSED_PAD src0_sel:DWORD src1_sel:BYTE_0
	v_mov_b32_e32 v3, v1
	v_readlane_b32 s1, v252, 29
	v_lshl_add_u64 v[58:59], v[56:57], 0, s[66:67]
	v_lshl_add_u64 v[64:65], v[56:57], 0, s[8:9]
	v_mul_u32_u24_e32 v147, 0x210, v144
	v_mul_u32_u24_e32 v151, 0x210, v150
	v_mul_u32_u24_e32 v156, 0x210, v155
	v_mul_u32_u24_e32 v161, 0x210, v160
	v_mul_u32_u24_e32 v166, 0x210, v165
	v_lshl_add_u64 v[68:69], v[56:57], 0, s[62:63]
	v_add_u32_e32 v167, 64, v146
	v_lshl_add_u64 v[86:87], s[0:1], 0, v[2:3]
	v_add_u32_e32 v168, v143, v8
	v_add_u32_e32 v0, v10, v0
	v_add_u32_e32 v169, v6, v4
	v_add_u32_e32 v170, v6, v5
	v_add_u32_e32 v171, v6, v7
	v_add_u32_e32 v172, v6, v9
	v_add_u32_e32 v173, v6, v12
	v_add_u32_e32 v174, v6, v13
	v_add_u32_e32 v175, v6, v14
	v_add_u32_e32 v176, v6, v15
	v_add_u32_e32 v177, v6, v16
	v_add_u32_e32 v178, v6, v17
	v_add_u32_e32 v179, v6, v18
	v_add_u32_e32 v180, v6, v19
	v_add_u32_e32 v181, v6, v20
	v_add_u32_e32 v182, v6, v21
	v_add_u32_e32 v183, v6, v22
	v_add_u32_e32 v184, v6, v11
	global_load_dwordx4 v[186:189], v[56:57], off
	global_load_dwordx4 v[190:193], v[56:57], off offset:32
	global_load_dwordx4 v[194:197], v[58:59], off
	global_load_dwordx4 v[202:205], v[60:61], off
	global_load_dwordx4 v[206:209], v[56:57], off offset:64
	global_load_dwordx4 v[226:229], v[62:63], off
	global_load_dwordx4 v[230:233], v[56:57], off offset:96
	global_load_dwordx4 v[234:237], v[64:65], off
	global_load_dwordx4 v[238:241], v[68:69], off
	global_load_dwordx4 v[242:245], v[70:71], off
	global_load_dwordx4 v[246:249], v[72:73], off
	s_mov_b32 s10, s79
	s_branch .LBB0_552

; __device__ __forceinline__ void lru_pass1_unit(int cu4, const Args& a, int l, const bf16* LX, const bf16* WLRU, h2* AD, float2* LCS4, lds_t* lds, int tid, int lane, int wave, const LruGateC& gc) {
;     ...
;         for (int i = 0; i < 2; ++i) { const int t = 32 * rt0 + tr + 16 * i; float acc[8];
; #pragma unroll
;             for (int e = 0; e < 8; ++e) acc[e] = cb[e];
; #pragma unroll
;             for (int j = 0; j < 4; ++j) { const int m = m0 + t + j - 2;
;                 if (m >= ms && m < me) { const v4u xv = *(const v4u*)(LX + (size_t)m * 256 + w8);
; #pragma unroll
;                     for (int e = 0; e < 4; ++e) { acc[2 * e] += bflo(xv[e]) * cw[j][2 * e]; acc[2 * e + 1] += bfhi(xv[e]) * cw[j][2 * e + 1]; } } }
.LBB0_556:
	global_load_dwordx4 v[2:5], v[52:53], off offset:16
	global_load_dwordx4 v[6:9], v[52:53], off
	global_load_dwordx4 v[26:29], v[50:51], off offset:1040
	global_load_dwordx4 v[30:33], v[50:51], off offset:1024
	global_load_dwordx4 v[18:21], v[50:51], off offset:2064
	global_load_dwordx4 v[22:25], v[50:51], off offset:2048
	global_load_dwordx4 v[10:13], v[50:51], off offset:3088
	global_load_dwordx4 v[14:17], v[50:51], off offset:3072
	global_load_dwordx4 v[34:37], v[50:51], off offset:16
	global_load_dwordx4 v[38:41], v[50:51], off
	s_and_b32 s8, s10, 3
	s_and_b64 s[18:19], s[0:1], exec
	s_cselect_b32 s9, s13, s14
	s_lshl_b32 s13, s9, 8
	s_add_i32 s13, s13, 0x8000
	s_and_b64 s[0:1], s[0:1], exec
	s_cselect_b32 s14, s15, s13
	s_lshl_b32 s13, s8, 5
	s_add_i32 s16, s12, -2
	v_add_u32_e32 v94, s13, v142
	s_add_i32 s15, s17, s14
	v_add_u32_e32 v48, s16, v94
	v_cmp_le_i32_e32 vcc, s14, v48
	v_cmp_gt_i32_e64 s[0:1], s15, v48
	s_and_b64 s[18:19], vcc, s[0:1]
	s_waitcnt vmcnt(9)
	v_mov_b64_e32 v[90:91], v[4:5]
	s_waitcnt vmcnt(8)
	v_mov_b32_e32 v46, v6
	v_mov_b32_e32 v47, v7
	v_mov_b32_e32 v44, v8
	v_mov_b32_e32 v45, v9
	v_mov_b32_e32 v42, v2
	v_mov_b32_e32 v43, v3
	v_mov_b32_e32 v88, v4
	v_mov_b32_e32 v89, v5
	v_mov_b32_e32 v100, v48
	v_cmp_le_i32_e32 vcc, s14, v100
	v_cmp_gt_i32_e64 s[20:21], s15, v100
	v_ashrrev_i32_e32 v101, 31, v100
	s_and_b64 s[20:21], vcc, s[20:21]
	v_lshlrev_b64 v[100:101], 9, v[100:101]
	v_lshl_add_u64 v[100:101], v[54:55], 0, v[100:101]
	s_and_saveexec_b64 s[22:23], s[20:21]
	global_load_dwordx4 v[100:103], v[100:101], off
	s_mov_b64 exec, s[22:23]
	v_add_u32_e32 v104, 1, v48
	v_cmp_le_i32_e32 vcc, s14, v104
	v_cmp_gt_i32_e64 s[20:21], s15, v104
	v_ashrrev_i32_e32 v105, 31, v104
	s_and_b64 s[20:21], vcc, s[20:21]
	v_lshlrev_b64 v[104:105], 9, v[104:105]
	v_lshl_add_u64 v[104:105], v[54:55], 0, v[104:105]
	s_and_saveexec_b64 s[22:23], s[20:21]
	global_load_dwordx4 v[104:107], v[104:105], off
	s_mov_b64 exec, s[22:23]
	v_add_u32_e32 v108, s12, v94
	v_cmp_le_i32_e32 vcc, s14, v108
	v_cmp_gt_i32_e64 s[20:21], s15, v108
	v_ashrrev_i32_e32 v109, 31, v108
	s_and_b64 s[20:21], vcc, s[20:21]
	v_lshlrev_b64 v[108:109], 9, v[108:109]
	v_lshl_add_u64 v[108:109], v[54:55], 0, v[108:109]
	s_and_saveexec_b64 s[22:23], s[20:21]
	global_load_dwordx4 v[108:111], v[108:109], off
	s_mov_b64 exec, s[22:23]
	v_add_u32_e32 v130, 3, v48
	v_cmp_le_i32_e32 vcc, s14, v130
	v_cmp_gt_i32_e64 s[20:21], s15, v130
	v_ashrrev_i32_e32 v131, 31, v130
	s_and_b64 s[20:21], vcc, s[20:21]
	v_lshlrev_b64 v[130:131], 9, v[130:131]
	v_lshl_add_u64 v[130:131], v[54:55], 0, v[130:131]
	s_and_saveexec_b64 s[22:23], s[20:21]
	global_load_dwordx4 v[130:133], v[130:131], off
	s_mov_b64 exec, s[22:23]
	v_add_u32_e32 v114, 16, v48
	v_cmp_le_i32_e32 vcc, s14, v114
	v_cmp_gt_i32_e64 s[20:21], s15, v114
	v_ashrrev_i32_e32 v115, 31, v114
	s_and_b64 s[20:21], vcc, s[20:21]
	v_lshlrev_b64 v[114:115], 9, v[114:115]
	v_lshl_add_u64 v[114:115], v[54:55], 0, v[114:115]
	s_and_saveexec_b64 s[22:23], s[20:21]
	global_load_dwordx4 v[114:117], v[114:115], off
	s_mov_b64 exec, s[22:23]
	v_add_u32_e32 v118, 17, v48
	v_cmp_le_i32_e32 vcc, s14, v118
	v_cmp_gt_i32_e64 s[20:21], s15, v118
	v_ashrrev_i32_e32 v119, 31, v118
	s_and_b64 s[20:21], vcc, s[20:21]
	v_lshlrev_b64 v[118:119], 9, v[118:119]
	v_lshl_add_u64 v[118:119], v[54:55], 0, v[118:119]
	s_and_saveexec_b64 s[22:23], s[20:21]
	global_load_dwordx4 v[118:121], v[118:119], off
	s_mov_b64 exec, s[22:23]
	v_add_u32_e32 v122, s12, v94
	v_add_u32_e32 v122, 16, v122
	v_cmp_le_i32_e32 vcc, s14, v122
	v_cmp_gt_i32_e64 s[20:21], s15, v122
	v_ashrrev_i32_e32 v123, 31, v122
	s_and_b64 s[20:21], vcc, s[20:21]
	v_lshlrev_b64 v[122:123], 9, v[122:123]
	v_lshl_add_u64 v[122:123], v[54:55], 0, v[122:123]
	s_and_saveexec_b64 s[22:23], s[20:21]
	global_load_dwordx4 v[122:125], v[122:123], off
	s_mov_b64 exec, s[22:23]
	v_add_u32_e32 v126, 19, v48
	v_cmp_le_i32_e32 vcc, s14, v126
	v_cmp_gt_i32_e64 s[20:21], s15, v126
	v_ashrrev_i32_e32 v127, 31, v126
	s_and_b64 s[20:21], vcc, s[20:21]
	v_lshlrev_b64 v[126:127], 9, v[126:127]
	v_lshl_add_u64 v[126:127], v[54:55], 0, v[126:127]
	s_and_saveexec_b64 s[22:23], s[20:21]
	global_load_dwordx4 v[126:129], v[126:127], off
	s_mov_b64 exec, s[22:23]
	s_waitcnt vmcnt(0)
	s_and_saveexec_b64 s[0:1], s[18:19]
	s_cbranch_execz .LBB0_558
	v_ashrrev_i32_e32 v49, 31, v48
	v_lshlrev_b64 v[42:43], 9, v[48:49]
	v_lshl_add_u64 v[42:43], v[54:55], 0, v[42:43]
	s_waitcnt vmcnt(0)
	v_lshlrev_b32_e32 v90, 16, v103
	v_and_b32_e32 v91, 0xffff0000, v103
	v_lshlrev_b32_e32 v46, 16, v100
	v_and_b32_e32 v47, 0xffff0000, v100
	v_lshlrev_b32_e32 v42, 16, v101
	v_and_b32_e32 v43, 0xffff0000, v101
	v_lshlrev_b32_e32 v88, 16, v102
	v_and_b32_e32 v89, 0xffff0000, v102
	v_pk_fma_f32 v[90:91], v[36:37], v[90:91], v[4:5]
	v_pk_fma_f32 v[46:47], v[38:39], v[46:47], v[6:7]
	v_pk_fma_f32 v[44:45], v[40:41], v[42:43], v[8:9]
	v_pk_fma_f32 v[42:43], v[34:35], v[88:89], v[2:3]
	v_mov_b32_e32 v88, v90
	v_mov_b32_e32 v89, v91
.LBB0_558:
	s_or_b64 exec, exec, s[0:1]
	v_add_u32_e32 v92, 1, v48
	v_cmp_le_i32_e32 vcc, s14, v92
	v_cmp_gt_i32_e64 s[0:1], s15, v92
	s_and_b64 s[18:19], vcc, s[0:1]
	s_and_saveexec_b64 s[0:1], s[18:19]
	s_cbranch_execz .LBB0_560
	v_ashrrev_i32_e32 v93, 31, v92
	v_lshlrev_b64 v[88:89], 9, v[92:93]
	v_lshl_add_u64 v[88:89], v[54:55], 0, v[88:89]
	s_waitcnt vmcnt(0)
	v_lshlrev_b32_e32 v88, 16, v104
	v_and_b32_e32 v89, 0xffff0000, v104
	v_pk_fma_f32 v[46:47], v[30:31], v[88:89], v[46:47]
	v_lshlrev_b32_e32 v88, 16, v105
	v_and_b32_e32 v89, 0xffff0000, v105
	v_pk_fma_f32 v[44:45], v[32:33], v[88:89], v[44:45]
	v_lshlrev_b32_e32 v88, 16, v106
	v_and_b32_e32 v89, 0xffff0000, v106
	v_pk_fma_f32 v[42:43], v[26:27], v[88:89], v[42:43]
	v_lshlrev_b32_e32 v88, 16, v107
	v_and_b32_e32 v89, 0xffff0000, v107
	v_pk_fma_f32 v[88:89], v[28:29], v[88:89], v[90:91]
; #define LAS __attribute__((address_space(3)))
; __device__ __forceinline__ unsigned pk2(float lo, float hi) { return f2bf(lo) | (f2bf(hi) << 16); }
; __device__ __forceinline__ void lru_pass1_unit(int cu4, const Args& a, int l, const bf16* LX, const bf16* WLRU, h2* AD, float2* LCS4, lds_t* lds, int tid, int lane, int wave, const LruGateC& gc) {
;     ...
;         for (int i = 0; i < 2; ++i) { const int t = 32 * rt0 + tr + 16 * i; float acc[8];
; #pragma unroll
;             for (int e = 0; e < 8; ++e) acc[e] = cb[e];
; #pragma unroll
;             for (int j = 0; j < 4; ++j) { const int m = m0 + t + j - 2;
;                 if (m >= ms && m < me) { const v4u xv = *(const v4u*)(LX + (size_t)m * 256 + w8);
; #pragma unroll
;                     for (int e = 0; e < 4; ++e) { acc[2 * e] += bflo(xv[e]) * cw[j][2 * e]; acc[2 * e + 1] += bfhi(xv[e]) * cw[j][2 * e + 1]; } } }
;             v4u ow;
; #pragma unroll
;             for (int e = 0; e < 4; ++e) ow[e] = pk2(acc[2 * e], acc[2 * e + 1]);
;             *(LAS v4u*)(XR + (t & 31) * LR_LDX + w8 * 2) = ow; } }
.LBB0_560:
	s_or_b64 exec, exec, s[0:1]
	v_add_u32_e32 v90, s12, v94
	v_cmp_le_i32_e32 vcc, s14, v90
	v_cmp_gt_i32_e64 s[0:1], s15, v90
	s_and_b64 s[18:19], vcc, s[0:1]
	s_and_saveexec_b64 s[0:1], s[18:19]
	s_cbranch_execz .LBB0_562
	v_ashrrev_i32_e32 v91, 31, v90
	v_lshlrev_b64 v[90:91], 9, v[90:91]
	v_lshl_add_u64 v[90:91], v[54:55], 0, v[90:91]
	s_waitcnt vmcnt(0)
	v_lshlrev_b32_e32 v96, 16, v108
	v_and_b32_e32 v97, 0xffff0000, v108
	v_lshlrev_b32_e32 v90, 16, v109
	v_and_b32_e32 v91, 0xffff0000, v109
	v_pk_fma_f32 v[44:45], v[24:25], v[90:91], v[44:45]
	v_lshlrev_b32_e32 v90, 16, v110
	v_and_b32_e32 v91, 0xffff0000, v110
	v_pk_fma_f32 v[42:43], v[18:19], v[90:91], v[42:43]
	v_lshlrev_b32_e32 v90, 16, v111
	v_and_b32_e32 v91, 0xffff0000, v111
	v_pk_fma_f32 v[46:47], v[22:23], v[96:97], v[46:47]
	v_pk_fma_f32 v[88:89], v[20:21], v[90:91], v[88:89]
.LBB0_562:
	s_or_b64 exec, exec, s[0:1]
	v_add_u32_e32 v48, 3, v48
	v_cmp_le_i32_e32 vcc, s14, v48
	v_cmp_gt_i32_e64 s[0:1], s15, v48
	s_and_b64 s[18:19], vcc, s[0:1]
	s_and_saveexec_b64 s[0:1], s[18:19]
	s_cbranch_execz .LBB0_564
	v_ashrrev_i32_e32 v49, 31, v48
	v_lshlrev_b64 v[48:49], 9, v[48:49]
	v_lshl_add_u64 v[48:49], v[54:55], 0, v[48:49]
	s_waitcnt vmcnt(0)
	v_lshlrev_b32_e32 v48, 16, v130
	v_and_b32_e32 v49, 0xffff0000, v130
	v_pk_fma_f32 v[46:47], v[14:15], v[48:49], v[46:47]
	v_lshlrev_b32_e32 v48, 16, v131
	v_and_b32_e32 v49, 0xffff0000, v131
	v_pk_fma_f32 v[44:45], v[16:17], v[48:49], v[44:45]
	v_lshlrev_b32_e32 v48, 16, v132
	v_and_b32_e32 v49, 0xffff0000, v132
	v_pk_fma_f32 v[42:43], v[10:11], v[48:49], v[42:43]
	v_lshlrev_b32_e32 v48, 16, v133
	v_and_b32_e32 v49, 0xffff0000, v133
	v_pk_fma_f32 v[88:89], v[12:13], v[48:49], v[88:89]
.LBB0_564:
	s_or_b64 exec, exec, s[0:1]
	v_bfe_u32 v48, v46, 16, 1
	v_add3_u32 v46, v46, v48, s33
	v_bfe_u32 v48, v47, 16, 1
	v_lshrrev_b32_e32 v46, 16, v46
	v_add3_u32 v47, v47, v48, s33
	v_and_or_b32 v46, v47, s87, v46
	v_bfe_u32 v47, v44, 16, 1
	v_add3_u32 v44, v44, v47, s33
	v_bfe_u32 v47, v45, 16, 1
	v_lshrrev_b32_e32 v44, 16, v44
	v_add3_u32 v45, v45, v47, s33
	v_and_or_b32 v47, v45, s87, v44
	v_bfe_u32 v44, v42, 16, 1
	v_add3_u32 v42, v42, v44, s33
	v_bfe_u32 v44, v43, 16, 1
	v_lshrrev_b32_e32 v42, 16, v42
	v_add3_u32 v43, v43, v44, s33
	v_and_or_b32 v48, v43, s87, v42
	v_bfe_u32 v42, v88, 16, 1
	v_add3_u32 v42, v88, v42, s33
	v_bfe_u32 v43, v89, 16, 1
	v_lshrrev_b32_e32 v42, 16, v42
	v_add3_u32 v43, v89, v43, s33
	v_add_u32_e32 v44, 16, v94
	v_and_or_b32 v49, v43, s87, v42
	v_add_u32_e32 v42, s16, v44
	v_cmp_le_i32_e32 vcc, s14, v42
	v_cmp_gt_i32_e64 s[0:1], s15, v42
	s_and_b64 s[16:17], vcc, s[0:1]
	ds_write_b128 v168, v[46:49]
	s_and_saveexec_b64 s[0:1], s[16:17]
	s_cbranch_execz .LBB0_566
	v_ashrrev_i32_e32 v43, 31, v42
	v_lshlrev_b64 v[46:47], 9, v[42:43]
	v_lshl_add_u64 v[46:47], v[54:55], 0, v[46:47]
	s_waitcnt vmcnt(0)
	v_lshlrev_b32_e32 v88, 16, v114
	v_and_b32_e32 v89, 0xffff0000, v114
	v_pk_fma_f32 v[6:7], v[38:39], v[88:89], v[6:7]
	v_lshlrev_b32_e32 v38, 16, v115
	v_and_b32_e32 v39, 0xffff0000, v115
	v_pk_fma_f32 v[8:9], v[40:41], v[38:39], v[8:9]
	v_lshlrev_b32_e32 v38, 16, v116
	v_and_b32_e32 v39, 0xffff0000, v116
	v_pk_fma_f32 v[2:3], v[34:35], v[38:39], v[2:3]
	v_lshlrev_b32_e32 v34, 16, v117
	v_and_b32_e32 v35, 0xffff0000, v117
	v_pk_fma_f32 v[4:5], v[36:37], v[34:35], v[4:5]
.LBB0_566:
	s_or_b64 exec, exec, s[0:1]
	s_waitcnt vmcnt(1)
	v_add_u32_e32 v34, 1, v42
	v_cmp_le_i32_e32 vcc, s14, v34
	v_cmp_gt_i32_e64 s[0:1], s15, v34
	s_and_b64 s[16:17], vcc, s[0:1]
	s_and_saveexec_b64 s[0:1], s[16:17]
	s_cbranch_execz .LBB0_568
	v_ashrrev_i32_e32 v35, 31, v34
	v_lshlrev_b64 v[34:35], 9, v[34:35]
	v_lshl_add_u64 v[34:35], v[54:55], 0, v[34:35]
	s_waitcnt vmcnt(0)
	v_lshlrev_b32_e32 v38, 16, v118
	v_and_b32_e32 v39, 0xffff0000, v118
	v_pk_fma_f32 v[6:7], v[30:31], v[38:39], v[6:7]
	v_lshlrev_b32_e32 v30, 16, v119
	v_and_b32_e32 v31, 0xffff0000, v119
	v_pk_fma_f32 v[8:9], v[32:33], v[30:31], v[8:9]
	v_lshlrev_b32_e32 v30, 16, v120
	v_and_b32_e32 v31, 0xffff0000, v120
	v_pk_fma_f32 v[2:3], v[26:27], v[30:31], v[2:3]
	v_lshlrev_b32_e32 v26, 16, v121
	v_and_b32_e32 v27, 0xffff0000, v121
	v_pk_fma_f32 v[4:5], v[28:29], v[26:27], v[4:5]
.LBB0_568:
	s_or_b64 exec, exec, s[0:1]
	v_add_u32_e32 v26, s12, v44
	v_cmp_le_i32_e32 vcc, s14, v26
	v_cmp_gt_i32_e64 s[0:1], s15, v26
	s_and_b64 s[16:17], vcc, s[0:1]
	s_and_saveexec_b64 s[0:1], s[16:17]
	s_cbranch_execz .LBB0_570
	v_ashrrev_i32_e32 v27, 31, v26
	v_lshlrev_b64 v[26:27], 9, v[26:27]
	v_lshl_add_u64 v[26:27], v[54:55], 0, v[26:27]
	s_waitcnt vmcnt(0)
	v_lshlrev_b32_e32 v30, 16, v122
	v_and_b32_e32 v31, 0xffff0000, v122
	v_pk_fma_f32 v[6:7], v[22:23], v[30:31], v[6:7]
	v_lshlrev_b32_e32 v22, 16, v123
	v_and_b32_e32 v23, 0xffff0000, v123
	v_pk_fma_f32 v[8:9], v[24:25], v[22:23], v[8:9]
	v_lshlrev_b32_e32 v22, 16, v124
	v_and_b32_e32 v23, 0xffff0000, v124
	v_pk_fma_f32 v[2:3], v[18:19], v[22:23], v[2:3]
	v_lshlrev_b32_e32 v18, 16, v125
	v_and_b32_e32 v19, 0xffff0000, v125
	v_pk_fma_f32 v[4:5], v[20:21], v[18:19], v[4:5]
.LBB0_570:
	s_or_b64 exec, exec, s[0:1]
	v_add_u32_e32 v18, 3, v42
	v_cmp_le_i32_e32 vcc, s14, v18
	v_cmp_gt_i32_e64 s[0:1], s15, v18
	s_and_b64 s[14:15], vcc, s[0:1]
	s_and_saveexec_b64 s[0:1], s[14:15]
	s_cbranch_execz .LBB0_572
	v_ashrrev_i32_e32 v19, 31, v18
	v_lshlrev_b64 v[18:19], 9, v[18:19]
	v_lshl_add_u64 v[18:19], v[54:55], 0, v[18:19]
	s_waitcnt vmcnt(0)
	v_lshlrev_b32_e32 v22, 16, v126
	v_and_b32_e32 v23, 0xffff0000, v126
	v_pk_fma_f32 v[6:7], v[14:15], v[22:23], v[6:7]
	v_lshlrev_b32_e32 v14, 16, v127
	v_and_b32_e32 v15, 0xffff0000, v127
	v_pk_fma_f32 v[8:9], v[16:17], v[14:15], v[8:9]
	v_lshlrev_b32_e32 v14, 16, v128
	v_and_b32_e32 v15, 0xffff0000, v128
	v_pk_fma_f32 v[2:3], v[10:11], v[14:15], v[2:3]
	v_lshlrev_b32_e32 v10, 16, v129
	v_and_b32_e32 v11, 0xffff0000, v129
	v_pk_fma_f32 v[4:5], v[12:13], v[10:11], v[4:5]
; #define LAS __attribute__((address_space(3)))
; __device__ __forceinline__ float fsig(float x) { return __builtin_amdgcn_rcpf(1.0f + __expf(-x)); }
; __device__ __forceinline__ int crow16(int r, int hi) { return (r & 3) + 8 * (r >> 2) + 4 * hi; }
; __device__ __forceinline__ void lru_pass1_unit(int cu4, const Args& a, int l, const bf16* LX, const bf16* WLRU, h2* AD, float2* LCS4, lds_t* lds, int tid, int lane, int wave, const LruGateC& gc) {
;     ...
;             *(LAS v4u*)(XR + (t & 31) * LR_LDX + w8 * 2) = ow; } }
;     __syncthreads();
;     const int k = wave & 3, dir = wave >> 2;
;     const float (&ba)[2] = gc.ba; const float (&bx)[2] = gc.bx; const float (&lsl)[2] = gc.lsl;
;     float At = 1.f, Ht = 0.f;
;     for (int rt = rt0; rt < rt0 + 1; ++rt) {
;         bf16x8 af[4];
; #pragma unroll
;         for (int ks = 0; ks < 4; ++ks) af[ks] = *(const LAS bf16x8*)(XR + (lane & 31) * LR_LDX + (64 * k + 16 * ks + 8 * (lane >> 5)) * 2);
; #pragma unroll
;         for (int ct = 0; ct < 2; ++ct) { f32x16 ga = {}, gx = {};
; #pragma unroll
;             for (int ks = 0; ks < 4; ++ks) { const bf16* wb = WLRU + (((size_t)(l * 2 + dir) * 2 * 4 + k) * 64 + 32 * ct + (lane & 31)) * 64 + 16 * ks + 8 * (lane >> 5);
;                 ga = __builtin_amdgcn_mfma_f32_32x32x16_bf16(af[ks], *(const bf16x8*)wb, ga, 0, 0, 0); gx = __builtin_amdgcn_mfma_f32_32x32x16_bf16(af[ks], *(const bf16x8*)(wb + 4 * 4096), gx, 0, 0, 0); }
;             const int ch = 64 * k + 32 * ct + (lane & 31);
; #pragma unroll
;             for (int r = 0; r < 16; ++r) { const int row = crow16(r, lane >> 5);
;                 const float rg = fsig(ga[r] + ba[ct]), ig = fsig(gx[r] + bx[ct]); const float la = lsl[ct] * rg;
;                 const float a_ = __expf(la); const float oma = 1.0f - a_, dr = __builtin_amdgcn_sqrtf(oma * (1.0f + a_)) * ig * bf2f(*(const LAS unsigned short*)(XR + row * LR_LDX + ch * 2));
;                 h2 hv; hv[0] = (_Float16)oma; hv[1] = (_Float16)dr;
;                 ADL[row * 512 + dir * 256 + ch] = hv; AD[((size_t)(m0 + 32 * rt + row) * 2 + dir) * 256 + ch] = hv; } }
.LBB0_572:
	s_or_b64 exec, exec, s[0:1]
	v_bfe_u32 v10, v6, 16, 1
	v_add3_u32 v6, v6, v10, s33
	v_bfe_u32 v10, v7, 16, 1
	v_lshrrev_b32_e32 v6, 16, v6
	v_add3_u32 v7, v7, v10, s33
	v_and_or_b32 v6, v7, s87, v6
	v_bfe_u32 v7, v8, 16, 1
	v_add3_u32 v7, v8, v7, s33
	v_bfe_u32 v8, v9, 16, 1
	v_lshrrev_b32_e32 v7, 16, v7
	v_add3_u32 v8, v9, v8, s33
	v_and_or_b32 v7, v8, s87, v7
	v_bfe_u32 v8, v2, 16, 1
	v_add3_u32 v2, v2, v8, s33
	v_bfe_u32 v8, v3, 16, 1
	v_lshrrev_b32_e32 v2, 16, v2
	v_add3_u32 v3, v3, v8, s33
	v_and_or_b32 v8, v3, s87, v2
	v_bfe_u32 v2, v4, 16, 1
	v_add3_u32 v2, v4, v2, s33
	v_bfe_u32 v3, v5, 16, 1
	v_lshrrev_b32_e32 v2, 16, v2
	v_add3_u32 v3, v5, v3, s33
	v_and_or_b32 v9, v3, s87, v2
	v_and_b32_e32 v2, 31, v44
	v_mad_u32_u24 v2, v2, s51, v143
	ds_write_b128 v2, v[6:9]
	global_load_dwordx4 v[114:117], v[74:75], off
	global_load_dwordx4 v[118:121], v[76:77], off
	global_load_dwordx4 v[122:125], v[78:79], off
	global_load_dwordx4 v[126:129], v[80:81], off
	s_waitcnt lgkmcnt(0)
	s_barrier
	ds_read_b128 v[46:49], v0
	ds_read_b128 v[42:45], v0 offset:32
	s_waitcnt vmcnt(0)
	ds_read_b128 v[38:41], v0 offset:64
	ds_read_b128 v[34:37], v0 offset:96
	s_add_i32 s0, s12, s13
	s_waitcnt vmcnt(1) lgkmcnt(3)
	v_mfma_f32_32x32x16_bf16 v[18:33], v[46:49], v[186:189], 0
	s_waitcnt vmcnt(1) lgkmcnt(2)
	v_mfma_f32_32x32x16_bf16 v[18:33], v[42:45], v[190:193], v[18:33]
	s_waitcnt vmcnt(1)
	v_mfma_f32_32x32x16_bf16 v[2:17], v[46:49], v[194:197], 0
	s_waitcnt vmcnt(0)
	v_mfma_f32_32x32x16_bf16 v[2:17], v[42:45], v[202:205], v[2:17]
	s_waitcnt vmcnt(0) lgkmcnt(1)
	v_mfma_f32_32x32x16_bf16 v[18:33], v[38:41], v[206:209], v[18:33]
	s_waitcnt vmcnt(0)
	v_mfma_f32_32x32x16_bf16 v[2:17], v[38:41], v[226:229], v[2:17]
	s_waitcnt vmcnt(0) lgkmcnt(0)
	v_mfma_f32_32x32x16_bf16 v[18:33], v[34:37], v[230:233], v[18:33]
	s_nop 10
	v_add_f32_e32 v18, v136, v18
	v_mul_f32_e32 v18, 0xbfb8aa3b, v18
	v_exp_f32_e32 v18, v18
	s_waitcnt vmcnt(0)
	v_mfma_f32_32x32x16_bf16 v[2:17], v[34:37], v[234:237], v[2:17]
	v_add_f32_e32 v18, 1.0, v18
	v_rcp_f32_e32 v18, v18
	s_nop 9
	v_add_f32_e32 v2, v138, v2
	v_mul_f32_e32 v18, v140, v18
	v_mul_f32_e32 v18, 0x3fb8aa3b, v18
	v_mul_f32_e32 v2, 0xbfb8aa3b, v2
	v_exp_f32_e32 v18, v18
	v_exp_f32_e32 v2, v2
	v_add_f32_e32 v3, v138, v3
	v_mul_f32_e32 v3, 0xbfb8aa3b, v3
	v_sub_f32_e32 v88, 1.0, v18
	v_add_f32_e32 v18, 1.0, v18
	v_add_f32_e32 v2, 1.0, v2
	v_mul_f32_e32 v18, v88, v18
	v_rcp_f32_e32 v2, v2
	v_sqrt_f32_e32 v18, v18
	v_exp_f32_e32 v3, v3
	v_add_f32_e32 v4, v138, v4
	v_mul_f32_e32 v4, 0xbfb8aa3b, v4
	v_mul_f32_e32 v18, v2, v18
	v_add_u32_e32 v2, v146, v147
	ds_read_u16 v89, v2
	v_add_f32_e32 v3, 1.0, v3
	v_rcp_f32_e32 v3, v3
	v_exp_f32_e32 v4, v4
	s_waitcnt lgkmcnt(0)
	v_lshlrev_b32_e32 v89, 16, v89
	v_mul_f32_e32 v18, v18, v89
	v_cvt_pk_f16_f32 v18, v88, v18
	v_add_u32_e32 v88, s0, v144
	v_ashrrev_i32_e32 v89, 31, v88
	v_lshlrev_b64 v[88:89], 11, v[88:89]
	v_lshl_add_u64 v[92:93], v[66:67], 0, v[88:89]
	ds_write_b32 v169, v18
	global_store_dword v[92:93], v18, off
	v_add_f32_e32 v18, v136, v19
	v_mul_f32_e32 v18, 0xbfb8aa3b, v18
	v_exp_f32_e32 v18, v18
	v_add_f32_e32 v4, 1.0, v4
	v_rcp_f32_e32 v4, v4
	v_add_f32_e32 v18, 1.0, v18
	v_rcp_f32_e32 v18, v18
	s_nop 0
	v_mul_f32_e32 v18, v140, v18
	v_mul_f32_e32 v18, 0x3fb8aa3b, v18
	v_exp_f32_e32 v18, v18
	s_nop 0
	v_sub_f32_e32 v19, 1.0, v18
	v_add_f32_e32 v18, 1.0, v18
	v_mul_f32_e32 v18, v19, v18
	v_sqrt_f32_e32 v18, v18
	s_nop 0
	v_mul_f32_e32 v3, v3, v18
	ds_read_u16 v18, v2 offset:528
	s_waitcnt lgkmcnt(0)
	v_lshlrev_b32_e32 v18, 16, v18
	v_mul_f32_e32 v3, v3, v18
	v_add_u32_e32 v18, s0, v148
	v_cvt_pk_f16_f32 v3, v19, v3
	v_ashrrev_i32_e32 v19, 31, v18
	v_lshlrev_b64 v[18:19], 11, v[18:19]
	v_lshl_add_u64 v[90:91], v[66:67], 0, v[18:19]
	ds_write_b32 v170, v3
	global_store_dword v[90:91], v3, off
	v_add_f32_e32 v3, v136, v20
	v_mul_f32_e32 v3, 0xbfb8aa3b, v3
	v_exp_f32_e32 v3, v3
	s_nop 0
	v_add_f32_e32 v3, 1.0, v3
	v_rcp_f32_e32 v3, v3
	s_nop 0
	v_mul_f32_e32 v3, v140, v3
	v_mul_f32_e32 v3, 0x3fb8aa3b, v3
	v_exp_f32_e32 v3, v3
	s_nop 0
	v_sub_f32_e32 v18, 1.0, v3
	v_add_f32_e32 v3, 1.0, v3
	v_mul_f32_e32 v3, v18, v3
	v_sqrt_f32_e32 v3, v3
	s_nop 0
	v_mul_f32_e32 v3, v4, v3
	ds_read_u16 v4, v2 offset:1056
	s_waitcnt lgkmcnt(0)
	v_lshlrev_b32_e32 v4, 16, v4
	v_mul_f32_e32 v3, v3, v4
	v_cvt_pk_f16_f32 v3, v18, v3
	v_add_u32_e32 v18, s0, v149
	v_ashrrev_i32_e32 v19, 31, v18
	v_lshlrev_b64 v[18:19], 11, v[18:19]
	v_lshl_add_u64 v[88:89], v[66:67], 0, v[18:19]
	ds_write_b32 v171, v3
	global_store_dword v[88:89], v3, off
	v_add_f32_e32 v3, v136, v21
	v_mul_f32_e32 v3, 0xbfb8aa3b, v3
	v_exp_f32_e32 v3, v3
	v_add_f32_e32 v4, v138, v5
	v_mul_f32_e32 v4, 0xbfb8aa3b, v4
	v_exp_f32_e32 v4, v4
	v_add_f32_e32 v3, 1.0, v3
	v_rcp_f32_e32 v3, v3
	v_add_f32_e32 v4, 1.0, v4
	v_rcp_f32_e32 v4, v4
	v_mul_f32_e32 v3, v140, v3
	v_mul_f32_e32 v3, 0x3fb8aa3b, v3
	v_exp_f32_e32 v3, v3
	s_nop 0
	v_sub_f32_e32 v5, 1.0, v3
	v_add_f32_e32 v3, 1.0, v3
	v_mul_f32_e32 v3, v5, v3
	v_sqrt_f32_e32 v3, v3
	s_nop 0
	v_mul_f32_e32 v3, v4, v3
	v_add_u32_e32 v4, v146, v151
	ds_read_u16 v4, v4
	s_waitcnt lgkmcnt(0)
	v_lshlrev_b32_e32 v4, 16, v4
	v_mul_f32_e32 v3, v3, v4
	v_add_u32_e32 v4, s0, v150
	v_cvt_pk_f16_f32 v3, v5, v3
	v_ashrrev_i32_e32 v5, 31, v4
	v_lshlrev_b64 v[4:5], 11, v[4:5]
	v_lshl_add_u64 v[94:95], v[66:67], 0, v[4:5]
	ds_write_b32 v172, v3
	global_store_dword v[94:95], v3, off
	v_add_f32_e32 v3, v136, v22
	v_mul_f32_e32 v3, 0xbfb8aa3b, v3
	v_exp_f32_e32 v3, v3
	v_add_f32_e32 v4, v138, v6
	v_mul_f32_e32 v4, 0xbfb8aa3b, v4
	v_exp_f32_e32 v4, v4
	v_add_f32_e32 v3, 1.0, v3
	v_rcp_f32_e32 v3, v3
	v_add_f32_e32 v4, 1.0, v4
	v_rcp_f32_e32 v4, v4
	v_mul_f32_e32 v3, v140, v3
	v_mul_f32_e32 v3, 0x3fb8aa3b, v3
	v_exp_f32_e32 v3, v3
	s_nop 0
	v_sub_f32_e32 v5, 1.0, v3
	v_add_f32_e32 v3, 1.0, v3
	v_mul_f32_e32 v3, v5, v3
	v_sqrt_f32_e32 v3, v3
	s_nop 0
	v_mul_f32_e32 v3, v4, v3
	ds_read_u16 v4, v2 offset:4224
	s_waitcnt lgkmcnt(0)
; #define LAS __attribute__((address_space(3)))
; __device__ __forceinline__ float fsig(float x) { return __builtin_amdgcn_rcpf(1.0f + __expf(-x)); }
; __device__ __forceinline__ int crow16(int r, int hi) { return (r & 3) + 8 * (r >> 2) + 4 * hi; }
; __device__ __forceinline__ void lru_pass1_unit(int cu4, const Args& a, int l, const bf16* LX, const bf16* WLRU, h2* AD, float2* LCS4, lds_t* lds, int tid, int lane, int wave, const LruGateC& gc) {
;     ...
;             const int ch = 64 * k + 32 * ct + (lane & 31);
; #pragma unroll
;             for (int r = 0; r < 16; ++r) { const int row = crow16(r, lane >> 5);
;                 const float rg = fsig(ga[r] + ba[ct]), ig = fsig(gx[r] + bx[ct]); const float la = lsl[ct] * rg;
;                 const float a_ = __expf(la); const float oma = 1.0f - a_, dr = __builtin_amdgcn_sqrtf(oma * (1.0f + a_)) * ig * bf2f(*(const LAS unsigned short*)(XR + row * LR_LDX + ch * 2));
;                 h2 hv; hv[0] = (_Float16)oma; hv[1] = (_Float16)dr;
;                 ADL[row * 512 + dir * 256 + ch] = hv; AD[((size_t)(m0 + 32 * rt + row) * 2 + dir) * 256 + ch] = hv; } }
	v_lshlrev_b32_e32 v4, 16, v4
	v_mul_f32_e32 v3, v3, v4
	v_add_u32_e32 v4, s0, v152
	v_cvt_pk_f16_f32 v3, v5, v3
	v_ashrrev_i32_e32 v5, 31, v4
	v_lshlrev_b64 v[4:5], 11, v[4:5]
	v_lshl_add_u64 v[96:97], v[66:67], 0, v[4:5]
	ds_write_b32 v173, v3
	global_store_dword v[96:97], v3, off
	v_add_f32_e32 v3, v136, v23
	v_mul_f32_e32 v3, 0xbfb8aa3b, v3
	v_exp_f32_e32 v3, v3
	v_add_f32_e32 v4, v138, v7
	v_mul_f32_e32 v4, 0xbfb8aa3b, v4
	v_exp_f32_e32 v4, v4
	v_add_f32_e32 v3, 1.0, v3
	v_rcp_f32_e32 v3, v3
	v_add_f32_e32 v4, 1.0, v4
	v_rcp_f32_e32 v4, v4
	v_mul_f32_e32 v3, v140, v3
	v_mul_f32_e32 v3, 0x3fb8aa3b, v3
	v_exp_f32_e32 v3, v3
	s_nop 0
	v_sub_f32_e32 v5, 1.0, v3
	v_add_f32_e32 v3, 1.0, v3
	v_mul_f32_e32 v3, v5, v3
	v_sqrt_f32_e32 v3, v3
	s_nop 0
	v_mul_f32_e32 v3, v4, v3
	ds_read_u16 v4, v2 offset:4752
	s_waitcnt lgkmcnt(0)
	v_lshlrev_b32_e32 v4, 16, v4
	v_mul_f32_e32 v3, v3, v4
	v_add_u32_e32 v4, s0, v153
	v_cvt_pk_f16_f32 v3, v5, v3
	v_ashrrev_i32_e32 v5, 31, v4
	v_lshlrev_b64 v[4:5], 11, v[4:5]
	v_lshl_add_u64 v[98:99], v[66:67], 0, v[4:5]
	ds_write_b32 v174, v3
	global_store_dword v[98:99], v3, off
	v_add_f32_e32 v3, v136, v24
	v_mul_f32_e32 v3, 0xbfb8aa3b, v3
	v_exp_f32_e32 v3, v3
	v_add_f32_e32 v4, v138, v8
	v_mul_f32_e32 v4, 0xbfb8aa3b, v4
	v_exp_f32_e32 v4, v4
	v_add_f32_e32 v3, 1.0, v3
	v_rcp_f32_e32 v3, v3
	v_add_f32_e32 v4, 1.0, v4
	v_rcp_f32_e32 v4, v4
	v_mul_f32_e32 v3, v140, v3
	v_mul_f32_e32 v3, 0x3fb8aa3b, v3
	v_exp_f32_e32 v3, v3
	s_nop 0
	v_sub_f32_e32 v5, 1.0, v3
	v_add_f32_e32 v3, 1.0, v3
	v_mul_f32_e32 v3, v5, v3
	v_sqrt_f32_e32 v3, v3
	s_nop 0
	v_mul_f32_e32 v3, v4, v3
	ds_read_u16 v4, v2 offset:5280
	s_waitcnt lgkmcnt(0)
	v_lshlrev_b32_e32 v4, 16, v4
	v_mul_f32_e32 v3, v3, v4
	v_add_u32_e32 v4, s0, v154
	v_cvt_pk_f16_f32 v3, v5, v3
	v_ashrrev_i32_e32 v5, 31, v4
	v_lshlrev_b64 v[4:5], 11, v[4:5]
	v_lshl_add_u64 v[100:101], v[66:67], 0, v[4:5]
	ds_write_b32 v175, v3
	global_store_dword v[100:101], v3, off
	v_add_f32_e32 v3, v136, v25
	v_mul_f32_e32 v3, 0xbfb8aa3b, v3
	v_exp_f32_e32 v3, v3
	v_add_f32_e32 v4, v138, v9
	v_mul_f32_e32 v4, 0xbfb8aa3b, v4
	v_exp_f32_e32 v4, v4
	v_add_f32_e32 v3, 1.0, v3
	v_rcp_f32_e32 v3, v3
	v_add_f32_e32 v4, 1.0, v4
	v_rcp_f32_e32 v4, v4
	v_mul_f32_e32 v3, v140, v3
	v_mul_f32_e32 v3, 0x3fb8aa3b, v3
	v_exp_f32_e32 v3, v3
	s_nop 0
	v_sub_f32_e32 v5, 1.0, v3
	v_add_f32_e32 v3, 1.0, v3
	v_mul_f32_e32 v3, v5, v3
	v_sqrt_f32_e32 v3, v3
	s_nop 0
	v_mul_f32_e32 v3, v4, v3
	v_add_u32_e32 v4, v146, v156
	ds_read_u16 v4, v4
	s_waitcnt lgkmcnt(0)
	v_lshlrev_b32_e32 v4, 16, v4
	v_mul_f32_e32 v3, v3, v4
	v_add_u32_e32 v4, s0, v155
	v_cvt_pk_f16_f32 v3, v5, v3
	v_ashrrev_i32_e32 v5, 31, v4
	v_lshlrev_b64 v[4:5], 11, v[4:5]
	v_lshl_add_u64 v[102:103], v[66:67], 0, v[4:5]
	ds_write_b32 v176, v3
	global_store_dword v[102:103], v3, off
	v_add_f32_e32 v3, v136, v26
	v_mul_f32_e32 v3, 0xbfb8aa3b, v3
	v_exp_f32_e32 v3, v3
	v_add_f32_e32 v4, v138, v10
	v_mul_f32_e32 v4, 0xbfb8aa3b, v4
	v_exp_f32_e32 v4, v4
	v_add_f32_e32 v3, 1.0, v3
	v_rcp_f32_e32 v3, v3
	v_add_f32_e32 v4, 1.0, v4
	v_rcp_f32_e32 v4, v4
	v_mul_f32_e32 v3, v140, v3
	v_mul_f32_e32 v3, 0x3fb8aa3b, v3
	v_exp_f32_e32 v3, v3
	s_nop 0
	v_sub_f32_e32 v5, 1.0, v3
	v_add_f32_e32 v3, 1.0, v3
	v_mul_f32_e32 v3, v5, v3
	v_sqrt_f32_e32 v3, v3
	s_nop 0
	v_mul_f32_e32 v3, v4, v3
	ds_read_u16 v4, v2 offset:8448
	s_waitcnt lgkmcnt(0)
	v_lshlrev_b32_e32 v4, 16, v4
	v_mul_f32_e32 v3, v3, v4
	v_add_u32_e32 v4, s0, v157
	v_cvt_pk_f16_f32 v3, v5, v3
	v_ashrrev_i32_e32 v5, 31, v4
	v_lshlrev_b64 v[4:5], 11, v[4:5]
	v_lshl_add_u64 v[104:105], v[66:67], 0, v[4:5]
	ds_write_b32 v177, v3
	global_store_dword v[104:105], v3, off
	v_add_f32_e32 v3, v136, v27
	v_mul_f32_e32 v3, 0xbfb8aa3b, v3
	v_exp_f32_e32 v3, v3
	v_add_f32_e32 v4, v138, v11
	v_mul_f32_e32 v4, 0xbfb8aa3b, v4
	v_exp_f32_e32 v4, v4
	v_add_f32_e32 v3, 1.0, v3
	v_rcp_f32_e32 v3, v3
	v_add_f32_e32 v4, 1.0, v4
	v_rcp_f32_e32 v4, v4
	v_mul_f32_e32 v3, v140, v3
	v_mul_f32_e32 v3, 0x3fb8aa3b, v3
	v_exp_f32_e32 v3, v3
	s_nop 0
	v_sub_f32_e32 v5, 1.0, v3
	v_add_f32_e32 v3, 1.0, v3
	v_mul_f32_e32 v3, v5, v3
	v_sqrt_f32_e32 v3, v3
	s_nop 0
	v_mul_f32_e32 v3, v4, v3
	ds_read_u16 v4, v2 offset:8976
	s_waitcnt lgkmcnt(0)
	v_lshlrev_b32_e32 v4, 16, v4
	v_mul_f32_e32 v3, v3, v4
	v_add_u32_e32 v4, s0, v158
	v_cvt_pk_f16_f32 v3, v5, v3
	v_ashrrev_i32_e32 v5, 31, v4
	v_lshlrev_b64 v[4:5], 11, v[4:5]
	v_lshl_add_u64 v[106:107], v[66:67], 0, v[4:5]
	ds_write_b32 v178, v3
	global_store_dword v[106:107], v3, off
	v_add_f32_e32 v3, v136, v28
	v_mul_f32_e32 v3, 0xbfb8aa3b, v3
	v_exp_f32_e32 v3, v3
	v_add_f32_e32 v4, v138, v12
	v_mul_f32_e32 v4, 0xbfb8aa3b, v4
	v_exp_f32_e32 v4, v4
	v_add_f32_e32 v3, 1.0, v3
	v_rcp_f32_e32 v3, v3
	v_add_f32_e32 v4, 1.0, v4
	v_rcp_f32_e32 v4, v4
	v_mul_f32_e32 v3, v140, v3
	v_mul_f32_e32 v3, 0x3fb8aa3b, v3
	v_exp_f32_e32 v3, v3
	s_nop 0
	v_sub_f32_e32 v5, 1.0, v3
	v_add_f32_e32 v3, 1.0, v3
	v_mul_f32_e32 v3, v5, v3
	v_sqrt_f32_e32 v3, v3
	s_nop 0
	v_mul_f32_e32 v3, v4, v3
	ds_read_u16 v4, v2 offset:9504
	s_waitcnt lgkmcnt(0)
	v_lshlrev_b32_e32 v4, 16, v4
	v_mul_f32_e32 v3, v3, v4
	v_add_u32_e32 v4, s0, v159
	v_cvt_pk_f16_f32 v3, v5, v3
	v_ashrrev_i32_e32 v5, 31, v4
	v_lshlrev_b64 v[4:5], 11, v[4:5]
	v_lshl_add_u64 v[108:109], v[66:67], 0, v[4:5]
	ds_write_b32 v179, v3
	global_store_dword v[108:109], v3, off
	v_add_f32_e32 v3, v136, v29
	v_mul_f32_e32 v3, 0xbfb8aa3b, v3
	v_exp_f32_e32 v3, v3
	v_add_f32_e32 v4, v138, v13
	v_mul_f32_e32 v4, 0xbfb8aa3b, v4
	v_exp_f32_e32 v4, v4
	v_add_f32_e32 v3, 1.0, v3
	v_rcp_f32_e32 v3, v3
	v_add_f32_e32 v4, 1.0, v4
	v_rcp_f32_e32 v4, v4
	v_mul_f32_e32 v3, v140, v3
	v_mul_f32_e32 v3, 0x3fb8aa3b, v3
	v_exp_f32_e32 v3, v3
	s_nop 0
	v_sub_f32_e32 v5, 1.0, v3
	v_add_f32_e32 v3, 1.0, v3
	v_mul_f32_e32 v3, v5, v3
	v_sqrt_f32_e32 v3, v3
	s_nop 0
	v_mul_f32_e32 v3, v4, v3
	v_add_u32_e32 v4, v146, v161
	ds_read_u16 v4, v4
	s_waitcnt lgkmcnt(0)
; #define LAS __attribute__((address_space(3)))
; __device__ __forceinline__ float fsig(float x) { return __builtin_amdgcn_rcpf(1.0f + __expf(-x)); }
; __device__ __forceinline__ int crow16(int r, int hi) { return (r & 3) + 8 * (r >> 2) + 4 * hi; }
; __device__ __forceinline__ void lru_pass1_unit(int cu4, const Args& a, int l, const bf16* LX, const bf16* WLRU, h2* AD, float2* LCS4, lds_t* lds, int tid, int lane, int wave, const LruGateC& gc) {
;     ...
;         for (int ct = 0; ct < 2; ++ct) { f32x16 ga = {}, gx = {};
; #pragma unroll
;             for (int ks = 0; ks < 4; ++ks) { const bf16* wb = WLRU + (((size_t)(l * 2 + dir) * 2 * 4 + k) * 64 + 32 * ct + (lane & 31)) * 64 + 16 * ks + 8 * (lane >> 5);
;                 ga = __builtin_amdgcn_mfma_f32_32x32x16_bf16(af[ks], *(const bf16x8*)wb, ga, 0, 0, 0); gx = __builtin_amdgcn_mfma_f32_32x32x16_bf16(af[ks], *(const bf16x8*)(wb + 4 * 4096), gx, 0, 0, 0); }
;             const int ch = 64 * k + 32 * ct + (lane & 31);
; #pragma unroll
;             for (int r = 0; r < 16; ++r) { const int row = crow16(r, lane >> 5);
;                 const float rg = fsig(ga[r] + ba[ct]), ig = fsig(gx[r] + bx[ct]); const float la = lsl[ct] * rg;
;                 const float a_ = __expf(la); const float oma = 1.0f - a_, dr = __builtin_amdgcn_sqrtf(oma * (1.0f + a_)) * ig * bf2f(*(const LAS unsigned short*)(XR + row * LR_LDX + ch * 2));
;                 h2 hv; hv[0] = (_Float16)oma; hv[1] = (_Float16)dr;
;                 ADL[row * 512 + dir * 256 + ch] = hv; AD[((size_t)(m0 + 32 * rt + row) * 2 + dir) * 256 + ch] = hv; } }
	v_lshlrev_b32_e32 v4, 16, v4
	v_mul_f32_e32 v3, v3, v4
	v_add_u32_e32 v4, s0, v160
	v_cvt_pk_f16_f32 v3, v5, v3
	v_ashrrev_i32_e32 v5, 31, v4
	v_lshlrev_b64 v[4:5], 11, v[4:5]
	v_lshl_add_u64 v[110:111], v[66:67], 0, v[4:5]
	ds_write_b32 v180, v3
	global_store_dword v[110:111], v3, off
	v_add_f32_e32 v3, v136, v30
	v_mul_f32_e32 v3, 0xbfb8aa3b, v3
	v_exp_f32_e32 v3, v3
	v_add_f32_e32 v4, v138, v14
	v_mul_f32_e32 v4, 0xbfb8aa3b, v4
	v_exp_f32_e32 v4, v4
	v_add_f32_e32 v3, 1.0, v3
	v_rcp_f32_e32 v3, v3
	v_add_f32_e32 v4, 1.0, v4
	v_rcp_f32_e32 v4, v4
	v_mul_f32_e32 v3, v140, v3
	v_mul_f32_e32 v3, 0x3fb8aa3b, v3
	v_exp_f32_e32 v3, v3
	s_nop 0
	v_sub_f32_e32 v5, 1.0, v3
	v_add_f32_e32 v3, 1.0, v3
	v_mul_f32_e32 v3, v5, v3
	v_sqrt_f32_e32 v3, v3
	s_nop 0
	v_mul_f32_e32 v3, v4, v3
	ds_read_u16 v4, v2 offset:12672
	s_waitcnt lgkmcnt(0)
	v_lshlrev_b32_e32 v4, 16, v4
	v_mul_f32_e32 v3, v3, v4
	v_add_u32_e32 v4, s0, v162
	v_cvt_pk_f16_f32 v3, v5, v3
	v_ashrrev_i32_e32 v5, 31, v4
	v_lshlrev_b64 v[4:5], 11, v[4:5]
	v_lshl_add_u64 v[112:113], v[66:67], 0, v[4:5]
	ds_write_b32 v181, v3
	global_store_dword v[112:113], v3, off
	v_add_f32_e32 v3, v136, v31
	v_mul_f32_e32 v3, 0xbfb8aa3b, v3
	v_exp_f32_e32 v3, v3
	v_add_f32_e32 v4, v138, v15
	v_mul_f32_e32 v4, 0xbfb8aa3b, v4
	v_exp_f32_e32 v4, v4
	v_add_f32_e32 v3, 1.0, v3
	v_rcp_f32_e32 v3, v3
	v_add_f32_e32 v4, 1.0, v4
	v_rcp_f32_e32 v4, v4
	v_mul_f32_e32 v3, v140, v3
	v_mul_f32_e32 v3, 0x3fb8aa3b, v3
	v_exp_f32_e32 v3, v3
	s_nop 0
	v_sub_f32_e32 v5, 1.0, v3
	v_add_f32_e32 v3, 1.0, v3
	v_mul_f32_e32 v3, v5, v3
	v_sqrt_f32_e32 v3, v3
	s_nop 0
	v_mul_f32_e32 v3, v4, v3
	ds_read_u16 v4, v2 offset:13200
	s_waitcnt lgkmcnt(0)
	v_lshlrev_b32_e32 v4, 16, v4
	v_mul_f32_e32 v3, v3, v4
	v_add_u32_e32 v4, s0, v163
	v_cvt_pk_f16_f32 v3, v5, v3
	v_ashrrev_i32_e32 v5, 31, v4
	v_lshlrev_b64 v[4:5], 11, v[4:5]
	v_lshl_add_u64 v[130:131], v[66:67], 0, v[4:5]
	ds_write_b32 v182, v3
	global_store_dword v[130:131], v3, off
	v_add_f32_e32 v3, v136, v32
	v_mul_f32_e32 v3, 0xbfb8aa3b, v3
	v_exp_f32_e32 v3, v3
	v_add_f32_e32 v4, v138, v16
	v_mul_f32_e32 v4, 0xbfb8aa3b, v4
	v_exp_f32_e32 v4, v4
	v_add_f32_e32 v3, 1.0, v3
	v_rcp_f32_e32 v3, v3
	ds_read_u16 v2, v2 offset:13728
	v_add_f32_e32 v4, 1.0, v4
	v_rcp_f32_e32 v4, v4
	v_mul_f32_e32 v3, v140, v3
	v_mul_f32_e32 v3, 0x3fb8aa3b, v3
	v_exp_f32_e32 v3, v3
	s_waitcnt lgkmcnt(0)
	v_lshlrev_b32_e32 v2, 16, v2
	v_sub_f32_e32 v5, 1.0, v3
	v_add_f32_e32 v3, 1.0, v3
	v_mul_f32_e32 v3, v5, v3
	v_sqrt_f32_e32 v3, v3
	s_nop 0
	v_mul_f32_e32 v3, v4, v3
	v_mul_f32_e32 v2, v3, v2
	v_cvt_pk_f16_f32 v4, v5, v2
	v_add_u32_e32 v2, s0, v164
	v_ashrrev_i32_e32 v3, 31, v2
	v_lshlrev_b64 v[2:3], 11, v[2:3]
	v_lshl_add_u64 v[132:133], v[66:67], 0, v[2:3]
	v_add_f32_e32 v2, v136, v33
	v_mul_f32_e32 v2, 0xbfb8aa3b, v2
	v_exp_f32_e32 v2, v2
	v_add_f32_e32 v3, v138, v17
	v_mul_f32_e32 v3, 0xbfb8aa3b, v3
	v_exp_f32_e32 v3, v3
	v_add_f32_e32 v2, 1.0, v2
	v_rcp_f32_e32 v2, v2
	ds_write_b32 v183, v4
	global_store_dword v[132:133], v4, off
	v_add_f32_e32 v3, 1.0, v3
	v_mul_f32_e32 v2, v140, v2
	v_mul_f32_e32 v2, 0x3fb8aa3b, v2
	v_exp_f32_e32 v2, v2
	v_rcp_f32_e32 v3, v3
	v_sub_f32_e32 v4, 1.0, v2
	v_add_f32_e32 v2, 1.0, v2
	v_mul_f32_e32 v2, v4, v2
	v_sqrt_f32_e32 v2, v2
	s_nop 0
	v_mul_f32_e32 v2, v3, v2
	v_add_u32_e32 v3, v146, v166
	ds_read_u16 v3, v3
	s_waitcnt lgkmcnt(0)
	v_lshlrev_b32_e32 v3, 16, v3
	v_mul_f32_e32 v2, v2, v3
	v_cvt_pk_f16_f32 v4, v4, v2
	v_add_u32_e32 v2, s0, v165
	v_ashrrev_i32_e32 v3, 31, v2
	v_lshlrev_b64 v[2:3], 11, v[2:3]
	v_lshl_add_u64 v[134:135], v[66:67], 0, v[2:3]
	global_store_dword v[134:135], v4, off
	ds_write_b32 v184, v4
	s_waitcnt vmcnt(0)
	v_mfma_f32_32x32x16_bf16 v[18:33], v[46:49], v[238:241], 0
	s_waitcnt vmcnt(0)
	v_mfma_f32_32x32x16_bf16 v[2:17], v[46:49], v[242:245], 0
	s_waitcnt vmcnt(0)
	v_mfma_f32_32x32x16_bf16 v[18:33], v[42:45], v[246:249], v[18:33]
	s_waitcnt vmcnt(0)
	v_mfma_f32_32x32x16_bf16 v[2:17], v[42:45], v[114:117], v[2:17]
	s_waitcnt vmcnt(0)
	v_mfma_f32_32x32x16_bf16 v[18:33], v[38:41], v[118:121], v[18:33]
	s_waitcnt vmcnt(0)
	v_mfma_f32_32x32x16_bf16 v[2:17], v[38:41], v[122:125], v[2:17]
	s_waitcnt vmcnt(0)
	v_mfma_f32_32x32x16_bf16 v[18:33], v[34:37], v[126:129], v[18:33]
	global_load_dwordx4 v[38:41], v[82:83], off
	s_nop 10
	v_add_f32_e32 v18, v137, v18
	v_mul_f32_e32 v18, 0xbfb8aa3b, v18
	v_exp_f32_e32 v18, v18
	s_waitcnt vmcnt(0)
	v_mfma_f32_32x32x16_bf16 v[2:17], v[34:37], v[38:41], v[2:17]
	v_add_f32_e32 v18, 1.0, v18
	v_rcp_f32_e32 v18, v18
	s_nop 9
	v_add_f32_e32 v2, v139, v2
	v_mul_f32_e32 v18, v141, v18
	v_mul_f32_e32 v18, 0x3fb8aa3b, v18
	v_mul_f32_e32 v2, 0xbfb8aa3b, v2
	v_exp_f32_e32 v18, v18
	v_exp_f32_e32 v2, v2
	v_add_f32_e32 v3, v139, v3
	v_mul_f32_e32 v3, 0xbfb8aa3b, v3
	v_sub_f32_e32 v34, 1.0, v18
	v_add_f32_e32 v18, 1.0, v18
	v_add_f32_e32 v2, 1.0, v2
	v_mul_f32_e32 v18, v34, v18
	v_rcp_f32_e32 v2, v2
	v_sqrt_f32_e32 v18, v18
	v_exp_f32_e32 v3, v3
	v_add_f32_e32 v4, v139, v4
	v_mul_f32_e32 v4, 0xbfb8aa3b, v4
	v_mul_f32_e32 v18, v2, v18
	v_add_u32_e32 v2, v167, v147
	ds_read_u16 v35, v2
	v_add_f32_e32 v3, 1.0, v3
	v_rcp_f32_e32 v3, v3
	v_exp_f32_e32 v4, v4
	s_waitcnt lgkmcnt(0)
	v_lshlrev_b32_e32 v35, 16, v35
	v_mul_f32_e32 v18, v18, v35
	v_cvt_pk_f16_f32 v18, v34, v18
	ds_write_b32 v169, v18 offset:128
	global_store_dword v[92:93], v18, off offset:128
	v_add_f32_e32 v18, v137, v19
	v_mul_f32_e32 v18, 0xbfb8aa3b, v18
	v_exp_f32_e32 v18, v18
	v_add_f32_e32 v4, 1.0, v4
	v_rcp_f32_e32 v4, v4
	v_add_f32_e32 v18, 1.0, v18
	v_rcp_f32_e32 v18, v18
	s_nop 0
	v_mul_f32_e32 v18, v141, v18
	v_mul_f32_e32 v18, 0x3fb8aa3b, v18
	v_exp_f32_e32 v18, v18
	s_nop 0
	v_sub_f32_e32 v19, 1.0, v18
	v_add_f32_e32 v18, 1.0, v18
	v_mul_f32_e32 v18, v19, v18
	v_sqrt_f32_e32 v18, v18
	s_nop 0
	v_mul_f32_e32 v3, v3, v18
	ds_read_u16 v18, v2 offset:528
	s_waitcnt lgkmcnt(0)
; #define LAS __attribute__((address_space(3)))
; __device__ __forceinline__ float fsig(float x) { return __builtin_amdgcn_rcpf(1.0f + __expf(-x)); }
; __device__ __forceinline__ int crow16(int r, int hi) { return (r & 3) + 8 * (r >> 2) + 4 * hi; }
; __device__ __forceinline__ void lru_pass1_unit(int cu4, const Args& a, int l, const bf16* LX, const bf16* WLRU, h2* AD, float2* LCS4, lds_t* lds, int tid, int lane, int wave, const LruGateC& gc) {
;     ...
;             const int ch = 64 * k + 32 * ct + (lane & 31);
; #pragma unroll
;             for (int r = 0; r < 16; ++r) { const int row = crow16(r, lane >> 5);
;                 const float rg = fsig(ga[r] + ba[ct]), ig = fsig(gx[r] + bx[ct]); const float la = lsl[ct] * rg;
;                 const float a_ = __expf(la); const float oma = 1.0f - a_, dr = __builtin_amdgcn_sqrtf(oma * (1.0f + a_)) * ig * bf2f(*(const LAS unsigned short*)(XR + row * LR_LDX + ch * 2));
;                 h2 hv; hv[0] = (_Float16)oma; hv[1] = (_Float16)dr;
;                 ADL[row * 512 + dir * 256 + ch] = hv; AD[((size_t)(m0 + 32 * rt + row) * 2 + dir) * 256 + ch] = hv; } }
	v_lshlrev_b32_e32 v18, 16, v18
	v_mul_f32_e32 v3, v3, v18
	v_cvt_pk_f16_f32 v3, v19, v3
	ds_write_b32 v170, v3 offset:128
	global_store_dword v[90:91], v3, off offset:128
	v_add_f32_e32 v3, v137, v20
	v_mul_f32_e32 v3, 0xbfb8aa3b, v3
	v_exp_f32_e32 v3, v3
	s_nop 0
	v_add_f32_e32 v3, 1.0, v3
	v_rcp_f32_e32 v3, v3
	s_nop 0
	v_mul_f32_e32 v3, v141, v3
	v_mul_f32_e32 v3, 0x3fb8aa3b, v3
	v_exp_f32_e32 v3, v3
	s_nop 0
	v_sub_f32_e32 v18, 1.0, v3
	v_add_f32_e32 v3, 1.0, v3
	v_mul_f32_e32 v3, v18, v3
	v_sqrt_f32_e32 v3, v3
	s_nop 0
	v_mul_f32_e32 v3, v4, v3
	ds_read_u16 v4, v2 offset:1056
	s_waitcnt lgkmcnt(0)
	v_lshlrev_b32_e32 v4, 16, v4
	v_mul_f32_e32 v3, v3, v4
	v_cvt_pk_f16_f32 v3, v18, v3
	ds_write_b32 v171, v3 offset:128
	global_store_dword v[88:89], v3, off offset:128
	v_add_f32_e32 v3, v137, v21
	v_mul_f32_e32 v3, 0xbfb8aa3b, v3
	v_exp_f32_e32 v3, v3
	v_add_f32_e32 v4, v139, v5
	v_mul_f32_e32 v4, 0xbfb8aa3b, v4
	v_exp_f32_e32 v4, v4
	v_add_f32_e32 v3, 1.0, v3
	v_rcp_f32_e32 v3, v3
	v_add_f32_e32 v4, 1.0, v4
	v_rcp_f32_e32 v4, v4
	v_mul_f32_e32 v3, v141, v3
	v_mul_f32_e32 v3, 0x3fb8aa3b, v3
	v_exp_f32_e32 v3, v3
	s_nop 0
	v_sub_f32_e32 v5, 1.0, v3
	v_add_f32_e32 v3, 1.0, v3
	v_mul_f32_e32 v3, v5, v3
	v_sqrt_f32_e32 v3, v3
	s_nop 0
	v_mul_f32_e32 v3, v4, v3
	v_add_u32_e32 v4, v167, v151
	ds_read_u16 v4, v4
	s_waitcnt lgkmcnt(0)
	v_lshlrev_b32_e32 v4, 16, v4
	v_mul_f32_e32 v3, v3, v4
	v_cvt_pk_f16_f32 v3, v5, v3
	ds_write_b32 v172, v3 offset:128
	global_store_dword v[94:95], v3, off offset:128
	v_add_f32_e32 v3, v137, v22
	v_mul_f32_e32 v3, 0xbfb8aa3b, v3
	v_exp_f32_e32 v3, v3
	v_add_f32_e32 v4, v139, v6
	v_mul_f32_e32 v4, 0xbfb8aa3b, v4
	v_exp_f32_e32 v4, v4
	v_add_f32_e32 v3, 1.0, v3
	v_rcp_f32_e32 v3, v3
	v_add_f32_e32 v4, 1.0, v4
	v_rcp_f32_e32 v4, v4
	v_mul_f32_e32 v3, v141, v3
	v_mul_f32_e32 v3, 0x3fb8aa3b, v3
	v_exp_f32_e32 v3, v3
	s_nop 0
	v_sub_f32_e32 v5, 1.0, v3
	v_add_f32_e32 v3, 1.0, v3
	v_mul_f32_e32 v3, v5, v3
	v_sqrt_f32_e32 v3, v3
	s_nop 0
	v_mul_f32_e32 v3, v4, v3
	ds_read_u16 v4, v2 offset:4224
	s_waitcnt lgkmcnt(0)
	v_lshlrev_b32_e32 v4, 16, v4
	v_mul_f32_e32 v3, v3, v4
	v_cvt_pk_f16_f32 v3, v5, v3
	ds_write_b32 v173, v3 offset:128
	global_store_dword v[96:97], v3, off offset:128
	v_add_f32_e32 v3, v137, v23
	v_mul_f32_e32 v3, 0xbfb8aa3b, v3
	v_exp_f32_e32 v3, v3
	v_add_f32_e32 v4, v139, v7
	v_mul_f32_e32 v4, 0xbfb8aa3b, v4
	v_exp_f32_e32 v4, v4
	v_add_f32_e32 v3, 1.0, v3
	v_rcp_f32_e32 v3, v3
	v_add_f32_e32 v4, 1.0, v4
	v_rcp_f32_e32 v4, v4
	v_mul_f32_e32 v3, v141, v3
	v_mul_f32_e32 v3, 0x3fb8aa3b, v3
	v_exp_f32_e32 v3, v3
	s_nop 0
	v_sub_f32_e32 v5, 1.0, v3
	v_add_f32_e32 v3, 1.0, v3
	v_mul_f32_e32 v3, v5, v3
	v_sqrt_f32_e32 v3, v3
	s_nop 0
	v_mul_f32_e32 v3, v4, v3
	ds_read_u16 v4, v2 offset:4752
	s_waitcnt lgkmcnt(0)
	v_lshlrev_b32_e32 v4, 16, v4
	v_mul_f32_e32 v3, v3, v4
	v_cvt_pk_f16_f32 v3, v5, v3
	ds_write_b32 v174, v3 offset:128
	global_store_dword v[98:99], v3, off offset:128
	v_add_f32_e32 v3, v137, v24
	v_mul_f32_e32 v3, 0xbfb8aa3b, v3
	v_exp_f32_e32 v3, v3
	v_add_f32_e32 v4, v139, v8
	v_mul_f32_e32 v4, 0xbfb8aa3b, v4
	v_exp_f32_e32 v4, v4
	v_add_f32_e32 v3, 1.0, v3
	v_rcp_f32_e32 v3, v3
	v_add_f32_e32 v4, 1.0, v4
	v_rcp_f32_e32 v4, v4
	v_mul_f32_e32 v3, v141, v3
	v_mul_f32_e32 v3, 0x3fb8aa3b, v3
	v_exp_f32_e32 v3, v3
	s_nop 0
	v_sub_f32_e32 v5, 1.0, v3
	v_add_f32_e32 v3, 1.0, v3
	v_mul_f32_e32 v3, v5, v3
	v_sqrt_f32_e32 v3, v3
	s_nop 0
	v_mul_f32_e32 v3, v4, v3
	ds_read_u16 v4, v2 offset:5280
	s_waitcnt lgkmcnt(0)
	v_lshlrev_b32_e32 v4, 16, v4
	v_mul_f32_e32 v3, v3, v4
	v_cvt_pk_f16_f32 v3, v5, v3
	ds_write_b32 v175, v3 offset:128
	global_store_dword v[100:101], v3, off offset:128
	v_add_f32_e32 v3, v137, v25
	v_mul_f32_e32 v3, 0xbfb8aa3b, v3
	v_exp_f32_e32 v3, v3
	v_add_f32_e32 v4, v139, v9
	v_mul_f32_e32 v4, 0xbfb8aa3b, v4
	v_exp_f32_e32 v4, v4
	v_add_f32_e32 v3, 1.0, v3
	v_rcp_f32_e32 v3, v3
	v_add_f32_e32 v4, 1.0, v4
	v_rcp_f32_e32 v4, v4
	v_mul_f32_e32 v3, v141, v3
	v_mul_f32_e32 v3, 0x3fb8aa3b, v3
	v_exp_f32_e32 v3, v3
	s_nop 0
	v_sub_f32_e32 v5, 1.0, v3
	v_add_f32_e32 v3, 1.0, v3
	v_mul_f32_e32 v3, v5, v3
	v_sqrt_f32_e32 v3, v3
	s_nop 0
	v_mul_f32_e32 v3, v4, v3
	v_add_u32_e32 v4, v167, v156
	ds_read_u16 v4, v4
	s_waitcnt lgkmcnt(0)
	v_lshlrev_b32_e32 v4, 16, v4
	v_mul_f32_e32 v3, v3, v4
	v_cvt_pk_f16_f32 v3, v5, v3
	ds_write_b32 v176, v3 offset:128
	global_store_dword v[102:103], v3, off offset:128
	v_add_f32_e32 v3, v137, v26
	v_mul_f32_e32 v3, 0xbfb8aa3b, v3
	v_exp_f32_e32 v3, v3
	v_add_f32_e32 v4, v139, v10
	v_mul_f32_e32 v4, 0xbfb8aa3b, v4
	v_exp_f32_e32 v4, v4
	v_add_f32_e32 v3, 1.0, v3
	v_rcp_f32_e32 v3, v3
	v_add_f32_e32 v4, 1.0, v4
	v_rcp_f32_e32 v4, v4
	v_mul_f32_e32 v3, v141, v3
	v_mul_f32_e32 v3, 0x3fb8aa3b, v3
	v_exp_f32_e32 v3, v3
	s_nop 0
	v_sub_f32_e32 v5, 1.0, v3
	v_add_f32_e32 v3, 1.0, v3
	v_mul_f32_e32 v3, v5, v3
	v_sqrt_f32_e32 v3, v3
	s_nop 0
	v_mul_f32_e32 v3, v4, v3
	ds_read_u16 v4, v2 offset:8448
	s_waitcnt lgkmcnt(0)
	v_lshlrev_b32_e32 v4, 16, v4
	v_mul_f32_e32 v3, v3, v4
	v_cvt_pk_f16_f32 v3, v5, v3
	ds_write_b32 v177, v3 offset:128
	global_store_dword v[104:105], v3, off offset:128
	v_add_f32_e32 v3, v137, v27
	v_mul_f32_e32 v3, 0xbfb8aa3b, v3
	v_exp_f32_e32 v3, v3
	v_add_f32_e32 v4, v139, v11
	v_mul_f32_e32 v4, 0xbfb8aa3b, v4
	v_exp_f32_e32 v4, v4
	v_add_f32_e32 v3, 1.0, v3
	v_rcp_f32_e32 v3, v3
	v_add_f32_e32 v4, 1.0, v4
	v_rcp_f32_e32 v4, v4
	v_mul_f32_e32 v3, v141, v3
	v_mul_f32_e32 v3, 0x3fb8aa3b, v3
	v_exp_f32_e32 v3, v3
	s_nop 0
	v_sub_f32_e32 v5, 1.0, v3
	v_add_f32_e32 v3, 1.0, v3
	v_mul_f32_e32 v3, v5, v3
	v_sqrt_f32_e32 v3, v3
	s_nop 0
	v_mul_f32_e32 v3, v4, v3
	ds_read_u16 v4, v2 offset:8976
	s_waitcnt lgkmcnt(0)
; #define LAS __attribute__((address_space(3)))
; __device__ __forceinline__ float fsig(float x) { return __builtin_amdgcn_rcpf(1.0f + __expf(-x)); }
; __device__ __forceinline__ int crow16(int r, int hi) { return (r & 3) + 8 * (r >> 2) + 4 * hi; }
; __device__ __forceinline__ void lru_pass1_unit(int cu4, const Args& a, int l, const bf16* LX, const bf16* WLRU, h2* AD, float2* LCS4, lds_t* lds, int tid, int lane, int wave, const LruGateC& gc) {
;     ...
;             const int ch = 64 * k + 32 * ct + (lane & 31);
; #pragma unroll
;             for (int r = 0; r < 16; ++r) { const int row = crow16(r, lane >> 5);
;                 const float rg = fsig(ga[r] + ba[ct]), ig = fsig(gx[r] + bx[ct]); const float la = lsl[ct] * rg;
;                 const float a_ = __expf(la); const float oma = 1.0f - a_, dr = __builtin_amdgcn_sqrtf(oma * (1.0f + a_)) * ig * bf2f(*(const LAS unsigned short*)(XR + row * LR_LDX + ch * 2));
;                 h2 hv; hv[0] = (_Float16)oma; hv[1] = (_Float16)dr;
;                 ADL[row * 512 + dir * 256 + ch] = hv; AD[((size_t)(m0 + 32 * rt + row) * 2 + dir) * 256 + ch] = hv; } }
;         __syncthreads();
	v_lshlrev_b32_e32 v4, 16, v4
	v_mul_f32_e32 v3, v3, v4
	v_cvt_pk_f16_f32 v3, v5, v3
	ds_write_b32 v178, v3 offset:128
	global_store_dword v[106:107], v3, off offset:128
	v_add_f32_e32 v3, v137, v28
	v_mul_f32_e32 v3, 0xbfb8aa3b, v3
	v_exp_f32_e32 v3, v3
	v_add_f32_e32 v4, v139, v12
	v_mul_f32_e32 v4, 0xbfb8aa3b, v4
	v_exp_f32_e32 v4, v4
	v_add_f32_e32 v3, 1.0, v3
	v_rcp_f32_e32 v3, v3
	v_add_f32_e32 v4, 1.0, v4
	v_rcp_f32_e32 v4, v4
	v_mul_f32_e32 v3, v141, v3
	v_mul_f32_e32 v3, 0x3fb8aa3b, v3
	v_exp_f32_e32 v3, v3
	s_nop 0
	v_sub_f32_e32 v5, 1.0, v3
	v_add_f32_e32 v3, 1.0, v3
	v_mul_f32_e32 v3, v5, v3
	v_sqrt_f32_e32 v3, v3
	s_nop 0
	v_mul_f32_e32 v3, v4, v3
	ds_read_u16 v4, v2 offset:9504
	s_waitcnt lgkmcnt(0)
	v_lshlrev_b32_e32 v4, 16, v4
	v_mul_f32_e32 v3, v3, v4
	v_cvt_pk_f16_f32 v3, v5, v3
	ds_write_b32 v179, v3 offset:128
	global_store_dword v[108:109], v3, off offset:128
	v_add_f32_e32 v3, v137, v29
	v_mul_f32_e32 v3, 0xbfb8aa3b, v3
	v_exp_f32_e32 v3, v3
	v_add_f32_e32 v4, v139, v13
	v_mul_f32_e32 v4, 0xbfb8aa3b, v4
	v_exp_f32_e32 v4, v4
	v_add_f32_e32 v3, 1.0, v3
	v_rcp_f32_e32 v3, v3
	v_add_f32_e32 v4, 1.0, v4
	v_rcp_f32_e32 v4, v4
	v_mul_f32_e32 v3, v141, v3
	v_mul_f32_e32 v3, 0x3fb8aa3b, v3
	v_exp_f32_e32 v3, v3
	s_nop 0
	v_sub_f32_e32 v5, 1.0, v3
	v_add_f32_e32 v3, 1.0, v3
	v_mul_f32_e32 v3, v5, v3
	v_sqrt_f32_e32 v3, v3
	s_nop 0
	v_mul_f32_e32 v3, v4, v3
	v_add_u32_e32 v4, v167, v161
	ds_read_u16 v4, v4
	s_waitcnt lgkmcnt(0)
	v_lshlrev_b32_e32 v4, 16, v4
	v_mul_f32_e32 v3, v3, v4
	v_cvt_pk_f16_f32 v3, v5, v3
	ds_write_b32 v180, v3 offset:128
	global_store_dword v[110:111], v3, off offset:128
	v_add_f32_e32 v3, v137, v30
	v_mul_f32_e32 v3, 0xbfb8aa3b, v3
	v_exp_f32_e32 v3, v3
	v_add_f32_e32 v4, v139, v14
	v_mul_f32_e32 v4, 0xbfb8aa3b, v4
	v_exp_f32_e32 v4, v4
	v_add_f32_e32 v3, 1.0, v3
	v_rcp_f32_e32 v3, v3
	v_add_f32_e32 v4, 1.0, v4
	v_rcp_f32_e32 v4, v4
	v_mul_f32_e32 v3, v141, v3
	v_mul_f32_e32 v3, 0x3fb8aa3b, v3
	v_exp_f32_e32 v3, v3
	s_nop 0
	v_sub_f32_e32 v5, 1.0, v3
	v_add_f32_e32 v3, 1.0, v3
	v_mul_f32_e32 v3, v5, v3
	v_sqrt_f32_e32 v3, v3
	s_nop 0
	v_mul_f32_e32 v3, v4, v3
	ds_read_u16 v4, v2 offset:12672
	s_waitcnt lgkmcnt(0)
	v_lshlrev_b32_e32 v4, 16, v4
	v_mul_f32_e32 v3, v3, v4
	v_cvt_pk_f16_f32 v3, v5, v3
	ds_write_b32 v181, v3 offset:128
	global_store_dword v[112:113], v3, off offset:128
	v_add_f32_e32 v3, v137, v31
	v_mul_f32_e32 v3, 0xbfb8aa3b, v3
	v_exp_f32_e32 v3, v3
	v_add_f32_e32 v4, v139, v15
	v_mul_f32_e32 v4, 0xbfb8aa3b, v4
	v_exp_f32_e32 v4, v4
	v_add_f32_e32 v3, 1.0, v3
	v_rcp_f32_e32 v3, v3
	v_add_f32_e32 v4, 1.0, v4
	v_rcp_f32_e32 v4, v4
	v_mul_f32_e32 v3, v141, v3
	v_mul_f32_e32 v3, 0x3fb8aa3b, v3
	v_exp_f32_e32 v3, v3
	s_nop 0
	v_sub_f32_e32 v5, 1.0, v3
	v_add_f32_e32 v3, 1.0, v3
	v_mul_f32_e32 v3, v5, v3
	v_sqrt_f32_e32 v3, v3
	s_nop 0
	v_mul_f32_e32 v3, v4, v3
	ds_read_u16 v4, v2 offset:13200
	s_waitcnt lgkmcnt(0)
	v_lshlrev_b32_e32 v4, 16, v4
	v_mul_f32_e32 v3, v3, v4
	v_cvt_pk_f16_f32 v3, v5, v3
	ds_write_b32 v182, v3 offset:128
	global_store_dword v[130:131], v3, off offset:128
	v_add_f32_e32 v3, v137, v32
	v_mul_f32_e32 v3, 0xbfb8aa3b, v3
	v_exp_f32_e32 v3, v3
	v_add_f32_e32 v4, v139, v16
	v_mul_f32_e32 v4, 0xbfb8aa3b, v4
	v_exp_f32_e32 v4, v4
	v_add_f32_e32 v3, 1.0, v3
	v_rcp_f32_e32 v3, v3
	ds_read_u16 v2, v2 offset:13728
	v_add_f32_e32 v4, 1.0, v4
	v_rcp_f32_e32 v4, v4
	v_mul_f32_e32 v3, v141, v3
	v_mul_f32_e32 v3, 0x3fb8aa3b, v3
	v_exp_f32_e32 v3, v3
	s_waitcnt lgkmcnt(0)
	v_lshlrev_b32_e32 v2, 16, v2
	v_sub_f32_e32 v5, 1.0, v3
	v_add_f32_e32 v3, 1.0, v3
	v_mul_f32_e32 v3, v5, v3
	v_sqrt_f32_e32 v3, v3
	s_nop 0
	v_mul_f32_e32 v3, v4, v3
	v_mul_f32_e32 v2, v3, v2
	v_cvt_pk_f16_f32 v2, v5, v2
	ds_write_b32 v183, v2 offset:128
	global_store_dword v[132:133], v2, off offset:128
	v_add_f32_e32 v2, v137, v33
	v_mul_f32_e32 v2, 0xbfb8aa3b, v2
	v_exp_f32_e32 v2, v2
	v_add_f32_e32 v3, v139, v17
	v_mul_f32_e32 v3, 0xbfb8aa3b, v3
	v_exp_f32_e32 v3, v3
	v_add_f32_e32 v2, 1.0, v2
	v_rcp_f32_e32 v2, v2
	v_add_f32_e32 v3, 1.0, v3
	v_rcp_f32_e32 v3, v3
	v_mul_f32_e32 v2, v141, v2
	v_mul_f32_e32 v2, 0x3fb8aa3b, v2
	v_exp_f32_e32 v2, v2
	s_nop 0
	v_sub_f32_e32 v4, 1.0, v2
	v_add_f32_e32 v2, 1.0, v2
	v_mul_f32_e32 v2, v4, v2
	v_sqrt_f32_e32 v2, v2
	s_nop 0
	v_mul_f32_e32 v2, v3, v2
	v_add_u32_e32 v3, v167, v166
	ds_read_u16 v3, v3
	s_waitcnt lgkmcnt(0)
	v_lshlrev_b32_e32 v3, 16, v3
	v_mul_f32_e32 v2, v2, v3
	v_cvt_pk_f16_f32 v2, v4, v2
	ds_write_b32 v184, v2 offset:128
	global_store_dword v[134:135], v2, off offset:128
	s_waitcnt lgkmcnt(0)
	s_barrier
; __device__ __forceinline__ void lru_pass1_unit(int cu4, const Args& a, int l, const bf16* LX, const bf16* WLRU, h2* AD, float2* LCS4, lds_t* lds, int tid, int lane, int wave, const LruGateC& gc) {
;     ...
;         { const int sd = tid >> 8, sc = tid & 255; float A = 1.f, H = 0.f;
;             h2 fr_[32];
; #pragma unroll
;             for (int r = 0; r < 32; ++r) fr_[r] = ADL[r * 512 + sd * 256 + sc];
;             if (sd == 0) {
; #pragma unroll
;                 for (int r = 0; r < 32; ++r) { const float aa = 1.0f - (float)fr_[r][0]; H = aa * H + (float)fr_[r][1]; A *= aa; }
;                 Ht = A * Ht + H; At = A * At; }
	ds_read2st64_b32 v[2:3], v145 offset1:8
	ds_read2st64_b32 v[4:5], v145 offset0:16 offset1:24
	ds_read2st64_b32 v[6:7], v145 offset0:32 offset1:40
	ds_read2st64_b32 v[8:9], v145 offset0:48 offset1:56
	ds_read2st64_b32 v[10:11], v145 offset0:64 offset1:72
	ds_read2st64_b32 v[12:13], v145 offset0:80 offset1:88
	ds_read2st64_b32 v[14:15], v145 offset0:96 offset1:104
	ds_read2st64_b32 v[16:17], v145 offset0:112 offset1:120
	ds_read2st64_b32 v[18:19], v145 offset0:128 offset1:136
	ds_read2st64_b32 v[20:21], v145 offset0:144 offset1:152
	ds_read2st64_b32 v[22:23], v145 offset0:160 offset1:168
	ds_read2st64_b32 v[24:25], v145 offset0:176 offset1:184
	ds_read2st64_b32 v[26:27], v145 offset0:192 offset1:200
	ds_read2st64_b32 v[28:29], v145 offset0:208 offset1:216
	ds_read2st64_b32 v[30:31], v145 offset0:224 offset1:232
	ds_read2st64_b32 v[32:33], v145 offset0:240 offset1:248
	s_waitcnt lgkmcnt(4)
	v_cvt_f32_f16_e32 v44, v25
	s_waitcnt lgkmcnt(3)
	v_cvt_f32_f16_e32 v42, v27
	s_waitcnt lgkmcnt(2)
	v_cvt_f32_f16_e32 v40, v29
	s_waitcnt lgkmcnt(1)
	v_cvt_f32_f16_e32 v38, v31
	s_waitcnt lgkmcnt(0)
	v_cvt_f32_f16_e32 v36, v33
	v_cvt_f32_f16_e32 v37, v32
	v_cvt_f32_f16_e32 v39, v30
	v_cvt_f32_f16_e32 v41, v28
	v_cvt_f32_f16_e32 v43, v26
	v_cvt_f32_f16_e32 v45, v24
	v_cvt_f32_f16_e32 v46, v23
	v_cvt_f32_f16_e32 v47, v22
	v_cvt_f32_f16_e32 v48, v21
	v_cvt_f32_f16_e32 v49, v20
	v_cvt_f32_f16_e32 v88, v19
	v_cvt_f32_f16_e32 v89, v18
	v_cvt_f32_f16_e32 v90, v17
	v_cvt_f32_f16_e32 v91, v16
	v_cvt_f32_f16_e32 v92, v15
	v_cvt_f32_f16_e32 v93, v14
	v_cvt_f32_f16_e32 v94, v13
	v_cvt_f32_f16_e32 v95, v12
	v_cvt_f32_f16_e32 v96, v11
	v_cvt_f32_f16_e32 v97, v10
	v_cvt_f32_f16_e32 v98, v9
	v_cvt_f32_f16_e32 v99, v8
	v_cvt_f32_f16_e32 v100, v7
	v_cvt_f32_f16_e32 v101, v6
	v_cvt_f32_f16_e32 v102, v5
	v_cvt_f32_f16_e32 v103, v4
	v_cvt_f32_f16_e32 v104, v3
	v_cvt_f32_f16_e32 v105, v2
	s_and_saveexec_b64 s[0:1], s[6:7]
	s_xor_b64 s[0:1], exec, s[0:1]
	s_cbranch_execz .LBB0_574
	v_sub_f32_e32 v34, 1.0, v36
	v_fma_mix_f32 v33, v34, 0, v33 op_sel:[0,0,1] op_sel_hi:[0,0,1]
	v_sub_f32_e32 v35, 1.0, v37
	v_fma_mix_f32 v32, v35, v33, v32 op_sel:[0,0,1] op_sel_hi:[0,0,1]
	v_mul_f32_e32 v33, v35, v34
	v_sub_f32_e32 v34, 1.0, v38
	v_fma_mix_f32 v31, v34, v32, v31 op_sel:[0,0,1] op_sel_hi:[0,0,1]
	v_mul_f32_e32 v32, v34, v33
	v_sub_f32_e32 v33, 1.0, v39
	v_fma_mix_f32 v30, v33, v31, v30 op_sel:[0,0,1] op_sel_hi:[0,0,1]
	v_mul_f32_e32 v31, v33, v32
	v_sub_f32_e32 v32, 1.0, v40
	v_fma_mix_f32 v29, v32, v30, v29 op_sel:[0,0,1] op_sel_hi:[0,0,1]
	v_mul_f32_e32 v30, v32, v31
	v_sub_f32_e32 v31, 1.0, v41
	v_fma_mix_f32 v28, v31, v29, v28 op_sel:[0,0,1] op_sel_hi:[0,0,1]
	v_mul_f32_e32 v29, v31, v30
	v_sub_f32_e32 v30, 1.0, v42
	v_fma_mix_f32 v27, v30, v28, v27 op_sel:[0,0,1] op_sel_hi:[0,0,1]
	v_mul_f32_e32 v28, v30, v29
	v_sub_f32_e32 v29, 1.0, v43
	v_fma_mix_f32 v26, v29, v27, v26 op_sel:[0,0,1] op_sel_hi:[0,0,1]
	v_mul_f32_e32 v27, v29, v28
	v_sub_f32_e32 v28, 1.0, v44
	v_fma_mix_f32 v25, v28, v26, v25 op_sel:[0,0,1] op_sel_hi:[0,0,1]
	v_mul_f32_e32 v26, v28, v27
	v_sub_f32_e32 v27, 1.0, v45
	v_fma_mix_f32 v24, v27, v25, v24 op_sel:[0,0,1] op_sel_hi:[0,0,1]
	v_mul_f32_e32 v25, v27, v26
	v_sub_f32_e32 v26, 1.0, v46
	v_fma_mix_f32 v23, v26, v24, v23 op_sel:[0,0,1] op_sel_hi:[0,0,1]
	v_mul_f32_e32 v24, v26, v25
	v_sub_f32_e32 v25, 1.0, v47
	v_fma_mix_f32 v22, v25, v23, v22 op_sel:[0,0,1] op_sel_hi:[0,0,1]
	v_mul_f32_e32 v23, v25, v24
	v_sub_f32_e32 v24, 1.0, v48
	v_fma_mix_f32 v21, v24, v22, v21 op_sel:[0,0,1] op_sel_hi:[0,0,1]
	v_mul_f32_e32 v22, v24, v23
	v_sub_f32_e32 v23, 1.0, v49
	v_fma_mix_f32 v20, v23, v21, v20 op_sel:[0,0,1] op_sel_hi:[0,0,1]
	v_mul_f32_e32 v21, v23, v22
	v_sub_f32_e32 v22, 1.0, v88
	v_fma_mix_f32 v19, v22, v20, v19 op_sel:[0,0,1] op_sel_hi:[0,0,1]
	v_mul_f32_e32 v20, v22, v21
	v_sub_f32_e32 v21, 1.0, v89
	v_fma_mix_f32 v18, v21, v19, v18 op_sel:[0,0,1] op_sel_hi:[0,0,1]
	v_mul_f32_e32 v19, v21, v20
	v_sub_f32_e32 v20, 1.0, v90
	v_fma_mix_f32 v17, v20, v18, v17 op_sel:[0,0,1] op_sel_hi:[0,0,1]
	v_mul_f32_e32 v18, v20, v19
	v_sub_f32_e32 v19, 1.0, v91
	v_fma_mix_f32 v16, v19, v17, v16 op_sel:[0,0,1] op_sel_hi:[0,0,1]
	v_mul_f32_e32 v17, v19, v18
	v_sub_f32_e32 v18, 1.0, v92
	v_fma_mix_f32 v15, v18, v16, v15 op_sel:[0,0,1] op_sel_hi:[0,0,1]
	v_mul_f32_e32 v16, v18, v17
	v_sub_f32_e32 v17, 1.0, v93
	v_fma_mix_f32 v14, v17, v15, v14 op_sel:[0,0,1] op_sel_hi:[0,0,1]
	v_mul_f32_e32 v15, v17, v16
	v_sub_f32_e32 v16, 1.0, v94
	v_fma_mix_f32 v13, v16, v14, v13 op_sel:[0,0,1] op_sel_hi:[0,0,1]
	v_mul_f32_e32 v14, v16, v15
	v_sub_f32_e32 v15, 1.0, v95
	v_fma_mix_f32 v12, v15, v13, v12 op_sel:[0,0,1] op_sel_hi:[0,0,1]
	v_mul_f32_e32 v13, v15, v14
	v_sub_f32_e32 v14, 1.0, v96
	v_fma_mix_f32 v11, v14, v12, v11 op_sel:[0,0,1] op_sel_hi:[0,0,1]
	v_mul_f32_e32 v12, v14, v13
	v_sub_f32_e32 v13, 1.0, v97
	v_fma_mix_f32 v10, v13, v11, v10 op_sel:[0,0,1] op_sel_hi:[0,0,1]
	v_mul_f32_e32 v11, v13, v12
	v_sub_f32_e32 v12, 1.0, v98
	v_fma_mix_f32 v9, v12, v10, v9 op_sel:[0,0,1] op_sel_hi:[0,0,1]
	v_mul_f32_e32 v10, v12, v11
	v_sub_f32_e32 v11, 1.0, v99
	v_fma_mix_f32 v8, v11, v9, v8 op_sel:[0,0,1] op_sel_hi:[0,0,1]
	v_mul_f32_e32 v9, v11, v10
	v_sub_f32_e32 v10, 1.0, v100
	v_fma_mix_f32 v7, v10, v8, v7 op_sel:[0,0,1] op_sel_hi:[0,0,1]
	v_mul_f32_e32 v8, v10, v9
	v_sub_f32_e32 v9, 1.0, v101
	v_fma_mix_f32 v6, v9, v7, v6 op_sel:[0,0,1] op_sel_hi:[0,0,1]
	v_mul_f32_e32 v7, v9, v8
	v_sub_f32_e32 v8, 1.0, v102
	v_fma_mix_f32 v5, v8, v6, v5 op_sel:[0,0,1] op_sel_hi:[0,0,1]
	v_mul_f32_e32 v6, v8, v7
	v_sub_f32_e32 v7, 1.0, v103
	v_fma_mix_f32 v4, v7, v5, v4 op_sel:[0,0,1] op_sel_hi:[0,0,1]
	v_mul_f32_e32 v5, v7, v6
	v_sub_f32_e32 v6, 1.0, v104
	v_fma_mix_f32 v3, v6, v4, v3 op_sel:[0,0,1] op_sel_hi:[0,0,1]
	v_mul_f32_e32 v4, v6, v5
	v_sub_f32_e32 v5, 1.0, v105
	v_fma_mix_f32 v2, v5, v3, v2 op_sel:[0,0,1] op_sel_hi:[0,0,1]
	v_mul_f32_e32 v34, v5, v4
	v_add_f32_e32 v35, 0, v2

; __device__ __forceinline__ u32x4 pack8(const f32x4 a, const f32x4 b) { u32x4 w; w.x = cvt_pk_bf16(a[0], a[1]); w.y = cvt_pk_bf16(a[2], a[3]); w.z = cvt_pk_bf16(b[0], b[1]); w.w = cvt_pk_bf16(b[2], b[3]); return w; }
;     __device__ __forceinline__ void operator()(const f32x4 (&acc)[2][2][4][2], const Unit& u, int wr, int wc, int fr, int fq) const {
;     ...
;         const float* gp = gate + (size_t)bb * 6144 + col0;
;         f32x4 gv[2][2];
; #pragma unroll
;         for (int bj = 0; bj < 2; ++bj)
; #pragma unroll
;             for (int n = 0; n < 2; ++n) gv[bj][n] = *(const f32x4*)(gp + bj * 32 + n * 4);
;         const float* ib = lat ? rinL : rinC - (size_t)32768 * 1024; float* ob = lat ? routL : routC - (size_t)32768 * 1024;
;         const bool tobf = lat && vout != nullptr;
; #pragma unroll
;         for (int ai = 0; ai < 2; ++ai)
; #pragma unroll
;             for (int m = 0; m < 4; ++m) { const size_t off = (size_t)(rowb + ai * HALF + m * 16) * 1024 + col0;
; #pragma unroll
;                 for (int bj = 0; bj < 2; ++bj) { f32x4 o[2];
;                     if (lat && rinB) { const u32x4 w = *(const u32x4*)(rinB + off + bj * 32);
;                         const f32x4 b0 = {__builtin_bit_cast(float, w.x << 16), __builtin_bit_cast(float, w.x & 0xffff0000u), __builtin_bit_cast(float, w.y << 16), __builtin_bit_cast(float, w.y & 0xffff0000u)};
;                         const f32x4 b1 = {__builtin_bit_cast(float, w.z << 16), __builtin_bit_cast(float, w.z & 0xffff0000u), __builtin_bit_cast(float, w.w << 16), __builtin_bit_cast(float, w.w & 0xffff0000u)};
;                         o[0] = b0 * 1.6817928305074290f + gv[bj][0] * acc[ai][bj][m][0]; o[1] = b1 * 1.6817928305074290f + gv[bj][1] * acc[ai][bj][m][1]; }
;                     else {
; #pragma unroll
;                     for (int n = 0; n < 2; ++n) { const f32x4 bs = *(const f32x4*)(ib + off + bj * 32 + n * 4); o[n] = bs * 1.6817928305074290f + gv[bj][n] * acc[ai][bj][m][n]; } }
;                     if (tobf) *(u32x4*)(vout + off + bj * 32) = pack8(o[0], o[1]);
;                     else { *(f32x4*)(ob + off + bj * 32) = o[0]; *(f32x4*)(ob + off + bj * 32 + 4) = o[1]; } }
.LBB0_888:
	v_lshl_add_u32 v188, s34, 8, v204
	v_lshl_or_b32 v190, s30, 8, v206
	s_mov_b64 s[30:31], -1
	s_cmp_lt_i32 s18, 0
	v_ashrrev_i32_e32 v191, 31, v190
	v_ashrrev_i32_e32 v189, 31, v188
	s_cbranch_scc0 .LBB0_897
	s_lshl_b64 s[30:31], s[38:39], 2
	s_add_u32 s30, s42, s30
	s_addc_u32 s31, s43, s31
	v_lshl_add_u64 v[150:151], v[190:191], 2, s[30:31]
	global_load_dwordx4 v[154:157], v[150:151], off offset:16
	global_load_dwordx4 v[158:161], v[150:151], off
	global_load_dwordx4 v[146:149], v[150:151], off offset:144
	s_nop 0
	global_load_dwordx4 v[150:153], v[150:151], off offset:128
	v_readlane_b32 s0, v252, 8
	s_and_b64 s[30:31], exec, s[36:37]
	v_readlane_b32 s1, v252, 9
	s_cselect_b32 s35, s54, s1
	s_cselect_b32 s34, s53, s0
	v_lshlrev_b64 v[162:163], 10, v[188:189]
	s_or_b64 s[38:39], s[36:37], s[68:69]
	v_lshl_add_u64 v[192:193], v[162:163], 0, v[190:191]
	v_lshlrev_b32_e32 v250, 1, v192
	global_load_dwordx4 v[208:211], v250, s[92:93]
	global_load_dwordx4 v[226:229], v250, s[92:93] offset:64
	v_add_u32_e32 v251, 0x8000, v250
	global_load_dwordx4 v[230:233], v251, s[92:93]
	v_add_u32_e32 v251, 0x8000, v250
	global_load_dwordx4 v[234:237], v251, s[92:93] offset:64
	v_add_u32_e32 v251, 0x10000, v250
	global_load_dwordx4 v[238:241], v251, s[92:93]
	v_add_u32_e32 v251, 0x10000, v250
	global_load_dwordx4 v[242:245], v251, s[92:93] offset:64
	v_add_u32_e32 v251, 0x18000, v250
	global_load_dwordx4 v[246:249], v251, s[92:93]
	s_mov_b64 s[30:31], -1
	s_and_b64 vcc, exec, s[38:39]
	v_readlane_b32 s2, v252, 10
	v_readlane_b32 s3, v252, 11
	v_readlane_b32 s4, v252, 12
	v_readlane_b32 s5, v252, 13
	v_readlane_b32 s6, v252, 14
	v_readlane_b32 s7, v252, 15
	v_readlane_b32 s8, v252, 16
	v_readlane_b32 s9, v252, 17
	v_readlane_b32 s10, v252, 18
	v_readlane_b32 s11, v252, 19
	v_readlane_b32 s12, v252, 20
	v_readlane_b32 s13, v252, 21
	v_readlane_b32 s14, v252, 22
	v_readlane_b32 s15, v252, 23
	s_cbranch_vccnz .LBB0_891
	s_mov_b64 s[30:31], 0
	s_waitcnt vmcnt(6)
	v_lshlrev_b32_e32 v170, 16, v208
	v_and_b32_e32 v171, 0xffff0000, v208
	v_lshlrev_b32_e32 v162, 16, v209
	v_and_b32_e32 v163, 0xffff0000, v209
	v_pk_mul_f32 v[170:171], v[170:171], s[86:87] op_sel_hi:[1,0]
	v_pk_mul_f32 v[162:163], v[162:163], s[86:87] op_sel_hi:[1,0]
	v_lshlrev_b32_e32 v166, 16, v210
	v_and_b32_e32 v167, 0xffff0000, v210
	v_lshlrev_b32_e32 v168, 16, v211
	v_and_b32_e32 v169, 0xffff0000, v211
	v_pk_fma_f32 v[164:165], v[144:145], v[160:161], v[162:163]
	v_pk_fma_f32 v[162:163], v[142:143], v[158:159], v[170:171]
	v_add_u32_e32 v251, 0x18000, v250
	global_load_dwordx4 v[208:211], v251, s[92:93] offset:64
.LBB0_891:
	s_andn2_b64 vcc, exec, s[30:31]
	v_lshl_add_u64 v[196:197], v[192:193], 2, s[34:35]
	s_cbranch_vccnz .LBB0_893
	global_load_dwordx4 v[162:165], v[196:197], off
	global_load_dwordx4 v[166:169], v[196:197], off offset:16
	s_waitcnt vmcnt(0)
	v_pk_mul_f32 v[164:165], v[164:165], s[86:87] op_sel_hi:[1,0]
	v_pk_mul_f32 v[162:163], v[162:163], s[86:87] op_sel_hi:[1,0]
	v_pk_fma_f32 v[164:165], v[144:145], v[160:161], v[164:165]
	v_pk_fma_f32 v[162:163], v[142:143], v[158:159], v[162:163]
	s_waitcnt vmcnt(0)
.LBB0_893:
	v_readlane_b32 s0, v254, 35
	s_and_b64 s[30:31], exec, s[36:37]
	v_readlane_b32 s1, v254, 36
	v_pk_mul_f32 v[168:169], v[168:169], s[86:87] op_sel_hi:[1,0]
	v_pk_mul_f32 v[166:167], v[166:167], s[86:87] op_sel_hi:[1,0]
	s_cselect_b32 s31, s1, s93
	s_cselect_b32 s30, s0, s92
	v_pk_fma_f32 v[170:171], v[138:139], v[154:155], v[166:167]
	v_pk_fma_f32 v[172:173], v[140:141], v[156:157], v[168:169]
	s_andn2_b64 vcc, exec, s[28:29]
	v_lshl_add_u64 v[194:195], v[192:193], 1, s[64:65]
	v_readlane_b32 s2, v254, 33
	v_readlane_b32 s3, v252, 47
	s_cbranch_vccnz .LBB0_899
	v_cvt_pk_bf16_f32 v166, v162, v163
	v_cvt_pk_bf16_f32 v167, v164, v165
	v_cvt_pk_bf16_f32 v168, v170, v171
	v_cvt_pk_bf16_f32 v169, v172, v173
	s_mov_b64 s[36:37], -1
	s_and_b64 vcc, exec, s[16:17]
	global_store_dwordx4 v[194:195], v[166:169], off
	s_cbranch_vccz .LBB0_896
	s_nop 0
	s_mov_b64 s[36:37], 0
	s_waitcnt vmcnt(7)
	v_lshlrev_b32_e32 v202, 16, v226
	v_and_b32_e32 v203, 0xffff0000, v226
	v_lshlrev_b32_e32 v166, 16, v227
	v_and_b32_e32 v167, 0xffff0000, v227
	v_pk_mul_f32 v[202:203], v[202:203], s[86:87] op_sel_hi:[1,0]
	v_pk_mul_f32 v[166:167], v[166:167], s[86:87] op_sel_hi:[1,0]
	v_lshlrev_b32_e32 v174, 16, v228
	v_and_b32_e32 v175, 0xffff0000, v228
	v_lshlrev_b32_e32 v176, 16, v229
	v_and_b32_e32 v177, 0xffff0000, v229
	v_pk_fma_f32 v[168:169], v[132:133], v[152:153], v[166:167]
	v_pk_fma_f32 v[166:167], v[130:131], v[150:151], v[202:203]
	v_add_u32_e32 v251, 0x40000, v250
	global_load_dwordx4 v[226:229], v251, s[92:93]

; __device__ __forceinline__ u32x4 pack8(const f32x4 a, const f32x4 b) { u32x4 w; w.x = cvt_pk_bf16(a[0], a[1]); w.y = cvt_pk_bf16(a[2], a[3]); w.z = cvt_pk_bf16(b[0], b[1]); w.w = cvt_pk_bf16(b[2], b[3]); return w; }
;     __device__ __forceinline__ void operator()(const f32x4 (&acc)[2][2][4][2], const Unit& u, int wr, int wc, int fr, int fq) const {
;     ...
;                 for (int bj = 0; bj < 2; ++bj) { f32x4 o[2];
;                     if (lat && rinB) { const u32x4 w = *(const u32x4*)(rinB + off + bj * 32);
;                         const f32x4 b0 = {__builtin_bit_cast(float, w.x << 16), __builtin_bit_cast(float, w.x & 0xffff0000u), __builtin_bit_cast(float, w.y << 16), __builtin_bit_cast(float, w.y & 0xffff0000u)};
;                         const f32x4 b1 = {__builtin_bit_cast(float, w.z << 16), __builtin_bit_cast(float, w.z & 0xffff0000u), __builtin_bit_cast(float, w.w << 16), __builtin_bit_cast(float, w.w & 0xffff0000u)};
;                         o[0] = b0 * 1.6817928305074290f + gv[bj][0] * acc[ai][bj][m][0]; o[1] = b1 * 1.6817928305074290f + gv[bj][1] * acc[ai][bj][m][1]; }
;                     else {
; #pragma unroll
;                     for (int n = 0; n < 2; ++n) { const f32x4 bs = *(const f32x4*)(ib + off + bj * 32 + n * 4); o[n] = bs * 1.6817928305074290f + gv[bj][n] * acc[ai][bj][m][n]; } }
;                     if (tobf) *(u32x4*)(vout + off + bj * 32) = pack8(o[0], o[1]);
;                     else { *(f32x4*)(ob + off + bj * 32) = o[0]; *(f32x4*)(ob + off + bj * 32 + 4) = o[1]; } }
.LBB0_901:
	s_andn2_b64 vcc, exec, s[36:37]
	s_cbranch_vccnz .LBB0_903
	global_load_dwordx4 v[162:165], v[196:197], off offset:128
	global_load_dwordx4 v[174:177], v[196:197], off offset:144
	s_waitcnt vmcnt(1)
	v_pk_mul_f32 v[164:165], v[164:165], s[86:87] op_sel_hi:[1,0]
	v_pk_mul_f32 v[162:163], v[162:163], s[86:87] op_sel_hi:[1,0]
	v_pk_fma_f32 v[168:169], v[132:133], v[152:153], v[164:165]
	v_pk_fma_f32 v[166:167], v[130:131], v[150:151], v[162:163]
	s_waitcnt vmcnt(0)
.LBB0_903:
	v_pk_mul_f32 v[164:165], v[176:177], s[86:87] op_sel_hi:[1,0]
	v_pk_mul_f32 v[162:163], v[174:175], s[86:87] op_sel_hi:[1,0]
	v_pk_fma_f32 v[164:165], v[108:109], v[148:149], v[164:165]
	v_pk_fma_f32 v[162:163], v[106:107], v[146:147], v[162:163]
	s_mov_b64 s[36:37], -1
	s_and_b64 vcc, exec, s[28:29]
	s_cbranch_vccz .LBB0_905
	v_cvt_pk_bf16_f32 v170, v166, v167
	v_cvt_pk_bf16_f32 v171, v168, v169
	v_cvt_pk_bf16_f32 v172, v162, v163
	v_cvt_pk_bf16_f32 v173, v164, v165
	global_store_dwordx4 v[194:195], v[170:173], off offset:64
	s_mov_b64 s[36:37], 0

; __device__ __forceinline__ u32x4 pack8(const f32x4 a, const f32x4 b) { u32x4 w; w.x = cvt_pk_bf16(a[0], a[1]); w.y = cvt_pk_bf16(a[2], a[3]); w.z = cvt_pk_bf16(b[0], b[1]); w.w = cvt_pk_bf16(b[2], b[3]); return w; }
;     __device__ __forceinline__ void operator()(const f32x4 (&acc)[2][2][4][2], const Unit& u, int wr, int wc, int fr, int fq) const {
;     ...
;             for (int m = 0; m < 4; ++m) { const size_t off = (size_t)(rowb + ai * HALF + m * 16) * 1024 + col0;
; #pragma unroll
;                 for (int bj = 0; bj < 2; ++bj) { f32x4 o[2];
;                     if (lat && rinB) { const u32x4 w = *(const u32x4*)(rinB + off + bj * 32);
;                         const f32x4 b0 = {__builtin_bit_cast(float, w.x << 16), __builtin_bit_cast(float, w.x & 0xffff0000u), __builtin_bit_cast(float, w.y << 16), __builtin_bit_cast(float, w.y & 0xffff0000u)};
;                         const f32x4 b1 = {__builtin_bit_cast(float, w.z << 16), __builtin_bit_cast(float, w.z & 0xffff0000u), __builtin_bit_cast(float, w.w << 16), __builtin_bit_cast(float, w.w & 0xffff0000u)};
;                         o[0] = b0 * 1.6817928305074290f + gv[bj][0] * acc[ai][bj][m][0]; o[1] = b1 * 1.6817928305074290f + gv[bj][1] * acc[ai][bj][m][1]; }
;                     else {
; #pragma unroll
;                     for (int n = 0; n < 2; ++n) { const f32x4 bs = *(const f32x4*)(ib + off + bj * 32 + n * 4); o[n] = bs * 1.6817928305074290f + gv[bj][n] * acc[ai][bj][m][n]; } }
;                     if (tobf) *(u32x4*)(vout + off + bj * 32) = pack8(o[0], o[1]);
;                     else { *(f32x4*)(ob + off + bj * 32) = o[0]; *(f32x4*)(ob + off + bj * 32 + 4) = o[1]; } }
.LBB0_907:
	s_nop 1
	v_or_b32_e32 v162, 16, v188
	v_ashrrev_i32_e32 v163, 31, v162
	v_lshlrev_b64 v[162:163], 10, v[162:163]
	v_lshl_add_u64 v[192:193], v[162:163], 0, v[190:191]
	s_mov_b64 s[36:37], -1
	s_and_b64 vcc, exec, s[38:39]
	s_cbranch_vccnz .LBB0_909
	s_mov_b64 s[36:37], 0
	s_waitcnt vmcnt(8)
	v_lshlrev_b32_e32 v170, 16, v230
	v_and_b32_e32 v171, 0xffff0000, v230
	v_lshlrev_b32_e32 v162, 16, v231
	v_and_b32_e32 v163, 0xffff0000, v231
	v_pk_mul_f32 v[170:171], v[170:171], s[86:87] op_sel_hi:[1,0]
	v_pk_mul_f32 v[162:163], v[162:163], s[86:87] op_sel_hi:[1,0]
	v_lshlrev_b32_e32 v166, 16, v232
	v_and_b32_e32 v167, 0xffff0000, v232
	v_lshlrev_b32_e32 v168, 16, v233
	v_and_b32_e32 v169, 0xffff0000, v233
	v_pk_fma_f32 v[164:165], v[136:137], v[160:161], v[162:163]
	v_pk_fma_f32 v[162:163], v[134:135], v[158:159], v[170:171]
	v_add_u32_e32 v251, 0x40000, v250
	global_load_dwordx4 v[230:233], v251, s[92:93] offset:64
.LBB0_909:
	s_andn2_b64 vcc, exec, s[36:37]
	v_lshl_add_u64 v[196:197], v[192:193], 2, s[34:35]
	s_cbranch_vccnz .LBB0_911
	global_load_dwordx4 v[162:165], v[196:197], off
	global_load_dwordx4 v[166:169], v[196:197], off offset:16
	s_waitcnt vmcnt(1)
	v_pk_mul_f32 v[164:165], v[164:165], s[86:87] op_sel_hi:[1,0]
	v_pk_mul_f32 v[162:163], v[162:163], s[86:87] op_sel_hi:[1,0]
	v_pk_fma_f32 v[164:165], v[136:137], v[160:161], v[164:165]
	v_pk_fma_f32 v[162:163], v[134:135], v[158:159], v[162:163]
	s_waitcnt vmcnt(0)
.LBB0_911:
	v_pk_mul_f32 v[168:169], v[168:169], s[86:87] op_sel_hi:[1,0]
	v_pk_mul_f32 v[166:167], v[166:167], s[86:87] op_sel_hi:[1,0]
	v_pk_fma_f32 v[176:177], v[112:113], v[156:157], v[168:169]
	v_pk_fma_f32 v[174:175], v[110:111], v[154:155], v[166:167]
	s_and_b64 vcc, exec, s[28:29]
	v_lshl_add_u64 v[194:195], v[192:193], 1, s[64:65]
	s_cbranch_vccz .LBB0_915
	v_cvt_pk_bf16_f32 v166, v162, v163
	v_cvt_pk_bf16_f32 v167, v164, v165
	v_cvt_pk_bf16_f32 v168, v174, v175
	v_cvt_pk_bf16_f32 v169, v176, v177
	s_mov_b64 s[36:37], -1
	s_and_b64 vcc, exec, s[16:17]
	global_store_dwordx4 v[194:195], v[166:169], off
	s_cbranch_vccz .LBB0_914
	s_nop 0
	s_mov_b64 s[36:37], 0
	s_waitcnt vmcnt(9)
	v_lshlrev_b32_e32 v202, 16, v234
	v_and_b32_e32 v203, 0xffff0000, v234
	v_lshlrev_b32_e32 v166, 16, v235
	v_and_b32_e32 v167, 0xffff0000, v235
	v_pk_mul_f32 v[202:203], v[202:203], s[86:87] op_sel_hi:[1,0]
	v_pk_mul_f32 v[166:167], v[166:167], s[86:87] op_sel_hi:[1,0]
	v_lshlrev_b32_e32 v170, 16, v236
	v_and_b32_e32 v171, 0xffff0000, v236
	v_lshlrev_b32_e32 v172, 16, v237
	v_and_b32_e32 v173, 0xffff0000, v237
	v_pk_fma_f32 v[168:169], v[100:101], v[152:153], v[166:167]
	v_pk_fma_f32 v[166:167], v[98:99], v[150:151], v[202:203]
	v_add_u32_e32 v251, 0x48000, v250
	global_load_dwordx4 v[234:237], v251, s[92:93]

; __device__ __forceinline__ u32x4 pack8(const f32x4 a, const f32x4 b) { u32x4 w; w.x = cvt_pk_bf16(a[0], a[1]); w.y = cvt_pk_bf16(a[2], a[3]); w.z = cvt_pk_bf16(b[0], b[1]); w.w = cvt_pk_bf16(b[2], b[3]); return w; }
;     __device__ __forceinline__ void operator()(const f32x4 (&acc)[2][2][4][2], const Unit& u, int wr, int wc, int fr, int fq) const {
;     ...
;                 for (int bj = 0; bj < 2; ++bj) { f32x4 o[2];
;                     if (lat && rinB) { const u32x4 w = *(const u32x4*)(rinB + off + bj * 32);
;                         const f32x4 b0 = {__builtin_bit_cast(float, w.x << 16), __builtin_bit_cast(float, w.x & 0xffff0000u), __builtin_bit_cast(float, w.y << 16), __builtin_bit_cast(float, w.y & 0xffff0000u)};
;                         const f32x4 b1 = {__builtin_bit_cast(float, w.z << 16), __builtin_bit_cast(float, w.z & 0xffff0000u), __builtin_bit_cast(float, w.w << 16), __builtin_bit_cast(float, w.w & 0xffff0000u)};
;                         o[0] = b0 * 1.6817928305074290f + gv[bj][0] * acc[ai][bj][m][0]; o[1] = b1 * 1.6817928305074290f + gv[bj][1] * acc[ai][bj][m][1]; }
;                     else {
; #pragma unroll
;                     for (int n = 0; n < 2; ++n) { const f32x4 bs = *(const f32x4*)(ib + off + bj * 32 + n * 4); o[n] = bs * 1.6817928305074290f + gv[bj][n] * acc[ai][bj][m][n]; } }
;                     if (tobf) *(u32x4*)(vout + off + bj * 32) = pack8(o[0], o[1]);
;                     else { *(f32x4*)(ob + off + bj * 32) = o[0]; *(f32x4*)(ob + off + bj * 32 + 4) = o[1]; } }
.LBB0_917:
	s_andn2_b64 vcc, exec, s[36:37]
	s_cbranch_vccnz .LBB0_919
	global_load_dwordx4 v[162:165], v[196:197], off offset:128
	global_load_dwordx4 v[170:173], v[196:197], off offset:144
	s_waitcnt vmcnt(1)
	v_pk_mul_f32 v[164:165], v[164:165], s[86:87] op_sel_hi:[1,0]
	v_pk_mul_f32 v[162:163], v[162:163], s[86:87] op_sel_hi:[1,0]
	v_pk_fma_f32 v[168:169], v[100:101], v[152:153], v[164:165]
	v_pk_fma_f32 v[166:167], v[98:99], v[150:151], v[162:163]
	s_waitcnt vmcnt(0)
.LBB0_919:
	v_pk_mul_f32 v[162:163], v[172:173], s[86:87] op_sel_hi:[1,0]
	v_pk_mul_f32 v[170:171], v[170:171], s[86:87] op_sel_hi:[1,0]
	v_pk_fma_f32 v[164:165], v[92:93], v[148:149], v[162:163]
	v_pk_fma_f32 v[162:163], v[90:91], v[146:147], v[170:171]
	s_mov_b64 s[36:37], -1
	s_and_b64 vcc, exec, s[28:29]
	s_cbranch_vccz .LBB0_921
	v_cvt_pk_bf16_f32 v170, v166, v167
	v_cvt_pk_bf16_f32 v171, v168, v169
	v_cvt_pk_bf16_f32 v172, v162, v163
	v_cvt_pk_bf16_f32 v173, v164, v165
	global_store_dwordx4 v[194:195], v[170:173], off offset:64
	s_mov_b64 s[36:37], 0

; __device__ __forceinline__ u32x4 pack8(const f32x4 a, const f32x4 b) { u32x4 w; w.x = cvt_pk_bf16(a[0], a[1]); w.y = cvt_pk_bf16(a[2], a[3]); w.z = cvt_pk_bf16(b[0], b[1]); w.w = cvt_pk_bf16(b[2], b[3]); return w; }
;     __device__ __forceinline__ void operator()(const f32x4 (&acc)[2][2][4][2], const Unit& u, int wr, int wc, int fr, int fq) const {
;     ...
;         for (int ai = 0; ai < 2; ++ai)
; #pragma unroll
;             for (int m = 0; m < 4; ++m) { const size_t off = (size_t)(rowb + ai * HALF + m * 16) * 1024 + col0;
; #pragma unroll
;                 for (int bj = 0; bj < 2; ++bj) { f32x4 o[2];
;                     if (lat && rinB) { const u32x4 w = *(const u32x4*)(rinB + off + bj * 32);
;                         const f32x4 b0 = {__builtin_bit_cast(float, w.x << 16), __builtin_bit_cast(float, w.x & 0xffff0000u), __builtin_bit_cast(float, w.y << 16), __builtin_bit_cast(float, w.y & 0xffff0000u)};
;                         const f32x4 b1 = {__builtin_bit_cast(float, w.z << 16), __builtin_bit_cast(float, w.z & 0xffff0000u), __builtin_bit_cast(float, w.w << 16), __builtin_bit_cast(float, w.w & 0xffff0000u)};
;                         o[0] = b0 * 1.6817928305074290f + gv[bj][0] * acc[ai][bj][m][0]; o[1] = b1 * 1.6817928305074290f + gv[bj][1] * acc[ai][bj][m][1]; }
;                     else {
; #pragma unroll
;                     for (int n = 0; n < 2; ++n) { const f32x4 bs = *(const f32x4*)(ib + off + bj * 32 + n * 4); o[n] = bs * 1.6817928305074290f + gv[bj][n] * acc[ai][bj][m][n]; } }
;                     if (tobf) *(u32x4*)(vout + off + bj * 32) = pack8(o[0], o[1]);
;                     else { *(f32x4*)(ob + off + bj * 32) = o[0]; *(f32x4*)(ob + off + bj * 32 + 4) = o[1]; } }
.LBB0_923:
	s_nop 1
	v_or_b32_e32 v162, 32, v188
	v_ashrrev_i32_e32 v163, 31, v162
	v_lshlrev_b64 v[162:163], 10, v[162:163]
	v_lshl_add_u64 v[192:193], v[162:163], 0, v[190:191]
	s_mov_b64 s[36:37], -1
	s_and_b64 vcc, exec, s[38:39]
	s_cbranch_vccnz .LBB0_925
	s_mov_b64 s[36:37], 0
	s_waitcnt vmcnt(10)
	v_lshlrev_b32_e32 v170, 16, v238
	v_and_b32_e32 v171, 0xffff0000, v238
	v_lshlrev_b32_e32 v162, 16, v239
	v_and_b32_e32 v163, 0xffff0000, v239
	v_pk_mul_f32 v[170:171], v[170:171], s[86:87] op_sel_hi:[1,0]
	v_pk_mul_f32 v[162:163], v[162:163], s[86:87] op_sel_hi:[1,0]
	v_lshlrev_b32_e32 v166, 16, v240
	v_and_b32_e32 v167, 0xffff0000, v240
	v_lshlrev_b32_e32 v168, 16, v241
	v_and_b32_e32 v169, 0xffff0000, v241
	v_pk_fma_f32 v[164:165], v[104:105], v[160:161], v[162:163]
	v_pk_fma_f32 v[162:163], v[102:103], v[158:159], v[170:171]
	v_add_u32_e32 v251, 0x48000, v250
	global_load_dwordx4 v[238:241], v251, s[92:93] offset:64
.LBB0_925:
	s_andn2_b64 vcc, exec, s[36:37]
	v_lshl_add_u64 v[196:197], v[192:193], 2, s[34:35]
	s_cbranch_vccnz .LBB0_927
	global_load_dwordx4 v[162:165], v[196:197], off
	global_load_dwordx4 v[166:169], v[196:197], off offset:16
	s_waitcnt vmcnt(1)
	v_pk_mul_f32 v[164:165], v[164:165], s[86:87] op_sel_hi:[1,0]
	v_pk_mul_f32 v[162:163], v[162:163], s[86:87] op_sel_hi:[1,0]
	v_pk_fma_f32 v[164:165], v[104:105], v[160:161], v[164:165]
	v_pk_fma_f32 v[162:163], v[102:103], v[158:159], v[162:163]
	s_waitcnt vmcnt(0)
.LBB0_927:
	v_pk_mul_f32 v[168:169], v[168:169], s[86:87] op_sel_hi:[1,0]
	v_pk_mul_f32 v[166:167], v[166:167], s[86:87] op_sel_hi:[1,0]
	v_pk_fma_f32 v[172:173], v[96:97], v[156:157], v[168:169]
	v_pk_fma_f32 v[170:171], v[94:95], v[154:155], v[166:167]
	s_and_b64 vcc, exec, s[28:29]
	v_lshl_add_u64 v[194:195], v[192:193], 1, s[64:65]
	s_cbranch_vccz .LBB0_931
	v_cvt_pk_bf16_f32 v166, v162, v163
	v_cvt_pk_bf16_f32 v167, v164, v165
	v_cvt_pk_bf16_f32 v168, v170, v171
	v_cvt_pk_bf16_f32 v169, v172, v173
	s_mov_b64 s[36:37], -1
	s_and_b64 vcc, exec, s[16:17]
	global_store_dwordx4 v[194:195], v[166:169], off
	s_cbranch_vccz .LBB0_930
	s_nop 0
	s_mov_b64 s[36:37], 0
	s_waitcnt vmcnt(11)
	v_lshlrev_b32_e32 v202, 16, v242
	v_and_b32_e32 v203, 0xffff0000, v242
	v_lshlrev_b32_e32 v166, 16, v243
	v_and_b32_e32 v167, 0xffff0000, v243
	v_pk_mul_f32 v[202:203], v[202:203], s[86:87] op_sel_hi:[1,0]
	v_pk_mul_f32 v[166:167], v[166:167], s[86:87] op_sel_hi:[1,0]
	v_lshlrev_b32_e32 v174, 16, v244
	v_and_b32_e32 v175, 0xffff0000, v244
	v_lshlrev_b32_e32 v176, 16, v245
	v_and_b32_e32 v177, 0xffff0000, v245
	v_pk_fma_f32 v[168:169], v[84:85], v[152:153], v[166:167]
	v_pk_fma_f32 v[166:167], v[82:83], v[150:151], v[202:203]
	v_add_u32_e32 v251, 0x50000, v250
	global_load_dwordx4 v[242:245], v251, s[92:93]

; __device__ __forceinline__ u32x4 pack8(const f32x4 a, const f32x4 b) { u32x4 w; w.x = cvt_pk_bf16(a[0], a[1]); w.y = cvt_pk_bf16(a[2], a[3]); w.z = cvt_pk_bf16(b[0], b[1]); w.w = cvt_pk_bf16(b[2], b[3]); return w; }
;     __device__ __forceinline__ void operator()(const f32x4 (&acc)[2][2][4][2], const Unit& u, int wr, int wc, int fr, int fq) const {
;     ...
;                     else {
; #pragma unroll
;                     for (int n = 0; n < 2; ++n) { const f32x4 bs = *(const f32x4*)(ib + off + bj * 32 + n * 4); o[n] = bs * 1.6817928305074290f + gv[bj][n] * acc[ai][bj][m][n]; } }
;                     if (tobf) *(u32x4*)(vout + off + bj * 32) = pack8(o[0], o[1]);
;                     else { *(f32x4*)(ob + off + bj * 32) = o[0]; *(f32x4*)(ob + off + bj * 32 + 4) = o[1]; } }
.LBB0_933:
	s_andn2_b64 vcc, exec, s[36:37]
	s_cbranch_vccnz .LBB0_935
	global_load_dwordx4 v[162:165], v[196:197], off offset:128
	global_load_dwordx4 v[174:177], v[196:197], off offset:144
	s_waitcnt vmcnt(1)
	v_pk_mul_f32 v[164:165], v[164:165], s[86:87] op_sel_hi:[1,0]
	v_pk_mul_f32 v[162:163], v[162:163], s[86:87] op_sel_hi:[1,0]
	v_pk_fma_f32 v[168:169], v[84:85], v[152:153], v[164:165]
	v_pk_fma_f32 v[166:167], v[82:83], v[150:151], v[162:163]
	s_waitcnt vmcnt(0)
.LBB0_935:
	v_pk_mul_f32 v[162:163], v[176:177], s[86:87] op_sel_hi:[1,0]
	v_pk_mul_f32 v[170:171], v[174:175], s[86:87] op_sel_hi:[1,0]
	v_pk_fma_f32 v[164:165], v[76:77], v[148:149], v[162:163]
	v_pk_fma_f32 v[162:163], v[74:75], v[146:147], v[170:171]
	s_mov_b64 s[36:37], -1
	s_and_b64 vcc, exec, s[28:29]
	s_cbranch_vccz .LBB0_937
	v_cvt_pk_bf16_f32 v170, v166, v167
	v_cvt_pk_bf16_f32 v171, v168, v169
	v_cvt_pk_bf16_f32 v172, v162, v163
	v_cvt_pk_bf16_f32 v173, v164, v165
	global_store_dwordx4 v[194:195], v[170:173], off offset:64
	s_mov_b64 s[36:37], 0

; __device__ __forceinline__ u32x4 pack8(const f32x4 a, const f32x4 b) { u32x4 w; w.x = cvt_pk_bf16(a[0], a[1]); w.y = cvt_pk_bf16(a[2], a[3]); w.z = cvt_pk_bf16(b[0], b[1]); w.w = cvt_pk_bf16(b[2], b[3]); return w; }
;     __device__ __forceinline__ void operator()(const f32x4 (&acc)[2][2][4][2], const Unit& u, int wr, int wc, int fr, int fq) const {
;     ...
;         for (int ai = 0; ai < 2; ++ai)
; #pragma unroll
;             for (int m = 0; m < 4; ++m) { const size_t off = (size_t)(rowb + ai * HALF + m * 16) * 1024 + col0;
; #pragma unroll
;                 for (int bj = 0; bj < 2; ++bj) { f32x4 o[2];
;                     if (lat && rinB) { const u32x4 w = *(const u32x4*)(rinB + off + bj * 32);
;                         const f32x4 b0 = {__builtin_bit_cast(float, w.x << 16), __builtin_bit_cast(float, w.x & 0xffff0000u), __builtin_bit_cast(float, w.y << 16), __builtin_bit_cast(float, w.y & 0xffff0000u)};
;                         const f32x4 b1 = {__builtin_bit_cast(float, w.z << 16), __builtin_bit_cast(float, w.z & 0xffff0000u), __builtin_bit_cast(float, w.w << 16), __builtin_bit_cast(float, w.w & 0xffff0000u)};
;                         o[0] = b0 * 1.6817928305074290f + gv[bj][0] * acc[ai][bj][m][0]; o[1] = b1 * 1.6817928305074290f + gv[bj][1] * acc[ai][bj][m][1]; }
;                     else {
; #pragma unroll
;                     for (int n = 0; n < 2; ++n) { const f32x4 bs = *(const f32x4*)(ib + off + bj * 32 + n * 4); o[n] = bs * 1.6817928305074290f + gv[bj][n] * acc[ai][bj][m][n]; } }
;                     if (tobf) *(u32x4*)(vout + off + bj * 32) = pack8(o[0], o[1]);
;                     else { *(f32x4*)(ob + off + bj * 32) = o[0]; *(f32x4*)(ob + off + bj * 32 + 4) = o[1]; } }
.LBB0_939:
	s_nop 1
	v_or_b32_e32 v162, 48, v188
	v_ashrrev_i32_e32 v163, 31, v162
	v_lshlrev_b64 v[162:163], 10, v[162:163]
	v_lshl_add_u64 v[192:193], v[162:163], 0, v[190:191]
	s_mov_b64 s[36:37], -1
	s_and_b64 vcc, exec, s[38:39]
	s_cbranch_vccnz .LBB0_941
	s_mov_b64 s[36:37], 0
	s_waitcnt vmcnt(12)
	v_lshlrev_b32_e32 v170, 16, v246
	v_and_b32_e32 v171, 0xffff0000, v246
	v_lshlrev_b32_e32 v162, 16, v247
	v_and_b32_e32 v163, 0xffff0000, v247
	v_pk_mul_f32 v[170:171], v[170:171], s[86:87] op_sel_hi:[1,0]
	v_pk_mul_f32 v[162:163], v[162:163], s[86:87] op_sel_hi:[1,0]
	v_lshlrev_b32_e32 v166, 16, v248
	v_and_b32_e32 v167, 0xffff0000, v248
	v_lshlrev_b32_e32 v168, 16, v249
	v_and_b32_e32 v169, 0xffff0000, v249
	v_pk_fma_f32 v[164:165], v[88:89], v[160:161], v[162:163]
	v_pk_fma_f32 v[162:163], v[86:87], v[158:159], v[170:171]
	v_add_u32_e32 v251, 0x50000, v250
	global_load_dwordx4 v[246:249], v251, s[92:93] offset:64
.LBB0_941:
	s_andn2_b64 vcc, exec, s[36:37]
	v_lshl_add_u64 v[196:197], v[192:193], 2, s[34:35]
	s_cbranch_vccnz .LBB0_943
	global_load_dwordx4 v[162:165], v[196:197], off
	global_load_dwordx4 v[166:169], v[196:197], off offset:16
	s_waitcnt vmcnt(1)
	v_pk_mul_f32 v[164:165], v[164:165], s[86:87] op_sel_hi:[1,0]
	v_pk_mul_f32 v[162:163], v[162:163], s[86:87] op_sel_hi:[1,0]
	v_pk_fma_f32 v[164:165], v[88:89], v[160:161], v[164:165]
	v_pk_fma_f32 v[162:163], v[86:87], v[158:159], v[162:163]
	s_waitcnt vmcnt(0)
.LBB0_943:
	v_pk_mul_f32 v[168:169], v[168:169], s[86:87] op_sel_hi:[1,0]
	v_pk_mul_f32 v[166:167], v[166:167], s[86:87] op_sel_hi:[1,0]
	v_pk_fma_f32 v[172:173], v[80:81], v[156:157], v[168:169]
	v_pk_fma_f32 v[170:171], v[78:79], v[154:155], v[166:167]
	s_and_b64 vcc, exec, s[28:29]
	v_lshl_add_u64 v[194:195], v[192:193], 1, s[64:65]
	s_cbranch_vccz .LBB0_947
	v_cvt_pk_bf16_f32 v166, v162, v163
	v_cvt_pk_bf16_f32 v167, v164, v165
	v_cvt_pk_bf16_f32 v168, v170, v171
	v_cvt_pk_bf16_f32 v169, v172, v173
	s_mov_b64 s[36:37], -1
	s_and_b64 vcc, exec, s[16:17]
	global_store_dwordx4 v[194:195], v[166:169], off
	s_cbranch_vccz .LBB0_946
	s_nop 0
	s_mov_b64 s[36:37], 0
	s_waitcnt vmcnt(13)
	v_lshlrev_b32_e32 v202, 16, v208
	v_and_b32_e32 v203, 0xffff0000, v208
	v_lshlrev_b32_e32 v166, 16, v209
	v_and_b32_e32 v167, 0xffff0000, v209
	v_pk_mul_f32 v[202:203], v[202:203], s[86:87] op_sel_hi:[1,0]
	v_pk_mul_f32 v[166:167], v[166:167], s[86:87] op_sel_hi:[1,0]
	v_lshlrev_b32_e32 v174, 16, v210
	v_and_b32_e32 v175, 0xffff0000, v210
	v_lshlrev_b32_e32 v176, 16, v211
	v_and_b32_e32 v177, 0xffff0000, v211
	v_pk_fma_f32 v[168:169], v[72:73], v[152:153], v[166:167]
	v_pk_fma_f32 v[166:167], v[70:71], v[150:151], v[202:203]
	v_add_u32_e32 v251, 0x58000, v250
	global_load_dwordx4 v[208:211], v251, s[92:93]

; __device__ __forceinline__ u32x4 pack8(const f32x4 a, const f32x4 b) { u32x4 w; w.x = cvt_pk_bf16(a[0], a[1]); w.y = cvt_pk_bf16(a[2], a[3]); w.z = cvt_pk_bf16(b[0], b[1]); w.w = cvt_pk_bf16(b[2], b[3]); return w; }
;     __device__ __forceinline__ void operator()(const f32x4 (&acc)[2][2][4][2], const Unit& u, int wr, int wc, int fr, int fq) const {
;     ...
;                     else {
; #pragma unroll
;                     for (int n = 0; n < 2; ++n) { const f32x4 bs = *(const f32x4*)(ib + off + bj * 32 + n * 4); o[n] = bs * 1.6817928305074290f + gv[bj][n] * acc[ai][bj][m][n]; } }
;                     if (tobf) *(u32x4*)(vout + off + bj * 32) = pack8(o[0], o[1]);
;                     else { *(f32x4*)(ob + off + bj * 32) = o[0]; *(f32x4*)(ob + off + bj * 32 + 4) = o[1]; } }
.LBB0_949:
	s_andn2_b64 vcc, exec, s[36:37]
	s_cbranch_vccnz .LBB0_951
	global_load_dwordx4 v[162:165], v[196:197], off offset:128
	global_load_dwordx4 v[174:177], v[196:197], off offset:144
	s_waitcnt vmcnt(1)
	v_pk_mul_f32 v[164:165], v[164:165], s[86:87] op_sel_hi:[1,0]
	v_pk_mul_f32 v[162:163], v[162:163], s[86:87] op_sel_hi:[1,0]
	v_pk_fma_f32 v[168:169], v[72:73], v[152:153], v[164:165]
	v_pk_fma_f32 v[166:167], v[70:71], v[150:151], v[162:163]
	s_waitcnt vmcnt(0)
.LBB0_951:
	v_pk_mul_f32 v[162:163], v[176:177], s[86:87] op_sel_hi:[1,0]
	v_pk_mul_f32 v[170:171], v[174:175], s[86:87] op_sel_hi:[1,0]
	v_pk_fma_f32 v[164:165], v[68:69], v[148:149], v[162:163]
	v_pk_fma_f32 v[162:163], v[66:67], v[146:147], v[170:171]
	s_mov_b64 s[36:37], -1
	s_and_b64 vcc, exec, s[28:29]
	s_cbranch_vccz .LBB0_953
	v_cvt_pk_bf16_f32 v170, v166, v167
	v_cvt_pk_bf16_f32 v171, v168, v169
	v_cvt_pk_bf16_f32 v172, v162, v163
	v_cvt_pk_bf16_f32 v173, v164, v165
	global_store_dwordx4 v[194:195], v[170:173], off offset:64
	s_mov_b64 s[36:37], 0

; __device__ __forceinline__ u32x4 pack8(const f32x4 a, const f32x4 b) { u32x4 w; w.x = cvt_pk_bf16(a[0], a[1]); w.y = cvt_pk_bf16(a[2], a[3]); w.z = cvt_pk_bf16(b[0], b[1]); w.w = cvt_pk_bf16(b[2], b[3]); return w; }
;     __device__ __forceinline__ void operator()(const f32x4 (&acc)[2][2][4][2], const Unit& u, int wr, int wc, int fr, int fq) const {
;     ...
;         for (int ai = 0; ai < 2; ++ai)
; #pragma unroll
;             for (int m = 0; m < 4; ++m) { const size_t off = (size_t)(rowb + ai * HALF + m * 16) * 1024 + col0;
; #pragma unroll
;                 for (int bj = 0; bj < 2; ++bj) { f32x4 o[2];
;                     if (lat && rinB) { const u32x4 w = *(const u32x4*)(rinB + off + bj * 32);
;                         const f32x4 b0 = {__builtin_bit_cast(float, w.x << 16), __builtin_bit_cast(float, w.x & 0xffff0000u), __builtin_bit_cast(float, w.y << 16), __builtin_bit_cast(float, w.y & 0xffff0000u)};
;                         const f32x4 b1 = {__builtin_bit_cast(float, w.z << 16), __builtin_bit_cast(float, w.z & 0xffff0000u), __builtin_bit_cast(float, w.w << 16), __builtin_bit_cast(float, w.w & 0xffff0000u)};
;                         o[0] = b0 * 1.6817928305074290f + gv[bj][0] * acc[ai][bj][m][0]; o[1] = b1 * 1.6817928305074290f + gv[bj][1] * acc[ai][bj][m][1]; }
;                     else {
; #pragma unroll
;                     for (int n = 0; n < 2; ++n) { const f32x4 bs = *(const f32x4*)(ib + off + bj * 32 + n * 4); o[n] = bs * 1.6817928305074290f + gv[bj][n] * acc[ai][bj][m][n]; } }
;                     if (tobf) *(u32x4*)(vout + off + bj * 32) = pack8(o[0], o[1]);
;                     else { *(f32x4*)(ob + off + bj * 32) = o[0]; *(f32x4*)(ob + off + bj * 32 + 4) = o[1]; } }
.LBB0_955:
	s_nop 1
	v_lshlrev_b64 v[162:163], 10, v[188:189]
	v_lshl_add_u64 v[162:163], v[162:163], 0, v[190:191]
	v_lshl_add_u64 v[192:193], v[162:163], 0, s[96:97]
	s_mov_b64 s[36:37], -1
	s_and_b64 vcc, exec, s[38:39]
	s_cbranch_vccnz .LBB0_957
	s_mov_b64 s[36:37], 0
	s_waitcnt vmcnt(13)
	v_lshlrev_b32_e32 v170, 16, v226
	v_and_b32_e32 v171, 0xffff0000, v226
	v_lshlrev_b32_e32 v162, 16, v227
	v_and_b32_e32 v163, 0xffff0000, v227
	v_pk_mul_f32 v[170:171], v[170:171], s[86:87] op_sel_hi:[1,0]
	v_pk_mul_f32 v[162:163], v[162:163], s[86:87] op_sel_hi:[1,0]
	v_lshlrev_b32_e32 v166, 16, v228
	v_and_b32_e32 v167, 0xffff0000, v228
	v_lshlrev_b32_e32 v168, 16, v229
	v_and_b32_e32 v169, 0xffff0000, v229
	v_pk_fma_f32 v[164:165], v[64:65], v[160:161], v[162:163]
	v_pk_fma_f32 v[162:163], v[62:63], v[158:159], v[170:171]
	v_add_u32_e32 v251, 0x58000, v250
	global_load_dwordx4 v[226:229], v251, s[92:93] offset:64
.LBB0_957:
	s_andn2_b64 vcc, exec, s[36:37]
	v_lshl_add_u64 v[196:197], v[192:193], 2, s[34:35]
	s_cbranch_vccnz .LBB0_959
	global_load_dwordx4 v[162:165], v[196:197], off
	global_load_dwordx4 v[166:169], v[196:197], off offset:16
	s_waitcnt vmcnt(1)
	v_pk_mul_f32 v[164:165], v[164:165], s[86:87] op_sel_hi:[1,0]
	v_pk_mul_f32 v[162:163], v[162:163], s[86:87] op_sel_hi:[1,0]
	v_pk_fma_f32 v[164:165], v[64:65], v[160:161], v[164:165]
	v_pk_fma_f32 v[162:163], v[62:63], v[158:159], v[162:163]
	s_waitcnt vmcnt(0)
.LBB0_959:
	v_pk_mul_f32 v[168:169], v[168:169], s[86:87] op_sel_hi:[1,0]
	v_pk_mul_f32 v[166:167], v[166:167], s[86:87] op_sel_hi:[1,0]
	v_pk_fma_f32 v[172:173], v[60:61], v[156:157], v[168:169]
	v_pk_fma_f32 v[170:171], v[58:59], v[154:155], v[166:167]
	s_and_b64 vcc, exec, s[28:29]
	v_lshl_add_u64 v[194:195], v[192:193], 1, s[64:65]
	s_cbranch_vccz .LBB0_963
	v_cvt_pk_bf16_f32 v166, v162, v163
	v_cvt_pk_bf16_f32 v167, v164, v165
	v_cvt_pk_bf16_f32 v168, v170, v171
	v_cvt_pk_bf16_f32 v169, v172, v173
	s_mov_b64 s[36:37], -1
	s_and_b64 vcc, exec, s[16:17]
	global_store_dwordx4 v[194:195], v[166:169], off
	s_cbranch_vccz .LBB0_962
	s_nop 0
	s_mov_b64 s[36:37], 0
	s_waitcnt vmcnt(13)
	v_lshlrev_b32_e32 v202, 16, v230
	v_and_b32_e32 v203, 0xffff0000, v230
	v_lshlrev_b32_e32 v166, 16, v231
	v_and_b32_e32 v167, 0xffff0000, v231
	v_pk_mul_f32 v[202:203], v[202:203], s[86:87] op_sel_hi:[1,0]
	v_pk_mul_f32 v[166:167], v[166:167], s[86:87] op_sel_hi:[1,0]
	v_lshlrev_b32_e32 v174, 16, v232
	v_and_b32_e32 v175, 0xffff0000, v232
	v_lshlrev_b32_e32 v176, 16, v233
	v_and_b32_e32 v177, 0xffff0000, v233
	v_pk_fma_f32 v[168:169], v[52:53], v[152:153], v[166:167]
	v_pk_fma_f32 v[166:167], v[50:51], v[150:151], v[202:203]

; __device__ __forceinline__ u32x4 pack8(const f32x4 a, const f32x4 b) { u32x4 w; w.x = cvt_pk_bf16(a[0], a[1]); w.y = cvt_pk_bf16(a[2], a[3]); w.z = cvt_pk_bf16(b[0], b[1]); w.w = cvt_pk_bf16(b[2], b[3]); return w; }
;     __device__ __forceinline__ void operator()(const f32x4 (&acc)[2][2][4][2], const Unit& u, int wr, int wc, int fr, int fq) const {
;     ...
;                     else {
; #pragma unroll
;                     for (int n = 0; n < 2; ++n) { const f32x4 bs = *(const f32x4*)(ib + off + bj * 32 + n * 4); o[n] = bs * 1.6817928305074290f + gv[bj][n] * acc[ai][bj][m][n]; } }
;                     if (tobf) *(u32x4*)(vout + off + bj * 32) = pack8(o[0], o[1]);
;                     else { *(f32x4*)(ob + off + bj * 32) = o[0]; *(f32x4*)(ob + off + bj * 32 + 4) = o[1]; } }
.LBB0_965:
	s_andn2_b64 vcc, exec, s[36:37]
	s_cbranch_vccnz .LBB0_967
	global_load_dwordx4 v[162:165], v[196:197], off offset:128
	global_load_dwordx4 v[174:177], v[196:197], off offset:144
	s_waitcnt vmcnt(1)
	v_pk_mul_f32 v[164:165], v[164:165], s[86:87] op_sel_hi:[1,0]
	v_pk_mul_f32 v[162:163], v[162:163], s[86:87] op_sel_hi:[1,0]
	v_pk_fma_f32 v[168:169], v[52:53], v[152:153], v[164:165]
	v_pk_fma_f32 v[166:167], v[50:51], v[150:151], v[162:163]
	s_waitcnt vmcnt(0)
.LBB0_967:
	v_pk_mul_f32 v[162:163], v[176:177], s[86:87] op_sel_hi:[1,0]
	v_pk_mul_f32 v[170:171], v[174:175], s[86:87] op_sel_hi:[1,0]
	v_pk_fma_f32 v[164:165], v[44:45], v[148:149], v[162:163]
	v_pk_fma_f32 v[162:163], v[42:43], v[146:147], v[170:171]
	s_mov_b64 s[36:37], -1
	s_and_b64 vcc, exec, s[28:29]
	s_cbranch_vccz .LBB0_969
	v_cvt_pk_bf16_f32 v170, v166, v167
	v_cvt_pk_bf16_f32 v171, v168, v169
	v_cvt_pk_bf16_f32 v172, v162, v163
	v_cvt_pk_bf16_f32 v173, v164, v165
	global_store_dwordx4 v[194:195], v[170:173], off offset:64
	s_mov_b64 s[36:37], 0

; __device__ __forceinline__ u32x4 pack8(const f32x4 a, const f32x4 b) { u32x4 w; w.x = cvt_pk_bf16(a[0], a[1]); w.y = cvt_pk_bf16(a[2], a[3]); w.z = cvt_pk_bf16(b[0], b[1]); w.w = cvt_pk_bf16(b[2], b[3]); return w; }
;     __device__ __forceinline__ void operator()(const f32x4 (&acc)[2][2][4][2], const Unit& u, int wr, int wc, int fr, int fq) const {
;     ...
;         for (int ai = 0; ai < 2; ++ai)
; #pragma unroll
;             for (int m = 0; m < 4; ++m) { const size_t off = (size_t)(rowb + ai * HALF + m * 16) * 1024 + col0;
; #pragma unroll
;                 for (int bj = 0; bj < 2; ++bj) { f32x4 o[2];
;                     if (lat && rinB) { const u32x4 w = *(const u32x4*)(rinB + off + bj * 32);
;                         const f32x4 b0 = {__builtin_bit_cast(float, w.x << 16), __builtin_bit_cast(float, w.x & 0xffff0000u), __builtin_bit_cast(float, w.y << 16), __builtin_bit_cast(float, w.y & 0xffff0000u)};
;                         const f32x4 b1 = {__builtin_bit_cast(float, w.z << 16), __builtin_bit_cast(float, w.z & 0xffff0000u), __builtin_bit_cast(float, w.w << 16), __builtin_bit_cast(float, w.w & 0xffff0000u)};
;                         o[0] = b0 * 1.6817928305074290f + gv[bj][0] * acc[ai][bj][m][0]; o[1] = b1 * 1.6817928305074290f + gv[bj][1] * acc[ai][bj][m][1]; }
;                     else {
; #pragma unroll
;                     for (int n = 0; n < 2; ++n) { const f32x4 bs = *(const f32x4*)(ib + off + bj * 32 + n * 4); o[n] = bs * 1.6817928305074290f + gv[bj][n] * acc[ai][bj][m][n]; } }
;                     if (tobf) *(u32x4*)(vout + off + bj * 32) = pack8(o[0], o[1]);
;                     else { *(f32x4*)(ob + off + bj * 32) = o[0]; *(f32x4*)(ob + off + bj * 32 + 4) = o[1]; } }
.LBB0_971:
	s_nop 1
	v_lshlrev_b64 v[162:163], 10, v[188:189]
	v_lshl_add_u64 v[162:163], v[162:163], 0, v[190:191]
	s_mov_b64 s[0:1], 0x24000
	v_lshl_add_u64 v[192:193], v[162:163], 0, s[0:1]
	s_mov_b64 s[36:37], -1
	s_and_b64 vcc, exec, s[38:39]
	s_cbranch_vccnz .LBB0_973
	s_mov_b64 s[36:37], 0
	s_waitcnt vmcnt(12)
	v_lshlrev_b32_e32 v170, 16, v234
	v_and_b32_e32 v171, 0xffff0000, v234
	v_lshlrev_b32_e32 v162, 16, v235
	v_and_b32_e32 v163, 0xffff0000, v235
	v_pk_mul_f32 v[170:171], v[170:171], s[86:87] op_sel_hi:[1,0]
	v_pk_mul_f32 v[162:163], v[162:163], s[86:87] op_sel_hi:[1,0]
	v_lshlrev_b32_e32 v166, 16, v236
	v_and_b32_e32 v167, 0xffff0000, v236
	v_lshlrev_b32_e32 v168, 16, v237
	v_and_b32_e32 v169, 0xffff0000, v237
	v_pk_fma_f32 v[164:165], v[56:57], v[160:161], v[162:163]
	v_pk_fma_f32 v[162:163], v[54:55], v[158:159], v[170:171]
.LBB0_973:
	s_andn2_b64 vcc, exec, s[36:37]
	v_lshl_add_u64 v[196:197], v[192:193], 2, s[34:35]
	s_cbranch_vccnz .LBB0_975
	global_load_dwordx4 v[162:165], v[196:197], off
	global_load_dwordx4 v[166:169], v[196:197], off offset:16
	s_waitcnt vmcnt(1)
	v_pk_mul_f32 v[164:165], v[164:165], s[86:87] op_sel_hi:[1,0]
	v_pk_mul_f32 v[162:163], v[162:163], s[86:87] op_sel_hi:[1,0]
	v_pk_fma_f32 v[164:165], v[56:57], v[160:161], v[164:165]
	v_pk_fma_f32 v[162:163], v[54:55], v[158:159], v[162:163]
	s_waitcnt vmcnt(0)
.LBB0_975:
	v_pk_mul_f32 v[168:169], v[168:169], s[86:87] op_sel_hi:[1,0]
	v_pk_mul_f32 v[166:167], v[166:167], s[86:87] op_sel_hi:[1,0]
	v_pk_fma_f32 v[172:173], v[48:49], v[156:157], v[168:169]
	v_pk_fma_f32 v[170:171], v[46:47], v[154:155], v[166:167]
	s_and_b64 vcc, exec, s[28:29]
	v_lshl_add_u64 v[194:195], v[192:193], 1, s[64:65]
	s_cbranch_vccz .LBB0_979
	v_cvt_pk_bf16_f32 v166, v162, v163
	v_cvt_pk_bf16_f32 v167, v164, v165
	v_cvt_pk_bf16_f32 v168, v170, v171
	v_cvt_pk_bf16_f32 v169, v172, v173
	s_mov_b64 s[36:37], -1
	s_and_b64 vcc, exec, s[16:17]
	global_store_dwordx4 v[194:195], v[166:169], off
	s_cbranch_vccz .LBB0_978
	s_nop 0
	s_mov_b64 s[36:37], 0
	s_waitcnt vmcnt(11)
	v_lshlrev_b32_e32 v202, 16, v238
	v_and_b32_e32 v203, 0xffff0000, v238
	v_lshlrev_b32_e32 v166, 16, v239
	v_and_b32_e32 v167, 0xffff0000, v239
	v_pk_mul_f32 v[202:203], v[202:203], s[86:87] op_sel_hi:[1,0]
	v_pk_mul_f32 v[166:167], v[166:167], s[86:87] op_sel_hi:[1,0]
	v_lshlrev_b32_e32 v174, 16, v240
	v_and_b32_e32 v175, 0xffff0000, v240
	v_lshlrev_b32_e32 v176, 16, v241
	v_and_b32_e32 v177, 0xffff0000, v241
	v_pk_fma_f32 v[168:169], v[36:37], v[152:153], v[166:167]
	v_pk_fma_f32 v[166:167], v[34:35], v[150:151], v[202:203]

; __device__ __forceinline__ u32x4 pack8(const f32x4 a, const f32x4 b) { u32x4 w; w.x = cvt_pk_bf16(a[0], a[1]); w.y = cvt_pk_bf16(a[2], a[3]); w.z = cvt_pk_bf16(b[0], b[1]); w.w = cvt_pk_bf16(b[2], b[3]); return w; }
;     __device__ __forceinline__ void operator()(const f32x4 (&acc)[2][2][4][2], const Unit& u, int wr, int wc, int fr, int fq) const {
;     ...
;                     else {
; #pragma unroll
;                     for (int n = 0; n < 2; ++n) { const f32x4 bs = *(const f32x4*)(ib + off + bj * 32 + n * 4); o[n] = bs * 1.6817928305074290f + gv[bj][n] * acc[ai][bj][m][n]; } }
;                     if (tobf) *(u32x4*)(vout + off + bj * 32) = pack8(o[0], o[1]);
;                     else { *(f32x4*)(ob + off + bj * 32) = o[0]; *(f32x4*)(ob + off + bj * 32 + 4) = o[1]; } }
.LBB0_981:
	s_andn2_b64 vcc, exec, s[36:37]
	s_cbranch_vccnz .LBB0_983
	global_load_dwordx4 v[162:165], v[196:197], off offset:128
	global_load_dwordx4 v[174:177], v[196:197], off offset:144
	s_waitcnt vmcnt(1)
	v_pk_mul_f32 v[164:165], v[164:165], s[86:87] op_sel_hi:[1,0]
	v_pk_mul_f32 v[162:163], v[162:163], s[86:87] op_sel_hi:[1,0]
	v_pk_fma_f32 v[168:169], v[36:37], v[152:153], v[164:165]
	v_pk_fma_f32 v[166:167], v[34:35], v[150:151], v[162:163]
	s_waitcnt vmcnt(0)
.LBB0_983:
	v_pk_mul_f32 v[162:163], v[176:177], s[86:87] op_sel_hi:[1,0]
	v_pk_mul_f32 v[170:171], v[174:175], s[86:87] op_sel_hi:[1,0]
	v_pk_fma_f32 v[164:165], v[28:29], v[148:149], v[162:163]
	v_pk_fma_f32 v[162:163], v[26:27], v[146:147], v[170:171]
	s_mov_b64 s[36:37], -1
	s_and_b64 vcc, exec, s[28:29]
	s_cbranch_vccz .LBB0_985
	v_cvt_pk_bf16_f32 v170, v166, v167
	v_cvt_pk_bf16_f32 v171, v168, v169
	v_cvt_pk_bf16_f32 v172, v162, v163
	v_cvt_pk_bf16_f32 v173, v164, v165
	global_store_dwordx4 v[194:195], v[170:173], off offset:64
	s_mov_b64 s[36:37], 0

; __device__ __forceinline__ u32x4 pack8(const f32x4 a, const f32x4 b) { u32x4 w; w.x = cvt_pk_bf16(a[0], a[1]); w.y = cvt_pk_bf16(a[2], a[3]); w.z = cvt_pk_bf16(b[0], b[1]); w.w = cvt_pk_bf16(b[2], b[3]); return w; }
;     __device__ __forceinline__ void operator()(const f32x4 (&acc)[2][2][4][2], const Unit& u, int wr, int wc, int fr, int fq) const {
;     ...
;         for (int ai = 0; ai < 2; ++ai)
; #pragma unroll
;             for (int m = 0; m < 4; ++m) { const size_t off = (size_t)(rowb + ai * HALF + m * 16) * 1024 + col0;
; #pragma unroll
;                 for (int bj = 0; bj < 2; ++bj) { f32x4 o[2];
;                     if (lat && rinB) { const u32x4 w = *(const u32x4*)(rinB + off + bj * 32);
;                         const f32x4 b0 = {__builtin_bit_cast(float, w.x << 16), __builtin_bit_cast(float, w.x & 0xffff0000u), __builtin_bit_cast(float, w.y << 16), __builtin_bit_cast(float, w.y & 0xffff0000u)};
;                         const f32x4 b1 = {__builtin_bit_cast(float, w.z << 16), __builtin_bit_cast(float, w.z & 0xffff0000u), __builtin_bit_cast(float, w.w << 16), __builtin_bit_cast(float, w.w & 0xffff0000u)};
;                         o[0] = b0 * 1.6817928305074290f + gv[bj][0] * acc[ai][bj][m][0]; o[1] = b1 * 1.6817928305074290f + gv[bj][1] * acc[ai][bj][m][1]; }
;                     else {
; #pragma unroll
;                     for (int n = 0; n < 2; ++n) { const f32x4 bs = *(const f32x4*)(ib + off + bj * 32 + n * 4); o[n] = bs * 1.6817928305074290f + gv[bj][n] * acc[ai][bj][m][n]; } }
;                     if (tobf) *(u32x4*)(vout + off + bj * 32) = pack8(o[0], o[1]);
;                     else { *(f32x4*)(ob + off + bj * 32) = o[0]; *(f32x4*)(ob + off + bj * 32 + 4) = o[1]; } }
.LBB0_987:
	s_nop 1
	v_lshlrev_b64 v[162:163], 10, v[188:189]
	v_lshl_add_u64 v[162:163], v[162:163], 0, v[190:191]
	s_mov_b64 s[0:1], 0x28000
	v_lshl_add_u64 v[192:193], v[162:163], 0, s[0:1]
	s_mov_b64 s[36:37], -1
	s_and_b64 vcc, exec, s[38:39]
	s_cbranch_vccnz .LBB0_989
	s_mov_b64 s[36:37], 0
	s_waitcnt vmcnt(10)
	v_lshlrev_b32_e32 v170, 16, v242
	v_and_b32_e32 v171, 0xffff0000, v242
	v_lshlrev_b32_e32 v162, 16, v243
	v_and_b32_e32 v163, 0xffff0000, v243
	v_pk_mul_f32 v[170:171], v[170:171], s[86:87] op_sel_hi:[1,0]
	v_pk_mul_f32 v[162:163], v[162:163], s[86:87] op_sel_hi:[1,0]
	v_lshlrev_b32_e32 v166, 16, v244
	v_and_b32_e32 v167, 0xffff0000, v244
	v_lshlrev_b32_e32 v168, 16, v245
	v_and_b32_e32 v169, 0xffff0000, v245
	v_pk_fma_f32 v[164:165], v[40:41], v[160:161], v[162:163]
	v_pk_fma_f32 v[162:163], v[38:39], v[158:159], v[170:171]
.LBB0_989:
	s_andn2_b64 vcc, exec, s[36:37]
	v_lshl_add_u64 v[196:197], v[192:193], 2, s[34:35]
	s_cbranch_vccnz .LBB0_991
	global_load_dwordx4 v[162:165], v[196:197], off
	global_load_dwordx4 v[166:169], v[196:197], off offset:16
	s_waitcnt vmcnt(1)
	v_pk_mul_f32 v[164:165], v[164:165], s[86:87] op_sel_hi:[1,0]
	v_pk_mul_f32 v[162:163], v[162:163], s[86:87] op_sel_hi:[1,0]
	v_pk_fma_f32 v[164:165], v[40:41], v[160:161], v[164:165]
	v_pk_fma_f32 v[162:163], v[38:39], v[158:159], v[162:163]
	s_waitcnt vmcnt(0)
.LBB0_991:
	v_pk_mul_f32 v[168:169], v[168:169], s[86:87] op_sel_hi:[1,0]
	v_pk_mul_f32 v[166:167], v[166:167], s[86:87] op_sel_hi:[1,0]
	v_pk_fma_f32 v[172:173], v[32:33], v[156:157], v[168:169]
	v_pk_fma_f32 v[170:171], v[30:31], v[154:155], v[166:167]
	s_and_b64 vcc, exec, s[28:29]
	v_lshl_add_u64 v[194:195], v[192:193], 1, s[64:65]
	s_cbranch_vccz .LBB0_995
	v_cvt_pk_bf16_f32 v166, v162, v163
	v_cvt_pk_bf16_f32 v167, v164, v165
	v_cvt_pk_bf16_f32 v168, v170, v171
	v_cvt_pk_bf16_f32 v169, v172, v173
	s_mov_b64 s[36:37], -1
	s_and_b64 vcc, exec, s[16:17]
	global_store_dwordx4 v[194:195], v[166:169], off
	s_cbranch_vccz .LBB0_994
	s_nop 0
	s_mov_b64 s[36:37], 0
	s_waitcnt vmcnt(9)
	v_lshlrev_b32_e32 v202, 16, v246
	v_and_b32_e32 v203, 0xffff0000, v246
	v_lshlrev_b32_e32 v166, 16, v247
	v_and_b32_e32 v167, 0xffff0000, v247
	v_pk_mul_f32 v[202:203], v[202:203], s[86:87] op_sel_hi:[1,0]
	v_pk_mul_f32 v[166:167], v[166:167], s[86:87] op_sel_hi:[1,0]
	v_lshlrev_b32_e32 v174, 16, v248
	v_and_b32_e32 v175, 0xffff0000, v248
	v_lshlrev_b32_e32 v176, 16, v249
	v_and_b32_e32 v177, 0xffff0000, v249
	v_pk_fma_f32 v[168:169], v[20:21], v[152:153], v[166:167]
	v_pk_fma_f32 v[166:167], v[18:19], v[150:151], v[202:203]

; __device__ __forceinline__ u32x4 pack8(const f32x4 a, const f32x4 b) { u32x4 w; w.x = cvt_pk_bf16(a[0], a[1]); w.y = cvt_pk_bf16(a[2], a[3]); w.z = cvt_pk_bf16(b[0], b[1]); w.w = cvt_pk_bf16(b[2], b[3]); return w; }
;     __device__ __forceinline__ void operator()(const f32x4 (&acc)[2][2][4][2], const Unit& u, int wr, int wc, int fr, int fq) const {
;     ...
;                     else {
; #pragma unroll
;                     for (int n = 0; n < 2; ++n) { const f32x4 bs = *(const f32x4*)(ib + off + bj * 32 + n * 4); o[n] = bs * 1.6817928305074290f + gv[bj][n] * acc[ai][bj][m][n]; } }
;                     if (tobf) *(u32x4*)(vout + off + bj * 32) = pack8(o[0], o[1]);
;                     else { *(f32x4*)(ob + off + bj * 32) = o[0]; *(f32x4*)(ob + off + bj * 32 + 4) = o[1]; } }
.LBB0_997:
	s_andn2_b64 vcc, exec, s[36:37]
	s_cbranch_vccnz .LBB0_999
	global_load_dwordx4 v[162:165], v[196:197], off offset:128
	global_load_dwordx4 v[174:177], v[196:197], off offset:144
	s_waitcnt vmcnt(1)
	v_pk_mul_f32 v[164:165], v[164:165], s[86:87] op_sel_hi:[1,0]
	v_pk_mul_f32 v[162:163], v[162:163], s[86:87] op_sel_hi:[1,0]
	v_pk_fma_f32 v[168:169], v[20:21], v[152:153], v[164:165]
	v_pk_fma_f32 v[166:167], v[18:19], v[150:151], v[162:163]
	s_waitcnt vmcnt(0)
.LBB0_999:
	v_pk_mul_f32 v[162:163], v[176:177], s[86:87] op_sel_hi:[1,0]
	v_pk_mul_f32 v[170:171], v[174:175], s[86:87] op_sel_hi:[1,0]
	v_pk_fma_f32 v[164:165], v[12:13], v[148:149], v[162:163]
	v_pk_fma_f32 v[162:163], v[10:11], v[146:147], v[170:171]
	s_mov_b64 s[36:37], -1
	s_and_b64 vcc, exec, s[28:29]
	s_cbranch_vccz .LBB0_1001
	v_cvt_pk_bf16_f32 v170, v166, v167
	v_cvt_pk_bf16_f32 v171, v168, v169
	v_cvt_pk_bf16_f32 v172, v162, v163
	v_cvt_pk_bf16_f32 v173, v164, v165
	global_store_dwordx4 v[194:195], v[170:173], off offset:64
	s_mov_b64 s[36:37], 0

; __device__ __forceinline__ u32x4 pack8(const f32x4 a, const f32x4 b) { u32x4 w; w.x = cvt_pk_bf16(a[0], a[1]); w.y = cvt_pk_bf16(a[2], a[3]); w.z = cvt_pk_bf16(b[0], b[1]); w.w = cvt_pk_bf16(b[2], b[3]); return w; }
;     __device__ __forceinline__ void operator()(const f32x4 (&acc)[2][2][4][2], const Unit& u, int wr, int wc, int fr, int fq) const {
;     ...
;         for (int ai = 0; ai < 2; ++ai)
; #pragma unroll
;             for (int m = 0; m < 4; ++m) { const size_t off = (size_t)(rowb + ai * HALF + m * 16) * 1024 + col0;
; #pragma unroll
;                 for (int bj = 0; bj < 2; ++bj) { f32x4 o[2];
;                     if (lat && rinB) { const u32x4 w = *(const u32x4*)(rinB + off + bj * 32);
;                         const f32x4 b0 = {__builtin_bit_cast(float, w.x << 16), __builtin_bit_cast(float, w.x & 0xffff0000u), __builtin_bit_cast(float, w.y << 16), __builtin_bit_cast(float, w.y & 0xffff0000u)};
;                         const f32x4 b1 = {__builtin_bit_cast(float, w.z << 16), __builtin_bit_cast(float, w.z & 0xffff0000u), __builtin_bit_cast(float, w.w << 16), __builtin_bit_cast(float, w.w & 0xffff0000u)};
;                         o[0] = b0 * 1.6817928305074290f + gv[bj][0] * acc[ai][bj][m][0]; o[1] = b1 * 1.6817928305074290f + gv[bj][1] * acc[ai][bj][m][1]; }
;                     else {
; #pragma unroll
;                     for (int n = 0; n < 2; ++n) { const f32x4 bs = *(const f32x4*)(ib + off + bj * 32 + n * 4); o[n] = bs * 1.6817928305074290f + gv[bj][n] * acc[ai][bj][m][n]; } }
;                     if (tobf) *(u32x4*)(vout + off + bj * 32) = pack8(o[0], o[1]);
;                     else { *(f32x4*)(ob + off + bj * 32) = o[0]; *(f32x4*)(ob + off + bj * 32 + 4) = o[1]; } }
.LBB0_1003:
	s_nop 1
	v_lshlrev_b64 v[162:163], 10, v[188:189]
	v_lshl_add_u64 v[162:163], v[162:163], 0, v[190:191]
	s_mov_b64 s[0:1], 0x2c000
	v_lshl_add_u64 v[170:171], v[162:163], 0, s[0:1]
	s_mov_b64 s[36:37], -1
	s_and_b64 vcc, exec, s[38:39]
	s_cbranch_vccnz .LBB0_1005
	s_mov_b64 s[36:37], 0
	s_waitcnt vmcnt(8)
	v_lshlrev_b32_e32 v172, 16, v208
	v_and_b32_e32 v173, 0xffff0000, v208
	v_lshlrev_b32_e32 v162, 16, v209
	v_and_b32_e32 v163, 0xffff0000, v209
	v_pk_mul_f32 v[172:173], v[172:173], s[86:87] op_sel_hi:[1,0]
	v_pk_mul_f32 v[162:163], v[162:163], s[86:87] op_sel_hi:[1,0]
	v_lshlrev_b32_e32 v166, 16, v210
	v_and_b32_e32 v167, 0xffff0000, v210
	v_lshlrev_b32_e32 v168, 16, v211
	v_and_b32_e32 v169, 0xffff0000, v211
	v_pk_fma_f32 v[164:165], v[24:25], v[160:161], v[162:163]
	v_pk_fma_f32 v[162:163], v[22:23], v[158:159], v[172:173]
.LBB0_1005:
	s_andn2_b64 vcc, exec, s[36:37]
	v_lshl_add_u64 v[174:175], v[170:171], 2, s[34:35]
	s_cbranch_vccnz .LBB0_1007
	global_load_dwordx4 v[162:165], v[174:175], off
	global_load_dwordx4 v[166:169], v[174:175], off offset:16
	s_waitcnt vmcnt(1)
	v_pk_mul_f32 v[164:165], v[164:165], s[86:87] op_sel_hi:[1,0]
	v_pk_mul_f32 v[162:163], v[162:163], s[86:87] op_sel_hi:[1,0]
	v_pk_fma_f32 v[164:165], v[24:25], v[160:161], v[164:165]
	v_pk_fma_f32 v[162:163], v[22:23], v[158:159], v[162:163]
	s_waitcnt vmcnt(0)
.LBB0_1007:
	v_pk_mul_f32 v[158:159], v[168:169], s[86:87] op_sel_hi:[1,0]
	v_pk_mul_f32 v[166:167], v[166:167], s[86:87] op_sel_hi:[1,0]
	v_pk_fma_f32 v[160:161], v[16:17], v[156:157], v[158:159]
	v_pk_fma_f32 v[158:159], v[14:15], v[154:155], v[166:167]
	s_and_b64 vcc, exec, s[28:29]
	v_lshl_add_u64 v[172:173], v[170:171], 1, s[64:65]
	s_cbranch_vccz .LBB0_1011
	v_cvt_pk_bf16_f32 v154, v162, v163
	v_cvt_pk_bf16_f32 v155, v164, v165
	v_cvt_pk_bf16_f32 v156, v158, v159
	v_cvt_pk_bf16_f32 v157, v160, v161
	s_mov_b64 s[34:35], -1
	s_and_b64 vcc, exec, s[16:17]
	global_store_dwordx4 v[172:173], v[154:157], off
	s_cbranch_vccz .LBB0_1010
	s_nop 0
	s_mov_b64 s[34:35], 0
	s_waitcnt vmcnt(7)
	v_lshlrev_b32_e32 v176, 16, v226
	v_and_b32_e32 v177, 0xffff0000, v226
	v_lshlrev_b32_e32 v154, 16, v227
	v_and_b32_e32 v155, 0xffff0000, v227
	v_pk_mul_f32 v[176:177], v[176:177], s[86:87] op_sel_hi:[1,0]
	v_pk_mul_f32 v[154:155], v[154:155], s[86:87] op_sel_hi:[1,0]
	v_lshlrev_b32_e32 v166, 16, v228
	v_and_b32_e32 v167, 0xffff0000, v228
	v_lshlrev_b32_e32 v168, 16, v229
	v_and_b32_e32 v169, 0xffff0000, v229
	v_pk_fma_f32 v[156:157], v[8:9], v[152:153], v[154:155]
	v_pk_fma_f32 v[154:155], v[6:7], v[150:151], v[176:177]

; __device__ __forceinline__ u32x4 pack8(const f32x4 a, const f32x4 b) { u32x4 w; w.x = cvt_pk_bf16(a[0], a[1]); w.y = cvt_pk_bf16(a[2], a[3]); w.z = cvt_pk_bf16(b[0], b[1]); w.w = cvt_pk_bf16(b[2], b[3]); return w; }
;     __device__ __forceinline__ void operator()(const f32x4 (&acc)[2][2][4][2], const Unit& u, int wr, int wc, int fr, int fq) const {
;     ...
;                     else {
; #pragma unroll
;                     for (int n = 0; n < 2; ++n) { const f32x4 bs = *(const f32x4*)(ib + off + bj * 32 + n * 4); o[n] = bs * 1.6817928305074290f + gv[bj][n] * acc[ai][bj][m][n]; } }
;                     if (tobf) *(u32x4*)(vout + off + bj * 32) = pack8(o[0], o[1]);
;                     else { *(f32x4*)(ob + off + bj * 32) = o[0]; *(f32x4*)(ob + off + bj * 32 + 4) = o[1]; } }
.LBB0_1013:
	s_andn2_b64 vcc, exec, s[34:35]
	s_cbranch_vccnz .LBB0_1015
	global_load_dwordx4 v[154:157], v[174:175], off offset:128
	global_load_dwordx4 v[166:169], v[174:175], off offset:144
	s_waitcnt vmcnt(1)
	v_pk_mul_f32 v[156:157], v[156:157], s[86:87] op_sel_hi:[1,0]
	v_pk_mul_f32 v[154:155], v[154:155], s[86:87] op_sel_hi:[1,0]
	v_pk_fma_f32 v[156:157], v[8:9], v[152:153], v[156:157]
	v_pk_fma_f32 v[154:155], v[6:7], v[150:151], v[154:155]
	s_waitcnt vmcnt(0)
.LBB0_1015:
	v_pk_mul_f32 v[150:151], v[168:169], s[86:87] op_sel_hi:[1,0]
	v_pk_mul_f32 v[152:153], v[166:167], s[86:87] op_sel_hi:[1,0]
	v_pk_fma_f32 v[148:149], v[4:5], v[148:149], v[150:151]
	v_pk_fma_f32 v[146:147], v[2:3], v[146:147], v[152:153]
	s_mov_b64 s[30:31], -1
	s_and_b64 vcc, exec, s[28:29]
	s_cbranch_vccz .LBB0_1017
	v_cvt_pk_bf16_f32 v150, v154, v155
	v_cvt_pk_bf16_f32 v151, v156, v157
	v_cvt_pk_bf16_f32 v152, v146, v147
	v_cvt_pk_bf16_f32 v153, v148, v149
	global_store_dwordx4 v[172:173], v[150:153], off offset:64
	s_mov_b64 s[30:31], 0

; __device__ __forceinline__ u32x4 pack8(const f32x4 a, const f32x4 b) { u32x4 w; w.x = cvt_pk_bf16(a[0], a[1]); w.y = cvt_pk_bf16(a[2], a[3]); w.z = cvt_pk_bf16(b[0], b[1]); w.w = cvt_pk_bf16(b[2], b[3]); return w; }
;     __device__ __forceinline__ void operator()(const f32x4 (&acc)[2][2][4][2], const Unit& u, int wr, int wc, int fr, int fq) const {
;     ...
;         const float* gp = gate + (size_t)bb * 6144 + col0;
;         f32x4 gv[2][2];
; #pragma unroll
;         for (int bj = 0; bj < 2; ++bj)
; #pragma unroll
;             for (int n = 0; n < 2; ++n) gv[bj][n] = *(const f32x4*)(gp + bj * 32 + n * 4);
;         const float* ib = lat ? rinL : rinC - (size_t)32768 * 1024; float* ob = lat ? routL : routC - (size_t)32768 * 1024;
;         const bool tobf = lat && vout != nullptr;
; #pragma unroll
;         for (int ai = 0; ai < 2; ++ai)
; #pragma unroll
;             for (int m = 0; m < 4; ++m) { const size_t off = (size_t)(rowb + ai * HALF + m * 16) * 1024 + col0;
; #pragma unroll
;                 for (int bj = 0; bj < 2; ++bj) { f32x4 o[2];
;                     if (lat && rinB) { const u32x4 w = *(const u32x4*)(rinB + off + bj * 32);
;                         const f32x4 b0 = {__builtin_bit_cast(float, w.x << 16), __builtin_bit_cast(float, w.x & 0xffff0000u), __builtin_bit_cast(float, w.y << 16), __builtin_bit_cast(float, w.y & 0xffff0000u)};
;                         const f32x4 b1 = {__builtin_bit_cast(float, w.z << 16), __builtin_bit_cast(float, w.z & 0xffff0000u), __builtin_bit_cast(float, w.w << 16), __builtin_bit_cast(float, w.w & 0xffff0000u)};
;                         o[0] = b0 * 1.6817928305074290f + gv[bj][0] * acc[ai][bj][m][0]; o[1] = b1 * 1.6817928305074290f + gv[bj][1] * acc[ai][bj][m][1]; }
;                     else {
; #pragma unroll
;                     for (int n = 0; n < 2; ++n) { const f32x4 bs = *(const f32x4*)(ib + off + bj * 32 + n * 4); o[n] = bs * 1.6817928305074290f + gv[bj][n] * acc[ai][bj][m][n]; } }
;                     if (tobf) *(u32x4*)(vout + off + bj * 32) = pack8(o[0], o[1]);
;                     else { *(f32x4*)(ob + off + bj * 32) = o[0]; *(f32x4*)(ob + off + bj * 32 + 4) = o[1]; } }
.LBB0_1044:
	s_lshl_b64 s[36:37], s[36:37], 2
	v_lshl_or_b32 v182, s52, 8, v192
	s_add_u32 s36, s42, s36
	s_addc_u32 s37, s43, s37
	v_ashrrev_i32_e32 v183, 31, v182
	v_lshl_add_u64 v[54:55], v[182:183], 2, s[36:37]
	global_load_dwordx4 v[66:69], v[54:55], off offset:16
	global_load_dwordx4 v[70:73], v[54:55], off
	global_load_dwordx4 v[50:53], v[54:55], off offset:144
	s_nop 0
	global_load_dwordx4 v[54:57], v[54:55], off offset:128
	v_lshl_add_u32 v180, s53, 8, v190
	v_ashrrev_i32_e32 v181, 31, v180
	v_lshlrev_b64 v[162:163], 10, v[180:181]
	v_lshl_add_u64 v[184:185], v[162:163], 0, v[182:183]
	v_lshlrev_b32_e32 v250, 1, v184
	global_load_dwordx4 v[208:211], v250, s[92:93]
	global_load_dwordx4 v[226:229], v250, s[92:93] offset:64
	v_add_u32_e32 v251, 0x8000, v250
	global_load_dwordx4 v[230:233], v251, s[92:93]
	v_add_u32_e32 v251, 0x8000, v250
	global_load_dwordx4 v[234:237], v251, s[92:93] offset:64
	v_add_u32_e32 v251, 0x10000, v250
	global_load_dwordx4 v[238:241], v251, s[92:93]
	v_add_u32_e32 v251, 0x10000, v250
	global_load_dwordx4 v[242:245], v251, s[92:93] offset:64
	v_add_u32_e32 v251, 0x18000, v250
	global_load_dwordx4 v[246:249], v251, s[92:93]
	s_and_b64 vcc, exec, s[34:35]
	s_cbranch_vccnz .LBB0_1046
	s_mov_b64 s[30:31], 0
	s_waitcnt vmcnt(6)
	v_lshlrev_b32_e32 v186, 16, v208
	v_and_b32_e32 v187, 0xffff0000, v208
	v_lshlrev_b32_e32 v162, 16, v209
	v_and_b32_e32 v163, 0xffff0000, v209
	v_pk_mul_f32 v[186:187], v[186:187], s[86:87] op_sel_hi:[1,0]
	v_pk_mul_f32 v[162:163], v[162:163], s[86:87] op_sel_hi:[1,0]
	v_lshlrev_b32_e32 v166, 16, v210
	v_and_b32_e32 v167, 0xffff0000, v210
	v_lshlrev_b32_e32 v168, 16, v211
	v_and_b32_e32 v169, 0xffff0000, v211
	v_pk_fma_f32 v[164:165], v[160:161], v[72:73], v[162:163]
	v_pk_fma_f32 v[162:163], v[158:159], v[70:71], v[186:187]
	v_add_u32_e32 v251, 0x18000, v250
	global_load_dwordx4 v[208:211], v251, s[92:93] offset:64
.LBB0_1046:
	s_andn2_b64 vcc, exec, s[30:31]
	v_lshl_add_u64 v[188:189], v[184:185], 2, s[28:29]
	s_cbranch_vccnz .LBB0_1048
	global_load_dwordx4 v[162:165], v[188:189], off
	global_load_dwordx4 v[166:169], v[188:189], off offset:16
	s_waitcnt vmcnt(0)
	v_pk_mul_f32 v[164:165], v[164:165], s[86:87] op_sel_hi:[1,0]
	v_pk_mul_f32 v[162:163], v[162:163], s[86:87] op_sel_hi:[1,0]
	v_pk_fma_f32 v[164:165], v[160:161], v[72:73], v[164:165]
	v_pk_fma_f32 v[162:163], v[158:159], v[70:71], v[162:163]
	s_waitcnt vmcnt(0)
.LBB0_1048:
	v_pk_mul_f32 v[160:161], v[168:169], s[86:87] op_sel_hi:[1,0]
	v_pk_mul_f32 v[158:159], v[166:167], s[86:87] op_sel_hi:[1,0]
	v_pk_fma_f32 v[160:161], v[156:157], v[68:69], v[160:161]
	v_pk_fma_f32 v[158:159], v[154:155], v[66:67], v[158:159]
	s_andn2_b64 vcc, exec, s[24:25]
	v_lshl_add_u64 v[186:187], v[184:185], 1, s[64:65]
	s_cbranch_vccnz .LBB0_1052
	v_cvt_pk_bf16_f32 v154, v162, v163
	v_cvt_pk_bf16_f32 v155, v164, v165
	v_cvt_pk_bf16_f32 v156, v158, v159
	v_cvt_pk_bf16_f32 v157, v160, v161
	s_mov_b64 s[30:31], -1
	s_and_b64 vcc, exec, s[88:89]
	global_store_dwordx4 v[186:187], v[154:157], off
	s_cbranch_vccz .LBB0_1051
	s_nop 0
	s_mov_b64 s[30:31], 0
	s_waitcnt vmcnt(7)
	v_lshlrev_b32_e32 v194, 16, v226
	v_and_b32_e32 v195, 0xffff0000, v226
	v_lshlrev_b32_e32 v154, 16, v227
	v_and_b32_e32 v155, 0xffff0000, v227
	v_pk_mul_f32 v[194:195], v[194:195], s[86:87] op_sel_hi:[1,0]
	v_pk_mul_f32 v[154:155], v[154:155], s[86:87] op_sel_hi:[1,0]
	v_lshlrev_b32_e32 v166, 16, v228
	v_and_b32_e32 v167, 0xffff0000, v228
	v_lshlrev_b32_e32 v168, 16, v229
	v_and_b32_e32 v169, 0xffff0000, v229
	v_pk_fma_f32 v[156:157], v[152:153], v[56:57], v[154:155]
	v_pk_fma_f32 v[154:155], v[150:151], v[54:55], v[194:195]
	v_add_u32_e32 v251, 0x40000, v250
	global_load_dwordx4 v[226:229], v251, s[92:93]

; __device__ __forceinline__ u32x4 pack8(const f32x4 a, const f32x4 b) { u32x4 w; w.x = cvt_pk_bf16(a[0], a[1]); w.y = cvt_pk_bf16(a[2], a[3]); w.z = cvt_pk_bf16(b[0], b[1]); w.w = cvt_pk_bf16(b[2], b[3]); return w; }
;     __device__ __forceinline__ void operator()(const f32x4 (&acc)[2][2][4][2], const Unit& u, int wr, int wc, int fr, int fq) const {
;     ...
;                     else {
; #pragma unroll
;                     for (int n = 0; n < 2; ++n) { const f32x4 bs = *(const f32x4*)(ib + off + bj * 32 + n * 4); o[n] = bs * 1.6817928305074290f + gv[bj][n] * acc[ai][bj][m][n]; } }
;                     if (tobf) *(u32x4*)(vout + off + bj * 32) = pack8(o[0], o[1]);
;                     else { *(f32x4*)(ob + off + bj * 32) = o[0]; *(f32x4*)(ob + off + bj * 32 + 4) = o[1]; } }
.LBB0_1054:
	s_andn2_b64 vcc, exec, s[30:31]
	s_cbranch_vccnz .LBB0_1056
	global_load_dwordx4 v[154:157], v[188:189], off offset:128
	global_load_dwordx4 v[166:169], v[188:189], off offset:144
	s_waitcnt vmcnt(1)
	v_pk_mul_f32 v[156:157], v[156:157], s[86:87] op_sel_hi:[1,0]
	v_pk_mul_f32 v[154:155], v[154:155], s[86:87] op_sel_hi:[1,0]
	v_pk_fma_f32 v[156:157], v[152:153], v[56:57], v[156:157]
	v_pk_fma_f32 v[154:155], v[150:151], v[54:55], v[154:155]
	s_waitcnt vmcnt(0)
.LBB0_1056:
	v_pk_mul_f32 v[150:151], v[168:169], s[86:87] op_sel_hi:[1,0]
	v_pk_mul_f32 v[152:153], v[166:167], s[86:87] op_sel_hi:[1,0]
	v_pk_fma_f32 v[148:149], v[148:149], v[52:53], v[150:151]
	v_pk_fma_f32 v[146:147], v[146:147], v[50:51], v[152:153]
	s_mov_b64 s[30:31], -1
	s_and_b64 vcc, exec, s[24:25]
	s_cbranch_vccz .LBB0_1058
	v_cvt_pk_bf16_f32 v150, v154, v155
	v_cvt_pk_bf16_f32 v151, v156, v157
	v_cvt_pk_bf16_f32 v152, v146, v147
	v_cvt_pk_bf16_f32 v153, v148, v149
	global_store_dwordx4 v[186:187], v[150:153], off offset:64
	s_mov_b64 s[30:31], 0

; __device__ __forceinline__ u32x4 pack8(const f32x4 a, const f32x4 b) { u32x4 w; w.x = cvt_pk_bf16(a[0], a[1]); w.y = cvt_pk_bf16(a[2], a[3]); w.z = cvt_pk_bf16(b[0], b[1]); w.w = cvt_pk_bf16(b[2], b[3]); return w; }
;     __device__ __forceinline__ void operator()(const f32x4 (&acc)[2][2][4][2], const Unit& u, int wr, int wc, int fr, int fq) const {
;     ...
;         for (int ai = 0; ai < 2; ++ai)
; #pragma unroll
;             for (int m = 0; m < 4; ++m) { const size_t off = (size_t)(rowb + ai * HALF + m * 16) * 1024 + col0;
; #pragma unroll
;                 for (int bj = 0; bj < 2; ++bj) { f32x4 o[2];
;                     if (lat && rinB) { const u32x4 w = *(const u32x4*)(rinB + off + bj * 32);
;                         const f32x4 b0 = {__builtin_bit_cast(float, w.x << 16), __builtin_bit_cast(float, w.x & 0xffff0000u), __builtin_bit_cast(float, w.y << 16), __builtin_bit_cast(float, w.y & 0xffff0000u)};
;                         const f32x4 b1 = {__builtin_bit_cast(float, w.z << 16), __builtin_bit_cast(float, w.z & 0xffff0000u), __builtin_bit_cast(float, w.w << 16), __builtin_bit_cast(float, w.w & 0xffff0000u)};
;                         o[0] = b0 * 1.6817928305074290f + gv[bj][0] * acc[ai][bj][m][0]; o[1] = b1 * 1.6817928305074290f + gv[bj][1] * acc[ai][bj][m][1]; }
;                     else {
; #pragma unroll
;                     for (int n = 0; n < 2; ++n) { const f32x4 bs = *(const f32x4*)(ib + off + bj * 32 + n * 4); o[n] = bs * 1.6817928305074290f + gv[bj][n] * acc[ai][bj][m][n]; } }
;                     if (tobf) *(u32x4*)(vout + off + bj * 32) = pack8(o[0], o[1]);
;                     else { *(f32x4*)(ob + off + bj * 32) = o[0]; *(f32x4*)(ob + off + bj * 32 + 4) = o[1]; } }
.LBB0_1060:
	s_nop 1
	v_or_b32_e32 v146, 16, v180
	v_ashrrev_i32_e32 v147, 31, v146
	v_lshlrev_b64 v[146:147], 10, v[146:147]
	v_lshl_add_u64 v[154:155], v[146:147], 0, v[182:183]
	s_mov_b64 s[30:31], -1
	s_and_b64 vcc, exec, s[34:35]
	s_cbranch_vccnz .LBB0_1062
	s_mov_b64 s[30:31], 0
	s_waitcnt vmcnt(8)
	v_lshlrev_b32_e32 v156, 16, v230
	v_and_b32_e32 v157, 0xffff0000, v230
	v_lshlrev_b32_e32 v146, 16, v231
	v_and_b32_e32 v147, 0xffff0000, v231
	v_pk_mul_f32 v[156:157], v[156:157], s[86:87] op_sel_hi:[1,0]
	v_pk_mul_f32 v[146:147], v[146:147], s[86:87] op_sel_hi:[1,0]
	v_lshlrev_b32_e32 v150, 16, v232
	v_and_b32_e32 v151, 0xffff0000, v232
	v_lshlrev_b32_e32 v152, 16, v233
	v_and_b32_e32 v153, 0xffff0000, v233
	v_pk_fma_f32 v[148:149], v[144:145], v[72:73], v[146:147]
	v_pk_fma_f32 v[146:147], v[142:143], v[70:71], v[156:157]
	v_add_u32_e32 v251, 0x40000, v250
	global_load_dwordx4 v[230:233], v251, s[92:93] offset:64
.LBB0_1062:
	s_andn2_b64 vcc, exec, s[30:31]
	v_lshl_add_u64 v[158:159], v[154:155], 2, s[28:29]
	s_cbranch_vccnz .LBB0_1064
	global_load_dwordx4 v[146:149], v[158:159], off
	global_load_dwordx4 v[150:153], v[158:159], off offset:16
	s_waitcnt vmcnt(1)
	v_pk_mul_f32 v[148:149], v[148:149], s[86:87] op_sel_hi:[1,0]
	v_pk_mul_f32 v[146:147], v[146:147], s[86:87] op_sel_hi:[1,0]
	v_pk_fma_f32 v[148:149], v[144:145], v[72:73], v[148:149]
	v_pk_fma_f32 v[146:147], v[142:143], v[70:71], v[146:147]
	s_waitcnt vmcnt(0)
.LBB0_1064:
	v_pk_mul_f32 v[142:143], v[152:153], s[86:87] op_sel_hi:[1,0]
	v_pk_mul_f32 v[144:145], v[150:151], s[86:87] op_sel_hi:[1,0]
	v_pk_fma_f32 v[152:153], v[140:141], v[68:69], v[142:143]
	v_pk_fma_f32 v[150:151], v[138:139], v[66:67], v[144:145]
	s_and_b64 vcc, exec, s[24:25]
	v_lshl_add_u64 v[156:157], v[154:155], 1, s[64:65]
	s_cbranch_vccz .LBB0_1068
	v_cvt_pk_bf16_f32 v138, v146, v147
	v_cvt_pk_bf16_f32 v139, v148, v149
	v_cvt_pk_bf16_f32 v140, v150, v151
	v_cvt_pk_bf16_f32 v141, v152, v153
	s_mov_b64 s[30:31], -1
	s_and_b64 vcc, exec, s[88:89]
	global_store_dwordx4 v[156:157], v[138:141], off
	s_cbranch_vccz .LBB0_1067
	s_nop 0
	s_mov_b64 s[30:31], 0
	s_waitcnt vmcnt(9)
	v_lshlrev_b32_e32 v160, 16, v234
	v_and_b32_e32 v161, 0xffff0000, v234
	v_lshlrev_b32_e32 v138, 16, v235
	v_and_b32_e32 v139, 0xffff0000, v235
	v_pk_mul_f32 v[160:161], v[160:161], s[86:87] op_sel_hi:[1,0]
	v_pk_mul_f32 v[138:139], v[138:139], s[86:87] op_sel_hi:[1,0]
	v_lshlrev_b32_e32 v142, 16, v236
	v_and_b32_e32 v143, 0xffff0000, v236
	v_lshlrev_b32_e32 v144, 16, v237
	v_and_b32_e32 v145, 0xffff0000, v237
	v_pk_fma_f32 v[140:141], v[136:137], v[56:57], v[138:139]
	v_pk_fma_f32 v[138:139], v[134:135], v[54:55], v[160:161]
	v_add_u32_e32 v251, 0x48000, v250
	global_load_dwordx4 v[234:237], v251, s[92:93]

; __device__ __forceinline__ u32x4 pack8(const f32x4 a, const f32x4 b) { u32x4 w; w.x = cvt_pk_bf16(a[0], a[1]); w.y = cvt_pk_bf16(a[2], a[3]); w.z = cvt_pk_bf16(b[0], b[1]); w.w = cvt_pk_bf16(b[2], b[3]); return w; }
;     __device__ __forceinline__ void operator()(const f32x4 (&acc)[2][2][4][2], const Unit& u, int wr, int wc, int fr, int fq) const {
;     ...
;                     else {
; #pragma unroll
;                     for (int n = 0; n < 2; ++n) { const f32x4 bs = *(const f32x4*)(ib + off + bj * 32 + n * 4); o[n] = bs * 1.6817928305074290f + gv[bj][n] * acc[ai][bj][m][n]; } }
;                     if (tobf) *(u32x4*)(vout + off + bj * 32) = pack8(o[0], o[1]);
;                     else { *(f32x4*)(ob + off + bj * 32) = o[0]; *(f32x4*)(ob + off + bj * 32 + 4) = o[1]; } }
.LBB0_1070:
	s_andn2_b64 vcc, exec, s[30:31]
	s_cbranch_vccnz .LBB0_1072
	global_load_dwordx4 v[138:141], v[158:159], off offset:128
	global_load_dwordx4 v[142:145], v[158:159], off offset:144
	s_waitcnt vmcnt(1)
	v_pk_mul_f32 v[140:141], v[140:141], s[86:87] op_sel_hi:[1,0]
	v_pk_mul_f32 v[138:139], v[138:139], s[86:87] op_sel_hi:[1,0]
	v_pk_fma_f32 v[140:141], v[136:137], v[56:57], v[140:141]
	v_pk_fma_f32 v[138:139], v[134:135], v[54:55], v[138:139]
	s_waitcnt vmcnt(0)
.LBB0_1072:
	v_pk_mul_f32 v[134:135], v[144:145], s[86:87] op_sel_hi:[1,0]
	v_pk_mul_f32 v[136:137], v[142:143], s[86:87] op_sel_hi:[1,0]
	v_pk_fma_f32 v[132:133], v[132:133], v[52:53], v[134:135]
	v_pk_fma_f32 v[130:131], v[130:131], v[50:51], v[136:137]
	s_mov_b64 s[30:31], -1
	s_and_b64 vcc, exec, s[24:25]
	s_cbranch_vccz .LBB0_1074
	v_cvt_pk_bf16_f32 v134, v138, v139
	v_cvt_pk_bf16_f32 v135, v140, v141
	v_cvt_pk_bf16_f32 v136, v130, v131
	v_cvt_pk_bf16_f32 v137, v132, v133
	global_store_dwordx4 v[156:157], v[134:137], off offset:64
	s_mov_b64 s[30:31], 0

; __device__ __forceinline__ u32x4 pack8(const f32x4 a, const f32x4 b) { u32x4 w; w.x = cvt_pk_bf16(a[0], a[1]); w.y = cvt_pk_bf16(a[2], a[3]); w.z = cvt_pk_bf16(b[0], b[1]); w.w = cvt_pk_bf16(b[2], b[3]); return w; }
;     __device__ __forceinline__ void operator()(const f32x4 (&acc)[2][2][4][2], const Unit& u, int wr, int wc, int fr, int fq) const {
;     ...
;         for (int ai = 0; ai < 2; ++ai)
; #pragma unroll
;             for (int m = 0; m < 4; ++m) { const size_t off = (size_t)(rowb + ai * HALF + m * 16) * 1024 + col0;
; #pragma unroll
;                 for (int bj = 0; bj < 2; ++bj) { f32x4 o[2];
;                     if (lat && rinB) { const u32x4 w = *(const u32x4*)(rinB + off + bj * 32);
;                         const f32x4 b0 = {__builtin_bit_cast(float, w.x << 16), __builtin_bit_cast(float, w.x & 0xffff0000u), __builtin_bit_cast(float, w.y << 16), __builtin_bit_cast(float, w.y & 0xffff0000u)};
;                         const f32x4 b1 = {__builtin_bit_cast(float, w.z << 16), __builtin_bit_cast(float, w.z & 0xffff0000u), __builtin_bit_cast(float, w.w << 16), __builtin_bit_cast(float, w.w & 0xffff0000u)};
;                         o[0] = b0 * 1.6817928305074290f + gv[bj][0] * acc[ai][bj][m][0]; o[1] = b1 * 1.6817928305074290f + gv[bj][1] * acc[ai][bj][m][1]; }
;                     else {
; #pragma unroll
;                     for (int n = 0; n < 2; ++n) { const f32x4 bs = *(const f32x4*)(ib + off + bj * 32 + n * 4); o[n] = bs * 1.6817928305074290f + gv[bj][n] * acc[ai][bj][m][n]; } }
;                     if (tobf) *(u32x4*)(vout + off + bj * 32) = pack8(o[0], o[1]);
;                     else { *(f32x4*)(ob + off + bj * 32) = o[0]; *(f32x4*)(ob + off + bj * 32 + 4) = o[1]; } }
.LBB0_1076:
	s_nop 1
	v_or_b32_e32 v130, 32, v180
	v_ashrrev_i32_e32 v131, 31, v130
	v_lshlrev_b64 v[130:131], 10, v[130:131]
	v_lshl_add_u64 v[138:139], v[130:131], 0, v[182:183]
	s_mov_b64 s[30:31], -1
	s_and_b64 vcc, exec, s[34:35]
	s_cbranch_vccnz .LBB0_1078
	s_mov_b64 s[30:31], 0
	s_waitcnt vmcnt(10)
	v_lshlrev_b32_e32 v140, 16, v238
	v_and_b32_e32 v141, 0xffff0000, v238
	v_lshlrev_b32_e32 v130, 16, v239
	v_and_b32_e32 v131, 0xffff0000, v239
	v_pk_mul_f32 v[140:141], v[140:141], s[86:87] op_sel_hi:[1,0]
	v_pk_mul_f32 v[130:131], v[130:131], s[86:87] op_sel_hi:[1,0]
	v_lshlrev_b32_e32 v134, 16, v240
	v_and_b32_e32 v135, 0xffff0000, v240
	v_lshlrev_b32_e32 v136, 16, v241
	v_and_b32_e32 v137, 0xffff0000, v241
	v_pk_fma_f32 v[132:133], v[112:113], v[72:73], v[130:131]
	v_pk_fma_f32 v[130:131], v[110:111], v[70:71], v[140:141]
	v_add_u32_e32 v251, 0x48000, v250
	global_load_dwordx4 v[238:241], v251, s[92:93] offset:64
.LBB0_1078:
	s_andn2_b64 vcc, exec, s[30:31]
	v_lshl_add_u64 v[142:143], v[138:139], 2, s[28:29]
	s_cbranch_vccnz .LBB0_1080
	global_load_dwordx4 v[130:133], v[142:143], off
	global_load_dwordx4 v[134:137], v[142:143], off offset:16
	s_waitcnt vmcnt(1)
	v_pk_mul_f32 v[132:133], v[132:133], s[86:87] op_sel_hi:[1,0]
	v_pk_mul_f32 v[130:131], v[130:131], s[86:87] op_sel_hi:[1,0]
	v_pk_fma_f32 v[132:133], v[112:113], v[72:73], v[132:133]
	v_pk_fma_f32 v[130:131], v[110:111], v[70:71], v[130:131]
	s_waitcnt vmcnt(0)
.LBB0_1080:
	v_pk_mul_f32 v[110:111], v[136:137], s[86:87] op_sel_hi:[1,0]
	v_pk_mul_f32 v[134:135], v[134:135], s[86:87] op_sel_hi:[1,0]
	v_pk_fma_f32 v[112:113], v[108:109], v[68:69], v[110:111]
	v_pk_fma_f32 v[110:111], v[106:107], v[66:67], v[134:135]
	s_and_b64 vcc, exec, s[24:25]
	v_lshl_add_u64 v[140:141], v[138:139], 1, s[64:65]
	s_cbranch_vccz .LBB0_1084
	v_cvt_pk_bf16_f32 v106, v130, v131
	v_cvt_pk_bf16_f32 v107, v132, v133
	v_cvt_pk_bf16_f32 v108, v110, v111
	v_cvt_pk_bf16_f32 v109, v112, v113
	s_mov_b64 s[30:31], -1
	s_and_b64 vcc, exec, s[88:89]
	global_store_dwordx4 v[140:141], v[106:109], off
	s_cbranch_vccz .LBB0_1083
	s_nop 0
	s_mov_b64 s[30:31], 0
	s_waitcnt vmcnt(11)
	v_lshlrev_b32_e32 v144, 16, v242
	v_and_b32_e32 v145, 0xffff0000, v242
	v_lshlrev_b32_e32 v106, 16, v243
	v_and_b32_e32 v107, 0xffff0000, v243
	v_pk_mul_f32 v[144:145], v[144:145], s[86:87] op_sel_hi:[1,0]
	v_pk_mul_f32 v[106:107], v[106:107], s[86:87] op_sel_hi:[1,0]
	v_lshlrev_b32_e32 v134, 16, v244
	v_and_b32_e32 v135, 0xffff0000, v244
	v_lshlrev_b32_e32 v136, 16, v245
	v_and_b32_e32 v137, 0xffff0000, v245
	v_pk_fma_f32 v[108:109], v[104:105], v[56:57], v[106:107]
	v_pk_fma_f32 v[106:107], v[102:103], v[54:55], v[144:145]
	v_add_u32_e32 v251, 0x50000, v250
	global_load_dwordx4 v[242:245], v251, s[92:93]

; __device__ __forceinline__ u32x4 pack8(const f32x4 a, const f32x4 b) { u32x4 w; w.x = cvt_pk_bf16(a[0], a[1]); w.y = cvt_pk_bf16(a[2], a[3]); w.z = cvt_pk_bf16(b[0], b[1]); w.w = cvt_pk_bf16(b[2], b[3]); return w; }
;     __device__ __forceinline__ void operator()(const f32x4 (&acc)[2][2][4][2], const Unit& u, int wr, int wc, int fr, int fq) const {
;     ...
;                     else {
; #pragma unroll
;                     for (int n = 0; n < 2; ++n) { const f32x4 bs = *(const f32x4*)(ib + off + bj * 32 + n * 4); o[n] = bs * 1.6817928305074290f + gv[bj][n] * acc[ai][bj][m][n]; } }
;                     if (tobf) *(u32x4*)(vout + off + bj * 32) = pack8(o[0], o[1]);
;                     else { *(f32x4*)(ob + off + bj * 32) = o[0]; *(f32x4*)(ob + off + bj * 32 + 4) = o[1]; } }
.LBB0_1086:
	s_andn2_b64 vcc, exec, s[30:31]
	s_cbranch_vccnz .LBB0_1088
	global_load_dwordx4 v[106:109], v[142:143], off offset:128
	global_load_dwordx4 v[134:137], v[142:143], off offset:144
	s_waitcnt vmcnt(1)
	v_pk_mul_f32 v[108:109], v[108:109], s[86:87] op_sel_hi:[1,0]
	v_pk_mul_f32 v[106:107], v[106:107], s[86:87] op_sel_hi:[1,0]
	v_pk_fma_f32 v[108:109], v[104:105], v[56:57], v[108:109]
	v_pk_fma_f32 v[106:107], v[102:103], v[54:55], v[106:107]
	s_waitcnt vmcnt(0)
.LBB0_1088:
	v_pk_mul_f32 v[102:103], v[136:137], s[86:87] op_sel_hi:[1,0]
	v_pk_mul_f32 v[104:105], v[134:135], s[86:87] op_sel_hi:[1,0]
	v_pk_fma_f32 v[100:101], v[100:101], v[52:53], v[102:103]
	v_pk_fma_f32 v[98:99], v[98:99], v[50:51], v[104:105]
	s_mov_b64 s[30:31], -1
	s_and_b64 vcc, exec, s[24:25]
	s_cbranch_vccz .LBB0_1090
	v_cvt_pk_bf16_f32 v102, v106, v107
	v_cvt_pk_bf16_f32 v103, v108, v109
	v_cvt_pk_bf16_f32 v104, v98, v99
	v_cvt_pk_bf16_f32 v105, v100, v101
	global_store_dwordx4 v[140:141], v[102:105], off offset:64
	s_mov_b64 s[30:31], 0

; __device__ __forceinline__ u32x4 pack8(const f32x4 a, const f32x4 b) { u32x4 w; w.x = cvt_pk_bf16(a[0], a[1]); w.y = cvt_pk_bf16(a[2], a[3]); w.z = cvt_pk_bf16(b[0], b[1]); w.w = cvt_pk_bf16(b[2], b[3]); return w; }
;     __device__ __forceinline__ void operator()(const f32x4 (&acc)[2][2][4][2], const Unit& u, int wr, int wc, int fr, int fq) const {
;     ...
;         for (int ai = 0; ai < 2; ++ai)
; #pragma unroll
;             for (int m = 0; m < 4; ++m) { const size_t off = (size_t)(rowb + ai * HALF + m * 16) * 1024 + col0;
; #pragma unroll
;                 for (int bj = 0; bj < 2; ++bj) { f32x4 o[2];
;                     if (lat && rinB) { const u32x4 w = *(const u32x4*)(rinB + off + bj * 32);
;                         const f32x4 b0 = {__builtin_bit_cast(float, w.x << 16), __builtin_bit_cast(float, w.x & 0xffff0000u), __builtin_bit_cast(float, w.y << 16), __builtin_bit_cast(float, w.y & 0xffff0000u)};
;                         const f32x4 b1 = {__builtin_bit_cast(float, w.z << 16), __builtin_bit_cast(float, w.z & 0xffff0000u), __builtin_bit_cast(float, w.w << 16), __builtin_bit_cast(float, w.w & 0xffff0000u)};
;                         o[0] = b0 * 1.6817928305074290f + gv[bj][0] * acc[ai][bj][m][0]; o[1] = b1 * 1.6817928305074290f + gv[bj][1] * acc[ai][bj][m][1]; }
;                     else {
; #pragma unroll
;                     for (int n = 0; n < 2; ++n) { const f32x4 bs = *(const f32x4*)(ib + off + bj * 32 + n * 4); o[n] = bs * 1.6817928305074290f + gv[bj][n] * acc[ai][bj][m][n]; } }
;                     if (tobf) *(u32x4*)(vout + off + bj * 32) = pack8(o[0], o[1]);
;                     else { *(f32x4*)(ob + off + bj * 32) = o[0]; *(f32x4*)(ob + off + bj * 32 + 4) = o[1]; } }
.LBB0_1092:
	s_nop 1
	v_or_b32_e32 v98, 48, v180
	v_ashrrev_i32_e32 v99, 31, v98
	v_lshlrev_b64 v[98:99], 10, v[98:99]
	v_lshl_add_u64 v[106:107], v[98:99], 0, v[182:183]
	s_mov_b64 s[30:31], -1
	s_and_b64 vcc, exec, s[34:35]
	s_cbranch_vccnz .LBB0_1094
	s_mov_b64 s[30:31], 0
	s_waitcnt vmcnt(12)
	v_lshlrev_b32_e32 v108, 16, v246
	v_and_b32_e32 v109, 0xffff0000, v246
	v_lshlrev_b32_e32 v98, 16, v247
	v_and_b32_e32 v99, 0xffff0000, v247
	v_pk_mul_f32 v[108:109], v[108:109], s[86:87] op_sel_hi:[1,0]
	v_pk_mul_f32 v[98:99], v[98:99], s[86:87] op_sel_hi:[1,0]
	v_lshlrev_b32_e32 v102, 16, v248
	v_and_b32_e32 v103, 0xffff0000, v248
	v_lshlrev_b32_e32 v104, 16, v249
	v_and_b32_e32 v105, 0xffff0000, v249
	v_pk_fma_f32 v[100:101], v[96:97], v[72:73], v[98:99]
	v_pk_fma_f32 v[98:99], v[94:95], v[70:71], v[108:109]
	v_add_u32_e32 v251, 0x50000, v250
	global_load_dwordx4 v[246:249], v251, s[92:93] offset:64
.LBB0_1094:
	s_andn2_b64 vcc, exec, s[30:31]
	v_lshl_add_u64 v[110:111], v[106:107], 2, s[28:29]
	s_cbranch_vccnz .LBB0_1096
	global_load_dwordx4 v[98:101], v[110:111], off
	global_load_dwordx4 v[102:105], v[110:111], off offset:16
	s_waitcnt vmcnt(1)
	v_pk_mul_f32 v[100:101], v[100:101], s[86:87] op_sel_hi:[1,0]
	v_pk_mul_f32 v[98:99], v[98:99], s[86:87] op_sel_hi:[1,0]
	v_pk_fma_f32 v[100:101], v[96:97], v[72:73], v[100:101]
	v_pk_fma_f32 v[98:99], v[94:95], v[70:71], v[98:99]
	s_waitcnt vmcnt(0)
.LBB0_1096:
	v_pk_mul_f32 v[94:95], v[104:105], s[86:87] op_sel_hi:[1,0]
	v_pk_mul_f32 v[102:103], v[102:103], s[86:87] op_sel_hi:[1,0]
	v_pk_fma_f32 v[96:97], v[92:93], v[68:69], v[94:95]
	v_pk_fma_f32 v[94:95], v[90:91], v[66:67], v[102:103]
	s_and_b64 vcc, exec, s[24:25]
	v_lshl_add_u64 v[108:109], v[106:107], 1, s[64:65]
	s_cbranch_vccz .LBB0_1100
	v_cvt_pk_bf16_f32 v90, v98, v99
	v_cvt_pk_bf16_f32 v91, v100, v101
	v_cvt_pk_bf16_f32 v92, v94, v95
	v_cvt_pk_bf16_f32 v93, v96, v97
	s_mov_b64 s[30:31], -1
	s_and_b64 vcc, exec, s[88:89]
	global_store_dwordx4 v[108:109], v[90:93], off
	s_cbranch_vccz .LBB0_1099
	s_nop 0
	s_mov_b64 s[30:31], 0
	s_waitcnt vmcnt(13)
	v_lshlrev_b32_e32 v112, 16, v208
	v_and_b32_e32 v113, 0xffff0000, v208
	v_lshlrev_b32_e32 v90, 16, v209
	v_and_b32_e32 v91, 0xffff0000, v209
	v_pk_mul_f32 v[112:113], v[112:113], s[86:87] op_sel_hi:[1,0]
	v_pk_mul_f32 v[90:91], v[90:91], s[86:87] op_sel_hi:[1,0]
	v_lshlrev_b32_e32 v102, 16, v210
	v_and_b32_e32 v103, 0xffff0000, v210
	v_lshlrev_b32_e32 v104, 16, v211
	v_and_b32_e32 v105, 0xffff0000, v211
	v_pk_fma_f32 v[92:93], v[88:89], v[56:57], v[90:91]
	v_pk_fma_f32 v[90:91], v[86:87], v[54:55], v[112:113]
	v_add_u32_e32 v251, 0x58000, v250
	global_load_dwordx4 v[208:211], v251, s[92:93]

; __device__ __forceinline__ u32x4 pack8(const f32x4 a, const f32x4 b) { u32x4 w; w.x = cvt_pk_bf16(a[0], a[1]); w.y = cvt_pk_bf16(a[2], a[3]); w.z = cvt_pk_bf16(b[0], b[1]); w.w = cvt_pk_bf16(b[2], b[3]); return w; }
;     __device__ __forceinline__ void operator()(const f32x4 (&acc)[2][2][4][2], const Unit& u, int wr, int wc, int fr, int fq) const {
;     ...
;                     else {
; #pragma unroll
;                     for (int n = 0; n < 2; ++n) { const f32x4 bs = *(const f32x4*)(ib + off + bj * 32 + n * 4); o[n] = bs * 1.6817928305074290f + gv[bj][n] * acc[ai][bj][m][n]; } }
;                     if (tobf) *(u32x4*)(vout + off + bj * 32) = pack8(o[0], o[1]);
;                     else { *(f32x4*)(ob + off + bj * 32) = o[0]; *(f32x4*)(ob + off + bj * 32 + 4) = o[1]; } }
.LBB0_1102:
	s_andn2_b64 vcc, exec, s[30:31]
	s_cbranch_vccnz .LBB0_1104
	global_load_dwordx4 v[90:93], v[110:111], off offset:128
	global_load_dwordx4 v[102:105], v[110:111], off offset:144
	s_waitcnt vmcnt(1)
	v_pk_mul_f32 v[92:93], v[92:93], s[86:87] op_sel_hi:[1,0]
	v_pk_mul_f32 v[90:91], v[90:91], s[86:87] op_sel_hi:[1,0]
	v_pk_fma_f32 v[92:93], v[88:89], v[56:57], v[92:93]
	v_pk_fma_f32 v[90:91], v[86:87], v[54:55], v[90:91]
	s_waitcnt vmcnt(0)
.LBB0_1104:
	v_pk_mul_f32 v[86:87], v[104:105], s[86:87] op_sel_hi:[1,0]
	v_pk_mul_f32 v[88:89], v[102:103], s[86:87] op_sel_hi:[1,0]
	v_pk_fma_f32 v[84:85], v[84:85], v[52:53], v[86:87]
	v_pk_fma_f32 v[82:83], v[82:83], v[50:51], v[88:89]
	s_mov_b64 s[30:31], -1
	s_and_b64 vcc, exec, s[24:25]
	s_cbranch_vccz .LBB0_1106
	v_cvt_pk_bf16_f32 v86, v90, v91
	v_cvt_pk_bf16_f32 v87, v92, v93
	v_cvt_pk_bf16_f32 v88, v82, v83
	v_cvt_pk_bf16_f32 v89, v84, v85
	global_store_dwordx4 v[108:109], v[86:89], off offset:64
	s_mov_b64 s[30:31], 0

; __device__ __forceinline__ u32x4 pack8(const f32x4 a, const f32x4 b) { u32x4 w; w.x = cvt_pk_bf16(a[0], a[1]); w.y = cvt_pk_bf16(a[2], a[3]); w.z = cvt_pk_bf16(b[0], b[1]); w.w = cvt_pk_bf16(b[2], b[3]); return w; }
;     __device__ __forceinline__ void operator()(const f32x4 (&acc)[2][2][4][2], const Unit& u, int wr, int wc, int fr, int fq) const {
;     ...
;         for (int ai = 0; ai < 2; ++ai)
; #pragma unroll
;             for (int m = 0; m < 4; ++m) { const size_t off = (size_t)(rowb + ai * HALF + m * 16) * 1024 + col0;
; #pragma unroll
;                 for (int bj = 0; bj < 2; ++bj) { f32x4 o[2];
;                     if (lat && rinB) { const u32x4 w = *(const u32x4*)(rinB + off + bj * 32);
;                         const f32x4 b0 = {__builtin_bit_cast(float, w.x << 16), __builtin_bit_cast(float, w.x & 0xffff0000u), __builtin_bit_cast(float, w.y << 16), __builtin_bit_cast(float, w.y & 0xffff0000u)};
;                         const f32x4 b1 = {__builtin_bit_cast(float, w.z << 16), __builtin_bit_cast(float, w.z & 0xffff0000u), __builtin_bit_cast(float, w.w << 16), __builtin_bit_cast(float, w.w & 0xffff0000u)};
;                         o[0] = b0 * 1.6817928305074290f + gv[bj][0] * acc[ai][bj][m][0]; o[1] = b1 * 1.6817928305074290f + gv[bj][1] * acc[ai][bj][m][1]; }
;                     else {
; #pragma unroll
;                     for (int n = 0; n < 2; ++n) { const f32x4 bs = *(const f32x4*)(ib + off + bj * 32 + n * 4); o[n] = bs * 1.6817928305074290f + gv[bj][n] * acc[ai][bj][m][n]; } }
;                     if (tobf) *(u32x4*)(vout + off + bj * 32) = pack8(o[0], o[1]);
;                     else { *(f32x4*)(ob + off + bj * 32) = o[0]; *(f32x4*)(ob + off + bj * 32 + 4) = o[1]; } }
.LBB0_1108:
	s_nop 1
	v_lshlrev_b64 v[82:83], 10, v[180:181]
	v_lshl_add_u64 v[82:83], v[82:83], 0, v[182:183]
	v_lshl_add_u64 v[90:91], v[82:83], 0, s[96:97]
	s_mov_b64 s[30:31], -1
	s_and_b64 vcc, exec, s[34:35]
	s_cbranch_vccnz .LBB0_1110
	s_mov_b64 s[30:31], 0
	s_waitcnt vmcnt(13)
	v_lshlrev_b32_e32 v92, 16, v226
	v_and_b32_e32 v93, 0xffff0000, v226
	v_lshlrev_b32_e32 v82, 16, v227
	v_and_b32_e32 v83, 0xffff0000, v227
	v_pk_mul_f32 v[92:93], v[92:93], s[86:87] op_sel_hi:[1,0]
	v_pk_mul_f32 v[82:83], v[82:83], s[86:87] op_sel_hi:[1,0]
	v_lshlrev_b32_e32 v86, 16, v228
	v_and_b32_e32 v87, 0xffff0000, v228
	v_lshlrev_b32_e32 v88, 16, v229
	v_and_b32_e32 v89, 0xffff0000, v229
	v_pk_fma_f32 v[84:85], v[80:81], v[72:73], v[82:83]
	v_pk_fma_f32 v[82:83], v[78:79], v[70:71], v[92:93]
	v_add_u32_e32 v251, 0x58000, v250
	global_load_dwordx4 v[226:229], v251, s[92:93] offset:64
.LBB0_1110:
	s_andn2_b64 vcc, exec, s[30:31]
	v_lshl_add_u64 v[94:95], v[90:91], 2, s[28:29]
	s_cbranch_vccnz .LBB0_1112
	global_load_dwordx4 v[82:85], v[94:95], off
	global_load_dwordx4 v[86:89], v[94:95], off offset:16
	s_waitcnt vmcnt(1)
	v_pk_mul_f32 v[84:85], v[84:85], s[86:87] op_sel_hi:[1,0]
	v_pk_mul_f32 v[82:83], v[82:83], s[86:87] op_sel_hi:[1,0]
	v_pk_fma_f32 v[84:85], v[80:81], v[72:73], v[84:85]
	v_pk_fma_f32 v[82:83], v[78:79], v[70:71], v[82:83]
	s_waitcnt vmcnt(0)
.LBB0_1112:
	v_pk_mul_f32 v[78:79], v[88:89], s[86:87] op_sel_hi:[1,0]
	v_pk_mul_f32 v[86:87], v[86:87], s[86:87] op_sel_hi:[1,0]
	v_pk_fma_f32 v[80:81], v[76:77], v[68:69], v[78:79]
	v_pk_fma_f32 v[78:79], v[74:75], v[66:67], v[86:87]
	s_and_b64 vcc, exec, s[24:25]
	v_lshl_add_u64 v[92:93], v[90:91], 1, s[64:65]
	s_cbranch_vccz .LBB0_1116
	v_cvt_pk_bf16_f32 v74, v82, v83
	v_cvt_pk_bf16_f32 v75, v84, v85
	v_cvt_pk_bf16_f32 v76, v78, v79
	v_cvt_pk_bf16_f32 v77, v80, v81
	s_mov_b64 s[30:31], -1
	s_and_b64 vcc, exec, s[88:89]
	global_store_dwordx4 v[92:93], v[74:77], off
	s_cbranch_vccz .LBB0_1115
	s_nop 0
	s_mov_b64 s[30:31], 0
	s_waitcnt vmcnt(13)
	v_lshlrev_b32_e32 v96, 16, v230
	v_and_b32_e32 v97, 0xffff0000, v230
	v_lshlrev_b32_e32 v74, 16, v231
	v_and_b32_e32 v75, 0xffff0000, v231
	v_pk_mul_f32 v[96:97], v[96:97], s[86:87] op_sel_hi:[1,0]
	v_pk_mul_f32 v[74:75], v[74:75], s[86:87] op_sel_hi:[1,0]
	v_lshlrev_b32_e32 v86, 16, v232
	v_and_b32_e32 v87, 0xffff0000, v232
	v_lshlrev_b32_e32 v88, 16, v233
	v_and_b32_e32 v89, 0xffff0000, v233
	v_pk_fma_f32 v[76:77], v[64:65], v[56:57], v[74:75]
	v_pk_fma_f32 v[74:75], v[62:63], v[54:55], v[96:97]

; __device__ __forceinline__ u32x4 pack8(const f32x4 a, const f32x4 b) { u32x4 w; w.x = cvt_pk_bf16(a[0], a[1]); w.y = cvt_pk_bf16(a[2], a[3]); w.z = cvt_pk_bf16(b[0], b[1]); w.w = cvt_pk_bf16(b[2], b[3]); return w; }
;     __device__ __forceinline__ void operator()(const f32x4 (&acc)[2][2][4][2], const Unit& u, int wr, int wc, int fr, int fq) const {
;     ...
;                     else {
; #pragma unroll
;                     for (int n = 0; n < 2; ++n) { const f32x4 bs = *(const f32x4*)(ib + off + bj * 32 + n * 4); o[n] = bs * 1.6817928305074290f + gv[bj][n] * acc[ai][bj][m][n]; } }
;                     if (tobf) *(u32x4*)(vout + off + bj * 32) = pack8(o[0], o[1]);
;                     else { *(f32x4*)(ob + off + bj * 32) = o[0]; *(f32x4*)(ob + off + bj * 32 + 4) = o[1]; } }
.LBB0_1118:
	s_andn2_b64 vcc, exec, s[30:31]
	s_cbranch_vccnz .LBB0_1120
	global_load_dwordx4 v[74:77], v[94:95], off offset:128
	global_load_dwordx4 v[86:89], v[94:95], off offset:144
	s_waitcnt vmcnt(1)
	v_pk_mul_f32 v[76:77], v[76:77], s[86:87] op_sel_hi:[1,0]
	v_pk_mul_f32 v[74:75], v[74:75], s[86:87] op_sel_hi:[1,0]
	v_pk_fma_f32 v[76:77], v[64:65], v[56:57], v[76:77]
	v_pk_fma_f32 v[74:75], v[62:63], v[54:55], v[74:75]
	s_waitcnt vmcnt(0)
.LBB0_1120:
	v_pk_mul_f32 v[62:63], v[88:89], s[86:87] op_sel_hi:[1,0]
	v_pk_mul_f32 v[64:65], v[86:87], s[86:87] op_sel_hi:[1,0]
	v_pk_fma_f32 v[60:61], v[60:61], v[52:53], v[62:63]
	v_pk_fma_f32 v[58:59], v[58:59], v[50:51], v[64:65]
	s_mov_b64 s[30:31], -1
	s_and_b64 vcc, exec, s[24:25]
	s_cbranch_vccz .LBB0_1122
	v_cvt_pk_bf16_f32 v62, v74, v75
	v_cvt_pk_bf16_f32 v63, v76, v77
	v_cvt_pk_bf16_f32 v64, v58, v59
	v_cvt_pk_bf16_f32 v65, v60, v61
	global_store_dwordx4 v[92:93], v[62:65], off offset:64
	s_mov_b64 s[30:31], 0

; __device__ __forceinline__ u32x4 pack8(const f32x4 a, const f32x4 b) { u32x4 w; w.x = cvt_pk_bf16(a[0], a[1]); w.y = cvt_pk_bf16(a[2], a[3]); w.z = cvt_pk_bf16(b[0], b[1]); w.w = cvt_pk_bf16(b[2], b[3]); return w; }
;     __device__ __forceinline__ void operator()(const f32x4 (&acc)[2][2][4][2], const Unit& u, int wr, int wc, int fr, int fq) const {
;     ...
;         for (int ai = 0; ai < 2; ++ai)
; #pragma unroll
;             for (int m = 0; m < 4; ++m) { const size_t off = (size_t)(rowb + ai * HALF + m * 16) * 1024 + col0;
; #pragma unroll
;                 for (int bj = 0; bj < 2; ++bj) { f32x4 o[2];
;                     if (lat && rinB) { const u32x4 w = *(const u32x4*)(rinB + off + bj * 32);
;                         const f32x4 b0 = {__builtin_bit_cast(float, w.x << 16), __builtin_bit_cast(float, w.x & 0xffff0000u), __builtin_bit_cast(float, w.y << 16), __builtin_bit_cast(float, w.y & 0xffff0000u)};
;                         const f32x4 b1 = {__builtin_bit_cast(float, w.z << 16), __builtin_bit_cast(float, w.z & 0xffff0000u), __builtin_bit_cast(float, w.w << 16), __builtin_bit_cast(float, w.w & 0xffff0000u)};
;                         o[0] = b0 * 1.6817928305074290f + gv[bj][0] * acc[ai][bj][m][0]; o[1] = b1 * 1.6817928305074290f + gv[bj][1] * acc[ai][bj][m][1]; }
;                     else {
; #pragma unroll
;                     for (int n = 0; n < 2; ++n) { const f32x4 bs = *(const f32x4*)(ib + off + bj * 32 + n * 4); o[n] = bs * 1.6817928305074290f + gv[bj][n] * acc[ai][bj][m][n]; } }
;                     if (tobf) *(u32x4*)(vout + off + bj * 32) = pack8(o[0], o[1]);
;                     else { *(f32x4*)(ob + off + bj * 32) = o[0]; *(f32x4*)(ob + off + bj * 32 + 4) = o[1]; } }
.LBB0_1124:
	s_nop 1
	v_lshlrev_b64 v[58:59], 10, v[180:181]
	v_lshl_add_u64 v[58:59], v[58:59], 0, v[182:183]
	s_mov_b64 s[0:1], 0x24000
	v_lshl_add_u64 v[74:75], v[58:59], 0, s[0:1]
	s_mov_b64 s[30:31], -1
	s_and_b64 vcc, exec, s[34:35]
	s_cbranch_vccnz .LBB0_1126
	s_mov_b64 s[30:31], 0
	s_waitcnt vmcnt(12)
	v_lshlrev_b32_e32 v76, 16, v234
	v_and_b32_e32 v77, 0xffff0000, v234
	v_lshlrev_b32_e32 v58, 16, v235
	v_and_b32_e32 v59, 0xffff0000, v235
	v_pk_mul_f32 v[76:77], v[76:77], s[86:87] op_sel_hi:[1,0]
	v_pk_mul_f32 v[58:59], v[58:59], s[86:87] op_sel_hi:[1,0]
	v_lshlrev_b32_e32 v62, 16, v236
	v_and_b32_e32 v63, 0xffff0000, v236
	v_lshlrev_b32_e32 v64, 16, v237
	v_and_b32_e32 v65, 0xffff0000, v237
	v_pk_fma_f32 v[60:61], v[48:49], v[72:73], v[58:59]
	v_pk_fma_f32 v[58:59], v[46:47], v[70:71], v[76:77]
.LBB0_1126:
	s_andn2_b64 vcc, exec, s[30:31]
	v_lshl_add_u64 v[78:79], v[74:75], 2, s[28:29]
	s_cbranch_vccnz .LBB0_1128
	global_load_dwordx4 v[58:61], v[78:79], off
	global_load_dwordx4 v[62:65], v[78:79], off offset:16
	s_waitcnt vmcnt(1)
	v_pk_mul_f32 v[60:61], v[60:61], s[86:87] op_sel_hi:[1,0]
	v_pk_mul_f32 v[58:59], v[58:59], s[86:87] op_sel_hi:[1,0]
	v_pk_fma_f32 v[60:61], v[48:49], v[72:73], v[60:61]
	v_pk_fma_f32 v[58:59], v[46:47], v[70:71], v[58:59]
	s_waitcnt vmcnt(0)
.LBB0_1128:
	v_pk_mul_f32 v[46:47], v[64:65], s[86:87] op_sel_hi:[1,0]
	v_pk_mul_f32 v[62:63], v[62:63], s[86:87] op_sel_hi:[1,0]
	v_pk_fma_f32 v[48:49], v[44:45], v[68:69], v[46:47]
	v_pk_fma_f32 v[46:47], v[42:43], v[66:67], v[62:63]
	s_and_b64 vcc, exec, s[24:25]
	v_lshl_add_u64 v[76:77], v[74:75], 1, s[64:65]
	s_cbranch_vccz .LBB0_1132
	v_cvt_pk_bf16_f32 v42, v58, v59
	v_cvt_pk_bf16_f32 v43, v60, v61
	v_cvt_pk_bf16_f32 v44, v46, v47
	v_cvt_pk_bf16_f32 v45, v48, v49
	s_mov_b64 s[30:31], -1
	s_and_b64 vcc, exec, s[88:89]
	global_store_dwordx4 v[76:77], v[42:45], off
	s_cbranch_vccz .LBB0_1131
	s_nop 0
	s_mov_b64 s[30:31], 0
	s_waitcnt vmcnt(11)
	v_lshlrev_b32_e32 v80, 16, v238
	v_and_b32_e32 v81, 0xffff0000, v238
	v_lshlrev_b32_e32 v42, 16, v239
	v_and_b32_e32 v43, 0xffff0000, v239
	v_pk_mul_f32 v[80:81], v[80:81], s[86:87] op_sel_hi:[1,0]
	v_pk_mul_f32 v[42:43], v[42:43], s[86:87] op_sel_hi:[1,0]
	v_lshlrev_b32_e32 v62, 16, v240
	v_and_b32_e32 v63, 0xffff0000, v240
	v_lshlrev_b32_e32 v64, 16, v241
	v_and_b32_e32 v65, 0xffff0000, v241
	v_pk_fma_f32 v[44:45], v[40:41], v[56:57], v[42:43]
	v_pk_fma_f32 v[42:43], v[38:39], v[54:55], v[80:81]

; __device__ __forceinline__ u32x4 pack8(const f32x4 a, const f32x4 b) { u32x4 w; w.x = cvt_pk_bf16(a[0], a[1]); w.y = cvt_pk_bf16(a[2], a[3]); w.z = cvt_pk_bf16(b[0], b[1]); w.w = cvt_pk_bf16(b[2], b[3]); return w; }
;     __device__ __forceinline__ void operator()(const f32x4 (&acc)[2][2][4][2], const Unit& u, int wr, int wc, int fr, int fq) const {
;     ...
;                     else {
; #pragma unroll
;                     for (int n = 0; n < 2; ++n) { const f32x4 bs = *(const f32x4*)(ib + off + bj * 32 + n * 4); o[n] = bs * 1.6817928305074290f + gv[bj][n] * acc[ai][bj][m][n]; } }
;                     if (tobf) *(u32x4*)(vout + off + bj * 32) = pack8(o[0], o[1]);
;                     else { *(f32x4*)(ob + off + bj * 32) = o[0]; *(f32x4*)(ob + off + bj * 32 + 4) = o[1]; } }
.LBB0_1134:
	s_andn2_b64 vcc, exec, s[30:31]
	s_cbranch_vccnz .LBB0_1136
	global_load_dwordx4 v[42:45], v[78:79], off offset:128
	global_load_dwordx4 v[62:65], v[78:79], off offset:144
	s_waitcnt vmcnt(1)
	v_pk_mul_f32 v[44:45], v[44:45], s[86:87] op_sel_hi:[1,0]
	v_pk_mul_f32 v[42:43], v[42:43], s[86:87] op_sel_hi:[1,0]
	v_pk_fma_f32 v[44:45], v[40:41], v[56:57], v[44:45]
	v_pk_fma_f32 v[42:43], v[38:39], v[54:55], v[42:43]
	s_waitcnt vmcnt(0)
.LBB0_1136:
	v_pk_mul_f32 v[38:39], v[64:65], s[86:87] op_sel_hi:[1,0]
	v_pk_mul_f32 v[40:41], v[62:63], s[86:87] op_sel_hi:[1,0]
	v_pk_fma_f32 v[36:37], v[36:37], v[52:53], v[38:39]
	v_pk_fma_f32 v[34:35], v[34:35], v[50:51], v[40:41]
	s_mov_b64 s[30:31], -1
	s_and_b64 vcc, exec, s[24:25]
	s_cbranch_vccz .LBB0_1138
	v_cvt_pk_bf16_f32 v38, v42, v43
	v_cvt_pk_bf16_f32 v39, v44, v45
	v_cvt_pk_bf16_f32 v40, v34, v35
	v_cvt_pk_bf16_f32 v41, v36, v37
	global_store_dwordx4 v[76:77], v[38:41], off offset:64
	s_mov_b64 s[30:31], 0

; __device__ __forceinline__ u32x4 pack8(const f32x4 a, const f32x4 b) { u32x4 w; w.x = cvt_pk_bf16(a[0], a[1]); w.y = cvt_pk_bf16(a[2], a[3]); w.z = cvt_pk_bf16(b[0], b[1]); w.w = cvt_pk_bf16(b[2], b[3]); return w; }
;     __device__ __forceinline__ void operator()(const f32x4 (&acc)[2][2][4][2], const Unit& u, int wr, int wc, int fr, int fq) const {
;     ...
;         for (int ai = 0; ai < 2; ++ai)
; #pragma unroll
;             for (int m = 0; m < 4; ++m) { const size_t off = (size_t)(rowb + ai * HALF + m * 16) * 1024 + col0;
; #pragma unroll
;                 for (int bj = 0; bj < 2; ++bj) { f32x4 o[2];
;                     if (lat && rinB) { const u32x4 w = *(const u32x4*)(rinB + off + bj * 32);
;                         const f32x4 b0 = {__builtin_bit_cast(float, w.x << 16), __builtin_bit_cast(float, w.x & 0xffff0000u), __builtin_bit_cast(float, w.y << 16), __builtin_bit_cast(float, w.y & 0xffff0000u)};
;                         const f32x4 b1 = {__builtin_bit_cast(float, w.z << 16), __builtin_bit_cast(float, w.z & 0xffff0000u), __builtin_bit_cast(float, w.w << 16), __builtin_bit_cast(float, w.w & 0xffff0000u)};
;                         o[0] = b0 * 1.6817928305074290f + gv[bj][0] * acc[ai][bj][m][0]; o[1] = b1 * 1.6817928305074290f + gv[bj][1] * acc[ai][bj][m][1]; }
;                     else {
; #pragma unroll
;                     for (int n = 0; n < 2; ++n) { const f32x4 bs = *(const f32x4*)(ib + off + bj * 32 + n * 4); o[n] = bs * 1.6817928305074290f + gv[bj][n] * acc[ai][bj][m][n]; } }
;                     if (tobf) *(u32x4*)(vout + off + bj * 32) = pack8(o[0], o[1]);
;                     else { *(f32x4*)(ob + off + bj * 32) = o[0]; *(f32x4*)(ob + off + bj * 32 + 4) = o[1]; } }
.LBB0_1140:
	s_nop 1
	v_lshlrev_b64 v[34:35], 10, v[180:181]
	v_lshl_add_u64 v[34:35], v[34:35], 0, v[182:183]
	s_mov_b64 s[0:1], 0x28000
	v_lshl_add_u64 v[42:43], v[34:35], 0, s[0:1]
	s_mov_b64 s[30:31], -1
	s_and_b64 vcc, exec, s[34:35]
	s_cbranch_vccnz .LBB0_1142
	s_mov_b64 s[30:31], 0
	s_waitcnt vmcnt(10)
	v_lshlrev_b32_e32 v44, 16, v242
	v_and_b32_e32 v45, 0xffff0000, v242
	v_lshlrev_b32_e32 v34, 16, v243
	v_and_b32_e32 v35, 0xffff0000, v243
	v_pk_mul_f32 v[44:45], v[44:45], s[86:87] op_sel_hi:[1,0]
	v_pk_mul_f32 v[34:35], v[34:35], s[86:87] op_sel_hi:[1,0]
	v_lshlrev_b32_e32 v38, 16, v244
	v_and_b32_e32 v39, 0xffff0000, v244
	v_lshlrev_b32_e32 v40, 16, v245
	v_and_b32_e32 v41, 0xffff0000, v245
	v_pk_fma_f32 v[36:37], v[32:33], v[72:73], v[34:35]
	v_pk_fma_f32 v[34:35], v[30:31], v[70:71], v[44:45]
.LBB0_1142:
	s_andn2_b64 vcc, exec, s[30:31]
	v_lshl_add_u64 v[46:47], v[42:43], 2, s[28:29]
	s_cbranch_vccnz .LBB0_1144
	global_load_dwordx4 v[34:37], v[46:47], off
	global_load_dwordx4 v[38:41], v[46:47], off offset:16
	s_waitcnt vmcnt(1)
	v_pk_mul_f32 v[36:37], v[36:37], s[86:87] op_sel_hi:[1,0]
	v_pk_mul_f32 v[34:35], v[34:35], s[86:87] op_sel_hi:[1,0]
	v_pk_fma_f32 v[36:37], v[32:33], v[72:73], v[36:37]
	v_pk_fma_f32 v[34:35], v[30:31], v[70:71], v[34:35]
	s_waitcnt vmcnt(0)
.LBB0_1144:
	v_pk_mul_f32 v[30:31], v[40:41], s[86:87] op_sel_hi:[1,0]
	v_pk_mul_f32 v[38:39], v[38:39], s[86:87] op_sel_hi:[1,0]
	v_pk_fma_f32 v[32:33], v[28:29], v[68:69], v[30:31]
	v_pk_fma_f32 v[30:31], v[26:27], v[66:67], v[38:39]
	s_and_b64 vcc, exec, s[24:25]
	v_lshl_add_u64 v[44:45], v[42:43], 1, s[64:65]
	s_cbranch_vccz .LBB0_1148
	v_cvt_pk_bf16_f32 v26, v34, v35
	v_cvt_pk_bf16_f32 v27, v36, v37
	v_cvt_pk_bf16_f32 v28, v30, v31
	v_cvt_pk_bf16_f32 v29, v32, v33
	s_mov_b64 s[30:31], -1
	s_and_b64 vcc, exec, s[88:89]
	global_store_dwordx4 v[44:45], v[26:29], off
	s_cbranch_vccz .LBB0_1147
	s_nop 0
	s_mov_b64 s[30:31], 0
	s_waitcnt vmcnt(9)
	v_lshlrev_b32_e32 v48, 16, v246
	v_and_b32_e32 v49, 0xffff0000, v246
	v_lshlrev_b32_e32 v26, 16, v247
	v_and_b32_e32 v27, 0xffff0000, v247
	v_pk_mul_f32 v[48:49], v[48:49], s[86:87] op_sel_hi:[1,0]
	v_pk_mul_f32 v[26:27], v[26:27], s[86:87] op_sel_hi:[1,0]
	v_lshlrev_b32_e32 v38, 16, v248
	v_and_b32_e32 v39, 0xffff0000, v248
	v_lshlrev_b32_e32 v40, 16, v249
	v_and_b32_e32 v41, 0xffff0000, v249
	v_pk_fma_f32 v[28:29], v[24:25], v[56:57], v[26:27]
	v_pk_fma_f32 v[26:27], v[22:23], v[54:55], v[48:49]

; __device__ __forceinline__ u32x4 pack8(const f32x4 a, const f32x4 b) { u32x4 w; w.x = cvt_pk_bf16(a[0], a[1]); w.y = cvt_pk_bf16(a[2], a[3]); w.z = cvt_pk_bf16(b[0], b[1]); w.w = cvt_pk_bf16(b[2], b[3]); return w; }
;     __device__ __forceinline__ void operator()(const f32x4 (&acc)[2][2][4][2], const Unit& u, int wr, int wc, int fr, int fq) const {
;     ...
;                     else {
; #pragma unroll
;                     for (int n = 0; n < 2; ++n) { const f32x4 bs = *(const f32x4*)(ib + off + bj * 32 + n * 4); o[n] = bs * 1.6817928305074290f + gv[bj][n] * acc[ai][bj][m][n]; } }
;                     if (tobf) *(u32x4*)(vout + off + bj * 32) = pack8(o[0], o[1]);
;                     else { *(f32x4*)(ob + off + bj * 32) = o[0]; *(f32x4*)(ob + off + bj * 32 + 4) = o[1]; } }
.LBB0_1150:
	s_andn2_b64 vcc, exec, s[30:31]
	s_cbranch_vccnz .LBB0_1152
	global_load_dwordx4 v[26:29], v[46:47], off offset:128
	global_load_dwordx4 v[38:41], v[46:47], off offset:144
	s_waitcnt vmcnt(1)
	v_pk_mul_f32 v[28:29], v[28:29], s[86:87] op_sel_hi:[1,0]
	v_pk_mul_f32 v[26:27], v[26:27], s[86:87] op_sel_hi:[1,0]
	v_pk_fma_f32 v[28:29], v[24:25], v[56:57], v[28:29]
	v_pk_fma_f32 v[26:27], v[22:23], v[54:55], v[26:27]
	s_waitcnt vmcnt(0)
.LBB0_1152:
	v_pk_mul_f32 v[22:23], v[40:41], s[86:87] op_sel_hi:[1,0]
	v_pk_mul_f32 v[24:25], v[38:39], s[86:87] op_sel_hi:[1,0]
	v_pk_fma_f32 v[20:21], v[20:21], v[52:53], v[22:23]
	v_pk_fma_f32 v[18:19], v[18:19], v[50:51], v[24:25]
	s_mov_b64 s[30:31], -1
	s_and_b64 vcc, exec, s[24:25]
	s_cbranch_vccz .LBB0_1154
	v_cvt_pk_bf16_f32 v22, v26, v27
	v_cvt_pk_bf16_f32 v23, v28, v29
	v_cvt_pk_bf16_f32 v24, v18, v19
	v_cvt_pk_bf16_f32 v25, v20, v21
	global_store_dwordx4 v[44:45], v[22:25], off offset:64
	s_mov_b64 s[30:31], 0

; __device__ __forceinline__ u32x4 pack8(const f32x4 a, const f32x4 b) { u32x4 w; w.x = cvt_pk_bf16(a[0], a[1]); w.y = cvt_pk_bf16(a[2], a[3]); w.z = cvt_pk_bf16(b[0], b[1]); w.w = cvt_pk_bf16(b[2], b[3]); return w; }
;     __device__ __forceinline__ void operator()(const f32x4 (&acc)[2][2][4][2], const Unit& u, int wr, int wc, int fr, int fq) const {
;     ...
;         for (int ai = 0; ai < 2; ++ai)
; #pragma unroll
;             for (int m = 0; m < 4; ++m) { const size_t off = (size_t)(rowb + ai * HALF + m * 16) * 1024 + col0;
; #pragma unroll
;                 for (int bj = 0; bj < 2; ++bj) { f32x4 o[2];
;                     if (lat && rinB) { const u32x4 w = *(const u32x4*)(rinB + off + bj * 32);
;                         const f32x4 b0 = {__builtin_bit_cast(float, w.x << 16), __builtin_bit_cast(float, w.x & 0xffff0000u), __builtin_bit_cast(float, w.y << 16), __builtin_bit_cast(float, w.y & 0xffff0000u)};
;                         const f32x4 b1 = {__builtin_bit_cast(float, w.z << 16), __builtin_bit_cast(float, w.z & 0xffff0000u), __builtin_bit_cast(float, w.w << 16), __builtin_bit_cast(float, w.w & 0xffff0000u)};
;                         o[0] = b0 * 1.6817928305074290f + gv[bj][0] * acc[ai][bj][m][0]; o[1] = b1 * 1.6817928305074290f + gv[bj][1] * acc[ai][bj][m][1]; }
;                     else {
; #pragma unroll
;                     for (int n = 0; n < 2; ++n) { const f32x4 bs = *(const f32x4*)(ib + off + bj * 32 + n * 4); o[n] = bs * 1.6817928305074290f + gv[bj][n] * acc[ai][bj][m][n]; } }
;                     if (tobf) *(u32x4*)(vout + off + bj * 32) = pack8(o[0], o[1]);
;                     else { *(f32x4*)(ob + off + bj * 32) = o[0]; *(f32x4*)(ob + off + bj * 32 + 4) = o[1]; } }
.LBB0_1156:
	s_nop 1
	v_lshlrev_b64 v[18:19], 10, v[180:181]
	v_lshl_add_u64 v[18:19], v[18:19], 0, v[182:183]
	s_mov_b64 s[0:1], 0x2c000
	v_lshl_add_u64 v[26:27], v[18:19], 0, s[0:1]
	s_mov_b64 s[30:31], -1
	s_and_b64 vcc, exec, s[34:35]
	s_cbranch_vccnz .LBB0_1158
	s_mov_b64 s[30:31], 0
	s_waitcnt vmcnt(8)
	v_lshlrev_b32_e32 v28, 16, v208
	v_and_b32_e32 v29, 0xffff0000, v208
	v_lshlrev_b32_e32 v18, 16, v209
	v_and_b32_e32 v19, 0xffff0000, v209
	v_pk_mul_f32 v[28:29], v[28:29], s[86:87] op_sel_hi:[1,0]
	v_pk_mul_f32 v[18:19], v[18:19], s[86:87] op_sel_hi:[1,0]
	v_lshlrev_b32_e32 v22, 16, v210
	v_and_b32_e32 v23, 0xffff0000, v210
	v_lshlrev_b32_e32 v24, 16, v211
	v_and_b32_e32 v25, 0xffff0000, v211
	v_pk_fma_f32 v[20:21], v[16:17], v[72:73], v[18:19]
	v_pk_fma_f32 v[18:19], v[14:15], v[70:71], v[28:29]
.LBB0_1158:
	s_andn2_b64 vcc, exec, s[30:31]
	v_lshl_add_u64 v[30:31], v[26:27], 2, s[28:29]
	s_cbranch_vccnz .LBB0_1160
	global_load_dwordx4 v[18:21], v[30:31], off
	global_load_dwordx4 v[22:25], v[30:31], off offset:16
	s_waitcnt vmcnt(1)
	v_pk_mul_f32 v[20:21], v[20:21], s[86:87] op_sel_hi:[1,0]
	v_pk_mul_f32 v[18:19], v[18:19], s[86:87] op_sel_hi:[1,0]
	v_pk_fma_f32 v[20:21], v[16:17], v[72:73], v[20:21]
	v_pk_fma_f32 v[18:19], v[14:15], v[70:71], v[18:19]
	s_waitcnt vmcnt(0)
.LBB0_1160:
	v_pk_mul_f32 v[14:15], v[24:25], s[86:87] op_sel_hi:[1,0]
	v_pk_mul_f32 v[22:23], v[22:23], s[86:87] op_sel_hi:[1,0]
	v_pk_fma_f32 v[16:17], v[12:13], v[68:69], v[14:15]
	v_pk_fma_f32 v[14:15], v[10:11], v[66:67], v[22:23]
	s_and_b64 vcc, exec, s[24:25]
	v_lshl_add_u64 v[28:29], v[26:27], 1, s[64:65]
	s_cbranch_vccz .LBB0_1164
	v_cvt_pk_bf16_f32 v10, v18, v19
	v_cvt_pk_bf16_f32 v11, v20, v21
	v_cvt_pk_bf16_f32 v12, v14, v15
	v_cvt_pk_bf16_f32 v13, v16, v17
	s_mov_b64 s[28:29], -1
	s_and_b64 vcc, exec, s[88:89]
	global_store_dwordx4 v[28:29], v[10:13], off
	s_cbranch_vccz .LBB0_1163
	s_nop 0
	s_mov_b64 s[28:29], 0
	s_waitcnt vmcnt(7)
	v_lshlrev_b32_e32 v32, 16, v226
	v_and_b32_e32 v33, 0xffff0000, v226
	v_lshlrev_b32_e32 v10, 16, v227
	v_and_b32_e32 v11, 0xffff0000, v227
	v_pk_mul_f32 v[32:33], v[32:33], s[86:87] op_sel_hi:[1,0]
	v_pk_mul_f32 v[10:11], v[10:11], s[86:87] op_sel_hi:[1,0]
	v_lshlrev_b32_e32 v22, 16, v228
	v_and_b32_e32 v23, 0xffff0000, v228
	v_lshlrev_b32_e32 v24, 16, v229
	v_and_b32_e32 v25, 0xffff0000, v229
	v_pk_fma_f32 v[12:13], v[8:9], v[56:57], v[10:11]
	v_pk_fma_f32 v[10:11], v[6:7], v[54:55], v[32:33]

; __device__ __forceinline__ u32x4 pack8(const f32x4 a, const f32x4 b) { u32x4 w; w.x = cvt_pk_bf16(a[0], a[1]); w.y = cvt_pk_bf16(a[2], a[3]); w.z = cvt_pk_bf16(b[0], b[1]); w.w = cvt_pk_bf16(b[2], b[3]); return w; }
;     __device__ __forceinline__ void operator()(const f32x4 (&acc)[2][2][4][2], const Unit& u, int wr, int wc, int fr, int fq) const {
;     ...
;                     else {
; #pragma unroll
;                     for (int n = 0; n < 2; ++n) { const f32x4 bs = *(const f32x4*)(ib + off + bj * 32 + n * 4); o[n] = bs * 1.6817928305074290f + gv[bj][n] * acc[ai][bj][m][n]; } }
;                     if (tobf) *(u32x4*)(vout + off + bj * 32) = pack8(o[0], o[1]);
;                     else { *(f32x4*)(ob + off + bj * 32) = o[0]; *(f32x4*)(ob + off + bj * 32 + 4) = o[1]; } }
.LBB0_1166:
	s_andn2_b64 vcc, exec, s[28:29]
	s_cbranch_vccnz .LBB0_1168
	global_load_dwordx4 v[10:13], v[30:31], off offset:128
	global_load_dwordx4 v[22:25], v[30:31], off offset:144
	s_waitcnt vmcnt(1)
	v_pk_mul_f32 v[12:13], v[12:13], s[86:87] op_sel_hi:[1,0]
	v_pk_mul_f32 v[10:11], v[10:11], s[86:87] op_sel_hi:[1,0]
	v_pk_fma_f32 v[12:13], v[8:9], v[56:57], v[12:13]
	v_pk_fma_f32 v[10:11], v[6:7], v[54:55], v[10:11]
	s_waitcnt vmcnt(0)
.LBB0_1168:
	v_pk_mul_f32 v[6:7], v[24:25], s[86:87] op_sel_hi:[1,0]
	v_pk_mul_f32 v[8:9], v[22:23], s[86:87] op_sel_hi:[1,0]
	v_pk_fma_f32 v[4:5], v[4:5], v[52:53], v[6:7]
	v_pk_fma_f32 v[2:3], v[2:3], v[50:51], v[8:9]
	s_mov_b64 s[26:27], -1
	s_and_b64 vcc, exec, s[24:25]
	s_cbranch_vccz .LBB0_1171
	v_cvt_pk_bf16_f32 v6, v10, v11
	v_cvt_pk_bf16_f32 v7, v12, v13
	v_cvt_pk_bf16_f32 v8, v2, v3
	v_cvt_pk_bf16_f32 v9, v4, v5
	global_store_dwordx4 v[28:29], v[6:9], off offset:64
	s_cbranch_execz .LBB0_1172

; __device__ __forceinline__ u32x4 pack8(const f32x4 a, const f32x4 b) { u32x4 w; w.x = cvt_pk_bf16(a[0], a[1]); w.y = cvt_pk_bf16(a[2], a[3]); w.z = cvt_pk_bf16(b[0], b[1]); w.w = cvt_pk_bf16(b[2], b[3]); return w; }
;     __device__ __forceinline__ void operator()(const f32x4 (&acc)[2][2][4][2], const Unit& u, int wr, int wc, int fr, int fq) const {
;     ...
;         const float* gp = gate + (size_t)bb * 6144 + col0;
;         f32x4 gv[2][2];
; #pragma unroll
;         for (int bj = 0; bj < 2; ++bj)
; #pragma unroll
;             for (int n = 0; n < 2; ++n) gv[bj][n] = *(const f32x4*)(gp + bj * 32 + n * 4);
;         const float* ib = lat ? rinL : rinC - (size_t)32768 * 1024; float* ob = lat ? routL : routC - (size_t)32768 * 1024;
;         const bool tobf = lat && vout != nullptr;
; #pragma unroll
;         for (int ai = 0; ai < 2; ++ai)
; #pragma unroll
;             for (int m = 0; m < 4; ++m) { const size_t off = (size_t)(rowb + ai * HALF + m * 16) * 1024 + col0;
; #pragma unroll
;                 for (int bj = 0; bj < 2; ++bj) { f32x4 o[2];
;                     if (lat && rinB) { const u32x4 w = *(const u32x4*)(rinB + off + bj * 32);
;                         const f32x4 b0 = {__builtin_bit_cast(float, w.x << 16), __builtin_bit_cast(float, w.x & 0xffff0000u), __builtin_bit_cast(float, w.y << 16), __builtin_bit_cast(float, w.y & 0xffff0000u)};
;                         const f32x4 b1 = {__builtin_bit_cast(float, w.z << 16), __builtin_bit_cast(float, w.z & 0xffff0000u), __builtin_bit_cast(float, w.w << 16), __builtin_bit_cast(float, w.w & 0xffff0000u)};
;                         o[0] = b0 * 1.6817928305074290f + gv[bj][0] * acc[ai][bj][m][0]; o[1] = b1 * 1.6817928305074290f + gv[bj][1] * acc[ai][bj][m][1]; }
;                     else {
; #pragma unroll
;                     for (int n = 0; n < 2; ++n) { const f32x4 bs = *(const f32x4*)(ib + off + bj * 32 + n * 4); o[n] = bs * 1.6817928305074290f + gv[bj][n] * acc[ai][bj][m][n]; } }
;                     if (tobf) *(u32x4*)(vout + off + bj * 32) = pack8(o[0], o[1]);
;                     else { *(f32x4*)(ob + off + bj * 32) = o[0]; *(f32x4*)(ob + off + bj * 32 + 4) = o[1]; } }
.LBB0_1430:
	v_lshl_add_u32 v188, s30, 8, v204
	v_lshl_or_b32 v190, s28, 8, v206
	s_mov_b64 s[28:29], -1
	s_cmp_lt_i32 s16, 0
	v_ashrrev_i32_e32 v191, 31, v190
	v_ashrrev_i32_e32 v189, 31, v188
	s_cbranch_scc0 .LBB0_1439
	s_lshl_b64 s[28:29], s[36:37], 2
	s_add_u32 s28, s40, s28
	s_addc_u32 s29, s41, s29
	v_lshl_add_u64 v[150:151], v[190:191], 2, s[28:29]
	global_load_dwordx4 v[154:157], v[150:151], off offset:16
	global_load_dwordx4 v[158:161], v[150:151], off
	global_load_dwordx4 v[146:149], v[150:151], off offset:144
	s_nop 0
	global_load_dwordx4 v[150:153], v[150:151], off offset:128
	v_readlane_b32 s2, v254, 35
	s_and_b64 s[28:29], exec, s[34:35]
	v_readlane_b32 s3, v254, 36
	s_cselect_b32 s29, s3, s93
	s_cselect_b32 s28, s2, s92
	v_lshlrev_b64 v[162:163], 10, v[188:189]
	s_or_b64 s[34:35], s[34:35], s[90:91]
	v_lshl_add_u64 v[196:197], v[162:163], 0, v[190:191]
	v_lshlrev_b32_e32 v250, 1, v196
	global_load_dwordx4 v[208:211], v250, s[92:93]
	global_load_dwordx4 v[226:229], v250, s[92:93] offset:64
	v_add_u32_e32 v251, 0x8000, v250
	global_load_dwordx4 v[230:233], v251, s[92:93]
	v_add_u32_e32 v251, 0x8000, v250
	global_load_dwordx4 v[234:237], v251, s[92:93] offset:64
	v_add_u32_e32 v251, 0x10000, v250
	global_load_dwordx4 v[238:241], v251, s[92:93]
	v_add_u32_e32 v251, 0x10000, v250
	global_load_dwordx4 v[242:245], v251, s[92:93] offset:64
	v_add_u32_e32 v251, 0x18000, v250
	global_load_dwordx4 v[246:249], v251, s[92:93]
	s_mov_b64 s[30:31], -1
	s_and_b64 vcc, exec, s[34:35]
	s_cbranch_vccnz .LBB0_1433
	s_mov_b64 s[30:31], 0
	s_waitcnt vmcnt(6)
	v_lshlrev_b32_e32 v170, 16, v208
	v_and_b32_e32 v171, 0xffff0000, v208
	v_lshlrev_b32_e32 v162, 16, v209
	v_and_b32_e32 v163, 0xffff0000, v209
	v_pk_mul_f32 v[170:171], v[170:171], s[86:87] op_sel_hi:[1,0]
	v_pk_mul_f32 v[162:163], v[162:163], s[86:87] op_sel_hi:[1,0]
	v_lshlrev_b32_e32 v166, 16, v210
	v_and_b32_e32 v167, 0xffff0000, v210
	v_lshlrev_b32_e32 v168, 16, v211
	v_and_b32_e32 v169, 0xffff0000, v211
	v_pk_fma_f32 v[164:165], v[144:145], v[160:161], v[162:163]
	v_pk_fma_f32 v[162:163], v[142:143], v[158:159], v[170:171]
	v_add_u32_e32 v251, 0x18000, v250
	global_load_dwordx4 v[208:211], v251, s[92:93] offset:64
.LBB0_1433:
	s_andn2_b64 vcc, exec, s[30:31]
	v_lshl_add_u64 v[192:193], v[196:197], 2, s[28:29]
	s_cbranch_vccnz .LBB0_1435
	global_load_dwordx4 v[162:165], v[192:193], off
	global_load_dwordx4 v[166:169], v[192:193], off offset:16
	s_waitcnt vmcnt(0)
	v_pk_mul_f32 v[164:165], v[164:165], s[86:87] op_sel_hi:[1,0]
	v_pk_mul_f32 v[162:163], v[162:163], s[86:87] op_sel_hi:[1,0]
	v_pk_fma_f32 v[164:165], v[144:145], v[160:161], v[164:165]
	v_pk_fma_f32 v[162:163], v[142:143], v[158:159], v[162:163]
	s_waitcnt vmcnt(0)
.LBB0_1435:
	v_pk_mul_f32 v[168:169], v[168:169], s[86:87] op_sel_hi:[1,0]
	v_pk_mul_f32 v[166:167], v[166:167], s[86:87] op_sel_hi:[1,0]
	v_pk_fma_f32 v[172:173], v[140:141], v[156:157], v[168:169]
	v_pk_fma_f32 v[170:171], v[138:139], v[154:155], v[166:167]
	s_andn2_b64 vcc, exec, s[26:27]
	v_lshl_add_u64 v[194:195], v[196:197], 1, s[64:65]
	s_cbranch_vccnz .LBB0_1441
	v_cvt_pk_bf16_f32 v166, v162, v163
	v_cvt_pk_bf16_f32 v167, v164, v165
	v_cvt_pk_bf16_f32 v168, v170, v171
	v_cvt_pk_bf16_f32 v169, v172, v173
	s_mov_b64 s[30:31], -1
	s_and_b64 vcc, exec, s[88:89]
	global_store_dwordx4 v[194:195], v[166:169], off
	s_cbranch_vccz .LBB0_1438
	s_nop 0
	s_mov_b64 s[30:31], 0
	s_waitcnt vmcnt(7)
	v_lshlrev_b32_e32 v196, 16, v226
	v_and_b32_e32 v197, 0xffff0000, v226
	v_lshlrev_b32_e32 v166, 16, v227
	v_and_b32_e32 v167, 0xffff0000, v227
	v_pk_mul_f32 v[196:197], v[196:197], s[86:87] op_sel_hi:[1,0]
	v_pk_mul_f32 v[166:167], v[166:167], s[86:87] op_sel_hi:[1,0]
	v_lshlrev_b32_e32 v174, 16, v228
	v_and_b32_e32 v175, 0xffff0000, v228
	v_lshlrev_b32_e32 v176, 16, v229
	v_and_b32_e32 v177, 0xffff0000, v229
	v_pk_fma_f32 v[168:169], v[132:133], v[152:153], v[166:167]
	v_pk_fma_f32 v[166:167], v[130:131], v[150:151], v[196:197]
	v_add_u32_e32 v251, 0x40000, v250
	global_load_dwordx4 v[226:229], v251, s[92:93]

; __device__ __forceinline__ u32x4 pack8(const f32x4 a, const f32x4 b) { u32x4 w; w.x = cvt_pk_bf16(a[0], a[1]); w.y = cvt_pk_bf16(a[2], a[3]); w.z = cvt_pk_bf16(b[0], b[1]); w.w = cvt_pk_bf16(b[2], b[3]); return w; }
;     __device__ __forceinline__ void operator()(const f32x4 (&acc)[2][2][4][2], const Unit& u, int wr, int wc, int fr, int fq) const {
;     ...
;                     else {
; #pragma unroll
;                     for (int n = 0; n < 2; ++n) { const f32x4 bs = *(const f32x4*)(ib + off + bj * 32 + n * 4); o[n] = bs * 1.6817928305074290f + gv[bj][n] * acc[ai][bj][m][n]; } }
;                     if (tobf) *(u32x4*)(vout + off + bj * 32) = pack8(o[0], o[1]);
;                     else { *(f32x4*)(ob + off + bj * 32) = o[0]; *(f32x4*)(ob + off + bj * 32 + 4) = o[1]; } }
.LBB0_1443:
	s_andn2_b64 vcc, exec, s[30:31]
	s_cbranch_vccnz .LBB0_1445
	global_load_dwordx4 v[162:165], v[192:193], off offset:128
	global_load_dwordx4 v[174:177], v[192:193], off offset:144
	s_waitcnt vmcnt(1)
	v_pk_mul_f32 v[164:165], v[164:165], s[86:87] op_sel_hi:[1,0]
	v_pk_mul_f32 v[162:163], v[162:163], s[86:87] op_sel_hi:[1,0]
	v_pk_fma_f32 v[168:169], v[132:133], v[152:153], v[164:165]
	v_pk_fma_f32 v[166:167], v[130:131], v[150:151], v[162:163]
	s_waitcnt vmcnt(0)
.LBB0_1445:
	v_pk_mul_f32 v[164:165], v[176:177], s[86:87] op_sel_hi:[1,0]
	v_pk_mul_f32 v[162:163], v[174:175], s[86:87] op_sel_hi:[1,0]
	v_pk_fma_f32 v[164:165], v[108:109], v[148:149], v[164:165]
	v_pk_fma_f32 v[162:163], v[106:107], v[146:147], v[162:163]
	s_mov_b64 s[30:31], -1
	s_and_b64 vcc, exec, s[26:27]
	s_cbranch_vccz .LBB0_1447
	v_cvt_pk_bf16_f32 v170, v166, v167
	v_cvt_pk_bf16_f32 v171, v168, v169
	v_cvt_pk_bf16_f32 v172, v162, v163
	v_cvt_pk_bf16_f32 v173, v164, v165
	global_store_dwordx4 v[194:195], v[170:173], off offset:64
	s_mov_b64 s[30:31], 0

; __device__ __forceinline__ u32x4 pack8(const f32x4 a, const f32x4 b) { u32x4 w; w.x = cvt_pk_bf16(a[0], a[1]); w.y = cvt_pk_bf16(a[2], a[3]); w.z = cvt_pk_bf16(b[0], b[1]); w.w = cvt_pk_bf16(b[2], b[3]); return w; }
;     __device__ __forceinline__ void operator()(const f32x4 (&acc)[2][2][4][2], const Unit& u, int wr, int wc, int fr, int fq) const {
;     ...
;         for (int ai = 0; ai < 2; ++ai)
; #pragma unroll
;             for (int m = 0; m < 4; ++m) { const size_t off = (size_t)(rowb + ai * HALF + m * 16) * 1024 + col0;
; #pragma unroll
;                 for (int bj = 0; bj < 2; ++bj) { f32x4 o[2];
;                     if (lat && rinB) { const u32x4 w = *(const u32x4*)(rinB + off + bj * 32);
;                         const f32x4 b0 = {__builtin_bit_cast(float, w.x << 16), __builtin_bit_cast(float, w.x & 0xffff0000u), __builtin_bit_cast(float, w.y << 16), __builtin_bit_cast(float, w.y & 0xffff0000u)};
;                         const f32x4 b1 = {__builtin_bit_cast(float, w.z << 16), __builtin_bit_cast(float, w.z & 0xffff0000u), __builtin_bit_cast(float, w.w << 16), __builtin_bit_cast(float, w.w & 0xffff0000u)};
;                         o[0] = b0 * 1.6817928305074290f + gv[bj][0] * acc[ai][bj][m][0]; o[1] = b1 * 1.6817928305074290f + gv[bj][1] * acc[ai][bj][m][1]; }
;                     else {
; #pragma unroll
;                     for (int n = 0; n < 2; ++n) { const f32x4 bs = *(const f32x4*)(ib + off + bj * 32 + n * 4); o[n] = bs * 1.6817928305074290f + gv[bj][n] * acc[ai][bj][m][n]; } }
;                     if (tobf) *(u32x4*)(vout + off + bj * 32) = pack8(o[0], o[1]);
;                     else { *(f32x4*)(ob + off + bj * 32) = o[0]; *(f32x4*)(ob + off + bj * 32 + 4) = o[1]; } }
.LBB0_1449:
	s_nop 1
	v_or_b32_e32 v162, 16, v188
	v_ashrrev_i32_e32 v163, 31, v162
	v_lshlrev_b64 v[162:163], 10, v[162:163]
	v_lshl_add_u64 v[196:197], v[162:163], 0, v[190:191]
	s_mov_b64 s[30:31], -1
	s_and_b64 vcc, exec, s[34:35]
	s_cbranch_vccnz .LBB0_1451
	s_mov_b64 s[30:31], 0
	s_waitcnt vmcnt(8)
	v_lshlrev_b32_e32 v170, 16, v230
	v_and_b32_e32 v171, 0xffff0000, v230
	v_lshlrev_b32_e32 v162, 16, v231
	v_and_b32_e32 v163, 0xffff0000, v231
	v_pk_mul_f32 v[170:171], v[170:171], s[86:87] op_sel_hi:[1,0]
	v_pk_mul_f32 v[162:163], v[162:163], s[86:87] op_sel_hi:[1,0]
	v_lshlrev_b32_e32 v166, 16, v232
	v_and_b32_e32 v167, 0xffff0000, v232
	v_lshlrev_b32_e32 v168, 16, v233
	v_and_b32_e32 v169, 0xffff0000, v233
	v_pk_fma_f32 v[164:165], v[136:137], v[160:161], v[162:163]
	v_pk_fma_f32 v[162:163], v[134:135], v[158:159], v[170:171]
	v_add_u32_e32 v251, 0x40000, v250
	global_load_dwordx4 v[230:233], v251, s[92:93] offset:64
.LBB0_1451:
	s_andn2_b64 vcc, exec, s[30:31]
	v_lshl_add_u64 v[192:193], v[196:197], 2, s[28:29]
	s_cbranch_vccnz .LBB0_1453
	global_load_dwordx4 v[162:165], v[192:193], off
	global_load_dwordx4 v[166:169], v[192:193], off offset:16
	s_waitcnt vmcnt(1)
	v_pk_mul_f32 v[164:165], v[164:165], s[86:87] op_sel_hi:[1,0]
	v_pk_mul_f32 v[162:163], v[162:163], s[86:87] op_sel_hi:[1,0]
	v_pk_fma_f32 v[164:165], v[136:137], v[160:161], v[164:165]
	v_pk_fma_f32 v[162:163], v[134:135], v[158:159], v[162:163]
	s_waitcnt vmcnt(0)
.LBB0_1453:
	v_pk_mul_f32 v[168:169], v[168:169], s[86:87] op_sel_hi:[1,0]
	v_pk_mul_f32 v[166:167], v[166:167], s[86:87] op_sel_hi:[1,0]
	v_pk_fma_f32 v[176:177], v[112:113], v[156:157], v[168:169]
	v_pk_fma_f32 v[174:175], v[110:111], v[154:155], v[166:167]
	s_and_b64 vcc, exec, s[26:27]
	v_lshl_add_u64 v[194:195], v[196:197], 1, s[64:65]
	s_cbranch_vccz .LBB0_1457
	v_cvt_pk_bf16_f32 v166, v162, v163
	v_cvt_pk_bf16_f32 v167, v164, v165
	v_cvt_pk_bf16_f32 v168, v174, v175
	v_cvt_pk_bf16_f32 v169, v176, v177
	s_mov_b64 s[30:31], -1
	s_and_b64 vcc, exec, s[88:89]
	global_store_dwordx4 v[194:195], v[166:169], off
	s_cbranch_vccz .LBB0_1456
	s_nop 0
	s_mov_b64 s[30:31], 0
	s_waitcnt vmcnt(9)
	v_lshlrev_b32_e32 v196, 16, v234
	v_and_b32_e32 v197, 0xffff0000, v234
	v_lshlrev_b32_e32 v166, 16, v235
	v_and_b32_e32 v167, 0xffff0000, v235
	v_pk_mul_f32 v[196:197], v[196:197], s[86:87] op_sel_hi:[1,0]
	v_pk_mul_f32 v[166:167], v[166:167], s[86:87] op_sel_hi:[1,0]
	v_lshlrev_b32_e32 v170, 16, v236
	v_and_b32_e32 v171, 0xffff0000, v236
	v_lshlrev_b32_e32 v172, 16, v237
	v_and_b32_e32 v173, 0xffff0000, v237
	v_pk_fma_f32 v[168:169], v[100:101], v[152:153], v[166:167]
	v_pk_fma_f32 v[166:167], v[98:99], v[150:151], v[196:197]
	v_add_u32_e32 v251, 0x48000, v250
	global_load_dwordx4 v[234:237], v251, s[92:93]

; __device__ __forceinline__ u32x4 pack8(const f32x4 a, const f32x4 b) { u32x4 w; w.x = cvt_pk_bf16(a[0], a[1]); w.y = cvt_pk_bf16(a[2], a[3]); w.z = cvt_pk_bf16(b[0], b[1]); w.w = cvt_pk_bf16(b[2], b[3]); return w; }
;     __device__ __forceinline__ void operator()(const f32x4 (&acc)[2][2][4][2], const Unit& u, int wr, int wc, int fr, int fq) const {
;     ...
;                     else {
; #pragma unroll
;                     for (int n = 0; n < 2; ++n) { const f32x4 bs = *(const f32x4*)(ib + off + bj * 32 + n * 4); o[n] = bs * 1.6817928305074290f + gv[bj][n] * acc[ai][bj][m][n]; } }
;                     if (tobf) *(u32x4*)(vout + off + bj * 32) = pack8(o[0], o[1]);
;                     else { *(f32x4*)(ob + off + bj * 32) = o[0]; *(f32x4*)(ob + off + bj * 32 + 4) = o[1]; } }
.LBB0_1459:
	s_andn2_b64 vcc, exec, s[30:31]
	s_cbranch_vccnz .LBB0_1461
	global_load_dwordx4 v[162:165], v[192:193], off offset:128
	global_load_dwordx4 v[170:173], v[192:193], off offset:144
	s_waitcnt vmcnt(1)
	v_pk_mul_f32 v[164:165], v[164:165], s[86:87] op_sel_hi:[1,0]
	v_pk_mul_f32 v[162:163], v[162:163], s[86:87] op_sel_hi:[1,0]
	v_pk_fma_f32 v[168:169], v[100:101], v[152:153], v[164:165]
	v_pk_fma_f32 v[166:167], v[98:99], v[150:151], v[162:163]
	s_waitcnt vmcnt(0)
.LBB0_1461:
	v_pk_mul_f32 v[162:163], v[172:173], s[86:87] op_sel_hi:[1,0]
	v_pk_mul_f32 v[170:171], v[170:171], s[86:87] op_sel_hi:[1,0]
	v_pk_fma_f32 v[164:165], v[92:93], v[148:149], v[162:163]
	v_pk_fma_f32 v[162:163], v[90:91], v[146:147], v[170:171]
	s_mov_b64 s[30:31], -1
	s_and_b64 vcc, exec, s[26:27]
	s_cbranch_vccz .LBB0_1463
	v_cvt_pk_bf16_f32 v170, v166, v167
	v_cvt_pk_bf16_f32 v171, v168, v169
	v_cvt_pk_bf16_f32 v172, v162, v163
	v_cvt_pk_bf16_f32 v173, v164, v165
	global_store_dwordx4 v[194:195], v[170:173], off offset:64
	s_mov_b64 s[30:31], 0

; __device__ __forceinline__ u32x4 pack8(const f32x4 a, const f32x4 b) { u32x4 w; w.x = cvt_pk_bf16(a[0], a[1]); w.y = cvt_pk_bf16(a[2], a[3]); w.z = cvt_pk_bf16(b[0], b[1]); w.w = cvt_pk_bf16(b[2], b[3]); return w; }
;     __device__ __forceinline__ void operator()(const f32x4 (&acc)[2][2][4][2], const Unit& u, int wr, int wc, int fr, int fq) const {
;     ...
;         for (int ai = 0; ai < 2; ++ai)
; #pragma unroll
;             for (int m = 0; m < 4; ++m) { const size_t off = (size_t)(rowb + ai * HALF + m * 16) * 1024 + col0;
; #pragma unroll
;                 for (int bj = 0; bj < 2; ++bj) { f32x4 o[2];
;                     if (lat && rinB) { const u32x4 w = *(const u32x4*)(rinB + off + bj * 32);
;                         const f32x4 b0 = {__builtin_bit_cast(float, w.x << 16), __builtin_bit_cast(float, w.x & 0xffff0000u), __builtin_bit_cast(float, w.y << 16), __builtin_bit_cast(float, w.y & 0xffff0000u)};
;                         const f32x4 b1 = {__builtin_bit_cast(float, w.z << 16), __builtin_bit_cast(float, w.z & 0xffff0000u), __builtin_bit_cast(float, w.w << 16), __builtin_bit_cast(float, w.w & 0xffff0000u)};
;                         o[0] = b0 * 1.6817928305074290f + gv[bj][0] * acc[ai][bj][m][0]; o[1] = b1 * 1.6817928305074290f + gv[bj][1] * acc[ai][bj][m][1]; }
;                     else {
; #pragma unroll
;                     for (int n = 0; n < 2; ++n) { const f32x4 bs = *(const f32x4*)(ib + off + bj * 32 + n * 4); o[n] = bs * 1.6817928305074290f + gv[bj][n] * acc[ai][bj][m][n]; } }
;                     if (tobf) *(u32x4*)(vout + off + bj * 32) = pack8(o[0], o[1]);
;                     else { *(f32x4*)(ob + off + bj * 32) = o[0]; *(f32x4*)(ob + off + bj * 32 + 4) = o[1]; } }
.LBB0_1465:
	s_nop 1
	v_or_b32_e32 v162, 32, v188
	v_ashrrev_i32_e32 v163, 31, v162
	v_lshlrev_b64 v[162:163], 10, v[162:163]
	v_lshl_add_u64 v[196:197], v[162:163], 0, v[190:191]
	s_mov_b64 s[30:31], -1
	s_and_b64 vcc, exec, s[34:35]
	s_cbranch_vccnz .LBB0_1467
	s_mov_b64 s[30:31], 0
	s_waitcnt vmcnt(10)
	v_lshlrev_b32_e32 v170, 16, v238
	v_and_b32_e32 v171, 0xffff0000, v238
	v_lshlrev_b32_e32 v162, 16, v239
	v_and_b32_e32 v163, 0xffff0000, v239
	v_pk_mul_f32 v[170:171], v[170:171], s[86:87] op_sel_hi:[1,0]
	v_pk_mul_f32 v[162:163], v[162:163], s[86:87] op_sel_hi:[1,0]
	v_lshlrev_b32_e32 v166, 16, v240
	v_and_b32_e32 v167, 0xffff0000, v240
	v_lshlrev_b32_e32 v168, 16, v241
	v_and_b32_e32 v169, 0xffff0000, v241
	v_pk_fma_f32 v[164:165], v[104:105], v[160:161], v[162:163]
	v_pk_fma_f32 v[162:163], v[102:103], v[158:159], v[170:171]
	v_add_u32_e32 v251, 0x48000, v250
	global_load_dwordx4 v[238:241], v251, s[92:93] offset:64
.LBB0_1467:
	s_andn2_b64 vcc, exec, s[30:31]
	v_lshl_add_u64 v[192:193], v[196:197], 2, s[28:29]
	s_cbranch_vccnz .LBB0_1469
	global_load_dwordx4 v[162:165], v[192:193], off
	global_load_dwordx4 v[166:169], v[192:193], off offset:16
	s_waitcnt vmcnt(1)
	v_pk_mul_f32 v[164:165], v[164:165], s[86:87] op_sel_hi:[1,0]
	v_pk_mul_f32 v[162:163], v[162:163], s[86:87] op_sel_hi:[1,0]
	v_pk_fma_f32 v[164:165], v[104:105], v[160:161], v[164:165]
	v_pk_fma_f32 v[162:163], v[102:103], v[158:159], v[162:163]
	s_waitcnt vmcnt(0)
.LBB0_1469:
	v_pk_mul_f32 v[168:169], v[168:169], s[86:87] op_sel_hi:[1,0]
	v_pk_mul_f32 v[166:167], v[166:167], s[86:87] op_sel_hi:[1,0]
	v_pk_fma_f32 v[172:173], v[96:97], v[156:157], v[168:169]
	v_pk_fma_f32 v[170:171], v[94:95], v[154:155], v[166:167]
	s_and_b64 vcc, exec, s[26:27]
	v_lshl_add_u64 v[194:195], v[196:197], 1, s[64:65]
	s_cbranch_vccz .LBB0_1473
	v_cvt_pk_bf16_f32 v166, v162, v163
	v_cvt_pk_bf16_f32 v167, v164, v165
	v_cvt_pk_bf16_f32 v168, v170, v171
	v_cvt_pk_bf16_f32 v169, v172, v173
	s_mov_b64 s[30:31], -1
	s_and_b64 vcc, exec, s[88:89]
	global_store_dwordx4 v[194:195], v[166:169], off
	s_cbranch_vccz .LBB0_1472
	s_nop 0
	s_mov_b64 s[30:31], 0
	s_waitcnt vmcnt(11)
	v_lshlrev_b32_e32 v196, 16, v242
	v_and_b32_e32 v197, 0xffff0000, v242
	v_lshlrev_b32_e32 v166, 16, v243
	v_and_b32_e32 v167, 0xffff0000, v243
	v_pk_mul_f32 v[196:197], v[196:197], s[86:87] op_sel_hi:[1,0]
	v_pk_mul_f32 v[166:167], v[166:167], s[86:87] op_sel_hi:[1,0]
	v_lshlrev_b32_e32 v174, 16, v244
	v_and_b32_e32 v175, 0xffff0000, v244
	v_lshlrev_b32_e32 v176, 16, v245
	v_and_b32_e32 v177, 0xffff0000, v245
	v_pk_fma_f32 v[168:169], v[84:85], v[152:153], v[166:167]
	v_pk_fma_f32 v[166:167], v[82:83], v[150:151], v[196:197]
	v_add_u32_e32 v251, 0x50000, v250
	global_load_dwordx4 v[242:245], v251, s[92:93]

; __device__ __forceinline__ u32x4 pack8(const f32x4 a, const f32x4 b) { u32x4 w; w.x = cvt_pk_bf16(a[0], a[1]); w.y = cvt_pk_bf16(a[2], a[3]); w.z = cvt_pk_bf16(b[0], b[1]); w.w = cvt_pk_bf16(b[2], b[3]); return w; }
;     __device__ __forceinline__ void operator()(const f32x4 (&acc)[2][2][4][2], const Unit& u, int wr, int wc, int fr, int fq) const {
;     ...
;                     else {
; #pragma unroll
;                     for (int n = 0; n < 2; ++n) { const f32x4 bs = *(const f32x4*)(ib + off + bj * 32 + n * 4); o[n] = bs * 1.6817928305074290f + gv[bj][n] * acc[ai][bj][m][n]; } }
;                     if (tobf) *(u32x4*)(vout + off + bj * 32) = pack8(o[0], o[1]);
;                     else { *(f32x4*)(ob + off + bj * 32) = o[0]; *(f32x4*)(ob + off + bj * 32 + 4) = o[1]; } }
.LBB0_1475:
	s_andn2_b64 vcc, exec, s[30:31]
	s_cbranch_vccnz .LBB0_1477
	global_load_dwordx4 v[162:165], v[192:193], off offset:128
	global_load_dwordx4 v[174:177], v[192:193], off offset:144
	s_waitcnt vmcnt(1)
	v_pk_mul_f32 v[164:165], v[164:165], s[86:87] op_sel_hi:[1,0]
	v_pk_mul_f32 v[162:163], v[162:163], s[86:87] op_sel_hi:[1,0]
	v_pk_fma_f32 v[168:169], v[84:85], v[152:153], v[164:165]
	v_pk_fma_f32 v[166:167], v[82:83], v[150:151], v[162:163]
	s_waitcnt vmcnt(0)
.LBB0_1477:
	v_pk_mul_f32 v[162:163], v[176:177], s[86:87] op_sel_hi:[1,0]
	v_pk_mul_f32 v[170:171], v[174:175], s[86:87] op_sel_hi:[1,0]
	v_pk_fma_f32 v[164:165], v[76:77], v[148:149], v[162:163]
	v_pk_fma_f32 v[162:163], v[74:75], v[146:147], v[170:171]
	s_mov_b64 s[30:31], -1
	s_and_b64 vcc, exec, s[26:27]
	s_cbranch_vccz .LBB0_1479
	v_cvt_pk_bf16_f32 v170, v166, v167
	v_cvt_pk_bf16_f32 v171, v168, v169
	v_cvt_pk_bf16_f32 v172, v162, v163
	v_cvt_pk_bf16_f32 v173, v164, v165
	global_store_dwordx4 v[194:195], v[170:173], off offset:64
	s_mov_b64 s[30:31], 0

; __device__ __forceinline__ u32x4 pack8(const f32x4 a, const f32x4 b) { u32x4 w; w.x = cvt_pk_bf16(a[0], a[1]); w.y = cvt_pk_bf16(a[2], a[3]); w.z = cvt_pk_bf16(b[0], b[1]); w.w = cvt_pk_bf16(b[2], b[3]); return w; }
;     __device__ __forceinline__ void operator()(const f32x4 (&acc)[2][2][4][2], const Unit& u, int wr, int wc, int fr, int fq) const {
;     ...
;         for (int ai = 0; ai < 2; ++ai)
; #pragma unroll
;             for (int m = 0; m < 4; ++m) { const size_t off = (size_t)(rowb + ai * HALF + m * 16) * 1024 + col0;
; #pragma unroll
;                 for (int bj = 0; bj < 2; ++bj) { f32x4 o[2];
;                     if (lat && rinB) { const u32x4 w = *(const u32x4*)(rinB + off + bj * 32);
;                         const f32x4 b0 = {__builtin_bit_cast(float, w.x << 16), __builtin_bit_cast(float, w.x & 0xffff0000u), __builtin_bit_cast(float, w.y << 16), __builtin_bit_cast(float, w.y & 0xffff0000u)};
;                         const f32x4 b1 = {__builtin_bit_cast(float, w.z << 16), __builtin_bit_cast(float, w.z & 0xffff0000u), __builtin_bit_cast(float, w.w << 16), __builtin_bit_cast(float, w.w & 0xffff0000u)};
;                         o[0] = b0 * 1.6817928305074290f + gv[bj][0] * acc[ai][bj][m][0]; o[1] = b1 * 1.6817928305074290f + gv[bj][1] * acc[ai][bj][m][1]; }
;                     else {
; #pragma unroll
;                     for (int n = 0; n < 2; ++n) { const f32x4 bs = *(const f32x4*)(ib + off + bj * 32 + n * 4); o[n] = bs * 1.6817928305074290f + gv[bj][n] * acc[ai][bj][m][n]; } }
;                     if (tobf) *(u32x4*)(vout + off + bj * 32) = pack8(o[0], o[1]);
;                     else { *(f32x4*)(ob + off + bj * 32) = o[0]; *(f32x4*)(ob + off + bj * 32 + 4) = o[1]; } }
.LBB0_1481:
	s_nop 1
	v_or_b32_e32 v162, 48, v188
	v_ashrrev_i32_e32 v163, 31, v162
	v_lshlrev_b64 v[162:163], 10, v[162:163]
	v_lshl_add_u64 v[196:197], v[162:163], 0, v[190:191]
	s_mov_b64 s[30:31], -1
	s_and_b64 vcc, exec, s[34:35]
	s_cbranch_vccnz .LBB0_1483
	s_mov_b64 s[30:31], 0
	s_waitcnt vmcnt(12)
	v_lshlrev_b32_e32 v170, 16, v246
	v_and_b32_e32 v171, 0xffff0000, v246
	v_lshlrev_b32_e32 v162, 16, v247
	v_and_b32_e32 v163, 0xffff0000, v247
	v_pk_mul_f32 v[170:171], v[170:171], s[86:87] op_sel_hi:[1,0]
	v_pk_mul_f32 v[162:163], v[162:163], s[86:87] op_sel_hi:[1,0]
	v_lshlrev_b32_e32 v166, 16, v248
	v_and_b32_e32 v167, 0xffff0000, v248
	v_lshlrev_b32_e32 v168, 16, v249
	v_and_b32_e32 v169, 0xffff0000, v249
	v_pk_fma_f32 v[164:165], v[88:89], v[160:161], v[162:163]
	v_pk_fma_f32 v[162:163], v[86:87], v[158:159], v[170:171]
	v_add_u32_e32 v251, 0x50000, v250
	global_load_dwordx4 v[246:249], v251, s[92:93] offset:64
.LBB0_1483:
	s_andn2_b64 vcc, exec, s[30:31]
	v_lshl_add_u64 v[192:193], v[196:197], 2, s[28:29]
	s_cbranch_vccnz .LBB0_1485
	global_load_dwordx4 v[162:165], v[192:193], off
	global_load_dwordx4 v[166:169], v[192:193], off offset:16
	s_waitcnt vmcnt(1)
	v_pk_mul_f32 v[164:165], v[164:165], s[86:87] op_sel_hi:[1,0]
	v_pk_mul_f32 v[162:163], v[162:163], s[86:87] op_sel_hi:[1,0]
	v_pk_fma_f32 v[164:165], v[88:89], v[160:161], v[164:165]
	v_pk_fma_f32 v[162:163], v[86:87], v[158:159], v[162:163]
	s_waitcnt vmcnt(0)
.LBB0_1485:
	v_pk_mul_f32 v[168:169], v[168:169], s[86:87] op_sel_hi:[1,0]
	v_pk_mul_f32 v[166:167], v[166:167], s[86:87] op_sel_hi:[1,0]
	v_pk_fma_f32 v[172:173], v[80:81], v[156:157], v[168:169]
	v_pk_fma_f32 v[170:171], v[78:79], v[154:155], v[166:167]
	s_and_b64 vcc, exec, s[26:27]
	v_lshl_add_u64 v[194:195], v[196:197], 1, s[64:65]
	s_cbranch_vccz .LBB0_1489
	v_cvt_pk_bf16_f32 v166, v162, v163
	v_cvt_pk_bf16_f32 v167, v164, v165
	v_cvt_pk_bf16_f32 v168, v170, v171
	v_cvt_pk_bf16_f32 v169, v172, v173
	s_mov_b64 s[30:31], -1
	s_and_b64 vcc, exec, s[88:89]
	global_store_dwordx4 v[194:195], v[166:169], off
	s_cbranch_vccz .LBB0_1488
	s_nop 0
	s_mov_b64 s[30:31], 0
	s_waitcnt vmcnt(13)
	v_lshlrev_b32_e32 v196, 16, v208
	v_and_b32_e32 v197, 0xffff0000, v208
	v_lshlrev_b32_e32 v166, 16, v209
	v_and_b32_e32 v167, 0xffff0000, v209
	v_pk_mul_f32 v[196:197], v[196:197], s[86:87] op_sel_hi:[1,0]
	v_pk_mul_f32 v[166:167], v[166:167], s[86:87] op_sel_hi:[1,0]
	v_lshlrev_b32_e32 v174, 16, v210
	v_and_b32_e32 v175, 0xffff0000, v210
	v_lshlrev_b32_e32 v176, 16, v211
	v_and_b32_e32 v177, 0xffff0000, v211
	v_pk_fma_f32 v[168:169], v[72:73], v[152:153], v[166:167]
	v_pk_fma_f32 v[166:167], v[70:71], v[150:151], v[196:197]
	v_add_u32_e32 v251, 0x58000, v250
	global_load_dwordx4 v[208:211], v251, s[92:93]

; __device__ __forceinline__ u32x4 pack8(const f32x4 a, const f32x4 b) { u32x4 w; w.x = cvt_pk_bf16(a[0], a[1]); w.y = cvt_pk_bf16(a[2], a[3]); w.z = cvt_pk_bf16(b[0], b[1]); w.w = cvt_pk_bf16(b[2], b[3]); return w; }
;     __device__ __forceinline__ void operator()(const f32x4 (&acc)[2][2][4][2], const Unit& u, int wr, int wc, int fr, int fq) const {
;     ...
;                     else {
; #pragma unroll
;                     for (int n = 0; n < 2; ++n) { const f32x4 bs = *(const f32x4*)(ib + off + bj * 32 + n * 4); o[n] = bs * 1.6817928305074290f + gv[bj][n] * acc[ai][bj][m][n]; } }
;                     if (tobf) *(u32x4*)(vout + off + bj * 32) = pack8(o[0], o[1]);
;                     else { *(f32x4*)(ob + off + bj * 32) = o[0]; *(f32x4*)(ob + off + bj * 32 + 4) = o[1]; } }
.LBB0_1491:
	s_andn2_b64 vcc, exec, s[30:31]
	s_cbranch_vccnz .LBB0_1493
	global_load_dwordx4 v[162:165], v[192:193], off offset:128
	global_load_dwordx4 v[174:177], v[192:193], off offset:144
	s_waitcnt vmcnt(1)
	v_pk_mul_f32 v[164:165], v[164:165], s[86:87] op_sel_hi:[1,0]
	v_pk_mul_f32 v[162:163], v[162:163], s[86:87] op_sel_hi:[1,0]
	v_pk_fma_f32 v[168:169], v[72:73], v[152:153], v[164:165]
	v_pk_fma_f32 v[166:167], v[70:71], v[150:151], v[162:163]
	s_waitcnt vmcnt(0)
.LBB0_1493:
	v_pk_mul_f32 v[162:163], v[176:177], s[86:87] op_sel_hi:[1,0]
	v_pk_mul_f32 v[170:171], v[174:175], s[86:87] op_sel_hi:[1,0]
	v_pk_fma_f32 v[164:165], v[68:69], v[148:149], v[162:163]
	v_pk_fma_f32 v[162:163], v[66:67], v[146:147], v[170:171]
	s_mov_b64 s[30:31], -1
	s_and_b64 vcc, exec, s[26:27]
	s_cbranch_vccz .LBB0_1495
	v_cvt_pk_bf16_f32 v170, v166, v167
	v_cvt_pk_bf16_f32 v171, v168, v169
	v_cvt_pk_bf16_f32 v172, v162, v163
	v_cvt_pk_bf16_f32 v173, v164, v165
	global_store_dwordx4 v[194:195], v[170:173], off offset:64
	s_mov_b64 s[30:31], 0

; __device__ __forceinline__ u32x4 pack8(const f32x4 a, const f32x4 b) { u32x4 w; w.x = cvt_pk_bf16(a[0], a[1]); w.y = cvt_pk_bf16(a[2], a[3]); w.z = cvt_pk_bf16(b[0], b[1]); w.w = cvt_pk_bf16(b[2], b[3]); return w; }
;     __device__ __forceinline__ void operator()(const f32x4 (&acc)[2][2][4][2], const Unit& u, int wr, int wc, int fr, int fq) const {
;     ...
;         for (int ai = 0; ai < 2; ++ai)
; #pragma unroll
;             for (int m = 0; m < 4; ++m) { const size_t off = (size_t)(rowb + ai * HALF + m * 16) * 1024 + col0;
; #pragma unroll
;                 for (int bj = 0; bj < 2; ++bj) { f32x4 o[2];
;                     if (lat && rinB) { const u32x4 w = *(const u32x4*)(rinB + off + bj * 32);
;                         const f32x4 b0 = {__builtin_bit_cast(float, w.x << 16), __builtin_bit_cast(float, w.x & 0xffff0000u), __builtin_bit_cast(float, w.y << 16), __builtin_bit_cast(float, w.y & 0xffff0000u)};
;                         const f32x4 b1 = {__builtin_bit_cast(float, w.z << 16), __builtin_bit_cast(float, w.z & 0xffff0000u), __builtin_bit_cast(float, w.w << 16), __builtin_bit_cast(float, w.w & 0xffff0000u)};
;                         o[0] = b0 * 1.6817928305074290f + gv[bj][0] * acc[ai][bj][m][0]; o[1] = b1 * 1.6817928305074290f + gv[bj][1] * acc[ai][bj][m][1]; }
;                     else {
; #pragma unroll
;                     for (int n = 0; n < 2; ++n) { const f32x4 bs = *(const f32x4*)(ib + off + bj * 32 + n * 4); o[n] = bs * 1.6817928305074290f + gv[bj][n] * acc[ai][bj][m][n]; } }
;                     if (tobf) *(u32x4*)(vout + off + bj * 32) = pack8(o[0], o[1]);
;                     else { *(f32x4*)(ob + off + bj * 32) = o[0]; *(f32x4*)(ob + off + bj * 32 + 4) = o[1]; } }
.LBB0_1497:
	s_nop 1
	v_lshlrev_b64 v[162:163], 10, v[188:189]
	v_lshl_add_u64 v[162:163], v[162:163], 0, v[190:191]
	v_lshl_add_u64 v[196:197], v[162:163], 0, s[96:97]
	s_mov_b64 s[30:31], -1
	s_and_b64 vcc, exec, s[34:35]
	s_cbranch_vccnz .LBB0_1499
	s_mov_b64 s[30:31], 0
	s_waitcnt vmcnt(13)
	v_lshlrev_b32_e32 v170, 16, v226
	v_and_b32_e32 v171, 0xffff0000, v226
	v_lshlrev_b32_e32 v162, 16, v227
	v_and_b32_e32 v163, 0xffff0000, v227
	v_pk_mul_f32 v[170:171], v[170:171], s[86:87] op_sel_hi:[1,0]
	v_pk_mul_f32 v[162:163], v[162:163], s[86:87] op_sel_hi:[1,0]
	v_lshlrev_b32_e32 v166, 16, v228
	v_and_b32_e32 v167, 0xffff0000, v228
	v_lshlrev_b32_e32 v168, 16, v229
	v_and_b32_e32 v169, 0xffff0000, v229
	v_pk_fma_f32 v[164:165], v[64:65], v[160:161], v[162:163]
	v_pk_fma_f32 v[162:163], v[62:63], v[158:159], v[170:171]
	v_add_u32_e32 v251, 0x58000, v250
	global_load_dwordx4 v[226:229], v251, s[92:93] offset:64
.LBB0_1499:
	s_andn2_b64 vcc, exec, s[30:31]
	v_lshl_add_u64 v[192:193], v[196:197], 2, s[28:29]
	s_cbranch_vccnz .LBB0_1501
	global_load_dwordx4 v[162:165], v[192:193], off
	global_load_dwordx4 v[166:169], v[192:193], off offset:16
	s_waitcnt vmcnt(1)
	v_pk_mul_f32 v[164:165], v[164:165], s[86:87] op_sel_hi:[1,0]
	v_pk_mul_f32 v[162:163], v[162:163], s[86:87] op_sel_hi:[1,0]
	v_pk_fma_f32 v[164:165], v[64:65], v[160:161], v[164:165]
	v_pk_fma_f32 v[162:163], v[62:63], v[158:159], v[162:163]
	s_waitcnt vmcnt(0)
.LBB0_1501:
	v_pk_mul_f32 v[168:169], v[168:169], s[86:87] op_sel_hi:[1,0]
	v_pk_mul_f32 v[166:167], v[166:167], s[86:87] op_sel_hi:[1,0]
	v_pk_fma_f32 v[172:173], v[60:61], v[156:157], v[168:169]
	v_pk_fma_f32 v[170:171], v[58:59], v[154:155], v[166:167]
	s_and_b64 vcc, exec, s[26:27]
	v_lshl_add_u64 v[194:195], v[196:197], 1, s[64:65]
	s_cbranch_vccz .LBB0_1505
	v_cvt_pk_bf16_f32 v166, v162, v163
	v_cvt_pk_bf16_f32 v167, v164, v165
	v_cvt_pk_bf16_f32 v168, v170, v171
	v_cvt_pk_bf16_f32 v169, v172, v173
	s_mov_b64 s[30:31], -1
	s_and_b64 vcc, exec, s[88:89]
	global_store_dwordx4 v[194:195], v[166:169], off
	s_cbranch_vccz .LBB0_1504
	s_nop 0
	s_mov_b64 s[30:31], 0
	s_waitcnt vmcnt(13)
	v_lshlrev_b32_e32 v196, 16, v230
	v_and_b32_e32 v197, 0xffff0000, v230
	v_lshlrev_b32_e32 v166, 16, v231
	v_and_b32_e32 v167, 0xffff0000, v231
	v_pk_mul_f32 v[196:197], v[196:197], s[86:87] op_sel_hi:[1,0]
	v_pk_mul_f32 v[166:167], v[166:167], s[86:87] op_sel_hi:[1,0]
	v_lshlrev_b32_e32 v174, 16, v232
	v_and_b32_e32 v175, 0xffff0000, v232
	v_lshlrev_b32_e32 v176, 16, v233
	v_and_b32_e32 v177, 0xffff0000, v233
	v_pk_fma_f32 v[168:169], v[52:53], v[152:153], v[166:167]
	v_pk_fma_f32 v[166:167], v[50:51], v[150:151], v[196:197]

; __device__ __forceinline__ u32x4 pack8(const f32x4 a, const f32x4 b) { u32x4 w; w.x = cvt_pk_bf16(a[0], a[1]); w.y = cvt_pk_bf16(a[2], a[3]); w.z = cvt_pk_bf16(b[0], b[1]); w.w = cvt_pk_bf16(b[2], b[3]); return w; }
;     __device__ __forceinline__ void operator()(const f32x4 (&acc)[2][2][4][2], const Unit& u, int wr, int wc, int fr, int fq) const {
;     ...
;                     else {
; #pragma unroll
;                     for (int n = 0; n < 2; ++n) { const f32x4 bs = *(const f32x4*)(ib + off + bj * 32 + n * 4); o[n] = bs * 1.6817928305074290f + gv[bj][n] * acc[ai][bj][m][n]; } }
;                     if (tobf) *(u32x4*)(vout + off + bj * 32) = pack8(o[0], o[1]);
;                     else { *(f32x4*)(ob + off + bj * 32) = o[0]; *(f32x4*)(ob + off + bj * 32 + 4) = o[1]; } }
.LBB0_1507:
	s_andn2_b64 vcc, exec, s[30:31]
	s_cbranch_vccnz .LBB0_1509
	global_load_dwordx4 v[162:165], v[192:193], off offset:128
	global_load_dwordx4 v[174:177], v[192:193], off offset:144
	s_waitcnt vmcnt(1)
	v_pk_mul_f32 v[164:165], v[164:165], s[86:87] op_sel_hi:[1,0]
	v_pk_mul_f32 v[162:163], v[162:163], s[86:87] op_sel_hi:[1,0]
	v_pk_fma_f32 v[168:169], v[52:53], v[152:153], v[164:165]
	v_pk_fma_f32 v[166:167], v[50:51], v[150:151], v[162:163]
	s_waitcnt vmcnt(0)
.LBB0_1509:
	v_pk_mul_f32 v[162:163], v[176:177], s[86:87] op_sel_hi:[1,0]
	v_pk_mul_f32 v[170:171], v[174:175], s[86:87] op_sel_hi:[1,0]
	v_pk_fma_f32 v[164:165], v[44:45], v[148:149], v[162:163]
	v_pk_fma_f32 v[162:163], v[42:43], v[146:147], v[170:171]
	s_mov_b64 s[30:31], -1
	s_and_b64 vcc, exec, s[26:27]
	s_cbranch_vccz .LBB0_1511
	v_cvt_pk_bf16_f32 v170, v166, v167
	v_cvt_pk_bf16_f32 v171, v168, v169
	v_cvt_pk_bf16_f32 v172, v162, v163
	v_cvt_pk_bf16_f32 v173, v164, v165
	global_store_dwordx4 v[194:195], v[170:173], off offset:64
	s_mov_b64 s[30:31], 0

; __device__ __forceinline__ u32x4 pack8(const f32x4 a, const f32x4 b) { u32x4 w; w.x = cvt_pk_bf16(a[0], a[1]); w.y = cvt_pk_bf16(a[2], a[3]); w.z = cvt_pk_bf16(b[0], b[1]); w.w = cvt_pk_bf16(b[2], b[3]); return w; }
;     __device__ __forceinline__ void operator()(const f32x4 (&acc)[2][2][4][2], const Unit& u, int wr, int wc, int fr, int fq) const {
;     ...
;         for (int ai = 0; ai < 2; ++ai)
; #pragma unroll
;             for (int m = 0; m < 4; ++m) { const size_t off = (size_t)(rowb + ai * HALF + m * 16) * 1024 + col0;
; #pragma unroll
;                 for (int bj = 0; bj < 2; ++bj) { f32x4 o[2];
;                     if (lat && rinB) { const u32x4 w = *(const u32x4*)(rinB + off + bj * 32);
;                         const f32x4 b0 = {__builtin_bit_cast(float, w.x << 16), __builtin_bit_cast(float, w.x & 0xffff0000u), __builtin_bit_cast(float, w.y << 16), __builtin_bit_cast(float, w.y & 0xffff0000u)};
;                         const f32x4 b1 = {__builtin_bit_cast(float, w.z << 16), __builtin_bit_cast(float, w.z & 0xffff0000u), __builtin_bit_cast(float, w.w << 16), __builtin_bit_cast(float, w.w & 0xffff0000u)};
;                         o[0] = b0 * 1.6817928305074290f + gv[bj][0] * acc[ai][bj][m][0]; o[1] = b1 * 1.6817928305074290f + gv[bj][1] * acc[ai][bj][m][1]; }
;                     else {
; #pragma unroll
;                     for (int n = 0; n < 2; ++n) { const f32x4 bs = *(const f32x4*)(ib + off + bj * 32 + n * 4); o[n] = bs * 1.6817928305074290f + gv[bj][n] * acc[ai][bj][m][n]; } }
;                     if (tobf) *(u32x4*)(vout + off + bj * 32) = pack8(o[0], o[1]);
;                     else { *(f32x4*)(ob + off + bj * 32) = o[0]; *(f32x4*)(ob + off + bj * 32 + 4) = o[1]; } }
.LBB0_1513:
	s_nop 1
	v_lshlrev_b64 v[162:163], 10, v[188:189]
	v_lshl_add_u64 v[162:163], v[162:163], 0, v[190:191]
	s_mov_b64 s[2:3], 0x24000
	v_lshl_add_u64 v[196:197], v[162:163], 0, s[2:3]
	s_mov_b64 s[30:31], -1
	s_and_b64 vcc, exec, s[34:35]
	s_cbranch_vccnz .LBB0_1515
	s_mov_b64 s[30:31], 0
	s_waitcnt vmcnt(12)
	v_lshlrev_b32_e32 v170, 16, v234
	v_and_b32_e32 v171, 0xffff0000, v234
	v_lshlrev_b32_e32 v162, 16, v235
	v_and_b32_e32 v163, 0xffff0000, v235
	v_pk_mul_f32 v[170:171], v[170:171], s[86:87] op_sel_hi:[1,0]
	v_pk_mul_f32 v[162:163], v[162:163], s[86:87] op_sel_hi:[1,0]
	v_lshlrev_b32_e32 v166, 16, v236
	v_and_b32_e32 v167, 0xffff0000, v236
	v_lshlrev_b32_e32 v168, 16, v237
	v_and_b32_e32 v169, 0xffff0000, v237
	v_pk_fma_f32 v[164:165], v[56:57], v[160:161], v[162:163]
	v_pk_fma_f32 v[162:163], v[54:55], v[158:159], v[170:171]
.LBB0_1515:
	s_andn2_b64 vcc, exec, s[30:31]
	v_lshl_add_u64 v[192:193], v[196:197], 2, s[28:29]
	s_cbranch_vccnz .LBB0_1517
	global_load_dwordx4 v[162:165], v[192:193], off
	global_load_dwordx4 v[166:169], v[192:193], off offset:16
	s_waitcnt vmcnt(1)
	v_pk_mul_f32 v[164:165], v[164:165], s[86:87] op_sel_hi:[1,0]
	v_pk_mul_f32 v[162:163], v[162:163], s[86:87] op_sel_hi:[1,0]
	v_pk_fma_f32 v[164:165], v[56:57], v[160:161], v[164:165]
	v_pk_fma_f32 v[162:163], v[54:55], v[158:159], v[162:163]
	s_waitcnt vmcnt(0)
.LBB0_1517:
	v_pk_mul_f32 v[168:169], v[168:169], s[86:87] op_sel_hi:[1,0]
	v_pk_mul_f32 v[166:167], v[166:167], s[86:87] op_sel_hi:[1,0]
	v_pk_fma_f32 v[172:173], v[48:49], v[156:157], v[168:169]
	v_pk_fma_f32 v[170:171], v[46:47], v[154:155], v[166:167]
	s_and_b64 vcc, exec, s[26:27]
	v_lshl_add_u64 v[194:195], v[196:197], 1, s[64:65]
	s_cbranch_vccz .LBB0_1521
	v_cvt_pk_bf16_f32 v166, v162, v163
	v_cvt_pk_bf16_f32 v167, v164, v165
	v_cvt_pk_bf16_f32 v168, v170, v171
	v_cvt_pk_bf16_f32 v169, v172, v173
	s_mov_b64 s[30:31], -1
	s_and_b64 vcc, exec, s[88:89]
	global_store_dwordx4 v[194:195], v[166:169], off
	s_cbranch_vccz .LBB0_1520
	s_nop 0
	s_mov_b64 s[30:31], 0
	s_waitcnt vmcnt(11)
	v_lshlrev_b32_e32 v196, 16, v238
	v_and_b32_e32 v197, 0xffff0000, v238
	v_lshlrev_b32_e32 v166, 16, v239
	v_and_b32_e32 v167, 0xffff0000, v239
	v_pk_mul_f32 v[196:197], v[196:197], s[86:87] op_sel_hi:[1,0]
	v_pk_mul_f32 v[166:167], v[166:167], s[86:87] op_sel_hi:[1,0]
	v_lshlrev_b32_e32 v174, 16, v240
	v_and_b32_e32 v175, 0xffff0000, v240
	v_lshlrev_b32_e32 v176, 16, v241
	v_and_b32_e32 v177, 0xffff0000, v241
	v_pk_fma_f32 v[168:169], v[36:37], v[152:153], v[166:167]
	v_pk_fma_f32 v[166:167], v[34:35], v[150:151], v[196:197]

; __device__ __forceinline__ u32x4 pack8(const f32x4 a, const f32x4 b) { u32x4 w; w.x = cvt_pk_bf16(a[0], a[1]); w.y = cvt_pk_bf16(a[2], a[3]); w.z = cvt_pk_bf16(b[0], b[1]); w.w = cvt_pk_bf16(b[2], b[3]); return w; }
;     __device__ __forceinline__ void operator()(const f32x4 (&acc)[2][2][4][2], const Unit& u, int wr, int wc, int fr, int fq) const {
;     ...
;                     else {
; #pragma unroll
;                     for (int n = 0; n < 2; ++n) { const f32x4 bs = *(const f32x4*)(ib + off + bj * 32 + n * 4); o[n] = bs * 1.6817928305074290f + gv[bj][n] * acc[ai][bj][m][n]; } }
;                     if (tobf) *(u32x4*)(vout + off + bj * 32) = pack8(o[0], o[1]);
;                     else { *(f32x4*)(ob + off + bj * 32) = o[0]; *(f32x4*)(ob + off + bj * 32 + 4) = o[1]; } }
.LBB0_1523:
	s_andn2_b64 vcc, exec, s[30:31]
	s_cbranch_vccnz .LBB0_1525
	global_load_dwordx4 v[162:165], v[192:193], off offset:128
	global_load_dwordx4 v[174:177], v[192:193], off offset:144
	s_waitcnt vmcnt(1)
	v_pk_mul_f32 v[164:165], v[164:165], s[86:87] op_sel_hi:[1,0]
	v_pk_mul_f32 v[162:163], v[162:163], s[86:87] op_sel_hi:[1,0]
	v_pk_fma_f32 v[168:169], v[36:37], v[152:153], v[164:165]
	v_pk_fma_f32 v[166:167], v[34:35], v[150:151], v[162:163]
	s_waitcnt vmcnt(0)
.LBB0_1525:
	v_pk_mul_f32 v[162:163], v[176:177], s[86:87] op_sel_hi:[1,0]
	v_pk_mul_f32 v[170:171], v[174:175], s[86:87] op_sel_hi:[1,0]
	v_pk_fma_f32 v[164:165], v[28:29], v[148:149], v[162:163]
	v_pk_fma_f32 v[162:163], v[26:27], v[146:147], v[170:171]
	s_mov_b64 s[30:31], -1
	s_and_b64 vcc, exec, s[26:27]
	s_cbranch_vccz .LBB0_1527
	v_cvt_pk_bf16_f32 v170, v166, v167
	v_cvt_pk_bf16_f32 v171, v168, v169
	v_cvt_pk_bf16_f32 v172, v162, v163
	v_cvt_pk_bf16_f32 v173, v164, v165
	global_store_dwordx4 v[194:195], v[170:173], off offset:64
	s_mov_b64 s[30:31], 0

; __device__ __forceinline__ u32x4 pack8(const f32x4 a, const f32x4 b) { u32x4 w; w.x = cvt_pk_bf16(a[0], a[1]); w.y = cvt_pk_bf16(a[2], a[3]); w.z = cvt_pk_bf16(b[0], b[1]); w.w = cvt_pk_bf16(b[2], b[3]); return w; }
;     __device__ __forceinline__ void operator()(const f32x4 (&acc)[2][2][4][2], const Unit& u, int wr, int wc, int fr, int fq) const {
;     ...
;         for (int ai = 0; ai < 2; ++ai)
; #pragma unroll
;             for (int m = 0; m < 4; ++m) { const size_t off = (size_t)(rowb + ai * HALF + m * 16) * 1024 + col0;
; #pragma unroll
;                 for (int bj = 0; bj < 2; ++bj) { f32x4 o[2];
;                     if (lat && rinB) { const u32x4 w = *(const u32x4*)(rinB + off + bj * 32);
;                         const f32x4 b0 = {__builtin_bit_cast(float, w.x << 16), __builtin_bit_cast(float, w.x & 0xffff0000u), __builtin_bit_cast(float, w.y << 16), __builtin_bit_cast(float, w.y & 0xffff0000u)};
;                         const f32x4 b1 = {__builtin_bit_cast(float, w.z << 16), __builtin_bit_cast(float, w.z & 0xffff0000u), __builtin_bit_cast(float, w.w << 16), __builtin_bit_cast(float, w.w & 0xffff0000u)};
;                         o[0] = b0 * 1.6817928305074290f + gv[bj][0] * acc[ai][bj][m][0]; o[1] = b1 * 1.6817928305074290f + gv[bj][1] * acc[ai][bj][m][1]; }
;                     else {
; #pragma unroll
;                     for (int n = 0; n < 2; ++n) { const f32x4 bs = *(const f32x4*)(ib + off + bj * 32 + n * 4); o[n] = bs * 1.6817928305074290f + gv[bj][n] * acc[ai][bj][m][n]; } }
;                     if (tobf) *(u32x4*)(vout + off + bj * 32) = pack8(o[0], o[1]);
;                     else { *(f32x4*)(ob + off + bj * 32) = o[0]; *(f32x4*)(ob + off + bj * 32 + 4) = o[1]; } }
.LBB0_1529:
	s_nop 1
	v_lshlrev_b64 v[162:163], 10, v[188:189]
	v_lshl_add_u64 v[162:163], v[162:163], 0, v[190:191]
	s_mov_b64 s[2:3], 0x28000
	v_lshl_add_u64 v[196:197], v[162:163], 0, s[2:3]
	s_mov_b64 s[30:31], -1
	s_and_b64 vcc, exec, s[34:35]
	s_cbranch_vccnz .LBB0_1531
	s_mov_b64 s[30:31], 0
	s_waitcnt vmcnt(10)
	v_lshlrev_b32_e32 v170, 16, v242
	v_and_b32_e32 v171, 0xffff0000, v242
	v_lshlrev_b32_e32 v162, 16, v243
	v_and_b32_e32 v163, 0xffff0000, v243
	v_pk_mul_f32 v[170:171], v[170:171], s[86:87] op_sel_hi:[1,0]
	v_pk_mul_f32 v[162:163], v[162:163], s[86:87] op_sel_hi:[1,0]
	v_lshlrev_b32_e32 v166, 16, v244
	v_and_b32_e32 v167, 0xffff0000, v244
	v_lshlrev_b32_e32 v168, 16, v245
	v_and_b32_e32 v169, 0xffff0000, v245
	v_pk_fma_f32 v[164:165], v[40:41], v[160:161], v[162:163]
	v_pk_fma_f32 v[162:163], v[38:39], v[158:159], v[170:171]
.LBB0_1531:
	s_andn2_b64 vcc, exec, s[30:31]
	v_lshl_add_u64 v[192:193], v[196:197], 2, s[28:29]
	s_cbranch_vccnz .LBB0_1533
	global_load_dwordx4 v[162:165], v[192:193], off
	global_load_dwordx4 v[166:169], v[192:193], off offset:16
	s_waitcnt vmcnt(1)
	v_pk_mul_f32 v[164:165], v[164:165], s[86:87] op_sel_hi:[1,0]
	v_pk_mul_f32 v[162:163], v[162:163], s[86:87] op_sel_hi:[1,0]
	v_pk_fma_f32 v[164:165], v[40:41], v[160:161], v[164:165]
	v_pk_fma_f32 v[162:163], v[38:39], v[158:159], v[162:163]
	s_waitcnt vmcnt(0)
.LBB0_1533:
	v_pk_mul_f32 v[168:169], v[168:169], s[86:87] op_sel_hi:[1,0]
	v_pk_mul_f32 v[166:167], v[166:167], s[86:87] op_sel_hi:[1,0]
	v_pk_fma_f32 v[172:173], v[32:33], v[156:157], v[168:169]
	v_pk_fma_f32 v[170:171], v[30:31], v[154:155], v[166:167]
	s_and_b64 vcc, exec, s[26:27]
	v_lshl_add_u64 v[194:195], v[196:197], 1, s[64:65]
	s_cbranch_vccz .LBB0_1537
	v_cvt_pk_bf16_f32 v166, v162, v163
	v_cvt_pk_bf16_f32 v167, v164, v165
	v_cvt_pk_bf16_f32 v168, v170, v171
	v_cvt_pk_bf16_f32 v169, v172, v173
	s_mov_b64 s[30:31], -1
	s_and_b64 vcc, exec, s[88:89]
	global_store_dwordx4 v[194:195], v[166:169], off
	s_cbranch_vccz .LBB0_1536
	s_nop 0
	s_mov_b64 s[30:31], 0
	s_waitcnt vmcnt(9)
	v_lshlrev_b32_e32 v196, 16, v246
	v_and_b32_e32 v197, 0xffff0000, v246
	v_lshlrev_b32_e32 v166, 16, v247
	v_and_b32_e32 v167, 0xffff0000, v247
	v_pk_mul_f32 v[196:197], v[196:197], s[86:87] op_sel_hi:[1,0]
	v_pk_mul_f32 v[166:167], v[166:167], s[86:87] op_sel_hi:[1,0]
	v_lshlrev_b32_e32 v174, 16, v248
	v_and_b32_e32 v175, 0xffff0000, v248
	v_lshlrev_b32_e32 v176, 16, v249
	v_and_b32_e32 v177, 0xffff0000, v249
	v_pk_fma_f32 v[168:169], v[20:21], v[152:153], v[166:167]
	v_pk_fma_f32 v[166:167], v[18:19], v[150:151], v[196:197]

; __device__ __forceinline__ u32x4 pack8(const f32x4 a, const f32x4 b) { u32x4 w; w.x = cvt_pk_bf16(a[0], a[1]); w.y = cvt_pk_bf16(a[2], a[3]); w.z = cvt_pk_bf16(b[0], b[1]); w.w = cvt_pk_bf16(b[2], b[3]); return w; }
;     __device__ __forceinline__ void operator()(const f32x4 (&acc)[2][2][4][2], const Unit& u, int wr, int wc, int fr, int fq) const {
;     ...
;                     else {
; #pragma unroll
;                     for (int n = 0; n < 2; ++n) { const f32x4 bs = *(const f32x4*)(ib + off + bj * 32 + n * 4); o[n] = bs * 1.6817928305074290f + gv[bj][n] * acc[ai][bj][m][n]; } }
;                     if (tobf) *(u32x4*)(vout + off + bj * 32) = pack8(o[0], o[1]);
;                     else { *(f32x4*)(ob + off + bj * 32) = o[0]; *(f32x4*)(ob + off + bj * 32 + 4) = o[1]; } }
.LBB0_1539:
	s_andn2_b64 vcc, exec, s[30:31]
	s_cbranch_vccnz .LBB0_1541
	global_load_dwordx4 v[162:165], v[192:193], off offset:128
	global_load_dwordx4 v[174:177], v[192:193], off offset:144
	s_waitcnt vmcnt(1)
	v_pk_mul_f32 v[164:165], v[164:165], s[86:87] op_sel_hi:[1,0]
	v_pk_mul_f32 v[162:163], v[162:163], s[86:87] op_sel_hi:[1,0]
	v_pk_fma_f32 v[168:169], v[20:21], v[152:153], v[164:165]
	v_pk_fma_f32 v[166:167], v[18:19], v[150:151], v[162:163]
	s_waitcnt vmcnt(0)
.LBB0_1541:
	v_pk_mul_f32 v[162:163], v[176:177], s[86:87] op_sel_hi:[1,0]
	v_pk_mul_f32 v[170:171], v[174:175], s[86:87] op_sel_hi:[1,0]
	v_pk_fma_f32 v[164:165], v[12:13], v[148:149], v[162:163]
	v_pk_fma_f32 v[162:163], v[10:11], v[146:147], v[170:171]
	s_mov_b64 s[30:31], -1
	s_and_b64 vcc, exec, s[26:27]
	s_cbranch_vccz .LBB0_1543
	v_cvt_pk_bf16_f32 v170, v166, v167
	v_cvt_pk_bf16_f32 v171, v168, v169
	v_cvt_pk_bf16_f32 v172, v162, v163
	v_cvt_pk_bf16_f32 v173, v164, v165
	global_store_dwordx4 v[194:195], v[170:173], off offset:64
	s_mov_b64 s[30:31], 0

; __device__ __forceinline__ u32x4 pack8(const f32x4 a, const f32x4 b) { u32x4 w; w.x = cvt_pk_bf16(a[0], a[1]); w.y = cvt_pk_bf16(a[2], a[3]); w.z = cvt_pk_bf16(b[0], b[1]); w.w = cvt_pk_bf16(b[2], b[3]); return w; }
;     __device__ __forceinline__ void operator()(const f32x4 (&acc)[2][2][4][2], const Unit& u, int wr, int wc, int fr, int fq) const {
;     ...
;         for (int ai = 0; ai < 2; ++ai)
; #pragma unroll
;             for (int m = 0; m < 4; ++m) { const size_t off = (size_t)(rowb + ai * HALF + m * 16) * 1024 + col0;
; #pragma unroll
;                 for (int bj = 0; bj < 2; ++bj) { f32x4 o[2];
;                     if (lat && rinB) { const u32x4 w = *(const u32x4*)(rinB + off + bj * 32);
;                         const f32x4 b0 = {__builtin_bit_cast(float, w.x << 16), __builtin_bit_cast(float, w.x & 0xffff0000u), __builtin_bit_cast(float, w.y << 16), __builtin_bit_cast(float, w.y & 0xffff0000u)};
;                         const f32x4 b1 = {__builtin_bit_cast(float, w.z << 16), __builtin_bit_cast(float, w.z & 0xffff0000u), __builtin_bit_cast(float, w.w << 16), __builtin_bit_cast(float, w.w & 0xffff0000u)};
;                         o[0] = b0 * 1.6817928305074290f + gv[bj][0] * acc[ai][bj][m][0]; o[1] = b1 * 1.6817928305074290f + gv[bj][1] * acc[ai][bj][m][1]; }
;                     else {
; #pragma unroll
;                     for (int n = 0; n < 2; ++n) { const f32x4 bs = *(const f32x4*)(ib + off + bj * 32 + n * 4); o[n] = bs * 1.6817928305074290f + gv[bj][n] * acc[ai][bj][m][n]; } }
;                     if (tobf) *(u32x4*)(vout + off + bj * 32) = pack8(o[0], o[1]);
;                     else { *(f32x4*)(ob + off + bj * 32) = o[0]; *(f32x4*)(ob + off + bj * 32 + 4) = o[1]; } }
.LBB0_1545:
	s_nop 1
	v_lshlrev_b64 v[162:163], 10, v[188:189]
	v_lshl_add_u64 v[162:163], v[162:163], 0, v[190:191]
	s_mov_b64 s[2:3], 0x2c000
	v_lshl_add_u64 v[174:175], v[162:163], 0, s[2:3]
	s_mov_b64 s[30:31], -1
	s_and_b64 vcc, exec, s[34:35]
	s_cbranch_vccnz .LBB0_1547
	s_mov_b64 s[30:31], 0
	s_waitcnt vmcnt(8)
	v_lshlrev_b32_e32 v170, 16, v208
	v_and_b32_e32 v171, 0xffff0000, v208
	v_lshlrev_b32_e32 v162, 16, v209
	v_and_b32_e32 v163, 0xffff0000, v209
	v_pk_mul_f32 v[170:171], v[170:171], s[86:87] op_sel_hi:[1,0]
	v_pk_mul_f32 v[162:163], v[162:163], s[86:87] op_sel_hi:[1,0]
	v_lshlrev_b32_e32 v166, 16, v210
	v_and_b32_e32 v167, 0xffff0000, v210
	v_lshlrev_b32_e32 v168, 16, v211
	v_and_b32_e32 v169, 0xffff0000, v211
	v_pk_fma_f32 v[164:165], v[24:25], v[160:161], v[162:163]
	v_pk_fma_f32 v[162:163], v[22:23], v[158:159], v[170:171]
.LBB0_1547:
	s_andn2_b64 vcc, exec, s[30:31]
	v_lshl_add_u64 v[170:171], v[174:175], 2, s[28:29]
	s_cbranch_vccnz .LBB0_1549
	global_load_dwordx4 v[162:165], v[170:171], off
	global_load_dwordx4 v[166:169], v[170:171], off offset:16
	s_waitcnt vmcnt(1)
	v_pk_mul_f32 v[164:165], v[164:165], s[86:87] op_sel_hi:[1,0]
	v_pk_mul_f32 v[162:163], v[162:163], s[86:87] op_sel_hi:[1,0]
	v_pk_fma_f32 v[164:165], v[24:25], v[160:161], v[164:165]
	v_pk_fma_f32 v[162:163], v[22:23], v[158:159], v[162:163]
	s_waitcnt vmcnt(0)
.LBB0_1549:
	v_pk_mul_f32 v[158:159], v[168:169], s[86:87] op_sel_hi:[1,0]
	v_pk_mul_f32 v[166:167], v[166:167], s[86:87] op_sel_hi:[1,0]
	v_pk_fma_f32 v[160:161], v[16:17], v[156:157], v[158:159]
	v_pk_fma_f32 v[158:159], v[14:15], v[154:155], v[166:167]
	s_and_b64 vcc, exec, s[26:27]
	v_lshl_add_u64 v[172:173], v[174:175], 1, s[64:65]
	s_cbranch_vccz .LBB0_1553
	v_cvt_pk_bf16_f32 v154, v162, v163
	v_cvt_pk_bf16_f32 v155, v164, v165
	v_cvt_pk_bf16_f32 v156, v158, v159
	v_cvt_pk_bf16_f32 v157, v160, v161
	s_mov_b64 s[28:29], -1
	s_and_b64 vcc, exec, s[88:89]
	global_store_dwordx4 v[172:173], v[154:157], off
	s_cbranch_vccz .LBB0_1552
	s_nop 0
	s_mov_b64 s[28:29], 0
	s_waitcnt vmcnt(7)
	v_lshlrev_b32_e32 v174, 16, v226
	v_and_b32_e32 v175, 0xffff0000, v226
	v_lshlrev_b32_e32 v154, 16, v227
	v_and_b32_e32 v155, 0xffff0000, v227
	v_pk_mul_f32 v[174:175], v[174:175], s[86:87] op_sel_hi:[1,0]
	v_pk_mul_f32 v[154:155], v[154:155], s[86:87] op_sel_hi:[1,0]
	v_lshlrev_b32_e32 v166, 16, v228
	v_and_b32_e32 v167, 0xffff0000, v228
	v_lshlrev_b32_e32 v168, 16, v229
	v_and_b32_e32 v169, 0xffff0000, v229
	v_pk_fma_f32 v[156:157], v[8:9], v[152:153], v[154:155]
	v_pk_fma_f32 v[154:155], v[6:7], v[150:151], v[174:175]

; __device__ __forceinline__ u32x4 pack8(const f32x4 a, const f32x4 b) { u32x4 w; w.x = cvt_pk_bf16(a[0], a[1]); w.y = cvt_pk_bf16(a[2], a[3]); w.z = cvt_pk_bf16(b[0], b[1]); w.w = cvt_pk_bf16(b[2], b[3]); return w; }
;     __device__ __forceinline__ void operator()(const f32x4 (&acc)[2][2][4][2], const Unit& u, int wr, int wc, int fr, int fq) const {
;     ...
;                     else {
; #pragma unroll
;                     for (int n = 0; n < 2; ++n) { const f32x4 bs = *(const f32x4*)(ib + off + bj * 32 + n * 4); o[n] = bs * 1.6817928305074290f + gv[bj][n] * acc[ai][bj][m][n]; } }
;                     if (tobf) *(u32x4*)(vout + off + bj * 32) = pack8(o[0], o[1]);
;                     else { *(f32x4*)(ob + off + bj * 32) = o[0]; *(f32x4*)(ob + off + bj * 32 + 4) = o[1]; } }
.LBB0_1555:
	s_andn2_b64 vcc, exec, s[28:29]
	s_cbranch_vccnz .LBB0_1557
	global_load_dwordx4 v[154:157], v[170:171], off offset:128
	global_load_dwordx4 v[166:169], v[170:171], off offset:144
	s_waitcnt vmcnt(1)
	v_pk_mul_f32 v[156:157], v[156:157], s[86:87] op_sel_hi:[1,0]
	v_pk_mul_f32 v[154:155], v[154:155], s[86:87] op_sel_hi:[1,0]
	v_pk_fma_f32 v[156:157], v[8:9], v[152:153], v[156:157]
	v_pk_fma_f32 v[154:155], v[6:7], v[150:151], v[154:155]
	s_waitcnt vmcnt(0)
.LBB0_1557:
	v_pk_mul_f32 v[150:151], v[168:169], s[86:87] op_sel_hi:[1,0]
	v_pk_mul_f32 v[152:153], v[166:167], s[86:87] op_sel_hi:[1,0]
	v_pk_fma_f32 v[148:149], v[4:5], v[148:149], v[150:151]
	v_pk_fma_f32 v[146:147], v[2:3], v[146:147], v[152:153]
	s_mov_b64 s[28:29], -1
	s_and_b64 vcc, exec, s[26:27]
	s_cbranch_vccz .LBB0_1559
	v_cvt_pk_bf16_f32 v150, v154, v155
	v_cvt_pk_bf16_f32 v151, v156, v157
	v_cvt_pk_bf16_f32 v152, v146, v147
	v_cvt_pk_bf16_f32 v153, v148, v149
	global_store_dwordx4 v[172:173], v[150:153], off offset:64
	s_mov_b64 s[28:29], 0

; __device__ __forceinline__ u32x4 pack8(const f32x4 a, const f32x4 b) { u32x4 w; w.x = cvt_pk_bf16(a[0], a[1]); w.y = cvt_pk_bf16(a[2], a[3]); w.z = cvt_pk_bf16(b[0], b[1]); w.w = cvt_pk_bf16(b[2], b[3]); return w; }
;     __device__ __forceinline__ void operator()(const f32x4 (&acc)[2][2][4][2], const Unit& u, int wr, int wc, int fr, int fq) const {
;     ...
;         const float* gp = gate + (size_t)bb * 6144 + col0;
;         f32x4 gv[2][2];
; #pragma unroll
;         for (int bj = 0; bj < 2; ++bj)
; #pragma unroll
;             for (int n = 0; n < 2; ++n) gv[bj][n] = *(const f32x4*)(gp + bj * 32 + n * 4);
;         const float* ib = lat ? rinL : rinC - (size_t)32768 * 1024; float* ob = lat ? routL : routC - (size_t)32768 * 1024;
;         const bool tobf = lat && vout != nullptr;
; #pragma unroll
;         for (int ai = 0; ai < 2; ++ai)
; #pragma unroll
;             for (int m = 0; m < 4; ++m) { const size_t off = (size_t)(rowb + ai * HALF + m * 16) * 1024 + col0;
; #pragma unroll
;                 for (int bj = 0; bj < 2; ++bj) { f32x4 o[2];
;                     if (lat && rinB) { const u32x4 w = *(const u32x4*)(rinB + off + bj * 32);
;                         const f32x4 b0 = {__builtin_bit_cast(float, w.x << 16), __builtin_bit_cast(float, w.x & 0xffff0000u), __builtin_bit_cast(float, w.y << 16), __builtin_bit_cast(float, w.y & 0xffff0000u)};
;                         const f32x4 b1 = {__builtin_bit_cast(float, w.z << 16), __builtin_bit_cast(float, w.z & 0xffff0000u), __builtin_bit_cast(float, w.w << 16), __builtin_bit_cast(float, w.w & 0xffff0000u)};
;                         o[0] = b0 * 1.6817928305074290f + gv[bj][0] * acc[ai][bj][m][0]; o[1] = b1 * 1.6817928305074290f + gv[bj][1] * acc[ai][bj][m][1]; }
;                     else {
; #pragma unroll
;                     for (int n = 0; n < 2; ++n) { const f32x4 bs = *(const f32x4*)(ib + off + bj * 32 + n * 4); o[n] = bs * 1.6817928305074290f + gv[bj][n] * acc[ai][bj][m][n]; } }
;                     if (tobf) *(u32x4*)(vout + off + bj * 32) = pack8(o[0], o[1]);
;                     else { *(f32x4*)(ob + off + bj * 32) = o[0]; *(f32x4*)(ob + off + bj * 32 + 4) = o[1]; } }
.LBB0_1586:
	s_lshl_b64 s[30:31], s[30:31], 2
	v_lshl_or_b32 v182, s48, 8, v192
	s_add_u32 s30, s40, s30
	s_addc_u32 s31, s41, s31
	v_ashrrev_i32_e32 v183, 31, v182
	v_lshl_add_u64 v[54:55], v[182:183], 2, s[30:31]
	global_load_dwordx4 v[66:69], v[54:55], off offset:16
	global_load_dwordx4 v[70:73], v[54:55], off
	global_load_dwordx4 v[50:53], v[54:55], off offset:144
	s_nop 0
	global_load_dwordx4 v[54:57], v[54:55], off offset:128
	v_lshl_add_u32 v180, s49, 8, v190
	v_ashrrev_i32_e32 v181, 31, v180
	v_lshlrev_b64 v[162:163], 10, v[180:181]
	v_lshl_add_u64 v[188:189], v[162:163], 0, v[182:183]
	v_lshlrev_b32_e32 v250, 1, v188
	global_load_dwordx4 v[208:211], v250, s[92:93]
	global_load_dwordx4 v[226:229], v250, s[92:93] offset:64
	v_add_u32_e32 v251, 0x8000, v250
	global_load_dwordx4 v[230:233], v251, s[92:93]
	v_add_u32_e32 v251, 0x8000, v250
	global_load_dwordx4 v[234:237], v251, s[92:93] offset:64
	v_add_u32_e32 v251, 0x10000, v250
	global_load_dwordx4 v[238:241], v251, s[92:93]
	v_add_u32_e32 v251, 0x10000, v250
	global_load_dwordx4 v[242:245], v251, s[92:93] offset:64
	v_add_u32_e32 v251, 0x18000, v250
	global_load_dwordx4 v[246:249], v251, s[92:93]
	s_and_b64 vcc, exec, s[28:29]
	s_cbranch_vccnz .LBB0_1588
	s_mov_b64 s[26:27], 0
	s_waitcnt vmcnt(6)
	v_lshlrev_b32_e32 v184, 16, v208
	v_and_b32_e32 v185, 0xffff0000, v208
	v_lshlrev_b32_e32 v162, 16, v209
	v_and_b32_e32 v163, 0xffff0000, v209
	v_pk_mul_f32 v[184:185], v[184:185], s[86:87] op_sel_hi:[1,0]
	v_pk_mul_f32 v[162:163], v[162:163], s[86:87] op_sel_hi:[1,0]
	v_lshlrev_b32_e32 v166, 16, v210
	v_and_b32_e32 v167, 0xffff0000, v210
	v_lshlrev_b32_e32 v168, 16, v211
	v_and_b32_e32 v169, 0xffff0000, v211
	v_pk_fma_f32 v[164:165], v[160:161], v[72:73], v[162:163]
	v_pk_fma_f32 v[162:163], v[158:159], v[70:71], v[184:185]
	v_add_u32_e32 v251, 0x18000, v250
	global_load_dwordx4 v[208:211], v251, s[92:93] offset:64
.LBB0_1588:
	v_readlane_b32 s52, v255, 58
	s_andn2_b64 vcc, exec, s[26:27]
	v_lshl_add_u64 v[184:185], v[188:189], 2, s[24:25]
	v_readlane_b32 s53, v255, 59
	s_cbranch_vccnz .LBB0_1590
	global_load_dwordx4 v[162:165], v[184:185], off
	global_load_dwordx4 v[166:169], v[184:185], off offset:16
	s_waitcnt vmcnt(0)
	v_pk_mul_f32 v[164:165], v[164:165], s[86:87] op_sel_hi:[1,0]
	v_pk_mul_f32 v[162:163], v[162:163], s[86:87] op_sel_hi:[1,0]
	v_pk_fma_f32 v[164:165], v[160:161], v[72:73], v[164:165]
	v_pk_fma_f32 v[162:163], v[158:159], v[70:71], v[162:163]
	s_waitcnt vmcnt(0)
.LBB0_1590:
	v_pk_mul_f32 v[160:161], v[168:169], s[86:87] op_sel_hi:[1,0]
	v_pk_mul_f32 v[158:159], v[166:167], s[86:87] op_sel_hi:[1,0]
	v_pk_fma_f32 v[160:161], v[156:157], v[68:69], v[160:161]
	v_pk_fma_f32 v[158:159], v[154:155], v[66:67], v[158:159]
	s_andn2_b64 vcc, exec, s[22:23]
	v_lshl_add_u64 v[186:187], v[188:189], 1, s[64:65]
	s_cbranch_vccnz .LBB0_1594
	v_cvt_pk_bf16_f32 v154, v162, v163
	v_cvt_pk_bf16_f32 v155, v164, v165
	v_cvt_pk_bf16_f32 v156, v158, v159
	v_cvt_pk_bf16_f32 v157, v160, v161
	s_mov_b64 s[26:27], -1
	s_and_b64 vcc, exec, s[88:89]
	global_store_dwordx4 v[186:187], v[154:157], off
	s_cbranch_vccz .LBB0_1593
	s_nop 0
	s_mov_b64 s[26:27], 0
	s_waitcnt vmcnt(7)
	v_lshlrev_b32_e32 v188, 16, v226
	v_and_b32_e32 v189, 0xffff0000, v226
	v_lshlrev_b32_e32 v154, 16, v227
	v_and_b32_e32 v155, 0xffff0000, v227
	v_pk_mul_f32 v[188:189], v[188:189], s[86:87] op_sel_hi:[1,0]
	v_pk_mul_f32 v[154:155], v[154:155], s[86:87] op_sel_hi:[1,0]
	v_lshlrev_b32_e32 v166, 16, v228
	v_and_b32_e32 v167, 0xffff0000, v228
	v_lshlrev_b32_e32 v168, 16, v229
	v_and_b32_e32 v169, 0xffff0000, v229
	v_pk_fma_f32 v[156:157], v[152:153], v[56:57], v[154:155]
	v_pk_fma_f32 v[154:155], v[150:151], v[54:55], v[188:189]
	v_add_u32_e32 v251, 0x40000, v250
	global_load_dwordx4 v[226:229], v251, s[92:93]

; __device__ __forceinline__ u32x4 pack8(const f32x4 a, const f32x4 b) { u32x4 w; w.x = cvt_pk_bf16(a[0], a[1]); w.y = cvt_pk_bf16(a[2], a[3]); w.z = cvt_pk_bf16(b[0], b[1]); w.w = cvt_pk_bf16(b[2], b[3]); return w; }
;     __device__ __forceinline__ void operator()(const f32x4 (&acc)[2][2][4][2], const Unit& u, int wr, int wc, int fr, int fq) const {
;     ...
;                     else {
; #pragma unroll
;                     for (int n = 0; n < 2; ++n) { const f32x4 bs = *(const f32x4*)(ib + off + bj * 32 + n * 4); o[n] = bs * 1.6817928305074290f + gv[bj][n] * acc[ai][bj][m][n]; } }
;                     if (tobf) *(u32x4*)(vout + off + bj * 32) = pack8(o[0], o[1]);
;                     else { *(f32x4*)(ob + off + bj * 32) = o[0]; *(f32x4*)(ob + off + bj * 32 + 4) = o[1]; } }
.LBB0_1596:
	s_andn2_b64 vcc, exec, s[26:27]
	s_cbranch_vccnz .LBB0_1598
	global_load_dwordx4 v[154:157], v[184:185], off offset:128
	global_load_dwordx4 v[166:169], v[184:185], off offset:144
	s_waitcnt vmcnt(1)
	v_pk_mul_f32 v[156:157], v[156:157], s[86:87] op_sel_hi:[1,0]
	v_pk_mul_f32 v[154:155], v[154:155], s[86:87] op_sel_hi:[1,0]
	v_pk_fma_f32 v[156:157], v[152:153], v[56:57], v[156:157]
	v_pk_fma_f32 v[154:155], v[150:151], v[54:55], v[154:155]
	s_waitcnt vmcnt(0)
.LBB0_1598:
	v_pk_mul_f32 v[150:151], v[168:169], s[86:87] op_sel_hi:[1,0]
	v_pk_mul_f32 v[152:153], v[166:167], s[86:87] op_sel_hi:[1,0]
	v_pk_fma_f32 v[148:149], v[148:149], v[52:53], v[150:151]
	v_pk_fma_f32 v[146:147], v[146:147], v[50:51], v[152:153]
	s_mov_b64 s[26:27], -1
	s_and_b64 vcc, exec, s[22:23]
	s_cbranch_vccz .LBB0_1600
	v_cvt_pk_bf16_f32 v150, v154, v155
	v_cvt_pk_bf16_f32 v151, v156, v157
	v_cvt_pk_bf16_f32 v152, v146, v147
	v_cvt_pk_bf16_f32 v153, v148, v149
	global_store_dwordx4 v[186:187], v[150:153], off offset:64
	s_mov_b64 s[26:27], 0

; __device__ __forceinline__ u32x4 pack8(const f32x4 a, const f32x4 b) { u32x4 w; w.x = cvt_pk_bf16(a[0], a[1]); w.y = cvt_pk_bf16(a[2], a[3]); w.z = cvt_pk_bf16(b[0], b[1]); w.w = cvt_pk_bf16(b[2], b[3]); return w; }
;     __device__ __forceinline__ void operator()(const f32x4 (&acc)[2][2][4][2], const Unit& u, int wr, int wc, int fr, int fq) const {
;     ...
;         for (int ai = 0; ai < 2; ++ai)
; #pragma unroll
;             for (int m = 0; m < 4; ++m) { const size_t off = (size_t)(rowb + ai * HALF + m * 16) * 1024 + col0;
; #pragma unroll
;                 for (int bj = 0; bj < 2; ++bj) { f32x4 o[2];
;                     if (lat && rinB) { const u32x4 w = *(const u32x4*)(rinB + off + bj * 32);
;                         const f32x4 b0 = {__builtin_bit_cast(float, w.x << 16), __builtin_bit_cast(float, w.x & 0xffff0000u), __builtin_bit_cast(float, w.y << 16), __builtin_bit_cast(float, w.y & 0xffff0000u)};
;                         const f32x4 b1 = {__builtin_bit_cast(float, w.z << 16), __builtin_bit_cast(float, w.z & 0xffff0000u), __builtin_bit_cast(float, w.w << 16), __builtin_bit_cast(float, w.w & 0xffff0000u)};
;                         o[0] = b0 * 1.6817928305074290f + gv[bj][0] * acc[ai][bj][m][0]; o[1] = b1 * 1.6817928305074290f + gv[bj][1] * acc[ai][bj][m][1]; }
;                     else {
; #pragma unroll
;                     for (int n = 0; n < 2; ++n) { const f32x4 bs = *(const f32x4*)(ib + off + bj * 32 + n * 4); o[n] = bs * 1.6817928305074290f + gv[bj][n] * acc[ai][bj][m][n]; } }
;                     if (tobf) *(u32x4*)(vout + off + bj * 32) = pack8(o[0], o[1]);
;                     else { *(f32x4*)(ob + off + bj * 32) = o[0]; *(f32x4*)(ob + off + bj * 32 + 4) = o[1]; } }
.LBB0_1602:
	s_nop 1
	v_or_b32_e32 v146, 16, v180
	v_ashrrev_i32_e32 v147, 31, v146
	v_lshlrev_b64 v[146:147], 10, v[146:147]
	v_lshl_add_u64 v[158:159], v[146:147], 0, v[182:183]
	s_mov_b64 s[26:27], -1
	s_and_b64 vcc, exec, s[28:29]
	s_cbranch_vccnz .LBB0_1604
	s_mov_b64 s[26:27], 0
	s_waitcnt vmcnt(8)
	v_lshlrev_b32_e32 v154, 16, v230
	v_and_b32_e32 v155, 0xffff0000, v230
	v_lshlrev_b32_e32 v146, 16, v231
	v_and_b32_e32 v147, 0xffff0000, v231
	v_pk_mul_f32 v[154:155], v[154:155], s[86:87] op_sel_hi:[1,0]
	v_pk_mul_f32 v[146:147], v[146:147], s[86:87] op_sel_hi:[1,0]
	v_lshlrev_b32_e32 v150, 16, v232
	v_and_b32_e32 v151, 0xffff0000, v232
	v_lshlrev_b32_e32 v152, 16, v233
	v_and_b32_e32 v153, 0xffff0000, v233
	v_pk_fma_f32 v[148:149], v[144:145], v[72:73], v[146:147]
	v_pk_fma_f32 v[146:147], v[142:143], v[70:71], v[154:155]
	v_add_u32_e32 v251, 0x40000, v250
	global_load_dwordx4 v[230:233], v251, s[92:93] offset:64
.LBB0_1604:
	s_andn2_b64 vcc, exec, s[26:27]
	v_lshl_add_u64 v[154:155], v[158:159], 2, s[24:25]
	s_cbranch_vccnz .LBB0_1606
	global_load_dwordx4 v[146:149], v[154:155], off
	global_load_dwordx4 v[150:153], v[154:155], off offset:16
	s_waitcnt vmcnt(1)
	v_pk_mul_f32 v[148:149], v[148:149], s[86:87] op_sel_hi:[1,0]
	v_pk_mul_f32 v[146:147], v[146:147], s[86:87] op_sel_hi:[1,0]
	v_pk_fma_f32 v[148:149], v[144:145], v[72:73], v[148:149]
	v_pk_fma_f32 v[146:147], v[142:143], v[70:71], v[146:147]
	s_waitcnt vmcnt(0)
.LBB0_1606:
	v_pk_mul_f32 v[142:143], v[152:153], s[86:87] op_sel_hi:[1,0]
	v_pk_mul_f32 v[144:145], v[150:151], s[86:87] op_sel_hi:[1,0]
	v_pk_fma_f32 v[152:153], v[140:141], v[68:69], v[142:143]
	v_pk_fma_f32 v[150:151], v[138:139], v[66:67], v[144:145]
	s_and_b64 vcc, exec, s[22:23]
	v_lshl_add_u64 v[156:157], v[158:159], 1, s[64:65]
	s_cbranch_vccz .LBB0_1610
	v_cvt_pk_bf16_f32 v138, v146, v147
	v_cvt_pk_bf16_f32 v139, v148, v149
	v_cvt_pk_bf16_f32 v140, v150, v151
	v_cvt_pk_bf16_f32 v141, v152, v153
	s_mov_b64 s[26:27], -1
	s_and_b64 vcc, exec, s[88:89]
	global_store_dwordx4 v[156:157], v[138:141], off
	s_cbranch_vccz .LBB0_1609
	s_nop 0
	s_mov_b64 s[26:27], 0
	s_waitcnt vmcnt(9)
	v_lshlrev_b32_e32 v158, 16, v234
	v_and_b32_e32 v159, 0xffff0000, v234
	v_lshlrev_b32_e32 v138, 16, v235
	v_and_b32_e32 v139, 0xffff0000, v235
	v_pk_mul_f32 v[158:159], v[158:159], s[86:87] op_sel_hi:[1,0]
	v_pk_mul_f32 v[138:139], v[138:139], s[86:87] op_sel_hi:[1,0]
	v_lshlrev_b32_e32 v142, 16, v236
	v_and_b32_e32 v143, 0xffff0000, v236
	v_lshlrev_b32_e32 v144, 16, v237
	v_and_b32_e32 v145, 0xffff0000, v237
	v_pk_fma_f32 v[140:141], v[136:137], v[56:57], v[138:139]
	v_pk_fma_f32 v[138:139], v[134:135], v[54:55], v[158:159]
	v_add_u32_e32 v251, 0x48000, v250
	global_load_dwordx4 v[234:237], v251, s[92:93]

; __device__ __forceinline__ u32x4 pack8(const f32x4 a, const f32x4 b) { u32x4 w; w.x = cvt_pk_bf16(a[0], a[1]); w.y = cvt_pk_bf16(a[2], a[3]); w.z = cvt_pk_bf16(b[0], b[1]); w.w = cvt_pk_bf16(b[2], b[3]); return w; }
;     __device__ __forceinline__ void operator()(const f32x4 (&acc)[2][2][4][2], const Unit& u, int wr, int wc, int fr, int fq) const {
;     ...
;                     else {
; #pragma unroll
;                     for (int n = 0; n < 2; ++n) { const f32x4 bs = *(const f32x4*)(ib + off + bj * 32 + n * 4); o[n] = bs * 1.6817928305074290f + gv[bj][n] * acc[ai][bj][m][n]; } }
;                     if (tobf) *(u32x4*)(vout + off + bj * 32) = pack8(o[0], o[1]);
;                     else { *(f32x4*)(ob + off + bj * 32) = o[0]; *(f32x4*)(ob + off + bj * 32 + 4) = o[1]; } }
.LBB0_1612:
	s_andn2_b64 vcc, exec, s[26:27]
	s_cbranch_vccnz .LBB0_1614
	global_load_dwordx4 v[138:141], v[154:155], off offset:128
	global_load_dwordx4 v[142:145], v[154:155], off offset:144
	s_waitcnt vmcnt(1)
	v_pk_mul_f32 v[140:141], v[140:141], s[86:87] op_sel_hi:[1,0]
	v_pk_mul_f32 v[138:139], v[138:139], s[86:87] op_sel_hi:[1,0]
	v_pk_fma_f32 v[140:141], v[136:137], v[56:57], v[140:141]
	v_pk_fma_f32 v[138:139], v[134:135], v[54:55], v[138:139]
	s_waitcnt vmcnt(0)
.LBB0_1614:
	v_pk_mul_f32 v[134:135], v[144:145], s[86:87] op_sel_hi:[1,0]
	v_pk_mul_f32 v[136:137], v[142:143], s[86:87] op_sel_hi:[1,0]
	v_pk_fma_f32 v[132:133], v[132:133], v[52:53], v[134:135]
	v_pk_fma_f32 v[130:131], v[130:131], v[50:51], v[136:137]
	s_mov_b64 s[26:27], -1
	s_and_b64 vcc, exec, s[22:23]
	s_cbranch_vccz .LBB0_1616
	v_cvt_pk_bf16_f32 v134, v138, v139
	v_cvt_pk_bf16_f32 v135, v140, v141
	v_cvt_pk_bf16_f32 v136, v130, v131
	v_cvt_pk_bf16_f32 v137, v132, v133
	global_store_dwordx4 v[156:157], v[134:137], off offset:64
	s_mov_b64 s[26:27], 0

; __device__ __forceinline__ u32x4 pack8(const f32x4 a, const f32x4 b) { u32x4 w; w.x = cvt_pk_bf16(a[0], a[1]); w.y = cvt_pk_bf16(a[2], a[3]); w.z = cvt_pk_bf16(b[0], b[1]); w.w = cvt_pk_bf16(b[2], b[3]); return w; }
;     __device__ __forceinline__ void operator()(const f32x4 (&acc)[2][2][4][2], const Unit& u, int wr, int wc, int fr, int fq) const {
;     ...
;         for (int ai = 0; ai < 2; ++ai)
; #pragma unroll
;             for (int m = 0; m < 4; ++m) { const size_t off = (size_t)(rowb + ai * HALF + m * 16) * 1024 + col0;
; #pragma unroll
;                 for (int bj = 0; bj < 2; ++bj) { f32x4 o[2];
;                     if (lat && rinB) { const u32x4 w = *(const u32x4*)(rinB + off + bj * 32);
;                         const f32x4 b0 = {__builtin_bit_cast(float, w.x << 16), __builtin_bit_cast(float, w.x & 0xffff0000u), __builtin_bit_cast(float, w.y << 16), __builtin_bit_cast(float, w.y & 0xffff0000u)};
;                         const f32x4 b1 = {__builtin_bit_cast(float, w.z << 16), __builtin_bit_cast(float, w.z & 0xffff0000u), __builtin_bit_cast(float, w.w << 16), __builtin_bit_cast(float, w.w & 0xffff0000u)};
;                         o[0] = b0 * 1.6817928305074290f + gv[bj][0] * acc[ai][bj][m][0]; o[1] = b1 * 1.6817928305074290f + gv[bj][1] * acc[ai][bj][m][1]; }
;                     else {
; #pragma unroll
;                     for (int n = 0; n < 2; ++n) { const f32x4 bs = *(const f32x4*)(ib + off + bj * 32 + n * 4); o[n] = bs * 1.6817928305074290f + gv[bj][n] * acc[ai][bj][m][n]; } }
;                     if (tobf) *(u32x4*)(vout + off + bj * 32) = pack8(o[0], o[1]);
;                     else { *(f32x4*)(ob + off + bj * 32) = o[0]; *(f32x4*)(ob + off + bj * 32 + 4) = o[1]; } }
.LBB0_1618:
	s_nop 1
	v_or_b32_e32 v130, 32, v180
	v_ashrrev_i32_e32 v131, 31, v130
	v_lshlrev_b64 v[130:131], 10, v[130:131]
	v_lshl_add_u64 v[142:143], v[130:131], 0, v[182:183]
	s_mov_b64 s[26:27], -1
	s_and_b64 vcc, exec, s[28:29]
	s_cbranch_vccnz .LBB0_1620
	s_mov_b64 s[26:27], 0
	s_waitcnt vmcnt(10)
	v_lshlrev_b32_e32 v138, 16, v238
	v_and_b32_e32 v139, 0xffff0000, v238
	v_lshlrev_b32_e32 v130, 16, v239
	v_and_b32_e32 v131, 0xffff0000, v239
	v_pk_mul_f32 v[138:139], v[138:139], s[86:87] op_sel_hi:[1,0]
	v_pk_mul_f32 v[130:131], v[130:131], s[86:87] op_sel_hi:[1,0]
	v_lshlrev_b32_e32 v134, 16, v240
	v_and_b32_e32 v135, 0xffff0000, v240
	v_lshlrev_b32_e32 v136, 16, v241
	v_and_b32_e32 v137, 0xffff0000, v241
	v_pk_fma_f32 v[132:133], v[112:113], v[72:73], v[130:131]
	v_pk_fma_f32 v[130:131], v[110:111], v[70:71], v[138:139]
	v_add_u32_e32 v251, 0x48000, v250
	global_load_dwordx4 v[238:241], v251, s[92:93] offset:64
.LBB0_1620:
	s_andn2_b64 vcc, exec, s[26:27]
	v_lshl_add_u64 v[138:139], v[142:143], 2, s[24:25]
	s_cbranch_vccnz .LBB0_1622
	global_load_dwordx4 v[130:133], v[138:139], off
	global_load_dwordx4 v[134:137], v[138:139], off offset:16
	s_waitcnt vmcnt(1)
	v_pk_mul_f32 v[132:133], v[132:133], s[86:87] op_sel_hi:[1,0]
	v_pk_mul_f32 v[130:131], v[130:131], s[86:87] op_sel_hi:[1,0]
	v_pk_fma_f32 v[132:133], v[112:113], v[72:73], v[132:133]
	v_pk_fma_f32 v[130:131], v[110:111], v[70:71], v[130:131]
	s_waitcnt vmcnt(0)
.LBB0_1622:
	v_pk_mul_f32 v[110:111], v[136:137], s[86:87] op_sel_hi:[1,0]
	v_pk_mul_f32 v[134:135], v[134:135], s[86:87] op_sel_hi:[1,0]
	v_pk_fma_f32 v[112:113], v[108:109], v[68:69], v[110:111]
	v_pk_fma_f32 v[110:111], v[106:107], v[66:67], v[134:135]
	s_and_b64 vcc, exec, s[22:23]
	v_lshl_add_u64 v[140:141], v[142:143], 1, s[64:65]
	s_cbranch_vccz .LBB0_1626
	v_cvt_pk_bf16_f32 v106, v130, v131
	v_cvt_pk_bf16_f32 v107, v132, v133
	v_cvt_pk_bf16_f32 v108, v110, v111
	v_cvt_pk_bf16_f32 v109, v112, v113
	s_mov_b64 s[26:27], -1
	s_and_b64 vcc, exec, s[88:89]
	global_store_dwordx4 v[140:141], v[106:109], off
	s_cbranch_vccz .LBB0_1625
	s_nop 0
	s_mov_b64 s[26:27], 0
	s_waitcnt vmcnt(11)
	v_lshlrev_b32_e32 v142, 16, v242
	v_and_b32_e32 v143, 0xffff0000, v242
	v_lshlrev_b32_e32 v106, 16, v243
	v_and_b32_e32 v107, 0xffff0000, v243
	v_pk_mul_f32 v[142:143], v[142:143], s[86:87] op_sel_hi:[1,0]
	v_pk_mul_f32 v[106:107], v[106:107], s[86:87] op_sel_hi:[1,0]
	v_lshlrev_b32_e32 v134, 16, v244
	v_and_b32_e32 v135, 0xffff0000, v244
	v_lshlrev_b32_e32 v136, 16, v245
	v_and_b32_e32 v137, 0xffff0000, v245
	v_pk_fma_f32 v[108:109], v[104:105], v[56:57], v[106:107]
	v_pk_fma_f32 v[106:107], v[102:103], v[54:55], v[142:143]
	v_add_u32_e32 v251, 0x50000, v250
	global_load_dwordx4 v[242:245], v251, s[92:93]

; __device__ __forceinline__ u32x4 pack8(const f32x4 a, const f32x4 b) { u32x4 w; w.x = cvt_pk_bf16(a[0], a[1]); w.y = cvt_pk_bf16(a[2], a[3]); w.z = cvt_pk_bf16(b[0], b[1]); w.w = cvt_pk_bf16(b[2], b[3]); return w; }
;     __device__ __forceinline__ void operator()(const f32x4 (&acc)[2][2][4][2], const Unit& u, int wr, int wc, int fr, int fq) const {
;     ...
;                     else {
; #pragma unroll
;                     for (int n = 0; n < 2; ++n) { const f32x4 bs = *(const f32x4*)(ib + off + bj * 32 + n * 4); o[n] = bs * 1.6817928305074290f + gv[bj][n] * acc[ai][bj][m][n]; } }
;                     if (tobf) *(u32x4*)(vout + off + bj * 32) = pack8(o[0], o[1]);
;                     else { *(f32x4*)(ob + off + bj * 32) = o[0]; *(f32x4*)(ob + off + bj * 32 + 4) = o[1]; } }
.LBB0_1628:
	s_andn2_b64 vcc, exec, s[26:27]
	s_cbranch_vccnz .LBB0_1630
	global_load_dwordx4 v[106:109], v[138:139], off offset:128
	global_load_dwordx4 v[134:137], v[138:139], off offset:144
	s_waitcnt vmcnt(1)
	v_pk_mul_f32 v[108:109], v[108:109], s[86:87] op_sel_hi:[1,0]
	v_pk_mul_f32 v[106:107], v[106:107], s[86:87] op_sel_hi:[1,0]
	v_pk_fma_f32 v[108:109], v[104:105], v[56:57], v[108:109]
	v_pk_fma_f32 v[106:107], v[102:103], v[54:55], v[106:107]
	s_waitcnt vmcnt(0)
.LBB0_1630:
	v_pk_mul_f32 v[102:103], v[136:137], s[86:87] op_sel_hi:[1,0]
	v_pk_mul_f32 v[104:105], v[134:135], s[86:87] op_sel_hi:[1,0]
	v_pk_fma_f32 v[100:101], v[100:101], v[52:53], v[102:103]
	v_pk_fma_f32 v[98:99], v[98:99], v[50:51], v[104:105]
	s_mov_b64 s[26:27], -1
	s_and_b64 vcc, exec, s[22:23]
	s_cbranch_vccz .LBB0_1632
	v_cvt_pk_bf16_f32 v102, v106, v107
	v_cvt_pk_bf16_f32 v103, v108, v109
	v_cvt_pk_bf16_f32 v104, v98, v99
	v_cvt_pk_bf16_f32 v105, v100, v101
	global_store_dwordx4 v[140:141], v[102:105], off offset:64
	s_mov_b64 s[26:27], 0

; __device__ __forceinline__ u32x4 pack8(const f32x4 a, const f32x4 b) { u32x4 w; w.x = cvt_pk_bf16(a[0], a[1]); w.y = cvt_pk_bf16(a[2], a[3]); w.z = cvt_pk_bf16(b[0], b[1]); w.w = cvt_pk_bf16(b[2], b[3]); return w; }
;     __device__ __forceinline__ void operator()(const f32x4 (&acc)[2][2][4][2], const Unit& u, int wr, int wc, int fr, int fq) const {
;     ...
;         for (int ai = 0; ai < 2; ++ai)
; #pragma unroll
;             for (int m = 0; m < 4; ++m) { const size_t off = (size_t)(rowb + ai * HALF + m * 16) * 1024 + col0;
; #pragma unroll
;                 for (int bj = 0; bj < 2; ++bj) { f32x4 o[2];
;                     if (lat && rinB) { const u32x4 w = *(const u32x4*)(rinB + off + bj * 32);
;                         const f32x4 b0 = {__builtin_bit_cast(float, w.x << 16), __builtin_bit_cast(float, w.x & 0xffff0000u), __builtin_bit_cast(float, w.y << 16), __builtin_bit_cast(float, w.y & 0xffff0000u)};
;                         const f32x4 b1 = {__builtin_bit_cast(float, w.z << 16), __builtin_bit_cast(float, w.z & 0xffff0000u), __builtin_bit_cast(float, w.w << 16), __builtin_bit_cast(float, w.w & 0xffff0000u)};
;                         o[0] = b0 * 1.6817928305074290f + gv[bj][0] * acc[ai][bj][m][0]; o[1] = b1 * 1.6817928305074290f + gv[bj][1] * acc[ai][bj][m][1]; }
;                     else {
; #pragma unroll
;                     for (int n = 0; n < 2; ++n) { const f32x4 bs = *(const f32x4*)(ib + off + bj * 32 + n * 4); o[n] = bs * 1.6817928305074290f + gv[bj][n] * acc[ai][bj][m][n]; } }
;                     if (tobf) *(u32x4*)(vout + off + bj * 32) = pack8(o[0], o[1]);
;                     else { *(f32x4*)(ob + off + bj * 32) = o[0]; *(f32x4*)(ob + off + bj * 32 + 4) = o[1]; } }
.LBB0_1634:
	s_nop 1
	v_or_b32_e32 v98, 48, v180
	v_ashrrev_i32_e32 v99, 31, v98
	v_lshlrev_b64 v[98:99], 10, v[98:99]
	v_lshl_add_u64 v[110:111], v[98:99], 0, v[182:183]
	s_mov_b64 s[26:27], -1
	s_and_b64 vcc, exec, s[28:29]
	s_cbranch_vccnz .LBB0_1636
	s_mov_b64 s[26:27], 0
	s_waitcnt vmcnt(12)
	v_lshlrev_b32_e32 v106, 16, v246
	v_and_b32_e32 v107, 0xffff0000, v246
	v_lshlrev_b32_e32 v98, 16, v247
	v_and_b32_e32 v99, 0xffff0000, v247
	v_pk_mul_f32 v[106:107], v[106:107], s[86:87] op_sel_hi:[1,0]
	v_pk_mul_f32 v[98:99], v[98:99], s[86:87] op_sel_hi:[1,0]
	v_lshlrev_b32_e32 v102, 16, v248
	v_and_b32_e32 v103, 0xffff0000, v248
	v_lshlrev_b32_e32 v104, 16, v249
	v_and_b32_e32 v105, 0xffff0000, v249
	v_pk_fma_f32 v[100:101], v[96:97], v[72:73], v[98:99]
	v_pk_fma_f32 v[98:99], v[94:95], v[70:71], v[106:107]
	v_add_u32_e32 v251, 0x50000, v250
	global_load_dwordx4 v[246:249], v251, s[92:93] offset:64
.LBB0_1636:
	s_andn2_b64 vcc, exec, s[26:27]
	v_lshl_add_u64 v[106:107], v[110:111], 2, s[24:25]
	s_cbranch_vccnz .LBB0_1638
	global_load_dwordx4 v[98:101], v[106:107], off
	global_load_dwordx4 v[102:105], v[106:107], off offset:16
	s_waitcnt vmcnt(1)
	v_pk_mul_f32 v[100:101], v[100:101], s[86:87] op_sel_hi:[1,0]
	v_pk_mul_f32 v[98:99], v[98:99], s[86:87] op_sel_hi:[1,0]
	v_pk_fma_f32 v[100:101], v[96:97], v[72:73], v[100:101]
	v_pk_fma_f32 v[98:99], v[94:95], v[70:71], v[98:99]
	s_waitcnt vmcnt(0)
.LBB0_1638:
	v_pk_mul_f32 v[94:95], v[104:105], s[86:87] op_sel_hi:[1,0]
	v_pk_mul_f32 v[102:103], v[102:103], s[86:87] op_sel_hi:[1,0]
	v_pk_fma_f32 v[96:97], v[92:93], v[68:69], v[94:95]
	v_pk_fma_f32 v[94:95], v[90:91], v[66:67], v[102:103]
	s_and_b64 vcc, exec, s[22:23]
	v_lshl_add_u64 v[108:109], v[110:111], 1, s[64:65]
	s_cbranch_vccz .LBB0_1642
	v_cvt_pk_bf16_f32 v90, v98, v99
	v_cvt_pk_bf16_f32 v91, v100, v101
	v_cvt_pk_bf16_f32 v92, v94, v95
	v_cvt_pk_bf16_f32 v93, v96, v97
	s_mov_b64 s[26:27], -1
	s_and_b64 vcc, exec, s[88:89]
	global_store_dwordx4 v[108:109], v[90:93], off
	s_cbranch_vccz .LBB0_1641
	s_nop 0
	s_mov_b64 s[26:27], 0
	s_waitcnt vmcnt(13)
	v_lshlrev_b32_e32 v110, 16, v208
	v_and_b32_e32 v111, 0xffff0000, v208
	v_lshlrev_b32_e32 v90, 16, v209
	v_and_b32_e32 v91, 0xffff0000, v209
	v_pk_mul_f32 v[110:111], v[110:111], s[86:87] op_sel_hi:[1,0]
	v_pk_mul_f32 v[90:91], v[90:91], s[86:87] op_sel_hi:[1,0]
	v_lshlrev_b32_e32 v102, 16, v210
	v_and_b32_e32 v103, 0xffff0000, v210
	v_lshlrev_b32_e32 v104, 16, v211
	v_and_b32_e32 v105, 0xffff0000, v211
	v_pk_fma_f32 v[92:93], v[88:89], v[56:57], v[90:91]
	v_pk_fma_f32 v[90:91], v[86:87], v[54:55], v[110:111]
	v_add_u32_e32 v251, 0x58000, v250
	global_load_dwordx4 v[208:211], v251, s[92:93]

; __device__ __forceinline__ u32x4 pack8(const f32x4 a, const f32x4 b) { u32x4 w; w.x = cvt_pk_bf16(a[0], a[1]); w.y = cvt_pk_bf16(a[2], a[3]); w.z = cvt_pk_bf16(b[0], b[1]); w.w = cvt_pk_bf16(b[2], b[3]); return w; }
;     __device__ __forceinline__ void operator()(const f32x4 (&acc)[2][2][4][2], const Unit& u, int wr, int wc, int fr, int fq) const {
;     ...
;                     else {
; #pragma unroll
;                     for (int n = 0; n < 2; ++n) { const f32x4 bs = *(const f32x4*)(ib + off + bj * 32 + n * 4); o[n] = bs * 1.6817928305074290f + gv[bj][n] * acc[ai][bj][m][n]; } }
;                     if (tobf) *(u32x4*)(vout + off + bj * 32) = pack8(o[0], o[1]);
;                     else { *(f32x4*)(ob + off + bj * 32) = o[0]; *(f32x4*)(ob + off + bj * 32 + 4) = o[1]; } }
.LBB0_1644:
	s_andn2_b64 vcc, exec, s[26:27]
	s_cbranch_vccnz .LBB0_1646
	global_load_dwordx4 v[90:93], v[106:107], off offset:128
	global_load_dwordx4 v[102:105], v[106:107], off offset:144
	s_waitcnt vmcnt(1)
	v_pk_mul_f32 v[92:93], v[92:93], s[86:87] op_sel_hi:[1,0]
	v_pk_mul_f32 v[90:91], v[90:91], s[86:87] op_sel_hi:[1,0]
	v_pk_fma_f32 v[92:93], v[88:89], v[56:57], v[92:93]
	v_pk_fma_f32 v[90:91], v[86:87], v[54:55], v[90:91]
	s_waitcnt vmcnt(0)
.LBB0_1646:
	v_pk_mul_f32 v[86:87], v[104:105], s[86:87] op_sel_hi:[1,0]
	v_pk_mul_f32 v[88:89], v[102:103], s[86:87] op_sel_hi:[1,0]
	v_pk_fma_f32 v[84:85], v[84:85], v[52:53], v[86:87]
	v_pk_fma_f32 v[82:83], v[82:83], v[50:51], v[88:89]
	s_mov_b64 s[26:27], -1
	s_and_b64 vcc, exec, s[22:23]
	s_cbranch_vccz .LBB0_1648
	v_cvt_pk_bf16_f32 v86, v90, v91
	v_cvt_pk_bf16_f32 v87, v92, v93
	v_cvt_pk_bf16_f32 v88, v82, v83
	v_cvt_pk_bf16_f32 v89, v84, v85
	global_store_dwordx4 v[108:109], v[86:89], off offset:64
	s_mov_b64 s[26:27], 0

; __device__ __forceinline__ u32x4 pack8(const f32x4 a, const f32x4 b) { u32x4 w; w.x = cvt_pk_bf16(a[0], a[1]); w.y = cvt_pk_bf16(a[2], a[3]); w.z = cvt_pk_bf16(b[0], b[1]); w.w = cvt_pk_bf16(b[2], b[3]); return w; }
;     __device__ __forceinline__ void operator()(const f32x4 (&acc)[2][2][4][2], const Unit& u, int wr, int wc, int fr, int fq) const {
;     ...
; #pragma unroll
;         for (int ai = 0; ai < 2; ++ai)
; #pragma unroll
;             for (int m = 0; m < 4; ++m) { const size_t off = (size_t)(rowb + ai * HALF + m * 16) * 1024 + col0;
; #pragma unroll
;                 for (int bj = 0; bj < 2; ++bj) { f32x4 o[2];
;                     if (lat && rinB) { const u32x4 w = *(const u32x4*)(rinB + off + bj * 32);
;                         const f32x4 b0 = {__builtin_bit_cast(float, w.x << 16), __builtin_bit_cast(float, w.x & 0xffff0000u), __builtin_bit_cast(float, w.y << 16), __builtin_bit_cast(float, w.y & 0xffff0000u)};
;                         const f32x4 b1 = {__builtin_bit_cast(float, w.z << 16), __builtin_bit_cast(float, w.z & 0xffff0000u), __builtin_bit_cast(float, w.w << 16), __builtin_bit_cast(float, w.w & 0xffff0000u)};
;                         o[0] = b0 * 1.6817928305074290f + gv[bj][0] * acc[ai][bj][m][0]; o[1] = b1 * 1.6817928305074290f + gv[bj][1] * acc[ai][bj][m][1]; }
;                     else {
; #pragma unroll
;                     for (int n = 0; n < 2; ++n) { const f32x4 bs = *(const f32x4*)(ib + off + bj * 32 + n * 4); o[n] = bs * 1.6817928305074290f + gv[bj][n] * acc[ai][bj][m][n]; } }
;                     if (tobf) *(u32x4*)(vout + off + bj * 32) = pack8(o[0], o[1]);
;                     else { *(f32x4*)(ob + off + bj * 32) = o[0]; *(f32x4*)(ob + off + bj * 32 + 4) = o[1]; } }
.LBB0_1650:
	s_nop 1
	v_lshlrev_b64 v[82:83], 10, v[180:181]
	v_lshl_add_u64 v[82:83], v[82:83], 0, v[182:183]
	v_lshl_add_u64 v[94:95], v[82:83], 0, s[96:97]
	s_mov_b64 s[26:27], -1
	s_and_b64 vcc, exec, s[28:29]
	s_cbranch_vccnz .LBB0_1652
	s_mov_b64 s[26:27], 0
	s_waitcnt vmcnt(13)
	v_lshlrev_b32_e32 v90, 16, v226
	v_and_b32_e32 v91, 0xffff0000, v226
	v_lshlrev_b32_e32 v82, 16, v227
	v_and_b32_e32 v83, 0xffff0000, v227
	v_pk_mul_f32 v[90:91], v[90:91], s[86:87] op_sel_hi:[1,0]
	v_pk_mul_f32 v[82:83], v[82:83], s[86:87] op_sel_hi:[1,0]
	v_lshlrev_b32_e32 v86, 16, v228
	v_and_b32_e32 v87, 0xffff0000, v228
	v_lshlrev_b32_e32 v88, 16, v229
	v_and_b32_e32 v89, 0xffff0000, v229
	v_pk_fma_f32 v[84:85], v[80:81], v[72:73], v[82:83]
	v_pk_fma_f32 v[82:83], v[78:79], v[70:71], v[90:91]
	v_add_u32_e32 v251, 0x58000, v250
	global_load_dwordx4 v[226:229], v251, s[92:93] offset:64
.LBB0_1652:
	s_andn2_b64 vcc, exec, s[26:27]
	v_lshl_add_u64 v[90:91], v[94:95], 2, s[24:25]
	s_cbranch_vccnz .LBB0_1654
	global_load_dwordx4 v[82:85], v[90:91], off
	global_load_dwordx4 v[86:89], v[90:91], off offset:16
	s_waitcnt vmcnt(1)
	v_pk_mul_f32 v[84:85], v[84:85], s[86:87] op_sel_hi:[1,0]
	v_pk_mul_f32 v[82:83], v[82:83], s[86:87] op_sel_hi:[1,0]
	v_pk_fma_f32 v[84:85], v[80:81], v[72:73], v[84:85]
	v_pk_fma_f32 v[82:83], v[78:79], v[70:71], v[82:83]
	s_waitcnt vmcnt(0)
.LBB0_1654:
	v_pk_mul_f32 v[78:79], v[88:89], s[86:87] op_sel_hi:[1,0]
	v_pk_mul_f32 v[86:87], v[86:87], s[86:87] op_sel_hi:[1,0]
	v_pk_fma_f32 v[80:81], v[76:77], v[68:69], v[78:79]
	v_pk_fma_f32 v[78:79], v[74:75], v[66:67], v[86:87]
	s_and_b64 vcc, exec, s[22:23]
	v_lshl_add_u64 v[92:93], v[94:95], 1, s[64:65]
	s_cbranch_vccz .LBB0_1658
	v_cvt_pk_bf16_f32 v74, v82, v83
	v_cvt_pk_bf16_f32 v75, v84, v85
	v_cvt_pk_bf16_f32 v76, v78, v79
	v_cvt_pk_bf16_f32 v77, v80, v81
	s_mov_b64 s[26:27], -1
	s_and_b64 vcc, exec, s[88:89]
	global_store_dwordx4 v[92:93], v[74:77], off
	s_cbranch_vccz .LBB0_1657
	s_nop 0
	s_mov_b64 s[26:27], 0
	s_waitcnt vmcnt(13)
	v_lshlrev_b32_e32 v94, 16, v230
	v_and_b32_e32 v95, 0xffff0000, v230
	v_lshlrev_b32_e32 v74, 16, v231
	v_and_b32_e32 v75, 0xffff0000, v231
	v_pk_mul_f32 v[94:95], v[94:95], s[86:87] op_sel_hi:[1,0]
	v_pk_mul_f32 v[74:75], v[74:75], s[86:87] op_sel_hi:[1,0]
	v_lshlrev_b32_e32 v86, 16, v232
	v_and_b32_e32 v87, 0xffff0000, v232
	v_lshlrev_b32_e32 v88, 16, v233
	v_and_b32_e32 v89, 0xffff0000, v233
	v_pk_fma_f32 v[76:77], v[64:65], v[56:57], v[74:75]
	v_pk_fma_f32 v[74:75], v[62:63], v[54:55], v[94:95]

; __device__ __forceinline__ u32x4 pack8(const f32x4 a, const f32x4 b) { u32x4 w; w.x = cvt_pk_bf16(a[0], a[1]); w.y = cvt_pk_bf16(a[2], a[3]); w.z = cvt_pk_bf16(b[0], b[1]); w.w = cvt_pk_bf16(b[2], b[3]); return w; }
;     __device__ __forceinline__ void operator()(const f32x4 (&acc)[2][2][4][2], const Unit& u, int wr, int wc, int fr, int fq) const {
;     ...
;                 for (int bj = 0; bj < 2; ++bj) { f32x4 o[2];
;                     if (lat && rinB) { const u32x4 w = *(const u32x4*)(rinB + off + bj * 32);
;                         const f32x4 b0 = {__builtin_bit_cast(float, w.x << 16), __builtin_bit_cast(float, w.x & 0xffff0000u), __builtin_bit_cast(float, w.y << 16), __builtin_bit_cast(float, w.y & 0xffff0000u)};
;                         const f32x4 b1 = {__builtin_bit_cast(float, w.z << 16), __builtin_bit_cast(float, w.z & 0xffff0000u), __builtin_bit_cast(float, w.w << 16), __builtin_bit_cast(float, w.w & 0xffff0000u)};
;                         o[0] = b0 * 1.6817928305074290f + gv[bj][0] * acc[ai][bj][m][0]; o[1] = b1 * 1.6817928305074290f + gv[bj][1] * acc[ai][bj][m][1]; }
;                     else {
; #pragma unroll
;                     for (int n = 0; n < 2; ++n) { const f32x4 bs = *(const f32x4*)(ib + off + bj * 32 + n * 4); o[n] = bs * 1.6817928305074290f + gv[bj][n] * acc[ai][bj][m][n]; } }
;                     if (tobf) *(u32x4*)(vout + off + bj * 32) = pack8(o[0], o[1]);
;                     else { *(f32x4*)(ob + off + bj * 32) = o[0]; *(f32x4*)(ob + off + bj * 32 + 4) = o[1]; } }
.LBB0_1660:
	s_andn2_b64 vcc, exec, s[26:27]
	s_cbranch_vccnz .LBB0_1662
	global_load_dwordx4 v[74:77], v[90:91], off offset:128
	global_load_dwordx4 v[86:89], v[90:91], off offset:144
	s_waitcnt vmcnt(1)
	v_pk_mul_f32 v[76:77], v[76:77], s[86:87] op_sel_hi:[1,0]
	v_pk_mul_f32 v[74:75], v[74:75], s[86:87] op_sel_hi:[1,0]
	v_pk_fma_f32 v[76:77], v[64:65], v[56:57], v[76:77]
	v_pk_fma_f32 v[74:75], v[62:63], v[54:55], v[74:75]
	s_waitcnt vmcnt(0)
.LBB0_1662:
	v_pk_mul_f32 v[62:63], v[88:89], s[86:87] op_sel_hi:[1,0]
	v_pk_mul_f32 v[64:65], v[86:87], s[86:87] op_sel_hi:[1,0]
	v_pk_fma_f32 v[60:61], v[60:61], v[52:53], v[62:63]
	v_pk_fma_f32 v[58:59], v[58:59], v[50:51], v[64:65]
	s_mov_b64 s[26:27], -1
	s_and_b64 vcc, exec, s[22:23]
	s_cbranch_vccz .LBB0_1664
	v_cvt_pk_bf16_f32 v62, v74, v75
	v_cvt_pk_bf16_f32 v63, v76, v77
	v_cvt_pk_bf16_f32 v64, v58, v59
	v_cvt_pk_bf16_f32 v65, v60, v61
	global_store_dwordx4 v[92:93], v[62:65], off offset:64
	s_mov_b64 s[26:27], 0

; __device__ __forceinline__ u32x4 pack8(const f32x4 a, const f32x4 b) { u32x4 w; w.x = cvt_pk_bf16(a[0], a[1]); w.y = cvt_pk_bf16(a[2], a[3]); w.z = cvt_pk_bf16(b[0], b[1]); w.w = cvt_pk_bf16(b[2], b[3]); return w; }
;     __device__ __forceinline__ void operator()(const f32x4 (&acc)[2][2][4][2], const Unit& u, int wr, int wc, int fr, int fq) const {
;     ...
; #pragma unroll
;         for (int ai = 0; ai < 2; ++ai)
; #pragma unroll
;             for (int m = 0; m < 4; ++m) { const size_t off = (size_t)(rowb + ai * HALF + m * 16) * 1024 + col0;
; #pragma unroll
;                 for (int bj = 0; bj < 2; ++bj) { f32x4 o[2];
;                     if (lat && rinB) { const u32x4 w = *(const u32x4*)(rinB + off + bj * 32);
;                         const f32x4 b0 = {__builtin_bit_cast(float, w.x << 16), __builtin_bit_cast(float, w.x & 0xffff0000u), __builtin_bit_cast(float, w.y << 16), __builtin_bit_cast(float, w.y & 0xffff0000u)};
;                         const f32x4 b1 = {__builtin_bit_cast(float, w.z << 16), __builtin_bit_cast(float, w.z & 0xffff0000u), __builtin_bit_cast(float, w.w << 16), __builtin_bit_cast(float, w.w & 0xffff0000u)};
;                         o[0] = b0 * 1.6817928305074290f + gv[bj][0] * acc[ai][bj][m][0]; o[1] = b1 * 1.6817928305074290f + gv[bj][1] * acc[ai][bj][m][1]; }
;                     else {
; #pragma unroll
;                     for (int n = 0; n < 2; ++n) { const f32x4 bs = *(const f32x4*)(ib + off + bj * 32 + n * 4); o[n] = bs * 1.6817928305074290f + gv[bj][n] * acc[ai][bj][m][n]; } }
;                     if (tobf) *(u32x4*)(vout + off + bj * 32) = pack8(o[0], o[1]);
;                     else { *(f32x4*)(ob + off + bj * 32) = o[0]; *(f32x4*)(ob + off + bj * 32 + 4) = o[1]; } }
.LBB0_1666:
	s_nop 1
	v_lshlrev_b64 v[58:59], 10, v[180:181]
	v_lshl_add_u64 v[58:59], v[58:59], 0, v[182:183]
	s_mov_b64 s[2:3], 0x24000
	v_lshl_add_u64 v[78:79], v[58:59], 0, s[2:3]
	s_mov_b64 s[26:27], -1
	s_and_b64 vcc, exec, s[28:29]
	s_cbranch_vccnz .LBB0_1668
	s_mov_b64 s[26:27], 0
	s_waitcnt vmcnt(12)
	v_lshlrev_b32_e32 v74, 16, v234
	v_and_b32_e32 v75, 0xffff0000, v234
	v_lshlrev_b32_e32 v58, 16, v235
	v_and_b32_e32 v59, 0xffff0000, v235
	v_pk_mul_f32 v[74:75], v[74:75], s[86:87] op_sel_hi:[1,0]
	v_pk_mul_f32 v[58:59], v[58:59], s[86:87] op_sel_hi:[1,0]
	v_lshlrev_b32_e32 v62, 16, v236
	v_and_b32_e32 v63, 0xffff0000, v236
	v_lshlrev_b32_e32 v64, 16, v237
	v_and_b32_e32 v65, 0xffff0000, v237
	v_pk_fma_f32 v[60:61], v[48:49], v[72:73], v[58:59]
	v_pk_fma_f32 v[58:59], v[46:47], v[70:71], v[74:75]
.LBB0_1668:
	s_andn2_b64 vcc, exec, s[26:27]
	v_lshl_add_u64 v[74:75], v[78:79], 2, s[24:25]
	s_cbranch_vccnz .LBB0_1670
	global_load_dwordx4 v[58:61], v[74:75], off
	global_load_dwordx4 v[62:65], v[74:75], off offset:16
	s_waitcnt vmcnt(1)
	v_pk_mul_f32 v[60:61], v[60:61], s[86:87] op_sel_hi:[1,0]
	v_pk_mul_f32 v[58:59], v[58:59], s[86:87] op_sel_hi:[1,0]
	v_pk_fma_f32 v[60:61], v[48:49], v[72:73], v[60:61]
	v_pk_fma_f32 v[58:59], v[46:47], v[70:71], v[58:59]
	s_waitcnt vmcnt(0)
.LBB0_1670:
	v_pk_mul_f32 v[46:47], v[64:65], s[86:87] op_sel_hi:[1,0]
	v_pk_mul_f32 v[62:63], v[62:63], s[86:87] op_sel_hi:[1,0]
	v_pk_fma_f32 v[48:49], v[44:45], v[68:69], v[46:47]
	v_pk_fma_f32 v[46:47], v[42:43], v[66:67], v[62:63]
	s_and_b64 vcc, exec, s[22:23]
	v_lshl_add_u64 v[76:77], v[78:79], 1, s[64:65]
	s_cbranch_vccz .LBB0_1674
	v_cvt_pk_bf16_f32 v42, v58, v59
	v_cvt_pk_bf16_f32 v43, v60, v61
	v_cvt_pk_bf16_f32 v44, v46, v47
	v_cvt_pk_bf16_f32 v45, v48, v49
	s_mov_b64 s[26:27], -1
	s_and_b64 vcc, exec, s[88:89]
	global_store_dwordx4 v[76:77], v[42:45], off
	s_cbranch_vccz .LBB0_1673
	s_nop 0
	s_mov_b64 s[26:27], 0
	s_waitcnt vmcnt(11)
	v_lshlrev_b32_e32 v78, 16, v238
	v_and_b32_e32 v79, 0xffff0000, v238
	v_lshlrev_b32_e32 v42, 16, v239
	v_and_b32_e32 v43, 0xffff0000, v239
	v_pk_mul_f32 v[78:79], v[78:79], s[86:87] op_sel_hi:[1,0]
	v_pk_mul_f32 v[42:43], v[42:43], s[86:87] op_sel_hi:[1,0]
	v_lshlrev_b32_e32 v62, 16, v240
	v_and_b32_e32 v63, 0xffff0000, v240
	v_lshlrev_b32_e32 v64, 16, v241
	v_and_b32_e32 v65, 0xffff0000, v241
	v_pk_fma_f32 v[44:45], v[40:41], v[56:57], v[42:43]
	v_pk_fma_f32 v[42:43], v[38:39], v[54:55], v[78:79]

; __device__ __forceinline__ u32x4 pack8(const f32x4 a, const f32x4 b) { u32x4 w; w.x = cvt_pk_bf16(a[0], a[1]); w.y = cvt_pk_bf16(a[2], a[3]); w.z = cvt_pk_bf16(b[0], b[1]); w.w = cvt_pk_bf16(b[2], b[3]); return w; }
;     __device__ __forceinline__ void operator()(const f32x4 (&acc)[2][2][4][2], const Unit& u, int wr, int wc, int fr, int fq) const {
;     ...
;                 for (int bj = 0; bj < 2; ++bj) { f32x4 o[2];
;                     if (lat && rinB) { const u32x4 w = *(const u32x4*)(rinB + off + bj * 32);
;                         const f32x4 b0 = {__builtin_bit_cast(float, w.x << 16), __builtin_bit_cast(float, w.x & 0xffff0000u), __builtin_bit_cast(float, w.y << 16), __builtin_bit_cast(float, w.y & 0xffff0000u)};
;                         const f32x4 b1 = {__builtin_bit_cast(float, w.z << 16), __builtin_bit_cast(float, w.z & 0xffff0000u), __builtin_bit_cast(float, w.w << 16), __builtin_bit_cast(float, w.w & 0xffff0000u)};
;                         o[0] = b0 * 1.6817928305074290f + gv[bj][0] * acc[ai][bj][m][0]; o[1] = b1 * 1.6817928305074290f + gv[bj][1] * acc[ai][bj][m][1]; }
;                     else {
; #pragma unroll
;                     for (int n = 0; n < 2; ++n) { const f32x4 bs = *(const f32x4*)(ib + off + bj * 32 + n * 4); o[n] = bs * 1.6817928305074290f + gv[bj][n] * acc[ai][bj][m][n]; } }
;                     if (tobf) *(u32x4*)(vout + off + bj * 32) = pack8(o[0], o[1]);
;                     else { *(f32x4*)(ob + off + bj * 32) = o[0]; *(f32x4*)(ob + off + bj * 32 + 4) = o[1]; } }
.LBB0_1676:
	s_andn2_b64 vcc, exec, s[26:27]
	s_cbranch_vccnz .LBB0_1678
	global_load_dwordx4 v[42:45], v[74:75], off offset:128
	global_load_dwordx4 v[62:65], v[74:75], off offset:144
	s_waitcnt vmcnt(1)
	v_pk_mul_f32 v[44:45], v[44:45], s[86:87] op_sel_hi:[1,0]
	v_pk_mul_f32 v[42:43], v[42:43], s[86:87] op_sel_hi:[1,0]
	v_pk_fma_f32 v[44:45], v[40:41], v[56:57], v[44:45]
	v_pk_fma_f32 v[42:43], v[38:39], v[54:55], v[42:43]
	s_waitcnt vmcnt(0)
.LBB0_1678:
	v_pk_mul_f32 v[38:39], v[64:65], s[86:87] op_sel_hi:[1,0]
	v_pk_mul_f32 v[40:41], v[62:63], s[86:87] op_sel_hi:[1,0]
	v_pk_fma_f32 v[36:37], v[36:37], v[52:53], v[38:39]
	v_pk_fma_f32 v[34:35], v[34:35], v[50:51], v[40:41]
	s_mov_b64 s[26:27], -1
	s_and_b64 vcc, exec, s[22:23]
	s_cbranch_vccz .LBB0_1680
	v_cvt_pk_bf16_f32 v38, v42, v43
	v_cvt_pk_bf16_f32 v39, v44, v45
	v_cvt_pk_bf16_f32 v40, v34, v35
	v_cvt_pk_bf16_f32 v41, v36, v37
	global_store_dwordx4 v[76:77], v[38:41], off offset:64
	s_mov_b64 s[26:27], 0

; __device__ __forceinline__ u32x4 pack8(const f32x4 a, const f32x4 b) { u32x4 w; w.x = cvt_pk_bf16(a[0], a[1]); w.y = cvt_pk_bf16(a[2], a[3]); w.z = cvt_pk_bf16(b[0], b[1]); w.w = cvt_pk_bf16(b[2], b[3]); return w; }
;     __device__ __forceinline__ void operator()(const f32x4 (&acc)[2][2][4][2], const Unit& u, int wr, int wc, int fr, int fq) const {
;     ...
; #pragma unroll
;         for (int ai = 0; ai < 2; ++ai)
; #pragma unroll
;             for (int m = 0; m < 4; ++m) { const size_t off = (size_t)(rowb + ai * HALF + m * 16) * 1024 + col0;
; #pragma unroll
;                 for (int bj = 0; bj < 2; ++bj) { f32x4 o[2];
;                     if (lat && rinB) { const u32x4 w = *(const u32x4*)(rinB + off + bj * 32);
;                         const f32x4 b0 = {__builtin_bit_cast(float, w.x << 16), __builtin_bit_cast(float, w.x & 0xffff0000u), __builtin_bit_cast(float, w.y << 16), __builtin_bit_cast(float, w.y & 0xffff0000u)};
;                         const f32x4 b1 = {__builtin_bit_cast(float, w.z << 16), __builtin_bit_cast(float, w.z & 0xffff0000u), __builtin_bit_cast(float, w.w << 16), __builtin_bit_cast(float, w.w & 0xffff0000u)};
;                         o[0] = b0 * 1.6817928305074290f + gv[bj][0] * acc[ai][bj][m][0]; o[1] = b1 * 1.6817928305074290f + gv[bj][1] * acc[ai][bj][m][1]; }
;                     else {
; #pragma unroll
;                     for (int n = 0; n < 2; ++n) { const f32x4 bs = *(const f32x4*)(ib + off + bj * 32 + n * 4); o[n] = bs * 1.6817928305074290f + gv[bj][n] * acc[ai][bj][m][n]; } }
;                     if (tobf) *(u32x4*)(vout + off + bj * 32) = pack8(o[0], o[1]);
;                     else { *(f32x4*)(ob + off + bj * 32) = o[0]; *(f32x4*)(ob + off + bj * 32 + 4) = o[1]; } }
.LBB0_1682:
	s_nop 1
	v_lshlrev_b64 v[34:35], 10, v[180:181]
	v_lshl_add_u64 v[34:35], v[34:35], 0, v[182:183]
	s_mov_b64 s[2:3], 0x28000
	v_lshl_add_u64 v[46:47], v[34:35], 0, s[2:3]
	s_mov_b64 s[26:27], -1
	s_and_b64 vcc, exec, s[28:29]
	s_cbranch_vccnz .LBB0_1684
	s_mov_b64 s[26:27], 0
	s_waitcnt vmcnt(10)
	v_lshlrev_b32_e32 v42, 16, v242
	v_and_b32_e32 v43, 0xffff0000, v242
	v_lshlrev_b32_e32 v34, 16, v243
	v_and_b32_e32 v35, 0xffff0000, v243
	v_pk_mul_f32 v[42:43], v[42:43], s[86:87] op_sel_hi:[1,0]
	v_pk_mul_f32 v[34:35], v[34:35], s[86:87] op_sel_hi:[1,0]
	v_lshlrev_b32_e32 v38, 16, v244
	v_and_b32_e32 v39, 0xffff0000, v244
	v_lshlrev_b32_e32 v40, 16, v245
	v_and_b32_e32 v41, 0xffff0000, v245
	v_pk_fma_f32 v[36:37], v[32:33], v[72:73], v[34:35]
	v_pk_fma_f32 v[34:35], v[30:31], v[70:71], v[42:43]
.LBB0_1684:
	s_andn2_b64 vcc, exec, s[26:27]
	v_lshl_add_u64 v[42:43], v[46:47], 2, s[24:25]
	s_cbranch_vccnz .LBB0_1686
	global_load_dwordx4 v[34:37], v[42:43], off
	global_load_dwordx4 v[38:41], v[42:43], off offset:16
	s_waitcnt vmcnt(1)
	v_pk_mul_f32 v[36:37], v[36:37], s[86:87] op_sel_hi:[1,0]
	v_pk_mul_f32 v[34:35], v[34:35], s[86:87] op_sel_hi:[1,0]
	v_pk_fma_f32 v[36:37], v[32:33], v[72:73], v[36:37]
	v_pk_fma_f32 v[34:35], v[30:31], v[70:71], v[34:35]
	s_waitcnt vmcnt(0)
.LBB0_1686:
	v_pk_mul_f32 v[30:31], v[40:41], s[86:87] op_sel_hi:[1,0]
	v_pk_mul_f32 v[38:39], v[38:39], s[86:87] op_sel_hi:[1,0]
	v_pk_fma_f32 v[32:33], v[28:29], v[68:69], v[30:31]
	v_pk_fma_f32 v[30:31], v[26:27], v[66:67], v[38:39]
	s_and_b64 vcc, exec, s[22:23]
	v_lshl_add_u64 v[44:45], v[46:47], 1, s[64:65]
	s_cbranch_vccz .LBB0_1690
	v_cvt_pk_bf16_f32 v26, v34, v35
	v_cvt_pk_bf16_f32 v27, v36, v37
	v_cvt_pk_bf16_f32 v28, v30, v31
	v_cvt_pk_bf16_f32 v29, v32, v33
	s_mov_b64 s[26:27], -1
	s_and_b64 vcc, exec, s[88:89]
	global_store_dwordx4 v[44:45], v[26:29], off
	s_cbranch_vccz .LBB0_1689
	s_nop 0
	s_mov_b64 s[26:27], 0
	s_waitcnt vmcnt(9)
	v_lshlrev_b32_e32 v46, 16, v246
	v_and_b32_e32 v47, 0xffff0000, v246
	v_lshlrev_b32_e32 v26, 16, v247
	v_and_b32_e32 v27, 0xffff0000, v247
	v_pk_mul_f32 v[46:47], v[46:47], s[86:87] op_sel_hi:[1,0]
	v_pk_mul_f32 v[26:27], v[26:27], s[86:87] op_sel_hi:[1,0]
	v_lshlrev_b32_e32 v38, 16, v248
	v_and_b32_e32 v39, 0xffff0000, v248
	v_lshlrev_b32_e32 v40, 16, v249
	v_and_b32_e32 v41, 0xffff0000, v249
	v_pk_fma_f32 v[28:29], v[24:25], v[56:57], v[26:27]
	v_pk_fma_f32 v[26:27], v[22:23], v[54:55], v[46:47]

; __device__ __forceinline__ u32x4 pack8(const f32x4 a, const f32x4 b) { u32x4 w; w.x = cvt_pk_bf16(a[0], a[1]); w.y = cvt_pk_bf16(a[2], a[3]); w.z = cvt_pk_bf16(b[0], b[1]); w.w = cvt_pk_bf16(b[2], b[3]); return w; }
;     __device__ __forceinline__ void operator()(const f32x4 (&acc)[2][2][4][2], const Unit& u, int wr, int wc, int fr, int fq) const {
;     ...
;                 for (int bj = 0; bj < 2; ++bj) { f32x4 o[2];
;                     if (lat && rinB) { const u32x4 w = *(const u32x4*)(rinB + off + bj * 32);
;                         const f32x4 b0 = {__builtin_bit_cast(float, w.x << 16), __builtin_bit_cast(float, w.x & 0xffff0000u), __builtin_bit_cast(float, w.y << 16), __builtin_bit_cast(float, w.y & 0xffff0000u)};
;                         const f32x4 b1 = {__builtin_bit_cast(float, w.z << 16), __builtin_bit_cast(float, w.z & 0xffff0000u), __builtin_bit_cast(float, w.w << 16), __builtin_bit_cast(float, w.w & 0xffff0000u)};
;                         o[0] = b0 * 1.6817928305074290f + gv[bj][0] * acc[ai][bj][m][0]; o[1] = b1 * 1.6817928305074290f + gv[bj][1] * acc[ai][bj][m][1]; }
;                     else {
; #pragma unroll
;                     for (int n = 0; n < 2; ++n) { const f32x4 bs = *(const f32x4*)(ib + off + bj * 32 + n * 4); o[n] = bs * 1.6817928305074290f + gv[bj][n] * acc[ai][bj][m][n]; } }
;                     if (tobf) *(u32x4*)(vout + off + bj * 32) = pack8(o[0], o[1]);
;                     else { *(f32x4*)(ob + off + bj * 32) = o[0]; *(f32x4*)(ob + off + bj * 32 + 4) = o[1]; } }
.LBB0_1692:
	s_andn2_b64 vcc, exec, s[26:27]
	s_cbranch_vccnz .LBB0_1694
	global_load_dwordx4 v[26:29], v[42:43], off offset:128
	global_load_dwordx4 v[38:41], v[42:43], off offset:144
	s_waitcnt vmcnt(1)
	v_pk_mul_f32 v[28:29], v[28:29], s[86:87] op_sel_hi:[1,0]
	v_pk_mul_f32 v[26:27], v[26:27], s[86:87] op_sel_hi:[1,0]
	v_pk_fma_f32 v[28:29], v[24:25], v[56:57], v[28:29]
	v_pk_fma_f32 v[26:27], v[22:23], v[54:55], v[26:27]
	s_waitcnt vmcnt(0)
.LBB0_1694:
	v_pk_mul_f32 v[22:23], v[40:41], s[86:87] op_sel_hi:[1,0]
	v_pk_mul_f32 v[24:25], v[38:39], s[86:87] op_sel_hi:[1,0]
	v_pk_fma_f32 v[20:21], v[20:21], v[52:53], v[22:23]
	v_pk_fma_f32 v[18:19], v[18:19], v[50:51], v[24:25]
	s_mov_b64 s[26:27], -1
	s_and_b64 vcc, exec, s[22:23]
	s_cbranch_vccz .LBB0_1696
	v_cvt_pk_bf16_f32 v22, v26, v27
	v_cvt_pk_bf16_f32 v23, v28, v29
	v_cvt_pk_bf16_f32 v24, v18, v19
	v_cvt_pk_bf16_f32 v25, v20, v21
	global_store_dwordx4 v[44:45], v[22:25], off offset:64
	s_mov_b64 s[26:27], 0

; __device__ __forceinline__ u32x4 pack8(const f32x4 a, const f32x4 b) { u32x4 w; w.x = cvt_pk_bf16(a[0], a[1]); w.y = cvt_pk_bf16(a[2], a[3]); w.z = cvt_pk_bf16(b[0], b[1]); w.w = cvt_pk_bf16(b[2], b[3]); return w; }
;     __device__ __forceinline__ void operator()(const f32x4 (&acc)[2][2][4][2], const Unit& u, int wr, int wc, int fr, int fq) const {
;     ...
; #pragma unroll
;         for (int ai = 0; ai < 2; ++ai)
; #pragma unroll
;             for (int m = 0; m < 4; ++m) { const size_t off = (size_t)(rowb + ai * HALF + m * 16) * 1024 + col0;
; #pragma unroll
;                 for (int bj = 0; bj < 2; ++bj) { f32x4 o[2];
;                     if (lat && rinB) { const u32x4 w = *(const u32x4*)(rinB + off + bj * 32);
;                         const f32x4 b0 = {__builtin_bit_cast(float, w.x << 16), __builtin_bit_cast(float, w.x & 0xffff0000u), __builtin_bit_cast(float, w.y << 16), __builtin_bit_cast(float, w.y & 0xffff0000u)};
;                         const f32x4 b1 = {__builtin_bit_cast(float, w.z << 16), __builtin_bit_cast(float, w.z & 0xffff0000u), __builtin_bit_cast(float, w.w << 16), __builtin_bit_cast(float, w.w & 0xffff0000u)};
;                         o[0] = b0 * 1.6817928305074290f + gv[bj][0] * acc[ai][bj][m][0]; o[1] = b1 * 1.6817928305074290f + gv[bj][1] * acc[ai][bj][m][1]; }
;                     else {
; #pragma unroll
;                     for (int n = 0; n < 2; ++n) { const f32x4 bs = *(const f32x4*)(ib + off + bj * 32 + n * 4); o[n] = bs * 1.6817928305074290f + gv[bj][n] * acc[ai][bj][m][n]; } }
;                     if (tobf) *(u32x4*)(vout + off + bj * 32) = pack8(o[0], o[1]);
;                     else { *(f32x4*)(ob + off + bj * 32) = o[0]; *(f32x4*)(ob + off + bj * 32 + 4) = o[1]; } }
.LBB0_1698:
	s_nop 1
	v_lshlrev_b64 v[18:19], 10, v[180:181]
	v_lshl_add_u64 v[18:19], v[18:19], 0, v[182:183]
	s_mov_b64 s[2:3], 0x2c000
	v_lshl_add_u64 v[30:31], v[18:19], 0, s[2:3]
	s_mov_b64 s[26:27], -1
	s_and_b64 vcc, exec, s[28:29]
	s_cbranch_vccnz .LBB0_1700
	s_mov_b64 s[26:27], 0
	s_waitcnt vmcnt(8)
	v_lshlrev_b32_e32 v26, 16, v208
	v_and_b32_e32 v27, 0xffff0000, v208
	v_lshlrev_b32_e32 v18, 16, v209
	v_and_b32_e32 v19, 0xffff0000, v209
	v_pk_mul_f32 v[26:27], v[26:27], s[86:87] op_sel_hi:[1,0]
	v_pk_mul_f32 v[18:19], v[18:19], s[86:87] op_sel_hi:[1,0]
	v_lshlrev_b32_e32 v22, 16, v210
	v_and_b32_e32 v23, 0xffff0000, v210
	v_lshlrev_b32_e32 v24, 16, v211
	v_and_b32_e32 v25, 0xffff0000, v211
	v_pk_fma_f32 v[20:21], v[16:17], v[72:73], v[18:19]
	v_pk_fma_f32 v[18:19], v[14:15], v[70:71], v[26:27]
.LBB0_1700:
	s_andn2_b64 vcc, exec, s[26:27]
	v_lshl_add_u64 v[26:27], v[30:31], 2, s[24:25]
	s_cbranch_vccnz .LBB0_1702
	global_load_dwordx4 v[18:21], v[26:27], off
	global_load_dwordx4 v[22:25], v[26:27], off offset:16
	s_waitcnt vmcnt(1)
	v_pk_mul_f32 v[20:21], v[20:21], s[86:87] op_sel_hi:[1,0]
	v_pk_mul_f32 v[18:19], v[18:19], s[86:87] op_sel_hi:[1,0]
	v_pk_fma_f32 v[20:21], v[16:17], v[72:73], v[20:21]
	v_pk_fma_f32 v[18:19], v[14:15], v[70:71], v[18:19]
	s_waitcnt vmcnt(0)
.LBB0_1702:
	v_pk_mul_f32 v[14:15], v[24:25], s[86:87] op_sel_hi:[1,0]
	v_pk_mul_f32 v[22:23], v[22:23], s[86:87] op_sel_hi:[1,0]
	v_pk_fma_f32 v[16:17], v[12:13], v[68:69], v[14:15]
	v_pk_fma_f32 v[14:15], v[10:11], v[66:67], v[22:23]
	s_and_b64 vcc, exec, s[22:23]
	v_lshl_add_u64 v[28:29], v[30:31], 1, s[64:65]
	s_cbranch_vccz .LBB0_1706
	v_cvt_pk_bf16_f32 v10, v18, v19
	v_cvt_pk_bf16_f32 v11, v20, v21
	v_cvt_pk_bf16_f32 v12, v14, v15
	v_cvt_pk_bf16_f32 v13, v16, v17
	s_mov_b64 s[24:25], -1
	s_and_b64 vcc, exec, s[88:89]
	global_store_dwordx4 v[28:29], v[10:13], off
	s_cbranch_vccz .LBB0_1705
	s_nop 0
	s_mov_b64 s[24:25], 0
	s_waitcnt vmcnt(7)
	v_lshlrev_b32_e32 v30, 16, v226
	v_and_b32_e32 v31, 0xffff0000, v226
	v_lshlrev_b32_e32 v10, 16, v227
	v_and_b32_e32 v11, 0xffff0000, v227
	v_pk_mul_f32 v[30:31], v[30:31], s[86:87] op_sel_hi:[1,0]
	v_pk_mul_f32 v[10:11], v[10:11], s[86:87] op_sel_hi:[1,0]
	v_lshlrev_b32_e32 v22, 16, v228
	v_and_b32_e32 v23, 0xffff0000, v228
	v_lshlrev_b32_e32 v24, 16, v229
	v_and_b32_e32 v25, 0xffff0000, v229
	v_pk_fma_f32 v[12:13], v[8:9], v[56:57], v[10:11]
	v_pk_fma_f32 v[10:11], v[6:7], v[54:55], v[30:31]

; __device__ __forceinline__ u32x4 pack8(const f32x4 a, const f32x4 b) { u32x4 w; w.x = cvt_pk_bf16(a[0], a[1]); w.y = cvt_pk_bf16(a[2], a[3]); w.z = cvt_pk_bf16(b[0], b[1]); w.w = cvt_pk_bf16(b[2], b[3]); return w; }
;     __device__ __forceinline__ void operator()(const f32x4 (&acc)[2][2][4][2], const Unit& u, int wr, int wc, int fr, int fq) const {
;     ...
;                 for (int bj = 0; bj < 2; ++bj) { f32x4 o[2];
;                     if (lat && rinB) { const u32x4 w = *(const u32x4*)(rinB + off + bj * 32);
;                         const f32x4 b0 = {__builtin_bit_cast(float, w.x << 16), __builtin_bit_cast(float, w.x & 0xffff0000u), __builtin_bit_cast(float, w.y << 16), __builtin_bit_cast(float, w.y & 0xffff0000u)};
;                         const f32x4 b1 = {__builtin_bit_cast(float, w.z << 16), __builtin_bit_cast(float, w.z & 0xffff0000u), __builtin_bit_cast(float, w.w << 16), __builtin_bit_cast(float, w.w & 0xffff0000u)};
;                         o[0] = b0 * 1.6817928305074290f + gv[bj][0] * acc[ai][bj][m][0]; o[1] = b1 * 1.6817928305074290f + gv[bj][1] * acc[ai][bj][m][1]; }
;                     else {
; #pragma unroll
;                     for (int n = 0; n < 2; ++n) { const f32x4 bs = *(const f32x4*)(ib + off + bj * 32 + n * 4); o[n] = bs * 1.6817928305074290f + gv[bj][n] * acc[ai][bj][m][n]; } }
;                     if (tobf) *(u32x4*)(vout + off + bj * 32) = pack8(o[0], o[1]);
;                     else { *(f32x4*)(ob + off + bj * 32) = o[0]; *(f32x4*)(ob + off + bj * 32 + 4) = o[1]; } }
.LBB0_1708:
	s_andn2_b64 vcc, exec, s[24:25]
	s_cbranch_vccnz .LBB0_1710
	global_load_dwordx4 v[10:13], v[26:27], off offset:128
	global_load_dwordx4 v[22:25], v[26:27], off offset:144
	s_waitcnt vmcnt(1)
	v_pk_mul_f32 v[12:13], v[12:13], s[86:87] op_sel_hi:[1,0]
	v_pk_mul_f32 v[10:11], v[10:11], s[86:87] op_sel_hi:[1,0]
	v_pk_fma_f32 v[12:13], v[8:9], v[56:57], v[12:13]
	v_pk_fma_f32 v[10:11], v[6:7], v[54:55], v[10:11]
	s_waitcnt vmcnt(0)
.LBB0_1710:
	v_pk_mul_f32 v[6:7], v[24:25], s[86:87] op_sel_hi:[1,0]
	v_pk_mul_f32 v[8:9], v[22:23], s[86:87] op_sel_hi:[1,0]
	v_pk_fma_f32 v[4:5], v[4:5], v[52:53], v[6:7]
	v_pk_fma_f32 v[2:3], v[2:3], v[50:51], v[8:9]
	s_mov_b64 s[24:25], -1
	s_and_b64 vcc, exec, s[22:23]
	s_cbranch_vccz .LBB0_1713
	v_cvt_pk_bf16_f32 v6, v10, v11
	v_cvt_pk_bf16_f32 v7, v12, v13
	v_cvt_pk_bf16_f32 v8, v2, v3
	v_cvt_pk_bf16_f32 v9, v4, v5
	global_store_dwordx4 v[28:29], v[6:9], off offset:64
	s_cbranch_execz .LBB0_1714
